# v20 + sc0 cache policy on GEMM LDS-DMA loads
# baseline (speedup 1.0000x reference)
.LBB0_206:
	v_lshrrev_b32_e32 v4, 1, v0
	v_and_b32_e32 v15, 24, v4
	v_lshrrev_b32_e32 v4, 5, v0
	s_add_u32 s2, s82, 0x400000
	v_lshlrev_b32_e32 v2, 4, v0
	v_and_b32_e32 v3, 32, v0
	v_and_b32_e32 v4, 4, v4
	v_bfe_u32 v5, v0, 2, 2
	s_addc_u32 s3, s83, 0
	v_bfe_u32 v14, v0, 2, 4
	v_bitop3_b32 v12, v2, v3, 48 bitop3:0x6c
	v_and_b32_e32 v13, 64, v0
	v_or3_b32 v4, v4, v5, v15
	v_lshrrev_b32_e32 v5, 3, v0
	s_ashr_i32 s20, s17, 31
	v_or_b32_e32 v3, v12, v13
	v_and_or_b32 v6, v5, 48, v14
	v_and_or_b32 v5, v5, 32, v4
	v_or_b32_e32 v16, 0x2000, v2
	s_lshr_b32 s20, s20, 29
	v_lshl_or_b32 v132, v5, 12, v3
	v_lshrrev_b32_e32 v5, 7, v16
	s_movk_i32 s16, 0x70
	s_add_i32 s20, s17, s20
	v_lshl_or_b32 v130, v6, 12, v3
	v_and_or_b32 v6, v5, s16, v14
	s_lshr_b32 s16, s18, 6
	s_ashr_i32 s21, s20, 3
	s_and_b32 s20, s20, -8
	s_lshr_b32 s7, s18, 8
	s_lshl_b32 s33, s16, 10
	s_sub_i32 s17, s17, s20
	s_cmp_lt_i32 s17, 0
	s_movk_i32 s46, 0x109
	s_cselect_b32 s20, s46, 0x108
	s_mul_i32 s17, s20, s17
	s_add_i32 s17, s17, s21
	s_mul_hi_i32 s20, s17, 0x2e8ba2e9
	s_lshr_b32 s21, s20, 31
	s_ashr_i32 s20, s20, 6
	s_add_i32 s20, s20, s21
	s_lshl_b32 s21, s20, 3
	s_sub_i32 s22, 48, s21
	s_min_i32 s22, s22, 8
	s_abs_i32 s23, s22
	v_cvt_f32_u32_e32 v7, s23
	s_movk_i32 s19, 0x60
	v_and_or_b32 v4, v5, s19, v4
	v_lshl_or_b32 v134, v6, 12, v3
	v_lshl_or_b32 v136, v4, 12, v3
	v_rcp_iflag_f32_e32 v3, v7
	s_sub_i32 s24, 0, s23
	s_mulk_i32 s20, 0x160
	s_sub_i32 s17, s17, s20
	v_mul_f32_e32 v3, 0x4f7ffffe, v3
	v_cvt_u32_f32_e32 v3, v3
	s_abs_i32 s20, s17
	s_xor_b32 s19, s17, s22
	s_ashr_i32 s19, s19, 31
	v_readfirstlane_b32 s25, v3
	s_mul_i32 s24, s24, s25
	s_mul_hi_u32 s24, s25, s24
	s_add_i32 s25, s25, s24
	s_mul_hi_u32 s24, s20, s25
	s_mul_i32 s25, s24, s23
	s_sub_i32 s20, s20, s25
	s_add_i32 s25, s24, 1
	s_sub_i32 s26, s20, s23
	s_cmp_ge_u32 s20, s23
	s_cselect_b32 s24, s25, s24
	s_cselect_b32 s20, s26, s20
	s_add_i32 s25, s24, 1
	s_cmp_ge_u32 s20, s23
	s_cselect_b32 s20, s25, s24
	s_xor_b32 s20, s20, s19
	s_sub_i32 s34, s20, s19
	s_mul_i32 s19, s34, s22
	s_sub_i32 s17, s17, s19
	s_add_i32 s30, s21, s17
	s_ashr_i32 s31, s30, 31
	s_lshl_b64 s[20:21], s[30:31], 20
	v_readlane_b32 s22, v249, 50
	v_readlane_b32 s23, v249, 51
	s_add_u32 s17, s22, s20
	s_addc_u32 s19, s23, s21
	s_ashr_i32 s35, s34, 31
	s_lshl_b64 s[20:21], s[34:35], 20
	s_add_u32 s20, s2, s20
	s_addc_u32 s21, s3, s21
	s_add_u32 s40, s20, s12
	s_addc_u32 s41, s21, s13
	s_add_i32 s35, s33, 0
	s_add_i32 m0, s35, 0x10000
	v_mov_b32_e32 v133, 0
	global_load_lds_dwordx4 v132, s[40:41] sc0
	s_add_i32 m0, s35, 0x12000
	s_add_u32 s20, s40, 0x80000
	global_load_lds_dwordx4 v136, s[40:41] sc0
	s_addc_u32 s21, s41, 0
	s_add_i32 m0, s35, 0x14000
	v_mov_b32_e32 v137, v133
	global_load_lds_dwordx4 v132, s[20:21] sc0
	s_add_i32 m0, s35, 0x16000
	s_add_u32 s38, s17, s12
	s_addc_u32 s39, s19, s13
	s_add_i32 s47, s35, 0x2000
	global_load_lds_dwordx4 v136, s[20:21] sc0
	s_mov_b32 m0, s35
	s_add_u32 s12, s38, 0x80000
	global_load_lds_dwordx4 v130, s[38:39] sc0
	s_mov_b32 m0, s47
	s_addc_u32 s13, s39, 0
	s_add_i32 s48, s35, 0x4000
	global_load_lds_dwordx4 v134, s[38:39] sc0
	s_mov_b32 m0, s48
	s_add_i32 s49, s35, 0x6000
	global_load_lds_dwordx4 v130, s[12:13] sc0
	s_mov_b32 m0, s49
	v_mov_b32_e32 v131, v133
	global_load_lds_dwordx4 v134, s[12:13] sc0
	v_mov_b32_e32 v135, v133
	s_cmp_eq_u32 s7, 1
	v_lshl_add_u64 v[8:9], s[40:41], 0, v[132:133]
	v_lshl_add_u64 v[4:5], s[40:41], 0, v[136:137]
	v_lshl_add_u64 v[6:7], s[38:39], 0, v[130:131]
	s_cselect_b64 s[12:13], -1, 0
	s_cmp_lg_u32 s7, 1
	v_lshl_add_u64 v[10:11], s[38:39], 0, v[134:135]
	s_cbranch_scc1 .LBB0_208
	s_barrier
.LBB0_208:
	s_lshl_b32 s16, s16, 5
	s_and_b32 s22, s16, 0x60
	s_mov_b64 s[16:17], 0x80
	s_add_i32 m0, s35, 0x18000
	v_lshl_add_u64 v[8:9], v[8:9], 0, s[16:17]
	s_lshl_b32 s19, s7, 13
	s_lshl_b32 s23, s22, 7
	s_waitcnt vmcnt(2)
	s_barrier
	global_load_lds_dwordx4 v[8:9], off sc0
	v_lshl_add_u64 v[4:5], v[4:5], 0, s[16:17]
	s_add_i32 m0, s35, 0x1a000
	s_add_i32 s50, s35, 0x8000
	s_add_i32 s51, s35, 0xa000
	global_load_lds_dwordx4 v[4:5], off sc0
	v_lshl_add_u64 v[4:5], v[6:7], 0, s[16:17]
	s_mov_b32 m0, s50
	s_add_u32 s20, s40, 0x80080
	global_load_lds_dwordx4 v[4:5], off sc0
	v_lshl_add_u64 v[4:5], v[10:11], 0, s[16:17]
	s_mov_b32 m0, s51
	s_addc_u32 s21, s41, 0
	global_load_lds_dwordx4 v[4:5], off sc0
	s_add_i32 m0, s35, 0x1c000
	v_lshl_add_u64 v[4:5], s[20:21], 0, v[132:133]
	global_load_lds_dwordx4 v[4:5], off sc0
	v_lshl_add_u64 v[4:5], s[20:21], 0, v[136:137]
	s_add_i32 m0, s35, 0x1e000
	v_and_b32_e32 v3, 15, v0
	global_load_lds_dwordx4 v[4:5], off sc0
	v_lshlrev_b32_e32 v4, 1, v15
	v_lshlrev_b32_e32 v5, 2, v0
	v_lshl_or_b32 v146, s7, 6, v3
	v_lshl_or_b32 v3, v3, 6, v4
	v_and_b32_e32 v5, 32, v5
	v_bitop3_b32 v6, v3, s19, v5 bitop3:0xde
	v_lshlrev_b32_e32 v3, 6, v0
	s_movk_i32 s7, 0x3c0
	v_readlane_b32 s21, v249, 0
	v_and_or_b32 v3, v3, s7, v4
	s_ashr_i32 s19, s21, 31
	v_bitop3_b32 v147, s23, v3, v5 bitop3:0xf6
	s_lshr_b32 s19, s19, 26
	v_mov_b32_e32 v3, v133
	s_add_i32 s19, s21, s19
	v_lshl_add_u64 v[138:139], s[78:79], 0, v[2:3]
	v_lshlrev_b32_e32 v2, 9, v0
	s_and_b32 s20, s19, 0xffffffc0
	v_and_b32_e32 v2, 0x30000, v2
	v_lshlrev_b32_e32 v3, 12, v14
	s_sub_i32 s52, s21, s20
	s_ashr_i32 s19, s19, 6
	v_or3_b32 v2, v12, v2, v3
	s_addk_i32 s52, 0x800
	s_lshl_b32 s53, s19, 3
	v_add_u32_e32 v140, v2, v13
	v_lshlrev_b32_e32 v2, 5, v16
	s_waitcnt vmcnt(6)
	s_cmpk_lt_u32 s18, 0x100
	v_and_b32_e32 v2, 0x70000, v2
	s_mov_b32 s7, 0
	s_cselect_b64 s[18:19], -1, 0
	v_or3_b32 v2, v12, v2, v3
	s_add_i32 s54, 0, 0x10000
	s_add_i32 s55, 0, 0x14000
	v_or_b32_e32 v148, s22, v15
	v_mov_b32_e32 v141, v133
	v_add_u32_e32 v142, v2, v13
	v_mov_b32_e32 v143, v133
	v_add_u32_e32 v149, s54, v147
	v_add_u32_e32 v150, s55, v147
	v_add_u32_e32 v151, 0, v6
	s_mov_b32 s56, 0xc000
	s_mov_b32 s57, 0xe000
	s_movk_i32 s58, 0x2c00
	s_mov_b32 s31, s7
	s_barrier
	s_branch .LBB0_211

.Lpeel_13:
	ds_read_b128 v[152:155], v149
	ds_read_b128 v[156:159], v149 offset:1024
	ds_read_b128 v[160:163], v149 offset:2048
	ds_read_b128 v[164:167], v149 offset:3072
	ds_read_b128 v[168:171], v150
	ds_read_b128 v[172:175], v150 offset:1024
	ds_read_b128 v[176:179], v150 offset:2048
	ds_read_b128 v[180:183], v150 offset:3072
	s_add_i32 s37, s25, 2
	s_add_u32 s40, s38, 0xfff80080
	s_addc_u32 s41, s39, -1
	s_cmp_eq_u32 s36, s25
	s_cselect_b32 s43, s27, s41
	s_cselect_b32 s42, s26, s40
	s_cselect_b32 s41, s29, s23
	s_cselect_b32 s40, s28, s21
	v_lshl_add_u64 v[144:145], s[38:39], 0, v[140:141]
	s_add_i32 m0, s35, 0xc000
	ds_read_b128 v[184:187], v151
	ds_read_b128 v[188:191], v151 offset:1024
	ds_read_b128 v[196:199], v151 offset:2048
	ds_read_b128 v[200:203], v151 offset:3072
	ds_read_b128 v[204:207], v151 offset:4096
	ds_read_b128 v[208:211], v151 offset:5120
	ds_read_b128 v[212:215], v151 offset:6144
	ds_read_b128 v[216:219], v151 offset:7168
	global_load_lds_dwordx4 v[144:145], off sc0
	v_lshl_add_u64 v[144:145], s[38:39], 0, v[142:143]
	s_add_i32 m0, s35, 0xe000
	s_nop 0
	global_load_lds_dwordx4 v[144:145], off sc0
	s_waitcnt vmcnt(8)
	s_waitcnt lgkmcnt(0)
	s_barrier
	s_setprio 1
	s_waitcnt lgkmcnt(0)
	v_mfma_f32_16x16x32_bf16 v[126:129], v[152:155], v[184:187], 0
	v_mfma_f32_16x16x32_bf16 v[122:125], v[160:163], v[184:187], 0
	v_mfma_f32_16x16x32_bf16 v[110:113], v[152:155], v[196:199], 0
	v_mfma_f32_16x16x32_bf16 v[106:109], v[160:163], v[196:199], 0
	v_mfma_f32_16x16x32_bf16 v[94:97], v[152:155], v[204:207], 0
	v_mfma_f32_16x16x32_bf16 v[90:93], v[160:163], v[204:207], 0
	v_mfma_f32_16x16x32_bf16 v[78:81], v[152:155], v[212:215], 0
	v_mfma_f32_16x16x32_bf16 v[74:77], v[160:163], v[212:215], 0
	v_mfma_f32_16x16x32_bf16 v[126:129], v[156:159], v[188:191], v[126:129]
	v_mfma_f32_16x16x32_bf16 v[122:125], v[164:167], v[188:191], v[122:125]
	v_mfma_f32_16x16x32_bf16 v[110:113], v[156:159], v[200:203], v[110:113]
	v_mfma_f32_16x16x32_bf16 v[106:109], v[164:167], v[200:203], v[106:109]
	v_mfma_f32_16x16x32_bf16 v[94:97], v[156:159], v[208:211], v[94:97]
	v_mfma_f32_16x16x32_bf16 v[90:93], v[164:167], v[208:211], v[90:93]
	v_mfma_f32_16x16x32_bf16 v[78:81], v[156:159], v[216:219], v[78:81]
	v_mfma_f32_16x16x32_bf16 v[74:77], v[164:167], v[216:219], v[74:77]
	s_setprio 0
	s_setprio 1
	v_mfma_f32_16x16x32_bf16 v[118:121], v[168:171], v[184:187], 0
	v_mfma_f32_16x16x32_bf16 v[114:117], v[176:179], v[184:187], 0
	v_mfma_f32_16x16x32_bf16 v[102:105], v[168:171], v[196:199], 0
	v_mfma_f32_16x16x32_bf16 v[98:101], v[176:179], v[196:199], 0
	v_mfma_f32_16x16x32_bf16 v[86:89], v[168:171], v[204:207], 0
	v_mfma_f32_16x16x32_bf16 v[82:85], v[176:179], v[204:207], 0
	v_mfma_f32_16x16x32_bf16 v[70:73], v[168:171], v[212:215], 0
	v_mfma_f32_16x16x32_bf16 v[66:69], v[176:179], v[212:215], 0
	v_mfma_f32_16x16x32_bf16 v[118:121], v[172:175], v[188:191], v[118:121]
	v_mfma_f32_16x16x32_bf16 v[114:117], v[180:183], v[188:191], v[114:117]
	v_mfma_f32_16x16x32_bf16 v[102:105], v[172:175], v[200:203], v[102:105]
	v_mfma_f32_16x16x32_bf16 v[98:101], v[180:183], v[200:203], v[98:101]
	v_mfma_f32_16x16x32_bf16 v[86:89], v[172:175], v[208:211], v[86:89]
	v_mfma_f32_16x16x32_bf16 v[82:85], v[180:183], v[208:211], v[82:85]
	v_mfma_f32_16x16x32_bf16 v[70:73], v[172:175], v[216:219], v[70:73]
	v_mfma_f32_16x16x32_bf16 v[66:69], v[180:183], v[216:219], v[66:69]
	s_setprio 0
	s_barrier
	s_add_i32 s25, s54, s33
	v_lshl_add_u64 v[144:145], s[40:41], 0, v[132:133]
	s_mov_b32 m0, s25
	ds_read_b128 v[184:187], v151 offset:16384
	ds_read_b128 v[188:191], v151 offset:17408
	ds_read_b128 v[196:199], v151 offset:18432
	ds_read_b128 v[200:203], v151 offset:19456
	ds_read_b128 v[204:207], v151 offset:20480
	ds_read_b128 v[208:211], v151 offset:21504
	ds_read_b128 v[212:215], v151 offset:22528
	ds_read_b128 v[216:219], v151 offset:23552
	global_load_lds_dwordx4 v[144:145], off sc0
	s_add_i32 m0, s25, 0x2000
	s_add_u32 s44, s40, 0x80000
	v_lshl_add_u64 v[192:193], s[40:41], 0, v[136:137]
	s_addc_u32 s45, s41, 0
	s_add_i32 s25, s55, s33
	global_load_lds_dwordx4 v[192:193], off sc0
	v_lshl_add_u64 v[220:221], s[44:45], 0, v[132:133]
	s_mov_b32 m0, s25
	v_lshl_add_u64 v[222:223], s[42:43], 0, v[134:135]
	global_load_lds_dwordx4 v[220:221], off sc0
	v_lshl_add_u64 v[220:221], s[44:45], 0, v[136:137]
	s_add_i32 m0, s25, 0x2000
	s_nop 0
	global_load_lds_dwordx4 v[220:221], off sc0
	v_lshl_add_u64 v[220:221], s[42:43], 0, v[130:131]
	s_mov_b32 m0, s35
	s_nop 0
	global_load_lds_dwordx4 v[220:221], off sc0
	s_mov_b32 m0, s47
	s_nop 0
	global_load_lds_dwordx4 v[222:223], off sc0
	s_waitcnt vmcnt(8)
	s_waitcnt lgkmcnt(0)
	s_barrier
	s_setprio 1
	s_waitcnt lgkmcnt(0)
	v_mfma_f32_16x16x32_bf16 v[62:65], v[152:155], v[184:187], 0
	v_mfma_f32_16x16x32_bf16 v[58:61], v[160:163], v[184:187], 0
	v_mfma_f32_16x16x32_bf16 v[46:49], v[152:155], v[196:199], 0
	v_mfma_f32_16x16x32_bf16 v[42:45], v[160:163], v[196:199], 0
	v_mfma_f32_16x16x32_bf16 v[30:33], v[152:155], v[204:207], 0
	v_mfma_f32_16x16x32_bf16 v[26:29], v[160:163], v[204:207], 0
	v_mfma_f32_16x16x32_bf16 v[14:17], v[152:155], v[212:215], 0
	v_mfma_f32_16x16x32_bf16 v[10:13], v[160:163], v[212:215], 0
	v_mfma_f32_16x16x32_bf16 v[62:65], v[156:159], v[188:191], v[62:65]
	v_mfma_f32_16x16x32_bf16 v[58:61], v[164:167], v[188:191], v[58:61]
	v_mfma_f32_16x16x32_bf16 v[46:49], v[156:159], v[200:203], v[46:49]
	v_mfma_f32_16x16x32_bf16 v[42:45], v[164:167], v[200:203], v[42:45]
	v_mfma_f32_16x16x32_bf16 v[30:33], v[156:159], v[208:211], v[30:33]
	v_mfma_f32_16x16x32_bf16 v[26:29], v[164:167], v[208:211], v[26:29]
	v_mfma_f32_16x16x32_bf16 v[14:17], v[156:159], v[216:219], v[14:17]
	v_mfma_f32_16x16x32_bf16 v[10:13], v[164:167], v[216:219], v[10:13]
	s_setprio 0
	s_setprio 1
	v_mfma_f32_16x16x32_bf16 v[54:57], v[168:171], v[184:187], 0
	v_mfma_f32_16x16x32_bf16 v[50:53], v[176:179], v[184:187], 0
	v_mfma_f32_16x16x32_bf16 v[38:41], v[168:171], v[196:199], 0
	v_mfma_f32_16x16x32_bf16 v[34:37], v[176:179], v[196:199], 0
	v_mfma_f32_16x16x32_bf16 v[22:25], v[168:171], v[204:207], 0
	v_mfma_f32_16x16x32_bf16 v[18:21], v[176:179], v[204:207], 0
	v_mfma_f32_16x16x32_bf16 v[6:9], v[168:171], v[212:215], 0
	v_mfma_f32_16x16x32_bf16 v[2:5], v[176:179], v[212:215], 0
	v_mfma_f32_16x16x32_bf16 v[54:57], v[172:175], v[188:191], v[54:57]
	v_mfma_f32_16x16x32_bf16 v[50:53], v[180:183], v[188:191], v[50:53]
	v_mfma_f32_16x16x32_bf16 v[38:41], v[172:175], v[200:203], v[38:41]
	v_mfma_f32_16x16x32_bf16 v[34:37], v[180:183], v[200:203], v[34:37]
	v_mfma_f32_16x16x32_bf16 v[22:25], v[172:175], v[208:211], v[22:25]
	v_mfma_f32_16x16x32_bf16 v[18:21], v[180:183], v[208:211], v[18:21]
	v_mfma_f32_16x16x32_bf16 v[6:9], v[172:175], v[216:219], v[6:9]
	v_mfma_f32_16x16x32_bf16 v[2:5], v[180:183], v[216:219], v[2:5]
	s_setprio 0
	s_barrier
	s_add_i32 s25, 0, 0x18000
	s_add_i32 s44, 0, 0x1c000
	v_add_u32_e32 v164, s25, v147
	v_add_u32_e32 v180, s44, v147
	ds_read_b128 v[152:155], v164
	ds_read_b128 v[156:159], v164 offset:1024
	ds_read_b128 v[160:163], v164 offset:2048
	ds_read_b128 v[164:167], v164 offset:3072
	ds_read_b128 v[168:171], v180
	ds_read_b128 v[172:175], v180 offset:1024
	ds_read_b128 v[176:179], v180 offset:2048
	ds_read_b128 v[180:183], v180 offset:3072
	s_add_u32 s42, s42, 0x80000
	s_addc_u32 s43, s43, 0
	s_mov_b32 m0, s48
	v_lshl_add_u64 v[224:225], s[42:43], 0, v[130:131]
	ds_read_b128 v[184:187], v151 offset:32768
	ds_read_b128 v[188:191], v151 offset:33792
	ds_read_b128 v[196:199], v151 offset:34816
	ds_read_b128 v[200:203], v151 offset:35840
	ds_read_b128 v[204:207], v151 offset:36864
	ds_read_b128 v[208:211], v151 offset:37888
	ds_read_b128 v[212:215], v151 offset:38912
	ds_read_b128 v[216:219], v151 offset:39936
	global_load_lds_dwordx4 v[224:225], off sc0
	v_lshl_add_u64 v[224:225], s[42:43], 0, v[134:135]
	s_mov_b32 m0, s49
	s_nop 0
	global_load_lds_dwordx4 v[224:225], off sc0
	s_waitcnt vmcnt(8)
	s_waitcnt lgkmcnt(0)
	s_barrier
	s_setprio 1
	s_waitcnt lgkmcnt(0)
	v_mfma_f32_16x16x32_bf16 v[126:129], v[152:155], v[184:187], v[126:129]
	v_mfma_f32_16x16x32_bf16 v[122:125], v[160:163], v[184:187], v[122:125]
	v_mfma_f32_16x16x32_bf16 v[110:113], v[152:155], v[196:199], v[110:113]
	v_mfma_f32_16x16x32_bf16 v[106:109], v[160:163], v[196:199], v[106:109]
	v_mfma_f32_16x16x32_bf16 v[94:97], v[152:155], v[204:207], v[94:97]
	v_mfma_f32_16x16x32_bf16 v[90:93], v[160:163], v[204:207], v[90:93]
	v_mfma_f32_16x16x32_bf16 v[78:81], v[152:155], v[212:215], v[78:81]
	v_mfma_f32_16x16x32_bf16 v[74:77], v[160:163], v[212:215], v[74:77]
	v_mfma_f32_16x16x32_bf16 v[126:129], v[156:159], v[188:191], v[126:129]
	v_mfma_f32_16x16x32_bf16 v[122:125], v[164:167], v[188:191], v[122:125]
	v_mfma_f32_16x16x32_bf16 v[110:113], v[156:159], v[200:203], v[110:113]
	v_mfma_f32_16x16x32_bf16 v[106:109], v[164:167], v[200:203], v[106:109]
	v_mfma_f32_16x16x32_bf16 v[94:97], v[156:159], v[208:211], v[94:97]
	v_mfma_f32_16x16x32_bf16 v[90:93], v[164:167], v[208:211], v[90:93]
	v_mfma_f32_16x16x32_bf16 v[78:81], v[156:159], v[216:219], v[78:81]
	v_mfma_f32_16x16x32_bf16 v[74:77], v[164:167], v[216:219], v[74:77]
	s_setprio 0
	s_setprio 1
	v_mfma_f32_16x16x32_bf16 v[118:121], v[168:171], v[184:187], v[118:121]
	v_mfma_f32_16x16x32_bf16 v[114:117], v[176:179], v[184:187], v[114:117]
	v_mfma_f32_16x16x32_bf16 v[102:105], v[168:171], v[196:199], v[102:105]
	v_mfma_f32_16x16x32_bf16 v[98:101], v[176:179], v[196:199], v[98:101]
	v_mfma_f32_16x16x32_bf16 v[86:89], v[168:171], v[204:207], v[86:89]
	v_mfma_f32_16x16x32_bf16 v[82:85], v[176:179], v[204:207], v[82:85]
	v_mfma_f32_16x16x32_bf16 v[70:73], v[168:171], v[212:215], v[70:73]
	v_mfma_f32_16x16x32_bf16 v[66:69], v[176:179], v[212:215], v[66:69]
	v_mfma_f32_16x16x32_bf16 v[118:121], v[172:175], v[188:191], v[118:121]
	v_mfma_f32_16x16x32_bf16 v[114:117], v[180:183], v[188:191], v[114:117]
	v_mfma_f32_16x16x32_bf16 v[102:105], v[172:175], v[200:203], v[102:105]
	v_mfma_f32_16x16x32_bf16 v[98:101], v[180:183], v[200:203], v[98:101]
	v_mfma_f32_16x16x32_bf16 v[86:89], v[172:175], v[208:211], v[86:89]
	v_mfma_f32_16x16x32_bf16 v[82:85], v[180:183], v[208:211], v[82:85]
	v_mfma_f32_16x16x32_bf16 v[70:73], v[172:175], v[216:219], v[70:73]
	v_mfma_f32_16x16x32_bf16 v[66:69], v[180:183], v[216:219], v[66:69]
	s_setprio 0
	s_barrier
	s_add_i32 s25, s25, s33
	v_lshl_add_u64 v[144:145], v[144:145], 0, s[16:17]
	s_mov_b32 m0, s25
	ds_read_b128 v[184:187], v151 offset:49152
	ds_read_b128 v[188:191], v151 offset:50176
	ds_read_b128 v[196:199], v151 offset:51200
	ds_read_b128 v[200:203], v151 offset:52224
	ds_read_b128 v[204:207], v151 offset:53248
	ds_read_b128 v[208:211], v151 offset:54272
	ds_read_b128 v[212:215], v151 offset:55296
	ds_read_b128 v[216:219], v151 offset:56320
	global_load_lds_dwordx4 v[144:145], off sc0
	s_add_i32 m0, s25, 0x2000
	s_add_u32 s40, s40, 0x80080
	v_lshl_add_u64 v[144:145], v[192:193], 0, s[16:17]
	s_addc_u32 s41, s41, 0
	s_add_i32 s25, s44, s33
	global_load_lds_dwordx4 v[144:145], off sc0
	v_lshl_add_u64 v[144:145], s[40:41], 0, v[132:133]
	s_mov_b32 m0, s25
	s_nop 0
	global_load_lds_dwordx4 v[144:145], off sc0
	v_lshl_add_u64 v[144:145], s[40:41], 0, v[136:137]
	s_add_i32 m0, s25, 0x2000
	s_nop 0
	global_load_lds_dwordx4 v[144:145], off sc0
	v_lshl_add_u64 v[144:145], v[220:221], 0, s[16:17]
	s_mov_b32 m0, s50
	s_nop 0
	global_load_lds_dwordx4 v[144:145], off sc0
	v_lshl_add_u64 v[144:145], v[222:223], 0, s[16:17]
	s_mov_b32 m0, s51
	s_nop 0
	global_load_lds_dwordx4 v[144:145], off sc0
	s_waitcnt vmcnt(8)
	s_waitcnt lgkmcnt(0)
	s_barrier
	s_setprio 1
	s_waitcnt lgkmcnt(0)
	v_mfma_f32_16x16x32_bf16 v[62:65], v[152:155], v[184:187], v[62:65]
	v_mfma_f32_16x16x32_bf16 v[58:61], v[160:163], v[184:187], v[58:61]
	v_mfma_f32_16x16x32_bf16 v[46:49], v[152:155], v[196:199], v[46:49]
	v_mfma_f32_16x16x32_bf16 v[42:45], v[160:163], v[196:199], v[42:45]
	v_mfma_f32_16x16x32_bf16 v[30:33], v[152:155], v[204:207], v[30:33]
	v_mfma_f32_16x16x32_bf16 v[26:29], v[160:163], v[204:207], v[26:29]
	v_mfma_f32_16x16x32_bf16 v[14:17], v[152:155], v[212:215], v[14:17]
	v_mfma_f32_16x16x32_bf16 v[10:13], v[160:163], v[212:215], v[10:13]
	v_mfma_f32_16x16x32_bf16 v[62:65], v[156:159], v[188:191], v[62:65]
	v_mfma_f32_16x16x32_bf16 v[58:61], v[164:167], v[188:191], v[58:61]
	v_mfma_f32_16x16x32_bf16 v[46:49], v[156:159], v[200:203], v[46:49]
	v_mfma_f32_16x16x32_bf16 v[42:45], v[164:167], v[200:203], v[42:45]
	v_mfma_f32_16x16x32_bf16 v[30:33], v[156:159], v[208:211], v[30:33]
	v_mfma_f32_16x16x32_bf16 v[26:29], v[164:167], v[208:211], v[26:29]
	v_mfma_f32_16x16x32_bf16 v[14:17], v[156:159], v[216:219], v[14:17]
	v_mfma_f32_16x16x32_bf16 v[10:13], v[164:167], v[216:219], v[10:13]
	s_setprio 0
	s_setprio 1
	v_mfma_f32_16x16x32_bf16 v[54:57], v[168:171], v[184:187], v[54:57]
	v_mfma_f32_16x16x32_bf16 v[50:53], v[176:179], v[184:187], v[50:53]
	v_mfma_f32_16x16x32_bf16 v[38:41], v[168:171], v[196:199], v[38:41]
	v_mfma_f32_16x16x32_bf16 v[34:37], v[176:179], v[196:199], v[34:37]
	v_mfma_f32_16x16x32_bf16 v[22:25], v[168:171], v[204:207], v[22:25]
	v_mfma_f32_16x16x32_bf16 v[18:21], v[176:179], v[204:207], v[18:21]
	v_mfma_f32_16x16x32_bf16 v[6:9], v[168:171], v[212:215], v[6:9]
	v_mfma_f32_16x16x32_bf16 v[2:5], v[176:179], v[212:215], v[2:5]
	v_mfma_f32_16x16x32_bf16 v[54:57], v[172:175], v[188:191], v[54:57]
	v_mfma_f32_16x16x32_bf16 v[50:53], v[180:183], v[188:191], v[50:53]
	v_mfma_f32_16x16x32_bf16 v[38:41], v[172:175], v[200:203], v[38:41]
	v_mfma_f32_16x16x32_bf16 v[34:37], v[180:183], v[200:203], v[34:37]
	v_mfma_f32_16x16x32_bf16 v[22:25], v[172:175], v[208:211], v[22:25]
	v_mfma_f32_16x16x32_bf16 v[18:21], v[180:183], v[208:211], v[18:21]
	v_mfma_f32_16x16x32_bf16 v[6:9], v[172:175], v[216:219], v[6:9]
	v_mfma_f32_16x16x32_bf16 v[2:5], v[180:183], v[216:219], v[2:5]
	s_setprio 0
	s_barrier
	s_add_u32 s38, s38, 0x100
	s_addc_u32 s39, s39, 0
	s_add_u32 s21, s21, 0x100
	s_addc_u32 s23, s23, 0
	s_cmp_ge_i32 s37, s62
	s_mov_b32 s25, s37
	s_cbranch_scc0 .LBB0_221
	s_branch .Lpeeldone_13
.LBB0_221:
	ds_read_b128 v[152:155], v149
	ds_read_b128 v[156:159], v149 offset:1024
	ds_read_b128 v[160:163], v149 offset:2048
	ds_read_b128 v[164:167], v149 offset:3072
	ds_read_b128 v[168:171], v150
	ds_read_b128 v[172:175], v150 offset:1024
	ds_read_b128 v[176:179], v150 offset:2048
	ds_read_b128 v[180:183], v150 offset:3072
	s_add_i32 s37, s25, 2
	s_add_u32 s40, s38, 0xfff80080
	s_addc_u32 s41, s39, -1
	s_cmp_eq_u32 s36, s25
	s_cselect_b32 s43, s27, s41
	s_cselect_b32 s42, s26, s40
	s_cselect_b32 s41, s29, s23
	s_cselect_b32 s40, s28, s21
	v_lshl_add_u64 v[144:145], s[38:39], 0, v[140:141]
	s_add_i32 m0, s35, 0xc000
	ds_read_b128 v[184:187], v151
	ds_read_b128 v[188:191], v151 offset:1024
	ds_read_b128 v[196:199], v151 offset:2048
	ds_read_b128 v[200:203], v151 offset:3072
	ds_read_b128 v[204:207], v151 offset:4096
	ds_read_b128 v[208:211], v151 offset:5120
	ds_read_b128 v[212:215], v151 offset:6144
	ds_read_b128 v[216:219], v151 offset:7168
	global_load_lds_dwordx4 v[144:145], off sc0
	v_lshl_add_u64 v[144:145], s[38:39], 0, v[142:143]
	s_add_i32 m0, s35, 0xe000
	s_nop 0
	global_load_lds_dwordx4 v[144:145], off sc0
	s_waitcnt vmcnt(8)
	s_waitcnt lgkmcnt(0)
	s_barrier
	s_setprio 1
	s_waitcnt lgkmcnt(0)
	v_mfma_f32_16x16x32_bf16 v[126:129], v[152:155], v[184:187], v[126:129]
	v_mfma_f32_16x16x32_bf16 v[122:125], v[160:163], v[184:187], v[122:125]
	v_mfma_f32_16x16x32_bf16 v[110:113], v[152:155], v[196:199], v[110:113]
	v_mfma_f32_16x16x32_bf16 v[106:109], v[160:163], v[196:199], v[106:109]
	v_mfma_f32_16x16x32_bf16 v[94:97], v[152:155], v[204:207], v[94:97]
	v_mfma_f32_16x16x32_bf16 v[90:93], v[160:163], v[204:207], v[90:93]
	v_mfma_f32_16x16x32_bf16 v[78:81], v[152:155], v[212:215], v[78:81]
	v_mfma_f32_16x16x32_bf16 v[74:77], v[160:163], v[212:215], v[74:77]
	v_mfma_f32_16x16x32_bf16 v[126:129], v[156:159], v[188:191], v[126:129]
	v_mfma_f32_16x16x32_bf16 v[122:125], v[164:167], v[188:191], v[122:125]
	v_mfma_f32_16x16x32_bf16 v[110:113], v[156:159], v[200:203], v[110:113]
	v_mfma_f32_16x16x32_bf16 v[106:109], v[164:167], v[200:203], v[106:109]
	v_mfma_f32_16x16x32_bf16 v[94:97], v[156:159], v[208:211], v[94:97]
	v_mfma_f32_16x16x32_bf16 v[90:93], v[164:167], v[208:211], v[90:93]
	v_mfma_f32_16x16x32_bf16 v[78:81], v[156:159], v[216:219], v[78:81]
	v_mfma_f32_16x16x32_bf16 v[74:77], v[164:167], v[216:219], v[74:77]
	s_setprio 0
	s_setprio 1
	v_mfma_f32_16x16x32_bf16 v[118:121], v[168:171], v[184:187], v[118:121]
	v_mfma_f32_16x16x32_bf16 v[114:117], v[176:179], v[184:187], v[114:117]
	v_mfma_f32_16x16x32_bf16 v[102:105], v[168:171], v[196:199], v[102:105]
	v_mfma_f32_16x16x32_bf16 v[98:101], v[176:179], v[196:199], v[98:101]
	v_mfma_f32_16x16x32_bf16 v[86:89], v[168:171], v[204:207], v[86:89]
	v_mfma_f32_16x16x32_bf16 v[82:85], v[176:179], v[204:207], v[82:85]
	v_mfma_f32_16x16x32_bf16 v[70:73], v[168:171], v[212:215], v[70:73]
	v_mfma_f32_16x16x32_bf16 v[66:69], v[176:179], v[212:215], v[66:69]
	v_mfma_f32_16x16x32_bf16 v[118:121], v[172:175], v[188:191], v[118:121]
	v_mfma_f32_16x16x32_bf16 v[114:117], v[180:183], v[188:191], v[114:117]
	v_mfma_f32_16x16x32_bf16 v[102:105], v[172:175], v[200:203], v[102:105]
	v_mfma_f32_16x16x32_bf16 v[98:101], v[180:183], v[200:203], v[98:101]
	v_mfma_f32_16x16x32_bf16 v[86:89], v[172:175], v[208:211], v[86:89]
	v_mfma_f32_16x16x32_bf16 v[82:85], v[180:183], v[208:211], v[82:85]
	v_mfma_f32_16x16x32_bf16 v[70:73], v[172:175], v[216:219], v[70:73]
	v_mfma_f32_16x16x32_bf16 v[66:69], v[180:183], v[216:219], v[66:69]
	s_setprio 0
	s_barrier
	s_add_i32 s25, s54, s33
	v_lshl_add_u64 v[144:145], s[40:41], 0, v[132:133]
	s_mov_b32 m0, s25
	ds_read_b128 v[184:187], v151 offset:16384
	ds_read_b128 v[188:191], v151 offset:17408
	ds_read_b128 v[196:199], v151 offset:18432
	ds_read_b128 v[200:203], v151 offset:19456
	ds_read_b128 v[204:207], v151 offset:20480
	ds_read_b128 v[208:211], v151 offset:21504
	ds_read_b128 v[212:215], v151 offset:22528
	ds_read_b128 v[216:219], v151 offset:23552
	global_load_lds_dwordx4 v[144:145], off sc0
	s_add_i32 m0, s25, 0x2000
	s_add_u32 s44, s40, 0x80000
	v_lshl_add_u64 v[192:193], s[40:41], 0, v[136:137]
	s_addc_u32 s45, s41, 0
	s_add_i32 s25, s55, s33
	global_load_lds_dwordx4 v[192:193], off sc0
	v_lshl_add_u64 v[220:221], s[44:45], 0, v[132:133]
	s_mov_b32 m0, s25
	v_lshl_add_u64 v[222:223], s[42:43], 0, v[134:135]
	global_load_lds_dwordx4 v[220:221], off sc0
	v_lshl_add_u64 v[220:221], s[44:45], 0, v[136:137]
	s_add_i32 m0, s25, 0x2000
	s_nop 0
	global_load_lds_dwordx4 v[220:221], off sc0
	v_lshl_add_u64 v[220:221], s[42:43], 0, v[130:131]
	s_mov_b32 m0, s35
	s_nop 0
	global_load_lds_dwordx4 v[220:221], off sc0
	s_mov_b32 m0, s47
	s_nop 0
	global_load_lds_dwordx4 v[222:223], off sc0
	s_waitcnt vmcnt(8)
	s_waitcnt lgkmcnt(0)
	s_barrier
	s_setprio 1
	s_waitcnt lgkmcnt(0)
	v_mfma_f32_16x16x32_bf16 v[62:65], v[152:155], v[184:187], v[62:65]
	v_mfma_f32_16x16x32_bf16 v[58:61], v[160:163], v[184:187], v[58:61]
	v_mfma_f32_16x16x32_bf16 v[46:49], v[152:155], v[196:199], v[46:49]
	v_mfma_f32_16x16x32_bf16 v[42:45], v[160:163], v[196:199], v[42:45]
	v_mfma_f32_16x16x32_bf16 v[30:33], v[152:155], v[204:207], v[30:33]
	v_mfma_f32_16x16x32_bf16 v[26:29], v[160:163], v[204:207], v[26:29]
	v_mfma_f32_16x16x32_bf16 v[14:17], v[152:155], v[212:215], v[14:17]
	v_mfma_f32_16x16x32_bf16 v[10:13], v[160:163], v[212:215], v[10:13]
	v_mfma_f32_16x16x32_bf16 v[62:65], v[156:159], v[188:191], v[62:65]
	v_mfma_f32_16x16x32_bf16 v[58:61], v[164:167], v[188:191], v[58:61]
	v_mfma_f32_16x16x32_bf16 v[46:49], v[156:159], v[200:203], v[46:49]
	v_mfma_f32_16x16x32_bf16 v[42:45], v[164:167], v[200:203], v[42:45]
	v_mfma_f32_16x16x32_bf16 v[30:33], v[156:159], v[208:211], v[30:33]
	v_mfma_f32_16x16x32_bf16 v[26:29], v[164:167], v[208:211], v[26:29]
	v_mfma_f32_16x16x32_bf16 v[14:17], v[156:159], v[216:219], v[14:17]
	v_mfma_f32_16x16x32_bf16 v[10:13], v[164:167], v[216:219], v[10:13]
	s_setprio 0
	s_setprio 1
	v_mfma_f32_16x16x32_bf16 v[54:57], v[168:171], v[184:187], v[54:57]
	v_mfma_f32_16x16x32_bf16 v[50:53], v[176:179], v[184:187], v[50:53]
	v_mfma_f32_16x16x32_bf16 v[38:41], v[168:171], v[196:199], v[38:41]
	v_mfma_f32_16x16x32_bf16 v[34:37], v[176:179], v[196:199], v[34:37]
	v_mfma_f32_16x16x32_bf16 v[22:25], v[168:171], v[204:207], v[22:25]
	v_mfma_f32_16x16x32_bf16 v[18:21], v[176:179], v[204:207], v[18:21]
	v_mfma_f32_16x16x32_bf16 v[6:9], v[168:171], v[212:215], v[6:9]
	v_mfma_f32_16x16x32_bf16 v[2:5], v[176:179], v[212:215], v[2:5]
	v_mfma_f32_16x16x32_bf16 v[54:57], v[172:175], v[188:191], v[54:57]
	v_mfma_f32_16x16x32_bf16 v[50:53], v[180:183], v[188:191], v[50:53]
	v_mfma_f32_16x16x32_bf16 v[38:41], v[172:175], v[200:203], v[38:41]
	v_mfma_f32_16x16x32_bf16 v[34:37], v[180:183], v[200:203], v[34:37]
	v_mfma_f32_16x16x32_bf16 v[22:25], v[172:175], v[208:211], v[22:25]
	v_mfma_f32_16x16x32_bf16 v[18:21], v[180:183], v[208:211], v[18:21]
	v_mfma_f32_16x16x32_bf16 v[6:9], v[172:175], v[216:219], v[6:9]
	v_mfma_f32_16x16x32_bf16 v[2:5], v[180:183], v[216:219], v[2:5]
	s_setprio 0
	s_barrier
	s_add_i32 s25, 0, 0x18000
	s_add_i32 s44, 0, 0x1c000
	v_add_u32_e32 v164, s25, v147
	v_add_u32_e32 v180, s44, v147
	ds_read_b128 v[152:155], v164
	ds_read_b128 v[156:159], v164 offset:1024
	ds_read_b128 v[160:163], v164 offset:2048
	ds_read_b128 v[164:167], v164 offset:3072
	ds_read_b128 v[168:171], v180
	ds_read_b128 v[172:175], v180 offset:1024
	ds_read_b128 v[176:179], v180 offset:2048
	ds_read_b128 v[180:183], v180 offset:3072
	s_add_u32 s42, s42, 0x80000
	s_addc_u32 s43, s43, 0
	s_mov_b32 m0, s48
	v_lshl_add_u64 v[224:225], s[42:43], 0, v[130:131]
	ds_read_b128 v[184:187], v151 offset:32768
	ds_read_b128 v[188:191], v151 offset:33792
	ds_read_b128 v[196:199], v151 offset:34816
	ds_read_b128 v[200:203], v151 offset:35840
	ds_read_b128 v[204:207], v151 offset:36864
	ds_read_b128 v[208:211], v151 offset:37888
	ds_read_b128 v[212:215], v151 offset:38912
	ds_read_b128 v[216:219], v151 offset:39936
	global_load_lds_dwordx4 v[224:225], off sc0
	v_lshl_add_u64 v[224:225], s[42:43], 0, v[134:135]
	s_mov_b32 m0, s49
	s_nop 0
	global_load_lds_dwordx4 v[224:225], off sc0
	s_waitcnt vmcnt(8)
	s_waitcnt lgkmcnt(0)
	s_barrier
	s_setprio 1
	s_waitcnt lgkmcnt(0)
	v_mfma_f32_16x16x32_bf16 v[126:129], v[152:155], v[184:187], v[126:129]
	v_mfma_f32_16x16x32_bf16 v[122:125], v[160:163], v[184:187], v[122:125]
	v_mfma_f32_16x16x32_bf16 v[110:113], v[152:155], v[196:199], v[110:113]
	v_mfma_f32_16x16x32_bf16 v[106:109], v[160:163], v[196:199], v[106:109]
	v_mfma_f32_16x16x32_bf16 v[94:97], v[152:155], v[204:207], v[94:97]
	v_mfma_f32_16x16x32_bf16 v[90:93], v[160:163], v[204:207], v[90:93]
	v_mfma_f32_16x16x32_bf16 v[78:81], v[152:155], v[212:215], v[78:81]
	v_mfma_f32_16x16x32_bf16 v[74:77], v[160:163], v[212:215], v[74:77]
	v_mfma_f32_16x16x32_bf16 v[126:129], v[156:159], v[188:191], v[126:129]
	v_mfma_f32_16x16x32_bf16 v[122:125], v[164:167], v[188:191], v[122:125]
	v_mfma_f32_16x16x32_bf16 v[110:113], v[156:159], v[200:203], v[110:113]
	v_mfma_f32_16x16x32_bf16 v[106:109], v[164:167], v[200:203], v[106:109]
	v_mfma_f32_16x16x32_bf16 v[94:97], v[156:159], v[208:211], v[94:97]
	v_mfma_f32_16x16x32_bf16 v[90:93], v[164:167], v[208:211], v[90:93]
	v_mfma_f32_16x16x32_bf16 v[78:81], v[156:159], v[216:219], v[78:81]
	v_mfma_f32_16x16x32_bf16 v[74:77], v[164:167], v[216:219], v[74:77]
	s_setprio 0
	s_setprio 1
	v_mfma_f32_16x16x32_bf16 v[118:121], v[168:171], v[184:187], v[118:121]
	v_mfma_f32_16x16x32_bf16 v[114:117], v[176:179], v[184:187], v[114:117]
	v_mfma_f32_16x16x32_bf16 v[102:105], v[168:171], v[196:199], v[102:105]
	v_mfma_f32_16x16x32_bf16 v[98:101], v[176:179], v[196:199], v[98:101]
	v_mfma_f32_16x16x32_bf16 v[86:89], v[168:171], v[204:207], v[86:89]
	v_mfma_f32_16x16x32_bf16 v[82:85], v[176:179], v[204:207], v[82:85]
	v_mfma_f32_16x16x32_bf16 v[70:73], v[168:171], v[212:215], v[70:73]
	v_mfma_f32_16x16x32_bf16 v[66:69], v[176:179], v[212:215], v[66:69]
	v_mfma_f32_16x16x32_bf16 v[118:121], v[172:175], v[188:191], v[118:121]
	v_mfma_f32_16x16x32_bf16 v[114:117], v[180:183], v[188:191], v[114:117]
	v_mfma_f32_16x16x32_bf16 v[102:105], v[172:175], v[200:203], v[102:105]
	v_mfma_f32_16x16x32_bf16 v[98:101], v[180:183], v[200:203], v[98:101]
	v_mfma_f32_16x16x32_bf16 v[86:89], v[172:175], v[208:211], v[86:89]
	v_mfma_f32_16x16x32_bf16 v[82:85], v[180:183], v[208:211], v[82:85]
	v_mfma_f32_16x16x32_bf16 v[70:73], v[172:175], v[216:219], v[70:73]
	v_mfma_f32_16x16x32_bf16 v[66:69], v[180:183], v[216:219], v[66:69]
	s_setprio 0
	s_barrier
	s_add_i32 s25, s25, s33
	v_lshl_add_u64 v[144:145], v[144:145], 0, s[16:17]
	s_mov_b32 m0, s25
	ds_read_b128 v[184:187], v151 offset:49152
	ds_read_b128 v[188:191], v151 offset:50176
	ds_read_b128 v[196:199], v151 offset:51200
	ds_read_b128 v[200:203], v151 offset:52224
	ds_read_b128 v[204:207], v151 offset:53248
	ds_read_b128 v[208:211], v151 offset:54272
	ds_read_b128 v[212:215], v151 offset:55296
	ds_read_b128 v[216:219], v151 offset:56320
	global_load_lds_dwordx4 v[144:145], off sc0
	s_add_i32 m0, s25, 0x2000
	s_add_u32 s40, s40, 0x80080
	v_lshl_add_u64 v[144:145], v[192:193], 0, s[16:17]
	s_addc_u32 s41, s41, 0
	s_add_i32 s25, s44, s33
	global_load_lds_dwordx4 v[144:145], off sc0
	v_lshl_add_u64 v[144:145], s[40:41], 0, v[132:133]
	s_mov_b32 m0, s25
	s_nop 0
	global_load_lds_dwordx4 v[144:145], off sc0
	v_lshl_add_u64 v[144:145], s[40:41], 0, v[136:137]
	s_add_i32 m0, s25, 0x2000
	s_nop 0
	global_load_lds_dwordx4 v[144:145], off sc0
	v_lshl_add_u64 v[144:145], v[220:221], 0, s[16:17]
	s_mov_b32 m0, s50
	s_nop 0
	global_load_lds_dwordx4 v[144:145], off sc0
	v_lshl_add_u64 v[144:145], v[222:223], 0, s[16:17]
	s_mov_b32 m0, s51
	s_nop 0
	global_load_lds_dwordx4 v[144:145], off sc0
	s_waitcnt vmcnt(8)
	s_waitcnt lgkmcnt(0)
	s_barrier
	s_setprio 1
	s_waitcnt lgkmcnt(0)
	v_mfma_f32_16x16x32_bf16 v[62:65], v[152:155], v[184:187], v[62:65]
	v_mfma_f32_16x16x32_bf16 v[58:61], v[160:163], v[184:187], v[58:61]
	v_mfma_f32_16x16x32_bf16 v[46:49], v[152:155], v[196:199], v[46:49]
	v_mfma_f32_16x16x32_bf16 v[42:45], v[160:163], v[196:199], v[42:45]
	v_mfma_f32_16x16x32_bf16 v[30:33], v[152:155], v[204:207], v[30:33]
	v_mfma_f32_16x16x32_bf16 v[26:29], v[160:163], v[204:207], v[26:29]
	v_mfma_f32_16x16x32_bf16 v[14:17], v[152:155], v[212:215], v[14:17]
	v_mfma_f32_16x16x32_bf16 v[10:13], v[160:163], v[212:215], v[10:13]
	v_mfma_f32_16x16x32_bf16 v[62:65], v[156:159], v[188:191], v[62:65]
	v_mfma_f32_16x16x32_bf16 v[58:61], v[164:167], v[188:191], v[58:61]
	v_mfma_f32_16x16x32_bf16 v[46:49], v[156:159], v[200:203], v[46:49]
	v_mfma_f32_16x16x32_bf16 v[42:45], v[164:167], v[200:203], v[42:45]
	v_mfma_f32_16x16x32_bf16 v[30:33], v[156:159], v[208:211], v[30:33]
	v_mfma_f32_16x16x32_bf16 v[26:29], v[164:167], v[208:211], v[26:29]
	v_mfma_f32_16x16x32_bf16 v[14:17], v[156:159], v[216:219], v[14:17]
	v_mfma_f32_16x16x32_bf16 v[10:13], v[164:167], v[216:219], v[10:13]
	s_setprio 0
	s_setprio 1
	v_mfma_f32_16x16x32_bf16 v[54:57], v[168:171], v[184:187], v[54:57]
	v_mfma_f32_16x16x32_bf16 v[50:53], v[176:179], v[184:187], v[50:53]
	v_mfma_f32_16x16x32_bf16 v[38:41], v[168:171], v[196:199], v[38:41]
	v_mfma_f32_16x16x32_bf16 v[34:37], v[176:179], v[196:199], v[34:37]
	v_mfma_f32_16x16x32_bf16 v[22:25], v[168:171], v[204:207], v[22:25]
	v_mfma_f32_16x16x32_bf16 v[18:21], v[176:179], v[204:207], v[18:21]
	v_mfma_f32_16x16x32_bf16 v[6:9], v[168:171], v[212:215], v[6:9]
	v_mfma_f32_16x16x32_bf16 v[2:5], v[176:179], v[212:215], v[2:5]
	v_mfma_f32_16x16x32_bf16 v[54:57], v[172:175], v[188:191], v[54:57]
	v_mfma_f32_16x16x32_bf16 v[50:53], v[180:183], v[188:191], v[50:53]
	v_mfma_f32_16x16x32_bf16 v[38:41], v[172:175], v[200:203], v[38:41]
	v_mfma_f32_16x16x32_bf16 v[34:37], v[180:183], v[200:203], v[34:37]
	v_mfma_f32_16x16x32_bf16 v[22:25], v[172:175], v[208:211], v[22:25]
	v_mfma_f32_16x16x32_bf16 v[18:21], v[180:183], v[208:211], v[18:21]
	v_mfma_f32_16x16x32_bf16 v[6:9], v[172:175], v[216:219], v[6:9]
	v_mfma_f32_16x16x32_bf16 v[2:5], v[180:183], v[216:219], v[2:5]
	s_setprio 0
	s_barrier
	s_add_u32 s38, s38, 0x100
	s_addc_u32 s39, s39, 0
	s_add_u32 s21, s21, 0x100
	s_addc_u32 s23, s23, 0
	s_cmp_ge_i32 s37, s62
	s_mov_b32 s25, s37
	s_cbranch_scc0 .LBB0_221

.LBB0_343:
	v_lshrrev_b32_e32 v5, 1, v0
	v_and_b32_e32 v14, 24, v5
	v_lshrrev_b32_e32 v5, 5, v0
	v_lshlrev_b32_e32 v2, 4, v0
	v_and_b32_e32 v3, 32, v0
	v_and_b32_e32 v5, 4, v5
	v_bfe_u32 v6, v0, 2, 2
	v_bfe_u32 v4, v0, 2, 4
	v_bitop3_b32 v12, v2, v3, 48 bitop3:0x6c
	v_and_b32_e32 v13, 64, v0
	v_or3_b32 v5, v5, v6, v14
	v_lshrrev_b32_e32 v6, 3, v0
	v_or_b32_e32 v3, v12, v13
	v_and_or_b32 v7, v6, 48, v4
	v_and_or_b32 v6, v6, 32, v5
	v_lshrrev_b32_e32 v3, 1, v3
	v_mul_u32_u24_e32 v6, 0x1600, v6
	v_or_b32_e32 v6, v6, v3
	v_lshlrev_b32_e32 v180, 1, v6
	v_bfe_u32 v6, v0, 3, 25
	v_or_b32_e32 v6, 64, v6
	s_movk_i32 s13, 0x70
	s_add_u32 s2, s82, 0xb400000
	v_and_or_b32 v4, v6, s13, v4
	s_movk_i32 s13, 0x60
	s_addc_u32 s3, s83, 0
	v_and_or_b32 v5, v6, s13, v5
	s_ashr_i32 s13, s12, 31
	s_lshr_b32 s13, s13, 29
	s_add_i32 s13, s12, s13
	s_lshr_b32 s18, s20, 6
	s_ashr_i32 s16, s13, 3
	s_and_b32 s13, s13, -8
	s_lshr_b32 s7, s20, 8
	s_lshl_b32 s33, s18, 10
	s_sub_i32 s12, s12, s13
	s_cmp_lt_i32 s12, 0
	s_cselect_b32 s13, 49, 48
	s_mul_i32 s12, s13, s12
	s_add_i32 s12, s12, s16
	s_ashr_i32 s13, s12, 31
	s_lshr_b32 s13, s13, 26
	s_add_i32 s13, s12, s13
	s_ashr_i32 s16, s13, 6
	s_lshl_b32 s16, s16, 3
	s_sub_i32 s17, 48, s16
	v_mul_u32_u24_e32 v16, 0x1600, v4
	s_min_i32 s17, s17, 8
	v_or_b32_e32 v4, v16, v3
	s_abs_i32 s19, s17
	v_lshlrev_b32_e32 v182, 1, v4
	v_cvt_f32_u32_e32 v4, s19
	v_mul_u32_u24_e32 v15, 0x1600, v7
	v_mul_u32_u24_e32 v5, 0x1600, v5
	v_or_b32_e32 v7, v3, v15
	v_or_b32_e32 v3, v5, v3
	v_lshlrev_b32_e32 v184, 1, v3
	v_rcp_iflag_f32_e32 v3, v4
	s_sub_i32 s23, 0, s19
	s_andn2_b32 s13, s13, 63
	s_sub_i32 s12, s12, s13
	v_mul_f32_e32 v3, 0x4f7ffffe, v3
	v_cvt_u32_f32_e32 v3, v3
	s_abs_i32 s21, s12
	s_xor_b32 s13, s12, s17
	s_ashr_i32 s13, s13, 31
	v_readfirstlane_b32 s24, v3
	s_mul_i32 s23, s23, s24
	s_mul_hi_u32 s23, s24, s23
	s_add_i32 s24, s24, s23
	s_mul_hi_u32 s23, s21, s24
	s_mul_i32 s24, s23, s19
	s_sub_i32 s21, s21, s24
	s_add_i32 s24, s23, 1
	s_sub_i32 s25, s21, s19
	s_cmp_ge_u32 s21, s19
	s_cselect_b32 s23, s24, s23
	s_cselect_b32 s21, s25, s21
	s_add_i32 s24, s23, 1
	s_cmp_ge_u32 s21, s19
	s_cselect_b32 s19, s24, s23
	s_xor_b32 s19, s19, s13
	s_sub_i32 s60, s19, s13
	s_mul_i32 s13, s60, s17
	s_sub_i32 s12, s12, s13
	s_add_i32 s59, s16, s12
	s_mul_i32 s13, s59, 0x2c0000
	s_mul_hi_i32 s12, s59, 0x2c0000
	s_add_u32 s16, s72, s13
	s_addc_u32 s17, s73, s12
	s_mul_i32 s13, s60, 0x2c0000
	s_mul_hi_i32 s12, s60, 0x2c0000
	s_add_u32 s13, s2, s13
	s_addc_u32 s12, s3, s12
	s_add_u32 s34, s13, s0
	s_addc_u32 s35, s12, s1
	s_add_i32 s40, s33, 0
	s_add_i32 m0, s40, 0x10000
	v_lshlrev_b32_e32 v178, 1, v7
	global_load_lds_dwordx4 v180, s[34:35] sc0
	s_add_i32 m0, s40, 0x12000
	s_add_u32 s12, s34, 0x160000
	global_load_lds_dwordx4 v184, s[34:35] sc0
	s_addc_u32 s13, s35, 0
	s_add_i32 m0, s40, 0x14000
	v_mov_b32_e32 v181, 0
	global_load_lds_dwordx4 v180, s[12:13] sc0
	s_add_i32 m0, s40, 0x16000
	s_add_u32 s30, s16, s0
	s_addc_u32 s31, s17, s1
	s_add_i32 s41, s40, 0x2000
	global_load_lds_dwordx4 v184, s[12:13] sc0
	s_mov_b32 m0, s40
	s_add_u32 s0, s30, 0x160000
	global_load_lds_dwordx4 v178, s[30:31] sc0
	s_mov_b32 m0, s41
	s_addc_u32 s1, s31, 0
	s_add_i32 s42, s40, 0x4000
	global_load_lds_dwordx4 v182, s[30:31] sc0
	s_mov_b32 m0, s42
	s_add_i32 s43, s40, 0x6000
	global_load_lds_dwordx4 v178, s[0:1] sc0
	s_mov_b32 m0, s43
	v_mov_b32_e32 v185, v181
	global_load_lds_dwordx4 v182, s[0:1] sc0
	v_mov_b32_e32 v179, v181
	v_mov_b32_e32 v183, v181
	s_cmp_eq_u32 s7, 1
	v_lshl_add_u64 v[10:11], s[34:35], 0, v[180:181]
	v_lshl_add_u64 v[8:9], s[34:35], 0, v[184:185]
	v_lshl_add_u64 v[4:5], s[30:31], 0, v[178:179]
	s_cselect_b64 s[12:13], -1, 0
	s_cmp_lg_u32 s7, 1
	v_lshl_add_u64 v[6:7], s[30:31], 0, v[182:183]
	s_cbranch_scc1 .LBB0_345
	s_barrier
.LBB0_345:
	s_add_u32 s16, s82, 0x27100000
	s_addc_u32 s17, s83, 0
	s_add_u32 s44, s82, 0x204000
	s_addc_u32 s45, s83, 0
	s_lshl_b32 s0, s18, 5
	s_mov_b64 s[18:19], 0x80
	s_and_b32 s23, s0, 0x60
	s_add_i32 m0, s40, 0x18000
	v_lshl_add_u64 v[10:11], v[10:11], 0, s[18:19]
	s_lshl_b32 s21, s7, 13
	s_lshl_b32 s24, s23, 7
	s_waitcnt vmcnt(2)
	s_barrier
	global_load_lds_dwordx4 v[10:11], off sc0
	v_lshl_add_u64 v[8:9], v[8:9], 0, s[18:19]
	s_add_i32 m0, s40, 0x1a000
	s_add_i32 s46, s40, 0x8000
	s_add_i32 s47, s40, 0xa000
	global_load_lds_dwordx4 v[8:9], off sc0
	v_lshl_add_u64 v[4:5], v[4:5], 0, s[18:19]
	s_mov_b32 m0, s46
	s_add_u32 s0, s34, 0x160080
	global_load_lds_dwordx4 v[4:5], off sc0
	v_lshl_add_u64 v[4:5], v[6:7], 0, s[18:19]
	s_mov_b32 m0, s47
	s_addc_u32 s1, s35, 0
	global_load_lds_dwordx4 v[4:5], off sc0
	s_add_i32 m0, s40, 0x1c000
	v_lshl_add_u64 v[4:5], s[0:1], 0, v[180:181]
	global_load_lds_dwordx4 v[4:5], off sc0
	v_lshl_add_u64 v[4:5], s[0:1], 0, v[184:185]
	s_add_i32 m0, s40, 0x1e000
	v_and_b32_e32 v3, 15, v0
	global_load_lds_dwordx4 v[4:5], off sc0
	v_lshlrev_b32_e32 v4, 1, v14
	v_lshlrev_b32_e32 v5, 2, v0
	v_lshl_or_b32 v212, s7, 6, v3
	v_lshl_or_b32 v3, v3, 6, v4
	v_and_b32_e32 v5, 32, v5
	v_bitop3_b32 v6, v3, s21, v5 bitop3:0xde
	v_lshlrev_b32_e32 v3, 6, v0
	s_movk_i32 s0, 0x3c0
	v_readlane_b32 s21, v249, 0
	v_and_or_b32 v3, v3, s0, v4
	s_ashr_i32 s0, s21, 31
	s_lshr_b32 s0, s0, 25
	s_add_i32 s0, s21, s0
	s_and_b32 s1, s0, 0xffffff80
	s_sub_i32 s48, s21, s1
	s_addk_i32 s48, 0x100
	s_ashr_i32 s49, s0, 7
	s_cmpk_lt_u32 s20, 0x100
	s_cselect_b64 s[20:21], -1, 0
	s_lshr_b32 s0, s22, 2
	v_bitop3_b32 v213, s24, v3, v5 bitop3:0xf6
	v_mov_b32_e32 v3, v181
	s_xor_b32 s50, s0, 1
	s_waitcnt vmcnt(6)
	v_lshl_add_u64 v[186:187], s[78:79], 0, v[2:3]
	s_add_u32 s51, s10, 0xfe000000
	v_add_u16_e32 v2, v12, v13
	s_mov_b32 s7, 0
	s_addc_u32 s52, s11, -1
	v_lshrrev_b16_e32 v2, 1, v2
	s_add_i32 s53, 0, 0x10000
	s_add_i32 s54, 0, 0x14000
	s_mul_i32 s49, s49, 44
	v_or_b32_e32 v214, s23, v14
	v_add_lshl_u32 v188, v15, v2, 1
	v_mov_b32_e32 v189, v181
	v_add_lshl_u32 v190, v16, v2, 1
	v_mov_b32_e32 v191, v181
	s_mov_b64 s[28:29], -1
	v_add_u32_e32 v215, s53, v213
	v_add_u32_e32 v216, s54, v213
	v_add_u32_e32 v217, 0, v6
	s_mov_b32 s23, s7
	s_barrier
	s_branch .LBB0_348

.Lpeel_12:
	ds_read_b128 v[130:133], v215
	ds_read_b128 v[134:137], v215 offset:1024
	ds_read_b128 v[138:141], v215 offset:2048
	ds_read_b128 v[142:145], v215 offset:3072
	ds_read_b128 v[146:149], v216
	ds_read_b128 v[150:153], v216 offset:1024
	ds_read_b128 v[154:157], v216 offset:2048
	ds_read_b128 v[158:161], v216 offset:3072
	s_add_i32 s38, s34, 2
	s_add_u32 s35, s30, 0xffea0080
	s_addc_u32 s36, s31, -1
	s_cmp_eq_u32 s28, s34
	s_cselect_b32 s34, s26, s23
	s_cselect_b32 s37, s25, s36
	s_cselect_b32 s36, s24, s35
	s_cselect_b32 s35, s27, s29
	v_lshl_add_u64 v[192:193], s[30:31], 0, v[188:189]
	s_add_i32 m0, s40, 0xc000
	ds_read_b128 v[162:165], v217
	ds_read_b128 v[166:169], v217 offset:1024
	ds_read_b128 v[170:173], v217 offset:2048
	ds_read_b128 v[174:177], v217 offset:3072
	ds_read_b128 v[196:199], v217 offset:4096
	ds_read_b128 v[200:203], v217 offset:5120
	ds_read_b128 v[204:207], v217 offset:6144
	ds_read_b128 v[208:211], v217 offset:7168
	global_load_lds_dwordx4 v[192:193], off sc0
	v_lshl_add_u64 v[192:193], s[30:31], 0, v[190:191]
	s_add_i32 m0, s40, 0xe000
	s_nop 0
	global_load_lds_dwordx4 v[192:193], off sc0
	s_waitcnt vmcnt(8)
	s_waitcnt lgkmcnt(0)
	s_barrier
	s_setprio 1
	s_waitcnt lgkmcnt(0)
	v_mfma_f32_16x16x32_bf16 v[126:129], v[130:133], v[162:165], 0
	v_mfma_f32_16x16x32_bf16 v[122:125], v[138:141], v[162:165], 0
	v_mfma_f32_16x16x32_bf16 v[118:121], v[130:133], v[170:173], 0
	v_mfma_f32_16x16x32_bf16 v[114:117], v[138:141], v[170:173], 0
	v_mfma_f32_16x16x32_bf16 v[94:97], v[130:133], v[196:199], 0
	v_mfma_f32_16x16x32_bf16 v[90:93], v[138:141], v[196:199], 0
	v_mfma_f32_16x16x32_bf16 v[86:89], v[130:133], v[204:207], 0
	v_mfma_f32_16x16x32_bf16 v[82:85], v[138:141], v[204:207], 0
	v_mfma_f32_16x16x32_bf16 v[126:129], v[134:137], v[166:169], v[126:129]
	v_mfma_f32_16x16x32_bf16 v[122:125], v[142:145], v[166:169], v[122:125]
	v_mfma_f32_16x16x32_bf16 v[118:121], v[134:137], v[174:177], v[118:121]
	v_mfma_f32_16x16x32_bf16 v[114:117], v[142:145], v[174:177], v[114:117]
	v_mfma_f32_16x16x32_bf16 v[94:97], v[134:137], v[200:203], v[94:97]
	v_mfma_f32_16x16x32_bf16 v[90:93], v[142:145], v[200:203], v[90:93]
	v_mfma_f32_16x16x32_bf16 v[86:89], v[134:137], v[208:211], v[86:89]
	v_mfma_f32_16x16x32_bf16 v[82:85], v[142:145], v[208:211], v[82:85]
	s_setprio 0
	s_setprio 1
	v_mfma_f32_16x16x32_bf16 v[110:113], v[146:149], v[162:165], 0
	v_mfma_f32_16x16x32_bf16 v[106:109], v[154:157], v[162:165], 0
	v_mfma_f32_16x16x32_bf16 v[102:105], v[146:149], v[170:173], 0
	v_mfma_f32_16x16x32_bf16 v[98:101], v[154:157], v[170:173], 0
	v_mfma_f32_16x16x32_bf16 v[78:81], v[146:149], v[196:199], 0
	v_mfma_f32_16x16x32_bf16 v[74:77], v[154:157], v[196:199], 0
	v_mfma_f32_16x16x32_bf16 v[70:73], v[146:149], v[204:207], 0
	v_mfma_f32_16x16x32_bf16 v[66:69], v[154:157], v[204:207], 0
	v_mfma_f32_16x16x32_bf16 v[110:113], v[150:153], v[166:169], v[110:113]
	v_mfma_f32_16x16x32_bf16 v[106:109], v[158:161], v[166:169], v[106:109]
	v_mfma_f32_16x16x32_bf16 v[102:105], v[150:153], v[174:177], v[102:105]
	v_mfma_f32_16x16x32_bf16 v[98:101], v[158:161], v[174:177], v[98:101]
	v_mfma_f32_16x16x32_bf16 v[78:81], v[150:153], v[200:203], v[78:81]
	v_mfma_f32_16x16x32_bf16 v[74:77], v[158:161], v[200:203], v[74:77]
	v_mfma_f32_16x16x32_bf16 v[70:73], v[150:153], v[208:211], v[70:73]
	v_mfma_f32_16x16x32_bf16 v[66:69], v[158:161], v[208:211], v[66:69]
	s_setprio 0
	s_barrier
	s_add_i32 s39, s53, s33
	v_lshl_add_u64 v[192:193], s[34:35], 0, v[180:181]
	s_mov_b32 m0, s39
	ds_read_b128 v[162:165], v217 offset:16384
	ds_read_b128 v[166:169], v217 offset:17408
	ds_read_b128 v[170:173], v217 offset:18432
	ds_read_b128 v[174:177], v217 offset:19456
	ds_read_b128 v[196:199], v217 offset:20480
	ds_read_b128 v[200:203], v217 offset:21504
	ds_read_b128 v[204:207], v217 offset:22528
	ds_read_b128 v[208:211], v217 offset:23552
	global_load_lds_dwordx4 v[192:193], off sc0
	s_add_i32 m0, s39, 0x2000
	s_add_u32 s62, s34, 0x160000
	v_lshl_add_u64 v[218:219], s[34:35], 0, v[184:185]
	s_addc_u32 s63, s35, 0
	s_add_i32 s39, s54, s33
	global_load_lds_dwordx4 v[218:219], off sc0
	v_lshl_add_u64 v[220:221], s[62:63], 0, v[180:181]
	s_mov_b32 m0, s39
	v_lshl_add_u64 v[222:223], s[36:37], 0, v[182:183]
	global_load_lds_dwordx4 v[220:221], off sc0
	v_lshl_add_u64 v[220:221], s[62:63], 0, v[184:185]
	s_add_i32 m0, s39, 0x2000
	s_nop 0
	global_load_lds_dwordx4 v[220:221], off sc0
	v_lshl_add_u64 v[220:221], s[36:37], 0, v[178:179]
	s_mov_b32 m0, s40
	s_nop 0
	global_load_lds_dwordx4 v[220:221], off sc0
	s_mov_b32 m0, s41
	s_nop 0
	global_load_lds_dwordx4 v[222:223], off sc0
	s_waitcnt vmcnt(8)
	s_waitcnt lgkmcnt(0)
	s_barrier
	s_setprio 1
	s_waitcnt lgkmcnt(0)
	v_mfma_f32_16x16x32_bf16 v[62:65], v[130:133], v[162:165], 0
	v_mfma_f32_16x16x32_bf16 v[58:61], v[138:141], v[162:165], 0
	v_mfma_f32_16x16x32_bf16 v[54:57], v[130:133], v[170:173], 0
	v_mfma_f32_16x16x32_bf16 v[50:53], v[138:141], v[170:173], 0
	v_mfma_f32_16x16x32_bf16 v[30:33], v[130:133], v[196:199], 0
	v_mfma_f32_16x16x32_bf16 v[26:29], v[138:141], v[196:199], 0
	v_mfma_f32_16x16x32_bf16 v[22:25], v[130:133], v[204:207], 0
	v_mfma_f32_16x16x32_bf16 v[18:21], v[138:141], v[204:207], 0
	v_mfma_f32_16x16x32_bf16 v[62:65], v[134:137], v[166:169], v[62:65]
	v_mfma_f32_16x16x32_bf16 v[58:61], v[142:145], v[166:169], v[58:61]
	v_mfma_f32_16x16x32_bf16 v[54:57], v[134:137], v[174:177], v[54:57]
	v_mfma_f32_16x16x32_bf16 v[50:53], v[142:145], v[174:177], v[50:53]
	v_mfma_f32_16x16x32_bf16 v[30:33], v[134:137], v[200:203], v[30:33]
	v_mfma_f32_16x16x32_bf16 v[26:29], v[142:145], v[200:203], v[26:29]
	v_mfma_f32_16x16x32_bf16 v[22:25], v[134:137], v[208:211], v[22:25]
	v_mfma_f32_16x16x32_bf16 v[18:21], v[142:145], v[208:211], v[18:21]
	s_setprio 0
	s_setprio 1
	v_mfma_f32_16x16x32_bf16 v[46:49], v[146:149], v[162:165], 0
	v_mfma_f32_16x16x32_bf16 v[42:45], v[154:157], v[162:165], 0
	v_mfma_f32_16x16x32_bf16 v[38:41], v[146:149], v[170:173], 0
	v_mfma_f32_16x16x32_bf16 v[34:37], v[154:157], v[170:173], 0
	v_mfma_f32_16x16x32_bf16 v[14:17], v[146:149], v[196:199], 0
	v_mfma_f32_16x16x32_bf16 v[10:13], v[154:157], v[196:199], 0
	v_mfma_f32_16x16x32_bf16 v[6:9], v[146:149], v[204:207], 0
	v_mfma_f32_16x16x32_bf16 v[2:5], v[154:157], v[204:207], 0
	v_mfma_f32_16x16x32_bf16 v[46:49], v[150:153], v[166:169], v[46:49]
	v_mfma_f32_16x16x32_bf16 v[42:45], v[158:161], v[166:169], v[42:45]
	v_mfma_f32_16x16x32_bf16 v[38:41], v[150:153], v[174:177], v[38:41]
	v_mfma_f32_16x16x32_bf16 v[34:37], v[158:161], v[174:177], v[34:37]
	v_mfma_f32_16x16x32_bf16 v[14:17], v[150:153], v[200:203], v[14:17]
	v_mfma_f32_16x16x32_bf16 v[10:13], v[158:161], v[200:203], v[10:13]
	v_mfma_f32_16x16x32_bf16 v[6:9], v[150:153], v[208:211], v[6:9]
	v_mfma_f32_16x16x32_bf16 v[2:5], v[158:161], v[208:211], v[2:5]
	s_setprio 0
	s_barrier
	s_add_i32 s39, 0, 0x18000
	s_add_i32 s62, 0, 0x1c000
	v_add_u32_e32 v142, s39, v213
	v_add_u32_e32 v158, s62, v213
	ds_read_b128 v[130:133], v142
	ds_read_b128 v[134:137], v142 offset:1024
	ds_read_b128 v[138:141], v142 offset:2048
	ds_read_b128 v[142:145], v142 offset:3072
	ds_read_b128 v[146:149], v158
	ds_read_b128 v[150:153], v158 offset:1024
	ds_read_b128 v[154:157], v158 offset:2048
	ds_read_b128 v[158:161], v158 offset:3072
	s_add_u32 s36, s36, 0x160000
	s_addc_u32 s37, s37, 0
	s_mov_b32 m0, s42
	v_lshl_add_u64 v[224:225], s[36:37], 0, v[178:179]
	ds_read_b128 v[162:165], v217 offset:32768
	ds_read_b128 v[166:169], v217 offset:33792
	ds_read_b128 v[170:173], v217 offset:34816
	ds_read_b128 v[174:177], v217 offset:35840
	ds_read_b128 v[196:199], v217 offset:36864
	ds_read_b128 v[200:203], v217 offset:37888
	ds_read_b128 v[204:207], v217 offset:38912
	ds_read_b128 v[208:211], v217 offset:39936
	global_load_lds_dwordx4 v[224:225], off sc0
	v_lshl_add_u64 v[224:225], s[36:37], 0, v[182:183]
	s_mov_b32 m0, s43
	s_nop 0
	global_load_lds_dwordx4 v[224:225], off sc0
	s_waitcnt vmcnt(8)
	s_waitcnt lgkmcnt(0)
	s_barrier
	s_setprio 1
	s_waitcnt lgkmcnt(0)
	v_mfma_f32_16x16x32_bf16 v[126:129], v[130:133], v[162:165], v[126:129]
	v_mfma_f32_16x16x32_bf16 v[122:125], v[138:141], v[162:165], v[122:125]
	v_mfma_f32_16x16x32_bf16 v[118:121], v[130:133], v[170:173], v[118:121]
	v_mfma_f32_16x16x32_bf16 v[114:117], v[138:141], v[170:173], v[114:117]
	v_mfma_f32_16x16x32_bf16 v[94:97], v[130:133], v[196:199], v[94:97]
	v_mfma_f32_16x16x32_bf16 v[90:93], v[138:141], v[196:199], v[90:93]
	v_mfma_f32_16x16x32_bf16 v[86:89], v[130:133], v[204:207], v[86:89]
	v_mfma_f32_16x16x32_bf16 v[82:85], v[138:141], v[204:207], v[82:85]
	v_mfma_f32_16x16x32_bf16 v[126:129], v[134:137], v[166:169], v[126:129]
	v_mfma_f32_16x16x32_bf16 v[122:125], v[142:145], v[166:169], v[122:125]
	v_mfma_f32_16x16x32_bf16 v[118:121], v[134:137], v[174:177], v[118:121]
	v_mfma_f32_16x16x32_bf16 v[114:117], v[142:145], v[174:177], v[114:117]
	v_mfma_f32_16x16x32_bf16 v[94:97], v[134:137], v[200:203], v[94:97]
	v_mfma_f32_16x16x32_bf16 v[90:93], v[142:145], v[200:203], v[90:93]
	v_mfma_f32_16x16x32_bf16 v[86:89], v[134:137], v[208:211], v[86:89]
	v_mfma_f32_16x16x32_bf16 v[82:85], v[142:145], v[208:211], v[82:85]
	s_setprio 0
	s_setprio 1
	v_mfma_f32_16x16x32_bf16 v[110:113], v[146:149], v[162:165], v[110:113]
	v_mfma_f32_16x16x32_bf16 v[106:109], v[154:157], v[162:165], v[106:109]
	v_mfma_f32_16x16x32_bf16 v[102:105], v[146:149], v[170:173], v[102:105]
	v_mfma_f32_16x16x32_bf16 v[98:101], v[154:157], v[170:173], v[98:101]
	v_mfma_f32_16x16x32_bf16 v[78:81], v[146:149], v[196:199], v[78:81]
	v_mfma_f32_16x16x32_bf16 v[74:77], v[154:157], v[196:199], v[74:77]
	v_mfma_f32_16x16x32_bf16 v[70:73], v[146:149], v[204:207], v[70:73]
	v_mfma_f32_16x16x32_bf16 v[66:69], v[154:157], v[204:207], v[66:69]
	v_mfma_f32_16x16x32_bf16 v[110:113], v[150:153], v[166:169], v[110:113]
	v_mfma_f32_16x16x32_bf16 v[106:109], v[158:161], v[166:169], v[106:109]
	v_mfma_f32_16x16x32_bf16 v[102:105], v[150:153], v[174:177], v[102:105]
	v_mfma_f32_16x16x32_bf16 v[98:101], v[158:161], v[174:177], v[98:101]
	v_mfma_f32_16x16x32_bf16 v[78:81], v[150:153], v[200:203], v[78:81]
	v_mfma_f32_16x16x32_bf16 v[74:77], v[158:161], v[200:203], v[74:77]
	v_mfma_f32_16x16x32_bf16 v[70:73], v[150:153], v[208:211], v[70:73]
	v_mfma_f32_16x16x32_bf16 v[66:69], v[158:161], v[208:211], v[66:69]
	s_setprio 0
	s_barrier
	s_add_i32 s36, s39, s33
	v_lshl_add_u64 v[192:193], v[192:193], 0, s[18:19]
	s_mov_b32 m0, s36
	ds_read_b128 v[162:165], v217 offset:49152
	ds_read_b128 v[166:169], v217 offset:50176
	ds_read_b128 v[170:173], v217 offset:51200
	ds_read_b128 v[174:177], v217 offset:52224
	ds_read_b128 v[196:199], v217 offset:53248
	ds_read_b128 v[200:203], v217 offset:54272
	ds_read_b128 v[204:207], v217 offset:55296
	ds_read_b128 v[208:211], v217 offset:56320
	global_load_lds_dwordx4 v[192:193], off sc0
	s_add_i32 m0, s36, 0x2000
	s_add_u32 s34, s34, 0x160080
	v_lshl_add_u64 v[192:193], v[218:219], 0, s[18:19]
	s_addc_u32 s35, s35, 0
	s_add_i32 s36, s62, s33
	global_load_lds_dwordx4 v[192:193], off sc0
	v_lshl_add_u64 v[192:193], s[34:35], 0, v[180:181]
	s_mov_b32 m0, s36
	s_nop 0
	global_load_lds_dwordx4 v[192:193], off sc0
	v_lshl_add_u64 v[192:193], s[34:35], 0, v[184:185]
	s_add_i32 m0, s36, 0x2000
	s_nop 0
	global_load_lds_dwordx4 v[192:193], off sc0
	v_lshl_add_u64 v[192:193], v[220:221], 0, s[18:19]
	s_mov_b32 m0, s46
	s_nop 0
	global_load_lds_dwordx4 v[192:193], off sc0
	v_lshl_add_u64 v[192:193], v[222:223], 0, s[18:19]
	s_mov_b32 m0, s47
	s_nop 0
	global_load_lds_dwordx4 v[192:193], off sc0
	s_waitcnt vmcnt(8)
	s_waitcnt lgkmcnt(0)
	s_barrier
	s_setprio 1
	s_waitcnt lgkmcnt(0)
	v_mfma_f32_16x16x32_bf16 v[62:65], v[130:133], v[162:165], v[62:65]
	v_mfma_f32_16x16x32_bf16 v[58:61], v[138:141], v[162:165], v[58:61]
	v_mfma_f32_16x16x32_bf16 v[54:57], v[130:133], v[170:173], v[54:57]
	v_mfma_f32_16x16x32_bf16 v[50:53], v[138:141], v[170:173], v[50:53]
	v_mfma_f32_16x16x32_bf16 v[30:33], v[130:133], v[196:199], v[30:33]
	v_mfma_f32_16x16x32_bf16 v[26:29], v[138:141], v[196:199], v[26:29]
	v_mfma_f32_16x16x32_bf16 v[22:25], v[130:133], v[204:207], v[22:25]
	v_mfma_f32_16x16x32_bf16 v[18:21], v[138:141], v[204:207], v[18:21]
	v_mfma_f32_16x16x32_bf16 v[62:65], v[134:137], v[166:169], v[62:65]
	v_mfma_f32_16x16x32_bf16 v[58:61], v[142:145], v[166:169], v[58:61]
	v_mfma_f32_16x16x32_bf16 v[54:57], v[134:137], v[174:177], v[54:57]
	v_mfma_f32_16x16x32_bf16 v[50:53], v[142:145], v[174:177], v[50:53]
	v_mfma_f32_16x16x32_bf16 v[30:33], v[134:137], v[200:203], v[30:33]
	v_mfma_f32_16x16x32_bf16 v[26:29], v[142:145], v[200:203], v[26:29]
	v_mfma_f32_16x16x32_bf16 v[22:25], v[134:137], v[208:211], v[22:25]
	v_mfma_f32_16x16x32_bf16 v[18:21], v[142:145], v[208:211], v[18:21]
	s_setprio 0
	s_setprio 1
	v_mfma_f32_16x16x32_bf16 v[46:49], v[146:149], v[162:165], v[46:49]
	v_mfma_f32_16x16x32_bf16 v[42:45], v[154:157], v[162:165], v[42:45]
	v_mfma_f32_16x16x32_bf16 v[38:41], v[146:149], v[170:173], v[38:41]
	v_mfma_f32_16x16x32_bf16 v[34:37], v[154:157], v[170:173], v[34:37]
	v_mfma_f32_16x16x32_bf16 v[14:17], v[146:149], v[196:199], v[14:17]
	v_mfma_f32_16x16x32_bf16 v[10:13], v[154:157], v[196:199], v[10:13]
	v_mfma_f32_16x16x32_bf16 v[6:9], v[146:149], v[204:207], v[6:9]
	v_mfma_f32_16x16x32_bf16 v[2:5], v[154:157], v[204:207], v[2:5]
	v_mfma_f32_16x16x32_bf16 v[46:49], v[150:153], v[166:169], v[46:49]
	v_mfma_f32_16x16x32_bf16 v[42:45], v[158:161], v[166:169], v[42:45]
	v_mfma_f32_16x16x32_bf16 v[38:41], v[150:153], v[174:177], v[38:41]
	v_mfma_f32_16x16x32_bf16 v[34:37], v[158:161], v[174:177], v[34:37]
	v_mfma_f32_16x16x32_bf16 v[14:17], v[150:153], v[200:203], v[14:17]
	v_mfma_f32_16x16x32_bf16 v[10:13], v[158:161], v[200:203], v[10:13]
	v_mfma_f32_16x16x32_bf16 v[6:9], v[150:153], v[208:211], v[6:9]
	v_mfma_f32_16x16x32_bf16 v[2:5], v[158:161], v[208:211], v[2:5]
	s_setprio 0
	s_barrier
	s_add_u32 s30, s30, 0x100
	s_addc_u32 s31, s31, 0
	s_add_u32 s23, s23, 0x100
	s_addc_u32 s29, s29, 0
	s_cmp_ge_i32 s38, s61
	s_mov_b32 s34, s38
	s_cbranch_scc0 .LBB0_357
	s_branch .Lpeeldone_12
.LBB0_357:
	ds_read_b128 v[130:133], v215
	ds_read_b128 v[134:137], v215 offset:1024
	ds_read_b128 v[138:141], v215 offset:2048
	ds_read_b128 v[142:145], v215 offset:3072
	ds_read_b128 v[146:149], v216
	ds_read_b128 v[150:153], v216 offset:1024
	ds_read_b128 v[154:157], v216 offset:2048
	ds_read_b128 v[158:161], v216 offset:3072
	s_add_i32 s38, s34, 2
	s_add_u32 s35, s30, 0xffea0080
	s_addc_u32 s36, s31, -1
	s_cmp_eq_u32 s28, s34
	s_cselect_b32 s34, s26, s23
	s_cselect_b32 s37, s25, s36
	s_cselect_b32 s36, s24, s35
	s_cselect_b32 s35, s27, s29
	v_lshl_add_u64 v[192:193], s[30:31], 0, v[188:189]
	s_add_i32 m0, s40, 0xc000
	ds_read_b128 v[162:165], v217
	ds_read_b128 v[166:169], v217 offset:1024
	ds_read_b128 v[170:173], v217 offset:2048
	ds_read_b128 v[174:177], v217 offset:3072
	ds_read_b128 v[196:199], v217 offset:4096
	ds_read_b128 v[200:203], v217 offset:5120
	ds_read_b128 v[204:207], v217 offset:6144
	ds_read_b128 v[208:211], v217 offset:7168
	global_load_lds_dwordx4 v[192:193], off sc0
	v_lshl_add_u64 v[192:193], s[30:31], 0, v[190:191]
	s_add_i32 m0, s40, 0xe000
	s_nop 0
	global_load_lds_dwordx4 v[192:193], off sc0
	s_waitcnt vmcnt(8)
	s_waitcnt lgkmcnt(0)
	s_barrier
	s_setprio 1
	s_waitcnt lgkmcnt(0)
	v_mfma_f32_16x16x32_bf16 v[126:129], v[130:133], v[162:165], v[126:129]
	v_mfma_f32_16x16x32_bf16 v[122:125], v[138:141], v[162:165], v[122:125]
	v_mfma_f32_16x16x32_bf16 v[118:121], v[130:133], v[170:173], v[118:121]
	v_mfma_f32_16x16x32_bf16 v[114:117], v[138:141], v[170:173], v[114:117]
	v_mfma_f32_16x16x32_bf16 v[94:97], v[130:133], v[196:199], v[94:97]
	v_mfma_f32_16x16x32_bf16 v[90:93], v[138:141], v[196:199], v[90:93]
	v_mfma_f32_16x16x32_bf16 v[86:89], v[130:133], v[204:207], v[86:89]
	v_mfma_f32_16x16x32_bf16 v[82:85], v[138:141], v[204:207], v[82:85]
	v_mfma_f32_16x16x32_bf16 v[126:129], v[134:137], v[166:169], v[126:129]
	v_mfma_f32_16x16x32_bf16 v[122:125], v[142:145], v[166:169], v[122:125]
	v_mfma_f32_16x16x32_bf16 v[118:121], v[134:137], v[174:177], v[118:121]
	v_mfma_f32_16x16x32_bf16 v[114:117], v[142:145], v[174:177], v[114:117]
	v_mfma_f32_16x16x32_bf16 v[94:97], v[134:137], v[200:203], v[94:97]
	v_mfma_f32_16x16x32_bf16 v[90:93], v[142:145], v[200:203], v[90:93]
	v_mfma_f32_16x16x32_bf16 v[86:89], v[134:137], v[208:211], v[86:89]
	v_mfma_f32_16x16x32_bf16 v[82:85], v[142:145], v[208:211], v[82:85]
	s_setprio 0
	s_setprio 1
	v_mfma_f32_16x16x32_bf16 v[110:113], v[146:149], v[162:165], v[110:113]
	v_mfma_f32_16x16x32_bf16 v[106:109], v[154:157], v[162:165], v[106:109]
	v_mfma_f32_16x16x32_bf16 v[102:105], v[146:149], v[170:173], v[102:105]
	v_mfma_f32_16x16x32_bf16 v[98:101], v[154:157], v[170:173], v[98:101]
	v_mfma_f32_16x16x32_bf16 v[78:81], v[146:149], v[196:199], v[78:81]
	v_mfma_f32_16x16x32_bf16 v[74:77], v[154:157], v[196:199], v[74:77]
	v_mfma_f32_16x16x32_bf16 v[70:73], v[146:149], v[204:207], v[70:73]
	v_mfma_f32_16x16x32_bf16 v[66:69], v[154:157], v[204:207], v[66:69]
	v_mfma_f32_16x16x32_bf16 v[110:113], v[150:153], v[166:169], v[110:113]
	v_mfma_f32_16x16x32_bf16 v[106:109], v[158:161], v[166:169], v[106:109]
	v_mfma_f32_16x16x32_bf16 v[102:105], v[150:153], v[174:177], v[102:105]
	v_mfma_f32_16x16x32_bf16 v[98:101], v[158:161], v[174:177], v[98:101]
	v_mfma_f32_16x16x32_bf16 v[78:81], v[150:153], v[200:203], v[78:81]
	v_mfma_f32_16x16x32_bf16 v[74:77], v[158:161], v[200:203], v[74:77]
	v_mfma_f32_16x16x32_bf16 v[70:73], v[150:153], v[208:211], v[70:73]
	v_mfma_f32_16x16x32_bf16 v[66:69], v[158:161], v[208:211], v[66:69]
	s_setprio 0
	s_barrier
	s_add_i32 s39, s53, s33
	v_lshl_add_u64 v[192:193], s[34:35], 0, v[180:181]
	s_mov_b32 m0, s39
	ds_read_b128 v[162:165], v217 offset:16384
	ds_read_b128 v[166:169], v217 offset:17408
	ds_read_b128 v[170:173], v217 offset:18432
	ds_read_b128 v[174:177], v217 offset:19456
	ds_read_b128 v[196:199], v217 offset:20480
	ds_read_b128 v[200:203], v217 offset:21504
	ds_read_b128 v[204:207], v217 offset:22528
	ds_read_b128 v[208:211], v217 offset:23552
	global_load_lds_dwordx4 v[192:193], off sc0
	s_add_i32 m0, s39, 0x2000
	s_add_u32 s62, s34, 0x160000
	v_lshl_add_u64 v[218:219], s[34:35], 0, v[184:185]
	s_addc_u32 s63, s35, 0
	s_add_i32 s39, s54, s33
	global_load_lds_dwordx4 v[218:219], off sc0
	v_lshl_add_u64 v[220:221], s[62:63], 0, v[180:181]
	s_mov_b32 m0, s39
	v_lshl_add_u64 v[222:223], s[36:37], 0, v[182:183]
	global_load_lds_dwordx4 v[220:221], off sc0
	v_lshl_add_u64 v[220:221], s[62:63], 0, v[184:185]
	s_add_i32 m0, s39, 0x2000
	s_nop 0
	global_load_lds_dwordx4 v[220:221], off sc0
	v_lshl_add_u64 v[220:221], s[36:37], 0, v[178:179]
	s_mov_b32 m0, s40
	s_nop 0
	global_load_lds_dwordx4 v[220:221], off sc0
	s_mov_b32 m0, s41
	s_nop 0
	global_load_lds_dwordx4 v[222:223], off sc0
	s_waitcnt vmcnt(8)
	s_waitcnt lgkmcnt(0)
	s_barrier
	s_setprio 1
	s_waitcnt lgkmcnt(0)
	v_mfma_f32_16x16x32_bf16 v[62:65], v[130:133], v[162:165], v[62:65]
	v_mfma_f32_16x16x32_bf16 v[58:61], v[138:141], v[162:165], v[58:61]
	v_mfma_f32_16x16x32_bf16 v[54:57], v[130:133], v[170:173], v[54:57]
	v_mfma_f32_16x16x32_bf16 v[50:53], v[138:141], v[170:173], v[50:53]
	v_mfma_f32_16x16x32_bf16 v[30:33], v[130:133], v[196:199], v[30:33]
	v_mfma_f32_16x16x32_bf16 v[26:29], v[138:141], v[196:199], v[26:29]
	v_mfma_f32_16x16x32_bf16 v[22:25], v[130:133], v[204:207], v[22:25]
	v_mfma_f32_16x16x32_bf16 v[18:21], v[138:141], v[204:207], v[18:21]
	v_mfma_f32_16x16x32_bf16 v[62:65], v[134:137], v[166:169], v[62:65]
	v_mfma_f32_16x16x32_bf16 v[58:61], v[142:145], v[166:169], v[58:61]
	v_mfma_f32_16x16x32_bf16 v[54:57], v[134:137], v[174:177], v[54:57]
	v_mfma_f32_16x16x32_bf16 v[50:53], v[142:145], v[174:177], v[50:53]
	v_mfma_f32_16x16x32_bf16 v[30:33], v[134:137], v[200:203], v[30:33]
	v_mfma_f32_16x16x32_bf16 v[26:29], v[142:145], v[200:203], v[26:29]
	v_mfma_f32_16x16x32_bf16 v[22:25], v[134:137], v[208:211], v[22:25]
	v_mfma_f32_16x16x32_bf16 v[18:21], v[142:145], v[208:211], v[18:21]
	s_setprio 0
	s_setprio 1
	v_mfma_f32_16x16x32_bf16 v[46:49], v[146:149], v[162:165], v[46:49]
	v_mfma_f32_16x16x32_bf16 v[42:45], v[154:157], v[162:165], v[42:45]
	v_mfma_f32_16x16x32_bf16 v[38:41], v[146:149], v[170:173], v[38:41]
	v_mfma_f32_16x16x32_bf16 v[34:37], v[154:157], v[170:173], v[34:37]
	v_mfma_f32_16x16x32_bf16 v[14:17], v[146:149], v[196:199], v[14:17]
	v_mfma_f32_16x16x32_bf16 v[10:13], v[154:157], v[196:199], v[10:13]
	v_mfma_f32_16x16x32_bf16 v[6:9], v[146:149], v[204:207], v[6:9]
	v_mfma_f32_16x16x32_bf16 v[2:5], v[154:157], v[204:207], v[2:5]
	v_mfma_f32_16x16x32_bf16 v[46:49], v[150:153], v[166:169], v[46:49]
	v_mfma_f32_16x16x32_bf16 v[42:45], v[158:161], v[166:169], v[42:45]
	v_mfma_f32_16x16x32_bf16 v[38:41], v[150:153], v[174:177], v[38:41]
	v_mfma_f32_16x16x32_bf16 v[34:37], v[158:161], v[174:177], v[34:37]
	v_mfma_f32_16x16x32_bf16 v[14:17], v[150:153], v[200:203], v[14:17]
	v_mfma_f32_16x16x32_bf16 v[10:13], v[158:161], v[200:203], v[10:13]
	v_mfma_f32_16x16x32_bf16 v[6:9], v[150:153], v[208:211], v[6:9]
	v_mfma_f32_16x16x32_bf16 v[2:5], v[158:161], v[208:211], v[2:5]
	s_setprio 0
	s_barrier
	s_add_i32 s39, 0, 0x18000
	s_add_i32 s62, 0, 0x1c000
	v_add_u32_e32 v142, s39, v213
	v_add_u32_e32 v158, s62, v213
	ds_read_b128 v[130:133], v142
	ds_read_b128 v[134:137], v142 offset:1024
	ds_read_b128 v[138:141], v142 offset:2048
	ds_read_b128 v[142:145], v142 offset:3072
	ds_read_b128 v[146:149], v158
	ds_read_b128 v[150:153], v158 offset:1024
	ds_read_b128 v[154:157], v158 offset:2048
	ds_read_b128 v[158:161], v158 offset:3072
	s_add_u32 s36, s36, 0x160000
	s_addc_u32 s37, s37, 0
	s_mov_b32 m0, s42
	v_lshl_add_u64 v[224:225], s[36:37], 0, v[178:179]
	ds_read_b128 v[162:165], v217 offset:32768
	ds_read_b128 v[166:169], v217 offset:33792
	ds_read_b128 v[170:173], v217 offset:34816
	ds_read_b128 v[174:177], v217 offset:35840
	ds_read_b128 v[196:199], v217 offset:36864
	ds_read_b128 v[200:203], v217 offset:37888
	ds_read_b128 v[204:207], v217 offset:38912
	ds_read_b128 v[208:211], v217 offset:39936
	global_load_lds_dwordx4 v[224:225], off sc0
	v_lshl_add_u64 v[224:225], s[36:37], 0, v[182:183]
	s_mov_b32 m0, s43
	s_nop 0
	global_load_lds_dwordx4 v[224:225], off sc0
	s_waitcnt vmcnt(8)
	s_waitcnt lgkmcnt(0)
	s_barrier
	s_setprio 1
	s_waitcnt lgkmcnt(0)
	v_mfma_f32_16x16x32_bf16 v[126:129], v[130:133], v[162:165], v[126:129]
	v_mfma_f32_16x16x32_bf16 v[122:125], v[138:141], v[162:165], v[122:125]
	v_mfma_f32_16x16x32_bf16 v[118:121], v[130:133], v[170:173], v[118:121]
	v_mfma_f32_16x16x32_bf16 v[114:117], v[138:141], v[170:173], v[114:117]
	v_mfma_f32_16x16x32_bf16 v[94:97], v[130:133], v[196:199], v[94:97]
	v_mfma_f32_16x16x32_bf16 v[90:93], v[138:141], v[196:199], v[90:93]
	v_mfma_f32_16x16x32_bf16 v[86:89], v[130:133], v[204:207], v[86:89]
	v_mfma_f32_16x16x32_bf16 v[82:85], v[138:141], v[204:207], v[82:85]
	v_mfma_f32_16x16x32_bf16 v[126:129], v[134:137], v[166:169], v[126:129]
	v_mfma_f32_16x16x32_bf16 v[122:125], v[142:145], v[166:169], v[122:125]
	v_mfma_f32_16x16x32_bf16 v[118:121], v[134:137], v[174:177], v[118:121]
	v_mfma_f32_16x16x32_bf16 v[114:117], v[142:145], v[174:177], v[114:117]
	v_mfma_f32_16x16x32_bf16 v[94:97], v[134:137], v[200:203], v[94:97]
	v_mfma_f32_16x16x32_bf16 v[90:93], v[142:145], v[200:203], v[90:93]
	v_mfma_f32_16x16x32_bf16 v[86:89], v[134:137], v[208:211], v[86:89]
	v_mfma_f32_16x16x32_bf16 v[82:85], v[142:145], v[208:211], v[82:85]
	s_setprio 0
	s_setprio 1
	v_mfma_f32_16x16x32_bf16 v[110:113], v[146:149], v[162:165], v[110:113]
	v_mfma_f32_16x16x32_bf16 v[106:109], v[154:157], v[162:165], v[106:109]
	v_mfma_f32_16x16x32_bf16 v[102:105], v[146:149], v[170:173], v[102:105]
	v_mfma_f32_16x16x32_bf16 v[98:101], v[154:157], v[170:173], v[98:101]
	v_mfma_f32_16x16x32_bf16 v[78:81], v[146:149], v[196:199], v[78:81]
	v_mfma_f32_16x16x32_bf16 v[74:77], v[154:157], v[196:199], v[74:77]
	v_mfma_f32_16x16x32_bf16 v[70:73], v[146:149], v[204:207], v[70:73]
	v_mfma_f32_16x16x32_bf16 v[66:69], v[154:157], v[204:207], v[66:69]
	v_mfma_f32_16x16x32_bf16 v[110:113], v[150:153], v[166:169], v[110:113]
	v_mfma_f32_16x16x32_bf16 v[106:109], v[158:161], v[166:169], v[106:109]
	v_mfma_f32_16x16x32_bf16 v[102:105], v[150:153], v[174:177], v[102:105]
	v_mfma_f32_16x16x32_bf16 v[98:101], v[158:161], v[174:177], v[98:101]
	v_mfma_f32_16x16x32_bf16 v[78:81], v[150:153], v[200:203], v[78:81]
	v_mfma_f32_16x16x32_bf16 v[74:77], v[158:161], v[200:203], v[74:77]
	v_mfma_f32_16x16x32_bf16 v[70:73], v[150:153], v[208:211], v[70:73]
	v_mfma_f32_16x16x32_bf16 v[66:69], v[158:161], v[208:211], v[66:69]
	s_setprio 0
	s_barrier
	s_add_i32 s36, s39, s33
	v_lshl_add_u64 v[192:193], v[192:193], 0, s[18:19]
	s_mov_b32 m0, s36
	ds_read_b128 v[162:165], v217 offset:49152
	ds_read_b128 v[166:169], v217 offset:50176
	ds_read_b128 v[170:173], v217 offset:51200
	ds_read_b128 v[174:177], v217 offset:52224
	ds_read_b128 v[196:199], v217 offset:53248
	ds_read_b128 v[200:203], v217 offset:54272
	ds_read_b128 v[204:207], v217 offset:55296
	ds_read_b128 v[208:211], v217 offset:56320
	global_load_lds_dwordx4 v[192:193], off sc0
	s_add_i32 m0, s36, 0x2000
	s_add_u32 s34, s34, 0x160080
	v_lshl_add_u64 v[192:193], v[218:219], 0, s[18:19]
	s_addc_u32 s35, s35, 0
	s_add_i32 s36, s62, s33
	global_load_lds_dwordx4 v[192:193], off sc0
	v_lshl_add_u64 v[192:193], s[34:35], 0, v[180:181]
	s_mov_b32 m0, s36
	s_nop 0
	global_load_lds_dwordx4 v[192:193], off sc0
	v_lshl_add_u64 v[192:193], s[34:35], 0, v[184:185]
	s_add_i32 m0, s36, 0x2000
	s_nop 0
	global_load_lds_dwordx4 v[192:193], off sc0
	v_lshl_add_u64 v[192:193], v[220:221], 0, s[18:19]
	s_mov_b32 m0, s46
	s_nop 0
	global_load_lds_dwordx4 v[192:193], off sc0
	v_lshl_add_u64 v[192:193], v[222:223], 0, s[18:19]
	s_mov_b32 m0, s47
	s_nop 0
	global_load_lds_dwordx4 v[192:193], off sc0
	s_waitcnt vmcnt(8)
	s_waitcnt lgkmcnt(0)
	s_barrier
	s_setprio 1
	s_waitcnt lgkmcnt(0)
	v_mfma_f32_16x16x32_bf16 v[62:65], v[130:133], v[162:165], v[62:65]
	v_mfma_f32_16x16x32_bf16 v[58:61], v[138:141], v[162:165], v[58:61]
	v_mfma_f32_16x16x32_bf16 v[54:57], v[130:133], v[170:173], v[54:57]
	v_mfma_f32_16x16x32_bf16 v[50:53], v[138:141], v[170:173], v[50:53]
	v_mfma_f32_16x16x32_bf16 v[30:33], v[130:133], v[196:199], v[30:33]
	v_mfma_f32_16x16x32_bf16 v[26:29], v[138:141], v[196:199], v[26:29]
	v_mfma_f32_16x16x32_bf16 v[22:25], v[130:133], v[204:207], v[22:25]
	v_mfma_f32_16x16x32_bf16 v[18:21], v[138:141], v[204:207], v[18:21]
	v_mfma_f32_16x16x32_bf16 v[62:65], v[134:137], v[166:169], v[62:65]
	v_mfma_f32_16x16x32_bf16 v[58:61], v[142:145], v[166:169], v[58:61]
	v_mfma_f32_16x16x32_bf16 v[54:57], v[134:137], v[174:177], v[54:57]
	v_mfma_f32_16x16x32_bf16 v[50:53], v[142:145], v[174:177], v[50:53]
	v_mfma_f32_16x16x32_bf16 v[30:33], v[134:137], v[200:203], v[30:33]
	v_mfma_f32_16x16x32_bf16 v[26:29], v[142:145], v[200:203], v[26:29]
	v_mfma_f32_16x16x32_bf16 v[22:25], v[134:137], v[208:211], v[22:25]
	v_mfma_f32_16x16x32_bf16 v[18:21], v[142:145], v[208:211], v[18:21]
	s_setprio 0
	s_setprio 1
	v_mfma_f32_16x16x32_bf16 v[46:49], v[146:149], v[162:165], v[46:49]
	v_mfma_f32_16x16x32_bf16 v[42:45], v[154:157], v[162:165], v[42:45]
	v_mfma_f32_16x16x32_bf16 v[38:41], v[146:149], v[170:173], v[38:41]
	v_mfma_f32_16x16x32_bf16 v[34:37], v[154:157], v[170:173], v[34:37]
	v_mfma_f32_16x16x32_bf16 v[14:17], v[146:149], v[196:199], v[14:17]
	v_mfma_f32_16x16x32_bf16 v[10:13], v[154:157], v[196:199], v[10:13]
	v_mfma_f32_16x16x32_bf16 v[6:9], v[146:149], v[204:207], v[6:9]
	v_mfma_f32_16x16x32_bf16 v[2:5], v[154:157], v[204:207], v[2:5]
	v_mfma_f32_16x16x32_bf16 v[46:49], v[150:153], v[166:169], v[46:49]
	v_mfma_f32_16x16x32_bf16 v[42:45], v[158:161], v[166:169], v[42:45]
	v_mfma_f32_16x16x32_bf16 v[38:41], v[150:153], v[174:177], v[38:41]
	v_mfma_f32_16x16x32_bf16 v[34:37], v[158:161], v[174:177], v[34:37]
	v_mfma_f32_16x16x32_bf16 v[14:17], v[150:153], v[200:203], v[14:17]
	v_mfma_f32_16x16x32_bf16 v[10:13], v[158:161], v[200:203], v[10:13]
	v_mfma_f32_16x16x32_bf16 v[6:9], v[150:153], v[208:211], v[6:9]
	v_mfma_f32_16x16x32_bf16 v[2:5], v[158:161], v[208:211], v[2:5]
	s_setprio 0
	s_barrier
	s_add_u32 s30, s30, 0x100
	s_addc_u32 s31, s31, 0
	s_add_u32 s23, s23, 0x100
	s_addc_u32 s29, s29, 0
	s_cmp_ge_i32 s38, s61
	s_mov_b32 s34, s38
	s_cbranch_scc0 .LBB0_357

.LBB0_531:
	v_readlane_b32 s2, v249, 11
	v_readlane_b32 s3, v249, 12
	s_cmp_gt_i32 s2, 7
	s_cselect_b64 s[0:1], -1, 0
	s_cmp_lt_i32 s3, 8
	s_cselect_b64 s[2:3], -1, 0
	s_or_b64 s[0:1], s[0:1], s[2:3]
	s_and_b64 vcc, exec, s[0:1]
	s_cbranch_vccnz .LBB0_548
	v_readlane_b32 s2, v249, 0
	s_cmpk_gt_i32 s2, 0x2ff
	v_readfirstlane_b32 s9, v0
	s_cbranch_scc1 .LBB0_548
	v_lshrrev_b32_e32 v2, 5, v0
	v_lshrrev_b32_e32 v4, 1, v0
	v_and_b32_e32 v2, 4, v2
	v_bfe_u32 v3, v0, 2, 2
	v_and_b32_e32 v13, 24, v4
	v_or3_b32 v2, v2, v3, v13
	v_lshlrev_b32_e32 v3, 4, v0
	v_or_b32_e32 v10, 0x2000, v3
	v_lshrrev_b32_e32 v4, 7, v10
	s_movk_i32 s4, 0x60
	s_add_u32 s2, s82, 0x10c00000
	v_and_or_b32 v5, v4, s4, v2
	v_bfe_u32 v14, v0, 2, 4
	s_movk_i32 s4, 0x70
	v_readlane_b32 s7, v249, 0
	s_addc_u32 s3, s83, 0
	v_and_or_b32 v4, v4, s4, v14
	s_ashr_i32 s4, s7, 31
	s_lshr_b32 s4, s4, 29
	s_add_i32 s4, s7, s4
	s_lshr_b32 s6, s9, 6
	s_and_b32 s5, s4, -8
	s_lshr_b32 s10, s9, 8
	s_lshl_b32 s33, s6, 10
	s_sub_i32 s5, s7, s5
	s_cmp_lt_i32 s5, 0
	s_movk_i32 s40, 0x61
	s_cselect_b32 s7, s40, 0x60
	s_mul_i32 s5, s7, s5
	s_ashr_i32 s4, s4, 3
	s_add_i32 s4, s5, s4
	s_ashr_i32 s5, s4, 31
	s_lshr_b32 s5, s5, 25
	s_add_i32 s5, s4, s5
	s_ashr_i32 s7, s5, 7
	s_and_b32 s5, s5, 0xffffff80
	s_sub_i32 s4, s4, s5
	s_bfe_i32 s5, s4, 0x80000
	s_bfe_u32 s5, s5, 0x3000c
	s_add_i32 s5, s4, s5
	s_bfe_i32 s8, s5, 0x80000
	s_and_b32 s5, s5, 0xf8
	s_sub_i32 s4, s4, s5
	s_lshl_b32 s7, s7, 3
	s_sext_i32_i16 s8, s8
	s_sext_i32_i8 s4, s4
	v_and_b32_e32 v6, 32, v0
	s_lshr_b32 s8, s8, 3
	s_add_i32 s26, s7, s4
	v_bitop3_b32 v11, v3, v6, 48 bitop3:0x6c
	v_and_b32_e32 v12, 64, v0
	s_ashr_i32 s27, s26, 31
	s_bfe_i64 s[12:13], s[8:9], 0x100000
	v_or_b32_e32 v3, v11, v12
	s_lshl_b64 s[4:5], s[26:27], 20
	s_lshl_b64 s[12:13], s[12:13], 20
	v_lshl_or_b32 v132, v4, 12, v3
	v_lshrrev_b32_e32 v4, 3, v0
	s_add_u32 s36, s2, s12
	v_and_or_b32 v2, v4, 32, v2
	s_addc_u32 s37, s3, s13
	s_add_i32 s27, s33, 0
	v_lshl_or_b32 v134, v2, 12, v3
	s_add_i32 m0, s27, 0x10000
	v_lshl_or_b32 v130, v5, 12, v3
	global_load_lds_dwordx4 v134, s[36:37] sc0
	s_add_i32 m0, s27, 0x12000
	s_add_u32 s12, s36, 0x80000
	global_load_lds_dwordx4 v130, s[36:37] sc0
	s_addc_u32 s13, s37, 0
	s_add_i32 m0, s27, 0x14000
	v_and_or_b32 v2, v4, 48, v14
	global_load_lds_dwordx4 v134, s[12:13] sc0
	s_add_i32 m0, s27, 0x16000
	v_lshl_or_b32 v136, v2, 12, v3
	global_load_lds_dwordx4 v130, s[12:13] sc0
	v_readlane_b32 s12, v249, 50
	v_readlane_b32 s13, v249, 51
	s_add_u32 s34, s12, s4
	s_addc_u32 s35, s13, s5
	s_add_i32 s41, s27, 0x2000
	s_mov_b32 m0, s27
	s_add_u32 s4, s34, 0x80000
	global_load_lds_dwordx4 v136, s[34:35] sc0
	s_mov_b32 m0, s41
	s_addc_u32 s5, s35, 0
	s_add_i32 s42, s27, 0x4000
	global_load_lds_dwordx4 v132, s[34:35] sc0
	s_mov_b32 m0, s42
	s_add_i32 s43, s27, 0x6000
	global_load_lds_dwordx4 v136, s[4:5] sc0
	s_mov_b32 m0, s43
	v_mov_b32_e32 v135, 0
	global_load_lds_dwordx4 v132, s[4:5] sc0
	v_mov_b32_e32 v131, v135
	v_mov_b32_e32 v137, v135
	v_mov_b32_e32 v133, v135
	s_cmp_eq_u32 s10, 1
	s_mov_b32 s44, 0
	v_lshl_add_u64 v[8:9], s[36:37], 0, v[134:135]
	v_lshl_add_u64 v[6:7], s[36:37], 0, v[130:131]
	v_lshl_add_u64 v[2:3], s[34:35], 0, v[136:137]
	s_cselect_b64 s[4:5], -1, 0
	s_cmp_lg_u32 s10, 1
	v_lshl_add_u64 v[4:5], s[34:35], 0, v[132:133]
	s_cbranch_scc1 .LBB0_535
	s_barrier
.LBB0_535:
	s_lshl_b32 s6, s6, 5
	s_and_b32 s16, s6, 0x60
	s_mov_b64 s[6:7], 0x80
	s_add_i32 m0, s27, 0x18000
	v_lshl_add_u64 v[8:9], v[8:9], 0, s[6:7]
	s_lshl_b32 s11, s10, 13
	s_lshl_b32 s17, s16, 7
	s_waitcnt vmcnt(2)
	s_barrier
	global_load_lds_dwordx4 v[8:9], off sc0
	v_lshl_add_u64 v[6:7], v[6:7], 0, s[6:7]
	s_add_i32 m0, s27, 0x1a000
	s_add_i32 s45, s27, 0x8000
	s_add_i32 s46, s27, 0xa000
	global_load_lds_dwordx4 v[6:7], off sc0
	v_lshl_add_u64 v[2:3], v[2:3], 0, s[6:7]
	s_mov_b32 m0, s45
	s_add_u32 s12, s36, 0x80080
	global_load_lds_dwordx4 v[2:3], off sc0
	v_lshl_add_u64 v[2:3], v[4:5], 0, s[6:7]
	s_mov_b32 m0, s46
	s_addc_u32 s13, s37, 0
	global_load_lds_dwordx4 v[2:3], off sc0
	s_add_i32 m0, s27, 0x1c000
	v_lshl_add_u64 v[2:3], s[12:13], 0, v[134:135]
	global_load_lds_dwordx4 v[2:3], off sc0
	v_lshl_add_u64 v[2:3], s[12:13], 0, v[130:131]
	s_add_i32 m0, s27, 0x1e000
	s_sext_i32_i8 s53, s8
	global_load_lds_dwordx4 v[2:3], off sc0
	v_and_b32_e32 v2, 15, v0
	v_lshlrev_b32_e32 v3, 1, v13
	v_lshlrev_b32_e32 v4, 2, v0
	v_lshlrev_b32_e32 v5, 6, v0
	s_movk_i32 s8, 0x3c0
	v_lshl_or_b32 v142, s10, 6, v2
	v_lshl_or_b32 v2, v2, 6, v3
	v_and_b32_e32 v4, 32, v4
	v_and_or_b32 v3, v5, s8, v3
	v_bitop3_b32 v143, s17, v3, v4 bitop3:0xf6
	v_lshlrev_b32_e32 v3, 9, v0
	v_bitop3_b32 v2, v2, s11, v4 bitop3:0xde
	v_and_b32_e32 v3, 0x30000, v3
	v_lshlrev_b32_e32 v4, 12, v14
	v_or3_b32 v3, v11, v3, v4
	v_add_u32_e32 v138, v3, v12
	v_lshlrev_b32_e32 v3, 5, v10
	s_waitcnt vmcnt(6)
	s_cmpk_lt_u32 s9, 0x100
	v_and_b32_e32 v3, 0x70000, v3
	s_cselect_b64 s[8:9], -1, 0
	v_or3_b32 v3, v11, v3, v4
	s_add_i32 s47, 0, 0x10000
	s_add_i32 s48, 0, 0x14000
	v_or_b32_e32 v144, s16, v13
	v_mov_b32_e32 v139, v135
	v_add_u32_e32 v140, v3, v12
	v_mov_b32_e32 v141, v135
	v_add_u32_e32 v145, s47, v143
	v_add_u32_e32 v146, s48, v143
	v_add_u32_e32 v147, 0, v2
	s_mov_b64 s[10:11], 0x100000
	s_mov_b32 s49, 0x100000
	s_mov_b64 s[12:13], 0x120000
	s_mov_b32 s50, 0x120000
	s_mov_b64 s[16:17], 0x140000
	s_mov_b32 s51, 0x140000
	s_mov_b64 s[18:19], 0x160000
	s_mov_b32 s52, 0x160000
	s_barrier
	s_branch .LBB0_538

.Lpeel_11:
	ds_read_b128 v[148:151], v145
	ds_read_b128 v[152:155], v145 offset:1024
	ds_read_b128 v[156:159], v145 offset:2048
	ds_read_b128 v[160:163], v145 offset:3072
	ds_read_b128 v[164:167], v146
	ds_read_b128 v[168:171], v146 offset:1024
	ds_read_b128 v[172:175], v146 offset:2048
	ds_read_b128 v[176:179], v146 offset:3072
	s_add_u32 s36, s34, 0xfff80080
	s_addc_u32 s37, s35, -1
	s_cmp_eq_u32 s58, 28
	s_cselect_b32 s39, s21, s37
	s_cselect_b32 s38, s54, s36
	s_cselect_b32 s37, s23, s57
	s_cselect_b32 s36, s55, s56
	v_lshl_add_u64 v[192:193], s[34:35], 0, v[138:139]
	s_add_i32 m0, s27, 0xc000
	ds_read_b128 v[180:183], v147
	ds_read_b128 v[184:187], v147 offset:1024
	ds_read_b128 v[188:191], v147 offset:2048
	ds_read_b128 v[196:199], v147 offset:3072
	ds_read_b128 v[200:203], v147 offset:4096
	ds_read_b128 v[204:207], v147 offset:5120
	ds_read_b128 v[208:211], v147 offset:6144
	ds_read_b128 v[212:215], v147 offset:7168
	global_load_lds_dwordx4 v[192:193], off sc0
	v_lshl_add_u64 v[192:193], s[34:35], 0, v[140:141]
	s_add_i32 m0, s27, 0xe000
	s_nop 0
	global_load_lds_dwordx4 v[192:193], off sc0
	s_waitcnt vmcnt(8)
	s_waitcnt lgkmcnt(0)
	s_barrier
	s_setprio 1
	s_waitcnt lgkmcnt(0)
	v_mfma_f32_16x16x32_bf16 v[126:129], v[148:151], v[180:183], 0
	v_mfma_f32_16x16x32_bf16 v[122:125], v[156:159], v[180:183], 0
	v_mfma_f32_16x16x32_bf16 v[118:121], v[148:151], v[188:191], 0
	v_mfma_f32_16x16x32_bf16 v[114:117], v[156:159], v[188:191], 0
	v_mfma_f32_16x16x32_bf16 v[102:105], v[148:151], v[200:203], 0
	v_mfma_f32_16x16x32_bf16 v[98:101], v[156:159], v[200:203], 0
	v_mfma_f32_16x16x32_bf16 v[86:89], v[148:151], v[208:211], 0
	v_mfma_f32_16x16x32_bf16 v[82:85], v[156:159], v[208:211], 0
	v_mfma_f32_16x16x32_bf16 v[126:129], v[152:155], v[184:187], v[126:129]
	v_mfma_f32_16x16x32_bf16 v[122:125], v[160:163], v[184:187], v[122:125]
	v_mfma_f32_16x16x32_bf16 v[118:121], v[152:155], v[196:199], v[118:121]
	v_mfma_f32_16x16x32_bf16 v[114:117], v[160:163], v[196:199], v[114:117]
	v_mfma_f32_16x16x32_bf16 v[102:105], v[152:155], v[204:207], v[102:105]
	v_mfma_f32_16x16x32_bf16 v[98:101], v[160:163], v[204:207], v[98:101]
	v_mfma_f32_16x16x32_bf16 v[86:89], v[152:155], v[212:215], v[86:89]
	v_mfma_f32_16x16x32_bf16 v[82:85], v[160:163], v[212:215], v[82:85]
	s_setprio 0
	s_setprio 1
	v_mfma_f32_16x16x32_bf16 v[110:113], v[164:167], v[180:183], 0
	v_mfma_f32_16x16x32_bf16 v[106:109], v[172:175], v[180:183], 0
	v_mfma_f32_16x16x32_bf16 v[94:97], v[164:167], v[188:191], 0
	v_mfma_f32_16x16x32_bf16 v[90:93], v[172:175], v[188:191], 0
	v_mfma_f32_16x16x32_bf16 v[78:81], v[164:167], v[200:203], 0
	v_mfma_f32_16x16x32_bf16 v[74:77], v[172:175], v[200:203], 0
	v_mfma_f32_16x16x32_bf16 v[70:73], v[164:167], v[208:211], 0
	v_mfma_f32_16x16x32_bf16 v[66:69], v[172:175], v[208:211], 0
	v_mfma_f32_16x16x32_bf16 v[110:113], v[168:171], v[184:187], v[110:113]
	v_mfma_f32_16x16x32_bf16 v[106:109], v[176:179], v[184:187], v[106:109]
	v_mfma_f32_16x16x32_bf16 v[94:97], v[168:171], v[196:199], v[94:97]
	v_mfma_f32_16x16x32_bf16 v[90:93], v[176:179], v[196:199], v[90:93]
	v_mfma_f32_16x16x32_bf16 v[78:81], v[168:171], v[204:207], v[78:81]
	v_mfma_f32_16x16x32_bf16 v[74:77], v[176:179], v[204:207], v[74:77]
	v_mfma_f32_16x16x32_bf16 v[70:73], v[168:171], v[212:215], v[70:73]
	v_mfma_f32_16x16x32_bf16 v[66:69], v[176:179], v[212:215], v[66:69]
	s_setprio 0
	s_barrier
	s_add_i32 s59, s47, s33
	v_lshl_add_u64 v[192:193], s[36:37], 0, v[134:135]
	s_mov_b32 m0, s59
	ds_read_b128 v[180:183], v147 offset:16384
	ds_read_b128 v[184:187], v147 offset:17408
	ds_read_b128 v[188:191], v147 offset:18432
	ds_read_b128 v[196:199], v147 offset:19456
	ds_read_b128 v[200:203], v147 offset:20480
	ds_read_b128 v[204:207], v147 offset:21504
	ds_read_b128 v[208:211], v147 offset:22528
	ds_read_b128 v[212:215], v147 offset:23552
	global_load_lds_dwordx4 v[192:193], off sc0
	s_add_i32 m0, s59, 0x2000
	s_add_u32 s60, s36, 0x80000
	v_lshl_add_u64 v[216:217], s[36:37], 0, v[130:131]
	s_addc_u32 s61, s37, 0
	s_add_i32 s59, s48, s33
	global_load_lds_dwordx4 v[216:217], off sc0
	v_lshl_add_u64 v[218:219], s[60:61], 0, v[134:135]
	s_mov_b32 m0, s59
	v_lshl_add_u64 v[220:221], s[38:39], 0, v[132:133]
	global_load_lds_dwordx4 v[218:219], off sc0
	v_lshl_add_u64 v[218:219], s[60:61], 0, v[130:131]
	s_add_i32 m0, s59, 0x2000
	s_nop 0
	global_load_lds_dwordx4 v[218:219], off sc0
	v_lshl_add_u64 v[218:219], s[38:39], 0, v[136:137]
	s_mov_b32 m0, s27
	s_nop 0
	global_load_lds_dwordx4 v[218:219], off sc0
	s_mov_b32 m0, s41
	s_nop 0
	global_load_lds_dwordx4 v[220:221], off sc0
	s_waitcnt vmcnt(8)
	s_waitcnt lgkmcnt(0)
	s_barrier
	s_setprio 1
	s_waitcnt lgkmcnt(0)
	v_mfma_f32_16x16x32_bf16 v[62:65], v[148:151], v[180:183], 0
	v_mfma_f32_16x16x32_bf16 v[58:61], v[156:159], v[180:183], 0
	v_mfma_f32_16x16x32_bf16 v[54:57], v[148:151], v[188:191], 0
	v_mfma_f32_16x16x32_bf16 v[50:53], v[156:159], v[188:191], 0
	v_mfma_f32_16x16x32_bf16 v[38:41], v[148:151], v[200:203], 0
	v_mfma_f32_16x16x32_bf16 v[34:37], v[156:159], v[200:203], 0
	v_mfma_f32_16x16x32_bf16 v[22:25], v[148:151], v[208:211], 0
	v_mfma_f32_16x16x32_bf16 v[18:21], v[156:159], v[208:211], 0
	v_mfma_f32_16x16x32_bf16 v[62:65], v[152:155], v[184:187], v[62:65]
	v_mfma_f32_16x16x32_bf16 v[58:61], v[160:163], v[184:187], v[58:61]
	v_mfma_f32_16x16x32_bf16 v[54:57], v[152:155], v[196:199], v[54:57]
	v_mfma_f32_16x16x32_bf16 v[50:53], v[160:163], v[196:199], v[50:53]
	v_mfma_f32_16x16x32_bf16 v[38:41], v[152:155], v[204:207], v[38:41]
	v_mfma_f32_16x16x32_bf16 v[34:37], v[160:163], v[204:207], v[34:37]
	v_mfma_f32_16x16x32_bf16 v[22:25], v[152:155], v[212:215], v[22:25]
	v_mfma_f32_16x16x32_bf16 v[18:21], v[160:163], v[212:215], v[18:21]
	s_setprio 0
	s_setprio 1
	v_mfma_f32_16x16x32_bf16 v[46:49], v[164:167], v[180:183], 0
	v_mfma_f32_16x16x32_bf16 v[42:45], v[172:175], v[180:183], 0
	v_mfma_f32_16x16x32_bf16 v[30:33], v[164:167], v[188:191], 0
	v_mfma_f32_16x16x32_bf16 v[26:29], v[172:175], v[188:191], 0
	v_mfma_f32_16x16x32_bf16 v[14:17], v[164:167], v[200:203], 0
	v_mfma_f32_16x16x32_bf16 v[10:13], v[172:175], v[200:203], 0
	v_mfma_f32_16x16x32_bf16 v[6:9], v[164:167], v[208:211], 0
	v_mfma_f32_16x16x32_bf16 v[2:5], v[172:175], v[208:211], 0
	v_mfma_f32_16x16x32_bf16 v[46:49], v[168:171], v[184:187], v[46:49]
	v_mfma_f32_16x16x32_bf16 v[42:45], v[176:179], v[184:187], v[42:45]
	v_mfma_f32_16x16x32_bf16 v[30:33], v[168:171], v[196:199], v[30:33]
	v_mfma_f32_16x16x32_bf16 v[26:29], v[176:179], v[196:199], v[26:29]
	v_mfma_f32_16x16x32_bf16 v[14:17], v[168:171], v[204:207], v[14:17]
	v_mfma_f32_16x16x32_bf16 v[10:13], v[176:179], v[204:207], v[10:13]
	v_mfma_f32_16x16x32_bf16 v[6:9], v[168:171], v[212:215], v[6:9]
	v_mfma_f32_16x16x32_bf16 v[2:5], v[176:179], v[212:215], v[2:5]
	s_setprio 0
	s_barrier
	s_add_i32 s59, 0, 0x18000
	s_add_i32 s60, 0, 0x1c000
	v_add_u32_e32 v160, s59, v143
	v_add_u32_e32 v176, s60, v143
	ds_read_b128 v[148:151], v160
	ds_read_b128 v[152:155], v160 offset:1024
	ds_read_b128 v[156:159], v160 offset:2048
	ds_read_b128 v[160:163], v160 offset:3072
	ds_read_b128 v[164:167], v176
	ds_read_b128 v[168:171], v176 offset:1024
	ds_read_b128 v[172:175], v176 offset:2048
	ds_read_b128 v[176:179], v176 offset:3072
	s_add_u32 s38, s38, 0x80000
	s_addc_u32 s39, s39, 0
	s_mov_b32 m0, s42
	v_lshl_add_u64 v[222:223], s[38:39], 0, v[136:137]
	ds_read_b128 v[180:183], v147 offset:32768
	ds_read_b128 v[184:187], v147 offset:33792
	ds_read_b128 v[188:191], v147 offset:34816
	ds_read_b128 v[196:199], v147 offset:35840
	ds_read_b128 v[200:203], v147 offset:36864
	ds_read_b128 v[204:207], v147 offset:37888
	ds_read_b128 v[208:211], v147 offset:38912
	ds_read_b128 v[212:215], v147 offset:39936
	global_load_lds_dwordx4 v[222:223], off sc0
	v_lshl_add_u64 v[222:223], s[38:39], 0, v[132:133]
	s_mov_b32 m0, s43
	s_nop 0
	global_load_lds_dwordx4 v[222:223], off sc0
	s_waitcnt vmcnt(8)
	s_waitcnt lgkmcnt(0)
	s_barrier
	s_setprio 1
	s_waitcnt lgkmcnt(0)
	v_mfma_f32_16x16x32_bf16 v[126:129], v[148:151], v[180:183], v[126:129]
	v_mfma_f32_16x16x32_bf16 v[122:125], v[156:159], v[180:183], v[122:125]
	v_mfma_f32_16x16x32_bf16 v[118:121], v[148:151], v[188:191], v[118:121]
	v_mfma_f32_16x16x32_bf16 v[114:117], v[156:159], v[188:191], v[114:117]
	v_mfma_f32_16x16x32_bf16 v[102:105], v[148:151], v[200:203], v[102:105]
	v_mfma_f32_16x16x32_bf16 v[98:101], v[156:159], v[200:203], v[98:101]
	v_mfma_f32_16x16x32_bf16 v[86:89], v[148:151], v[208:211], v[86:89]
	v_mfma_f32_16x16x32_bf16 v[82:85], v[156:159], v[208:211], v[82:85]
	v_mfma_f32_16x16x32_bf16 v[126:129], v[152:155], v[184:187], v[126:129]
	v_mfma_f32_16x16x32_bf16 v[122:125], v[160:163], v[184:187], v[122:125]
	v_mfma_f32_16x16x32_bf16 v[118:121], v[152:155], v[196:199], v[118:121]
	v_mfma_f32_16x16x32_bf16 v[114:117], v[160:163], v[196:199], v[114:117]
	v_mfma_f32_16x16x32_bf16 v[102:105], v[152:155], v[204:207], v[102:105]
	v_mfma_f32_16x16x32_bf16 v[98:101], v[160:163], v[204:207], v[98:101]
	v_mfma_f32_16x16x32_bf16 v[86:89], v[152:155], v[212:215], v[86:89]
	v_mfma_f32_16x16x32_bf16 v[82:85], v[160:163], v[212:215], v[82:85]
	s_setprio 0
	s_setprio 1
	v_mfma_f32_16x16x32_bf16 v[110:113], v[164:167], v[180:183], v[110:113]
	v_mfma_f32_16x16x32_bf16 v[106:109], v[172:175], v[180:183], v[106:109]
	v_mfma_f32_16x16x32_bf16 v[94:97], v[164:167], v[188:191], v[94:97]
	v_mfma_f32_16x16x32_bf16 v[90:93], v[172:175], v[188:191], v[90:93]
	v_mfma_f32_16x16x32_bf16 v[78:81], v[164:167], v[200:203], v[78:81]
	v_mfma_f32_16x16x32_bf16 v[74:77], v[172:175], v[200:203], v[74:77]
	v_mfma_f32_16x16x32_bf16 v[70:73], v[164:167], v[208:211], v[70:73]
	v_mfma_f32_16x16x32_bf16 v[66:69], v[172:175], v[208:211], v[66:69]
	v_mfma_f32_16x16x32_bf16 v[110:113], v[168:171], v[184:187], v[110:113]
	v_mfma_f32_16x16x32_bf16 v[106:109], v[176:179], v[184:187], v[106:109]
	v_mfma_f32_16x16x32_bf16 v[94:97], v[168:171], v[196:199], v[94:97]
	v_mfma_f32_16x16x32_bf16 v[90:93], v[176:179], v[196:199], v[90:93]
	v_mfma_f32_16x16x32_bf16 v[78:81], v[168:171], v[204:207], v[78:81]
	v_mfma_f32_16x16x32_bf16 v[74:77], v[176:179], v[204:207], v[74:77]
	v_mfma_f32_16x16x32_bf16 v[70:73], v[168:171], v[212:215], v[70:73]
	v_mfma_f32_16x16x32_bf16 v[66:69], v[176:179], v[212:215], v[66:69]
	s_setprio 0
	s_barrier
	s_add_i32 s38, s59, s33
	v_lshl_add_u64 v[192:193], v[192:193], 0, s[6:7]
	s_mov_b32 m0, s38
	ds_read_b128 v[180:183], v147 offset:49152
	ds_read_b128 v[184:187], v147 offset:50176
	ds_read_b128 v[188:191], v147 offset:51200
	ds_read_b128 v[196:199], v147 offset:52224
	ds_read_b128 v[200:203], v147 offset:53248
	ds_read_b128 v[204:207], v147 offset:54272
	ds_read_b128 v[208:211], v147 offset:55296
	ds_read_b128 v[212:215], v147 offset:56320
	global_load_lds_dwordx4 v[192:193], off sc0
	s_add_i32 m0, s38, 0x2000
	s_add_u32 s36, s36, 0x80080
	v_lshl_add_u64 v[192:193], v[216:217], 0, s[6:7]
	s_addc_u32 s37, s37, 0
	s_add_i32 s38, s60, s33
	global_load_lds_dwordx4 v[192:193], off sc0
	v_lshl_add_u64 v[192:193], s[36:37], 0, v[134:135]
	s_mov_b32 m0, s38
	s_nop 0
	global_load_lds_dwordx4 v[192:193], off sc0
	v_lshl_add_u64 v[192:193], s[36:37], 0, v[130:131]
	s_add_i32 m0, s38, 0x2000
	s_nop 0
	global_load_lds_dwordx4 v[192:193], off sc0
	v_lshl_add_u64 v[192:193], v[218:219], 0, s[6:7]
	s_mov_b32 m0, s45
	s_nop 0
	global_load_lds_dwordx4 v[192:193], off sc0
	v_lshl_add_u64 v[192:193], v[220:221], 0, s[6:7]
	s_mov_b32 m0, s46
	s_nop 0
	global_load_lds_dwordx4 v[192:193], off sc0
	s_waitcnt vmcnt(8)
	s_waitcnt lgkmcnt(0)
	s_barrier
	s_setprio 1
	s_waitcnt lgkmcnt(0)
	v_mfma_f32_16x16x32_bf16 v[62:65], v[148:151], v[180:183], v[62:65]
	v_mfma_f32_16x16x32_bf16 v[58:61], v[156:159], v[180:183], v[58:61]
	v_mfma_f32_16x16x32_bf16 v[54:57], v[148:151], v[188:191], v[54:57]
	v_mfma_f32_16x16x32_bf16 v[50:53], v[156:159], v[188:191], v[50:53]
	v_mfma_f32_16x16x32_bf16 v[38:41], v[148:151], v[200:203], v[38:41]
	v_mfma_f32_16x16x32_bf16 v[34:37], v[156:159], v[200:203], v[34:37]
	v_mfma_f32_16x16x32_bf16 v[22:25], v[148:151], v[208:211], v[22:25]
	v_mfma_f32_16x16x32_bf16 v[18:21], v[156:159], v[208:211], v[18:21]
	v_mfma_f32_16x16x32_bf16 v[62:65], v[152:155], v[184:187], v[62:65]
	v_mfma_f32_16x16x32_bf16 v[58:61], v[160:163], v[184:187], v[58:61]
	v_mfma_f32_16x16x32_bf16 v[54:57], v[152:155], v[196:199], v[54:57]
	v_mfma_f32_16x16x32_bf16 v[50:53], v[160:163], v[196:199], v[50:53]
	v_mfma_f32_16x16x32_bf16 v[38:41], v[152:155], v[204:207], v[38:41]
	v_mfma_f32_16x16x32_bf16 v[34:37], v[160:163], v[204:207], v[34:37]
	v_mfma_f32_16x16x32_bf16 v[22:25], v[152:155], v[212:215], v[22:25]
	v_mfma_f32_16x16x32_bf16 v[18:21], v[160:163], v[212:215], v[18:21]
	s_setprio 0
	s_setprio 1
	v_mfma_f32_16x16x32_bf16 v[46:49], v[164:167], v[180:183], v[46:49]
	v_mfma_f32_16x16x32_bf16 v[42:45], v[172:175], v[180:183], v[42:45]
	v_mfma_f32_16x16x32_bf16 v[30:33], v[164:167], v[188:191], v[30:33]
	v_mfma_f32_16x16x32_bf16 v[26:29], v[172:175], v[188:191], v[26:29]
	v_mfma_f32_16x16x32_bf16 v[14:17], v[164:167], v[200:203], v[14:17]
	v_mfma_f32_16x16x32_bf16 v[10:13], v[172:175], v[200:203], v[10:13]
	v_mfma_f32_16x16x32_bf16 v[6:9], v[164:167], v[208:211], v[6:9]
	v_mfma_f32_16x16x32_bf16 v[2:5], v[172:175], v[208:211], v[2:5]
	v_mfma_f32_16x16x32_bf16 v[46:49], v[168:171], v[184:187], v[46:49]
	v_mfma_f32_16x16x32_bf16 v[42:45], v[176:179], v[184:187], v[42:45]
	v_mfma_f32_16x16x32_bf16 v[30:33], v[168:171], v[196:199], v[30:33]
	v_mfma_f32_16x16x32_bf16 v[26:29], v[176:179], v[196:199], v[26:29]
	v_mfma_f32_16x16x32_bf16 v[14:17], v[168:171], v[204:207], v[14:17]
	v_mfma_f32_16x16x32_bf16 v[10:13], v[176:179], v[204:207], v[10:13]
	v_mfma_f32_16x16x32_bf16 v[6:9], v[168:171], v[212:215], v[6:9]
	v_mfma_f32_16x16x32_bf16 v[2:5], v[176:179], v[212:215], v[2:5]
	s_setprio 0
	s_barrier
	s_add_i32 s58, s58, 2
	s_add_u32 s34, s34, 0x100
	s_addc_u32 s35, s35, 0
	s_add_u32 s56, s56, 0x100
	s_addc_u32 s57, s57, 0
	s_cmp_gt_u32 s58, 29
	s_cbranch_scc0 .LBB0_541
	s_branch .Lpeeldone_11
.LBB0_541:
	ds_read_b128 v[148:151], v145
	ds_read_b128 v[152:155], v145 offset:1024
	ds_read_b128 v[156:159], v145 offset:2048
	ds_read_b128 v[160:163], v145 offset:3072
	ds_read_b128 v[164:167], v146
	ds_read_b128 v[168:171], v146 offset:1024
	ds_read_b128 v[172:175], v146 offset:2048
	ds_read_b128 v[176:179], v146 offset:3072
	s_add_u32 s36, s34, 0xfff80080
	s_addc_u32 s37, s35, -1
	s_cmp_eq_u32 s58, 28
	s_cselect_b32 s39, s21, s37
	s_cselect_b32 s38, s54, s36
	s_cselect_b32 s37, s23, s57
	s_cselect_b32 s36, s55, s56
	v_lshl_add_u64 v[192:193], s[34:35], 0, v[138:139]
	s_add_i32 m0, s27, 0xc000
	ds_read_b128 v[180:183], v147
	ds_read_b128 v[184:187], v147 offset:1024
	ds_read_b128 v[188:191], v147 offset:2048
	ds_read_b128 v[196:199], v147 offset:3072
	ds_read_b128 v[200:203], v147 offset:4096
	ds_read_b128 v[204:207], v147 offset:5120
	ds_read_b128 v[208:211], v147 offset:6144
	ds_read_b128 v[212:215], v147 offset:7168
	global_load_lds_dwordx4 v[192:193], off sc0
	v_lshl_add_u64 v[192:193], s[34:35], 0, v[140:141]
	s_add_i32 m0, s27, 0xe000
	s_nop 0
	global_load_lds_dwordx4 v[192:193], off sc0
	s_waitcnt vmcnt(8)
	s_waitcnt lgkmcnt(0)
	s_barrier
	s_setprio 1
	s_waitcnt lgkmcnt(0)
	v_mfma_f32_16x16x32_bf16 v[126:129], v[148:151], v[180:183], v[126:129]
	v_mfma_f32_16x16x32_bf16 v[122:125], v[156:159], v[180:183], v[122:125]
	v_mfma_f32_16x16x32_bf16 v[118:121], v[148:151], v[188:191], v[118:121]
	v_mfma_f32_16x16x32_bf16 v[114:117], v[156:159], v[188:191], v[114:117]
	v_mfma_f32_16x16x32_bf16 v[102:105], v[148:151], v[200:203], v[102:105]
	v_mfma_f32_16x16x32_bf16 v[98:101], v[156:159], v[200:203], v[98:101]
	v_mfma_f32_16x16x32_bf16 v[86:89], v[148:151], v[208:211], v[86:89]
	v_mfma_f32_16x16x32_bf16 v[82:85], v[156:159], v[208:211], v[82:85]
	v_mfma_f32_16x16x32_bf16 v[126:129], v[152:155], v[184:187], v[126:129]
	v_mfma_f32_16x16x32_bf16 v[122:125], v[160:163], v[184:187], v[122:125]
	v_mfma_f32_16x16x32_bf16 v[118:121], v[152:155], v[196:199], v[118:121]
	v_mfma_f32_16x16x32_bf16 v[114:117], v[160:163], v[196:199], v[114:117]
	v_mfma_f32_16x16x32_bf16 v[102:105], v[152:155], v[204:207], v[102:105]
	v_mfma_f32_16x16x32_bf16 v[98:101], v[160:163], v[204:207], v[98:101]
	v_mfma_f32_16x16x32_bf16 v[86:89], v[152:155], v[212:215], v[86:89]
	v_mfma_f32_16x16x32_bf16 v[82:85], v[160:163], v[212:215], v[82:85]
	s_setprio 0
	s_setprio 1
	v_mfma_f32_16x16x32_bf16 v[110:113], v[164:167], v[180:183], v[110:113]
	v_mfma_f32_16x16x32_bf16 v[106:109], v[172:175], v[180:183], v[106:109]
	v_mfma_f32_16x16x32_bf16 v[94:97], v[164:167], v[188:191], v[94:97]
	v_mfma_f32_16x16x32_bf16 v[90:93], v[172:175], v[188:191], v[90:93]
	v_mfma_f32_16x16x32_bf16 v[78:81], v[164:167], v[200:203], v[78:81]
	v_mfma_f32_16x16x32_bf16 v[74:77], v[172:175], v[200:203], v[74:77]
	v_mfma_f32_16x16x32_bf16 v[70:73], v[164:167], v[208:211], v[70:73]
	v_mfma_f32_16x16x32_bf16 v[66:69], v[172:175], v[208:211], v[66:69]
	v_mfma_f32_16x16x32_bf16 v[110:113], v[168:171], v[184:187], v[110:113]
	v_mfma_f32_16x16x32_bf16 v[106:109], v[176:179], v[184:187], v[106:109]
	v_mfma_f32_16x16x32_bf16 v[94:97], v[168:171], v[196:199], v[94:97]
	v_mfma_f32_16x16x32_bf16 v[90:93], v[176:179], v[196:199], v[90:93]
	v_mfma_f32_16x16x32_bf16 v[78:81], v[168:171], v[204:207], v[78:81]
	v_mfma_f32_16x16x32_bf16 v[74:77], v[176:179], v[204:207], v[74:77]
	v_mfma_f32_16x16x32_bf16 v[70:73], v[168:171], v[212:215], v[70:73]
	v_mfma_f32_16x16x32_bf16 v[66:69], v[176:179], v[212:215], v[66:69]
	s_setprio 0
	s_barrier
	s_add_i32 s59, s47, s33
	v_lshl_add_u64 v[192:193], s[36:37], 0, v[134:135]
	s_mov_b32 m0, s59
	ds_read_b128 v[180:183], v147 offset:16384
	ds_read_b128 v[184:187], v147 offset:17408
	ds_read_b128 v[188:191], v147 offset:18432
	ds_read_b128 v[196:199], v147 offset:19456
	ds_read_b128 v[200:203], v147 offset:20480
	ds_read_b128 v[204:207], v147 offset:21504
	ds_read_b128 v[208:211], v147 offset:22528
	ds_read_b128 v[212:215], v147 offset:23552
	global_load_lds_dwordx4 v[192:193], off sc0
	s_add_i32 m0, s59, 0x2000
	s_add_u32 s60, s36, 0x80000
	v_lshl_add_u64 v[216:217], s[36:37], 0, v[130:131]
	s_addc_u32 s61, s37, 0
	s_add_i32 s59, s48, s33
	global_load_lds_dwordx4 v[216:217], off sc0
	v_lshl_add_u64 v[218:219], s[60:61], 0, v[134:135]
	s_mov_b32 m0, s59
	v_lshl_add_u64 v[220:221], s[38:39], 0, v[132:133]
	global_load_lds_dwordx4 v[218:219], off sc0
	v_lshl_add_u64 v[218:219], s[60:61], 0, v[130:131]
	s_add_i32 m0, s59, 0x2000
	s_nop 0
	global_load_lds_dwordx4 v[218:219], off sc0
	v_lshl_add_u64 v[218:219], s[38:39], 0, v[136:137]
	s_mov_b32 m0, s27
	s_nop 0
	global_load_lds_dwordx4 v[218:219], off sc0
	s_mov_b32 m0, s41
	s_nop 0
	global_load_lds_dwordx4 v[220:221], off sc0
	s_waitcnt vmcnt(8)
	s_waitcnt lgkmcnt(0)
	s_barrier
	s_setprio 1
	s_waitcnt lgkmcnt(0)
	v_mfma_f32_16x16x32_bf16 v[62:65], v[148:151], v[180:183], v[62:65]
	v_mfma_f32_16x16x32_bf16 v[58:61], v[156:159], v[180:183], v[58:61]
	v_mfma_f32_16x16x32_bf16 v[54:57], v[148:151], v[188:191], v[54:57]
	v_mfma_f32_16x16x32_bf16 v[50:53], v[156:159], v[188:191], v[50:53]
	v_mfma_f32_16x16x32_bf16 v[38:41], v[148:151], v[200:203], v[38:41]
	v_mfma_f32_16x16x32_bf16 v[34:37], v[156:159], v[200:203], v[34:37]
	v_mfma_f32_16x16x32_bf16 v[22:25], v[148:151], v[208:211], v[22:25]
	v_mfma_f32_16x16x32_bf16 v[18:21], v[156:159], v[208:211], v[18:21]
	v_mfma_f32_16x16x32_bf16 v[62:65], v[152:155], v[184:187], v[62:65]
	v_mfma_f32_16x16x32_bf16 v[58:61], v[160:163], v[184:187], v[58:61]
	v_mfma_f32_16x16x32_bf16 v[54:57], v[152:155], v[196:199], v[54:57]
	v_mfma_f32_16x16x32_bf16 v[50:53], v[160:163], v[196:199], v[50:53]
	v_mfma_f32_16x16x32_bf16 v[38:41], v[152:155], v[204:207], v[38:41]
	v_mfma_f32_16x16x32_bf16 v[34:37], v[160:163], v[204:207], v[34:37]
	v_mfma_f32_16x16x32_bf16 v[22:25], v[152:155], v[212:215], v[22:25]
	v_mfma_f32_16x16x32_bf16 v[18:21], v[160:163], v[212:215], v[18:21]
	s_setprio 0
	s_setprio 1
	v_mfma_f32_16x16x32_bf16 v[46:49], v[164:167], v[180:183], v[46:49]
	v_mfma_f32_16x16x32_bf16 v[42:45], v[172:175], v[180:183], v[42:45]
	v_mfma_f32_16x16x32_bf16 v[30:33], v[164:167], v[188:191], v[30:33]
	v_mfma_f32_16x16x32_bf16 v[26:29], v[172:175], v[188:191], v[26:29]
	v_mfma_f32_16x16x32_bf16 v[14:17], v[164:167], v[200:203], v[14:17]
	v_mfma_f32_16x16x32_bf16 v[10:13], v[172:175], v[200:203], v[10:13]
	v_mfma_f32_16x16x32_bf16 v[6:9], v[164:167], v[208:211], v[6:9]
	v_mfma_f32_16x16x32_bf16 v[2:5], v[172:175], v[208:211], v[2:5]
	v_mfma_f32_16x16x32_bf16 v[46:49], v[168:171], v[184:187], v[46:49]
	v_mfma_f32_16x16x32_bf16 v[42:45], v[176:179], v[184:187], v[42:45]
	v_mfma_f32_16x16x32_bf16 v[30:33], v[168:171], v[196:199], v[30:33]
	v_mfma_f32_16x16x32_bf16 v[26:29], v[176:179], v[196:199], v[26:29]
	v_mfma_f32_16x16x32_bf16 v[14:17], v[168:171], v[204:207], v[14:17]
	v_mfma_f32_16x16x32_bf16 v[10:13], v[176:179], v[204:207], v[10:13]
	v_mfma_f32_16x16x32_bf16 v[6:9], v[168:171], v[212:215], v[6:9]
	v_mfma_f32_16x16x32_bf16 v[2:5], v[176:179], v[212:215], v[2:5]
	s_setprio 0
	s_barrier
	s_add_i32 s59, 0, 0x18000
	s_add_i32 s60, 0, 0x1c000
	v_add_u32_e32 v160, s59, v143
	v_add_u32_e32 v176, s60, v143
	ds_read_b128 v[148:151], v160
	ds_read_b128 v[152:155], v160 offset:1024
	ds_read_b128 v[156:159], v160 offset:2048
	ds_read_b128 v[160:163], v160 offset:3072
	ds_read_b128 v[164:167], v176
	ds_read_b128 v[168:171], v176 offset:1024
	ds_read_b128 v[172:175], v176 offset:2048
	ds_read_b128 v[176:179], v176 offset:3072
	s_add_u32 s38, s38, 0x80000
	s_addc_u32 s39, s39, 0
	s_mov_b32 m0, s42
	v_lshl_add_u64 v[222:223], s[38:39], 0, v[136:137]
	ds_read_b128 v[180:183], v147 offset:32768
	ds_read_b128 v[184:187], v147 offset:33792
	ds_read_b128 v[188:191], v147 offset:34816
	ds_read_b128 v[196:199], v147 offset:35840
	ds_read_b128 v[200:203], v147 offset:36864
	ds_read_b128 v[204:207], v147 offset:37888
	ds_read_b128 v[208:211], v147 offset:38912
	ds_read_b128 v[212:215], v147 offset:39936
	global_load_lds_dwordx4 v[222:223], off sc0
	v_lshl_add_u64 v[222:223], s[38:39], 0, v[132:133]
	s_mov_b32 m0, s43
	s_nop 0
	global_load_lds_dwordx4 v[222:223], off sc0
	s_waitcnt vmcnt(8)
	s_waitcnt lgkmcnt(0)
	s_barrier
	s_setprio 1
	s_waitcnt lgkmcnt(0)
	v_mfma_f32_16x16x32_bf16 v[126:129], v[148:151], v[180:183], v[126:129]
	v_mfma_f32_16x16x32_bf16 v[122:125], v[156:159], v[180:183], v[122:125]
	v_mfma_f32_16x16x32_bf16 v[118:121], v[148:151], v[188:191], v[118:121]
	v_mfma_f32_16x16x32_bf16 v[114:117], v[156:159], v[188:191], v[114:117]
	v_mfma_f32_16x16x32_bf16 v[102:105], v[148:151], v[200:203], v[102:105]
	v_mfma_f32_16x16x32_bf16 v[98:101], v[156:159], v[200:203], v[98:101]
	v_mfma_f32_16x16x32_bf16 v[86:89], v[148:151], v[208:211], v[86:89]
	v_mfma_f32_16x16x32_bf16 v[82:85], v[156:159], v[208:211], v[82:85]
	v_mfma_f32_16x16x32_bf16 v[126:129], v[152:155], v[184:187], v[126:129]
	v_mfma_f32_16x16x32_bf16 v[122:125], v[160:163], v[184:187], v[122:125]
	v_mfma_f32_16x16x32_bf16 v[118:121], v[152:155], v[196:199], v[118:121]
	v_mfma_f32_16x16x32_bf16 v[114:117], v[160:163], v[196:199], v[114:117]
	v_mfma_f32_16x16x32_bf16 v[102:105], v[152:155], v[204:207], v[102:105]
	v_mfma_f32_16x16x32_bf16 v[98:101], v[160:163], v[204:207], v[98:101]
	v_mfma_f32_16x16x32_bf16 v[86:89], v[152:155], v[212:215], v[86:89]
	v_mfma_f32_16x16x32_bf16 v[82:85], v[160:163], v[212:215], v[82:85]
	s_setprio 0
	s_setprio 1
	v_mfma_f32_16x16x32_bf16 v[110:113], v[164:167], v[180:183], v[110:113]
	v_mfma_f32_16x16x32_bf16 v[106:109], v[172:175], v[180:183], v[106:109]
	v_mfma_f32_16x16x32_bf16 v[94:97], v[164:167], v[188:191], v[94:97]
	v_mfma_f32_16x16x32_bf16 v[90:93], v[172:175], v[188:191], v[90:93]
	v_mfma_f32_16x16x32_bf16 v[78:81], v[164:167], v[200:203], v[78:81]
	v_mfma_f32_16x16x32_bf16 v[74:77], v[172:175], v[200:203], v[74:77]
	v_mfma_f32_16x16x32_bf16 v[70:73], v[164:167], v[208:211], v[70:73]
	v_mfma_f32_16x16x32_bf16 v[66:69], v[172:175], v[208:211], v[66:69]
	v_mfma_f32_16x16x32_bf16 v[110:113], v[168:171], v[184:187], v[110:113]
	v_mfma_f32_16x16x32_bf16 v[106:109], v[176:179], v[184:187], v[106:109]
	v_mfma_f32_16x16x32_bf16 v[94:97], v[168:171], v[196:199], v[94:97]
	v_mfma_f32_16x16x32_bf16 v[90:93], v[176:179], v[196:199], v[90:93]
	v_mfma_f32_16x16x32_bf16 v[78:81], v[168:171], v[204:207], v[78:81]
	v_mfma_f32_16x16x32_bf16 v[74:77], v[176:179], v[204:207], v[74:77]
	v_mfma_f32_16x16x32_bf16 v[70:73], v[168:171], v[212:215], v[70:73]
	v_mfma_f32_16x16x32_bf16 v[66:69], v[176:179], v[212:215], v[66:69]
	s_setprio 0
	s_barrier
	s_add_i32 s38, s59, s33
	v_lshl_add_u64 v[192:193], v[192:193], 0, s[6:7]
	s_mov_b32 m0, s38
	ds_read_b128 v[180:183], v147 offset:49152
	ds_read_b128 v[184:187], v147 offset:50176
	ds_read_b128 v[188:191], v147 offset:51200
	ds_read_b128 v[196:199], v147 offset:52224
	ds_read_b128 v[200:203], v147 offset:53248
	ds_read_b128 v[204:207], v147 offset:54272
	ds_read_b128 v[208:211], v147 offset:55296
	ds_read_b128 v[212:215], v147 offset:56320
	global_load_lds_dwordx4 v[192:193], off sc0
	s_add_i32 m0, s38, 0x2000
	s_add_u32 s36, s36, 0x80080
	v_lshl_add_u64 v[192:193], v[216:217], 0, s[6:7]
	s_addc_u32 s37, s37, 0
	s_add_i32 s38, s60, s33
	global_load_lds_dwordx4 v[192:193], off sc0
	v_lshl_add_u64 v[192:193], s[36:37], 0, v[134:135]
	s_mov_b32 m0, s38
	s_nop 0
	global_load_lds_dwordx4 v[192:193], off sc0
	v_lshl_add_u64 v[192:193], s[36:37], 0, v[130:131]
	s_add_i32 m0, s38, 0x2000
	s_nop 0
	global_load_lds_dwordx4 v[192:193], off sc0
	v_lshl_add_u64 v[192:193], v[218:219], 0, s[6:7]
	s_mov_b32 m0, s45
	s_nop 0
	global_load_lds_dwordx4 v[192:193], off sc0
	v_lshl_add_u64 v[192:193], v[220:221], 0, s[6:7]
	s_mov_b32 m0, s46
	s_nop 0
	global_load_lds_dwordx4 v[192:193], off sc0
	s_waitcnt vmcnt(8)
	s_waitcnt lgkmcnt(0)
	s_barrier
	s_setprio 1
	s_waitcnt lgkmcnt(0)
	v_mfma_f32_16x16x32_bf16 v[62:65], v[148:151], v[180:183], v[62:65]
	v_mfma_f32_16x16x32_bf16 v[58:61], v[156:159], v[180:183], v[58:61]
	v_mfma_f32_16x16x32_bf16 v[54:57], v[148:151], v[188:191], v[54:57]
	v_mfma_f32_16x16x32_bf16 v[50:53], v[156:159], v[188:191], v[50:53]
	v_mfma_f32_16x16x32_bf16 v[38:41], v[148:151], v[200:203], v[38:41]
	v_mfma_f32_16x16x32_bf16 v[34:37], v[156:159], v[200:203], v[34:37]
	v_mfma_f32_16x16x32_bf16 v[22:25], v[148:151], v[208:211], v[22:25]
	v_mfma_f32_16x16x32_bf16 v[18:21], v[156:159], v[208:211], v[18:21]
	v_mfma_f32_16x16x32_bf16 v[62:65], v[152:155], v[184:187], v[62:65]
	v_mfma_f32_16x16x32_bf16 v[58:61], v[160:163], v[184:187], v[58:61]
	v_mfma_f32_16x16x32_bf16 v[54:57], v[152:155], v[196:199], v[54:57]
	v_mfma_f32_16x16x32_bf16 v[50:53], v[160:163], v[196:199], v[50:53]
	v_mfma_f32_16x16x32_bf16 v[38:41], v[152:155], v[204:207], v[38:41]
	v_mfma_f32_16x16x32_bf16 v[34:37], v[160:163], v[204:207], v[34:37]
	v_mfma_f32_16x16x32_bf16 v[22:25], v[152:155], v[212:215], v[22:25]
	v_mfma_f32_16x16x32_bf16 v[18:21], v[160:163], v[212:215], v[18:21]
	s_setprio 0
	s_setprio 1
	v_mfma_f32_16x16x32_bf16 v[46:49], v[164:167], v[180:183], v[46:49]
	v_mfma_f32_16x16x32_bf16 v[42:45], v[172:175], v[180:183], v[42:45]
	v_mfma_f32_16x16x32_bf16 v[30:33], v[164:167], v[188:191], v[30:33]
	v_mfma_f32_16x16x32_bf16 v[26:29], v[172:175], v[188:191], v[26:29]
	v_mfma_f32_16x16x32_bf16 v[14:17], v[164:167], v[200:203], v[14:17]
	v_mfma_f32_16x16x32_bf16 v[10:13], v[172:175], v[200:203], v[10:13]
	v_mfma_f32_16x16x32_bf16 v[6:9], v[164:167], v[208:211], v[6:9]
	v_mfma_f32_16x16x32_bf16 v[2:5], v[172:175], v[208:211], v[2:5]
	v_mfma_f32_16x16x32_bf16 v[46:49], v[168:171], v[184:187], v[46:49]
	v_mfma_f32_16x16x32_bf16 v[42:45], v[176:179], v[184:187], v[42:45]
	v_mfma_f32_16x16x32_bf16 v[30:33], v[168:171], v[196:199], v[30:33]
	v_mfma_f32_16x16x32_bf16 v[26:29], v[176:179], v[196:199], v[26:29]
	v_mfma_f32_16x16x32_bf16 v[14:17], v[168:171], v[204:207], v[14:17]
	v_mfma_f32_16x16x32_bf16 v[10:13], v[176:179], v[204:207], v[10:13]
	v_mfma_f32_16x16x32_bf16 v[6:9], v[168:171], v[212:215], v[6:9]
	v_mfma_f32_16x16x32_bf16 v[2:5], v[176:179], v[212:215], v[2:5]
	s_setprio 0
	s_barrier
	s_add_i32 s58, s58, 2
	s_add_u32 s34, s34, 0x100
	s_addc_u32 s35, s35, 0
	s_add_u32 s56, s56, 0x100
	s_addc_u32 s57, s57, 0
	s_cmp_gt_u32 s58, 29
	s_cbranch_scc0 .LBB0_541

.LBB0_682:
	v_lshrrev_b32_e32 v3, 5, v0
	v_and_b32_e32 v3, 4, v3
	v_bfe_u32 v4, v0, 2, 2
	v_and_b32_e32 v2, 24, v2
	v_or3_b32 v2, v3, v4, v2
	v_lshlrev_b32_e32 v3, 4, v0
	s_add_u32 s2, s82, 0x30500000
	v_or_b32_e32 v10, 0x2000, v3
	s_mov_b32 s6, s3
	s_addc_u32 s3, s83, 0
	v_lshrrev_b32_e32 v4, 7, v10
	s_movk_i32 s4, 0x60
	s_add_u32 s33, s82, 0x11d00000
	v_and_or_b32 v5, v4, s4, v2
	v_bfe_u32 v13, v0, 2, 4
	s_movk_i32 s4, 0x70
	s_addc_u32 s34, s83, 0
	v_and_or_b32 v4, v4, s4, v13
	s_ashr_i32 s4, s6, 31
	s_lshr_b32 s4, s4, 29
	s_add_i32 s4, s6, s4
	s_lshr_b32 s8, s11, 6
	s_and_b32 s5, s4, -8
	s_lshr_b32 s12, s11, 8
	s_lshl_b32 s35, s8, 10
	s_sub_i32 s5, s6, s5
	s_cmp_lt_i32 s5, 0
	s_cselect_b32 s6, 37, 36
	s_mul_i32 s5, s6, s5
	s_ashr_i32 s4, s4, 3
	s_add_i32 s5, s5, s4
	s_mul_hi_i32 s4, s5, 0x2aaaaaab
	s_lshr_b32 s6, s4, 31
	s_ashr_i32 s4, s4, 3
	s_add_i32 s4, s4, s6
	s_lshl_b32 s6, s4, 3
	s_mul_i32 s4, s4, 48
	s_sub_i32 s4, s5, s4
	s_bfe_i32 s5, s4, 0x80000
	s_bfe_u32 s5, s5, 0x3000c
	s_add_i32 s5, s4, s5
	s_bfe_i32 s7, s5, 0x80000
	s_and_b32 s5, s5, 0xf8
	s_sub_i32 s4, s4, s5
	s_sext_i32_i16 s7, s7
	s_sext_i32_i8 s4, s4
	v_and_b32_e32 v6, 32, v0
	s_lshr_b32 s10, s7, 3
	s_add_i32 s18, s6, s4
	v_bitop3_b32 v11, v3, v6, 48 bitop3:0x6c
	v_and_b32_e32 v12, 64, v0
	s_ashr_i32 s19, s18, 31
	s_bfe_i64 s[6:7], s[10:11], 0x100000
	v_or_b32_e32 v3, v11, v12
	s_lshl_b64 s[4:5], s[18:19], 18
	s_lshl_b64 s[6:7], s[6:7], 18
	v_lshl_or_b32 v136, v4, 10, v3
	v_lshrrev_b32_e32 v4, 3, v0
	s_add_u32 s28, s33, s6
	v_and_or_b32 v2, v4, 32, v2
	s_addc_u32 s29, s34, s7
	s_add_i32 s36, s35, 0
	v_lshl_or_b32 v132, v2, 10, v3
	s_add_i32 m0, s36, 0x10000
	v_lshl_or_b32 v134, v5, 10, v3
	global_load_lds_dwordx4 v132, s[28:29] sc0
	s_add_i32 m0, s36, 0x12000
	s_add_u32 s6, s28, 0x20000
	global_load_lds_dwordx4 v134, s[28:29] sc0
	s_addc_u32 s7, s29, 0
	s_add_i32 m0, s36, 0x14000
	v_and_or_b32 v2, v4, 48, v13
	global_load_lds_dwordx4 v132, s[6:7] sc0
	s_add_i32 m0, s36, 0x16000
	s_add_u32 s26, s2, s4
	s_addc_u32 s27, s3, s5
	s_add_i32 s37, s36, 0x2000
	v_lshl_or_b32 v130, v2, 10, v3
	global_load_lds_dwordx4 v134, s[6:7] sc0
	s_mov_b32 m0, s36
	s_add_u32 s4, s26, 0x20000
	global_load_lds_dwordx4 v130, s[26:27] sc0
	s_mov_b32 m0, s37
	s_addc_u32 s5, s27, 0
	s_add_i32 s38, s36, 0x4000
	global_load_lds_dwordx4 v136, s[26:27] sc0
	s_mov_b32 m0, s38
	s_add_i32 s39, s36, 0x6000
	global_load_lds_dwordx4 v130, s[4:5] sc0
	s_mov_b32 m0, s39
	v_mov_b32_e32 v133, 0
	global_load_lds_dwordx4 v136, s[4:5] sc0
	v_mov_b32_e32 v135, v133
	v_mov_b32_e32 v131, v133
	v_mov_b32_e32 v137, v133
	s_cmp_eq_u32 s12, 1
	s_mov_b32 s40, 0
	v_lshl_add_u64 v[8:9], s[28:29], 0, v[132:133]
	v_lshl_add_u64 v[6:7], s[28:29], 0, v[134:135]
	v_lshl_add_u64 v[2:3], s[26:27], 0, v[130:131]
	s_cselect_b64 s[4:5], -1, 0
	s_cmp_lg_u32 s12, 1
	v_lshl_add_u64 v[4:5], s[26:27], 0, v[136:137]
	s_cbranch_scc1 .LBB0_684
	s_barrier
.LBB0_684:
	s_add_u32 s6, s82, 0x2bd00000
	s_addc_u32 s7, s83, 0
	s_lshl_b32 s8, s8, 5
	s_and_b32 s20, s8, 0x60
	s_mov_b64 s[8:9], 0x80
	s_add_i32 m0, s36, 0x18000
	v_lshl_add_u64 v[8:9], v[8:9], 0, s[8:9]
	s_lshl_b32 s13, s12, 13
	s_waitcnt vmcnt(2)
	s_barrier
	global_load_lds_dwordx4 v[8:9], off sc0
	v_lshl_add_u64 v[6:7], v[6:7], 0, s[8:9]
	s_add_i32 m0, s36, 0x1a000
	s_add_i32 s41, s36, 0x8000
	s_add_i32 s42, s36, 0xa000
	global_load_lds_dwordx4 v[6:7], off sc0
	v_lshl_add_u64 v[2:3], v[2:3], 0, s[8:9]
	s_mov_b32 m0, s41
	s_add_u32 s16, s28, 0x20080
	global_load_lds_dwordx4 v[2:3], off sc0
	v_lshl_add_u64 v[2:3], v[4:5], 0, s[8:9]
	s_mov_b32 m0, s42
	s_addc_u32 s17, s29, 0
	global_load_lds_dwordx4 v[2:3], off sc0
	s_add_i32 m0, s36, 0x1c000
	v_lshl_add_u64 v[2:3], s[16:17], 0, v[132:133]
	global_load_lds_dwordx4 v[2:3], off sc0
	v_lshl_add_u64 v[2:3], s[16:17], 0, v[134:135]
	s_add_i32 m0, s36, 0x1e000
	v_lshlrev_b32_e32 v4, 10, v13
	global_load_lds_dwordx4 v[2:3], off sc0
	v_lshlrev_b32_e32 v3, 2, v205
	v_lshl_or_b32 v2, v205, 6, v142
	v_and_b32_e32 v3, 32, v3
	v_bitop3_b32 v2, v2, s13, v3 bitop3:0xde
	v_lshlrev_b32_e32 v3, 7, v0
	v_and_b32_e32 v3, 0xc000, v3
	v_or3_b32 v3, v11, v3, v4
	v_add_u32_e32 v138, v3, v12
	v_lshlrev_b32_e32 v3, 3, v10
	s_waitcnt vmcnt(6)
	s_cmpk_lt_u32 s11, 0x100
	v_and_b32_e32 v3, 0x1c000, v3
	s_sext_i32_i8 s19, s10
	v_lshl_or_b32 v145, s20, 7, v143
	s_cselect_b64 s[10:11], -1, 0
	v_or3_b32 v3, v11, v3, v4
	s_add_i32 s43, 0, 0x10000
	s_add_i32 s44, 0, 0x14000
	v_lshl_or_b32 v144, s12, 6, v205
	v_or_b32_e32 v146, s20, v1
	v_mov_b32_e32 v139, v133
	v_add_u32_e32 v140, v3, v12
	v_mov_b32_e32 v141, v133
	v_add_u32_e32 v147, s43, v145
	v_add_u32_e32 v148, s44, v145
	v_add_u32_e32 v149, 0, v2
	s_movk_i32 s45, 0xc00
	s_barrier
	s_branch .LBB0_687

.Lpeel_10:
	ds_read_b128 v[150:153], v147
	ds_read_b128 v[154:157], v147 offset:1024
	ds_read_b128 v[158:161], v147 offset:2048
	ds_read_b128 v[162:165], v147 offset:3072
	ds_read_b128 v[166:169], v148
	ds_read_b128 v[170:173], v148 offset:1024
	ds_read_b128 v[174:177], v148 offset:2048
	ds_read_b128 v[178:181], v148 offset:3072
	s_add_u32 s28, s26, 0xfffe0080
	s_addc_u32 s29, s27, -1
	s_cmp_eq_u32 s50, 4
	s_cselect_b32 s31, s13, s29
	s_cselect_b32 s30, s46, s28
	s_cselect_b32 s29, s17, s49
	s_cselect_b32 s28, s47, s48
	v_lshl_add_u64 v[202:203], s[26:27], 0, v[138:139]
	s_add_i32 m0, s36, 0xc000
	ds_read_b128 v[182:185], v149
	ds_read_b128 v[186:189], v149 offset:1024
	ds_read_b128 v[190:193], v149 offset:2048
	ds_read_b128 v[198:201], v149 offset:3072
	ds_read_b128 v[210:213], v149 offset:4096
	ds_read_b128 v[214:217], v149 offset:5120
	ds_read_b128 v[218:221], v149 offset:6144
	ds_read_b128 v[222:225], v149 offset:7168
	global_load_lds_dwordx4 v[202:203], off sc0
	v_lshl_add_u64 v[202:203], s[26:27], 0, v[140:141]
	s_add_i32 m0, s36, 0xe000
	s_nop 0
	global_load_lds_dwordx4 v[202:203], off sc0
	s_waitcnt vmcnt(8)
	s_waitcnt lgkmcnt(0)
	s_barrier
	s_setprio 1
	s_waitcnt lgkmcnt(0)
	v_mfma_f32_16x16x32_bf16 v[126:129], v[150:153], v[182:185], 0
	v_mfma_f32_16x16x32_bf16 v[122:125], v[158:161], v[182:185], 0
	v_mfma_f32_16x16x32_bf16 v[118:121], v[150:153], v[190:193], 0
	v_mfma_f32_16x16x32_bf16 v[114:117], v[158:161], v[190:193], 0
	v_mfma_f32_16x16x32_bf16 v[102:105], v[150:153], v[210:213], 0
	v_mfma_f32_16x16x32_bf16 v[98:101], v[158:161], v[210:213], 0
	v_mfma_f32_16x16x32_bf16 v[86:89], v[150:153], v[218:221], 0
	v_mfma_f32_16x16x32_bf16 v[82:85], v[158:161], v[218:221], 0
	v_mfma_f32_16x16x32_bf16 v[126:129], v[154:157], v[186:189], v[126:129]
	v_mfma_f32_16x16x32_bf16 v[122:125], v[162:165], v[186:189], v[122:125]
	v_mfma_f32_16x16x32_bf16 v[118:121], v[154:157], v[198:201], v[118:121]
	v_mfma_f32_16x16x32_bf16 v[114:117], v[162:165], v[198:201], v[114:117]
	v_mfma_f32_16x16x32_bf16 v[102:105], v[154:157], v[214:217], v[102:105]
	v_mfma_f32_16x16x32_bf16 v[98:101], v[162:165], v[214:217], v[98:101]
	v_mfma_f32_16x16x32_bf16 v[86:89], v[154:157], v[222:225], v[86:89]
	v_mfma_f32_16x16x32_bf16 v[82:85], v[162:165], v[222:225], v[82:85]
	s_setprio 0
	s_setprio 1
	v_mfma_f32_16x16x32_bf16 v[110:113], v[166:169], v[182:185], 0
	v_mfma_f32_16x16x32_bf16 v[106:109], v[174:177], v[182:185], 0
	v_mfma_f32_16x16x32_bf16 v[94:97], v[166:169], v[190:193], 0
	v_mfma_f32_16x16x32_bf16 v[90:93], v[174:177], v[190:193], 0
	v_mfma_f32_16x16x32_bf16 v[78:81], v[166:169], v[210:213], 0
	v_mfma_f32_16x16x32_bf16 v[74:77], v[174:177], v[210:213], 0
	v_mfma_f32_16x16x32_bf16 v[70:73], v[166:169], v[218:221], 0
	v_mfma_f32_16x16x32_bf16 v[66:69], v[174:177], v[218:221], 0
	v_mfma_f32_16x16x32_bf16 v[110:113], v[170:173], v[186:189], v[110:113]
	v_mfma_f32_16x16x32_bf16 v[106:109], v[178:181], v[186:189], v[106:109]
	v_mfma_f32_16x16x32_bf16 v[94:97], v[170:173], v[198:201], v[94:97]
	v_mfma_f32_16x16x32_bf16 v[90:93], v[178:181], v[198:201], v[90:93]
	v_mfma_f32_16x16x32_bf16 v[78:81], v[170:173], v[214:217], v[78:81]
	v_mfma_f32_16x16x32_bf16 v[74:77], v[178:181], v[214:217], v[74:77]
	v_mfma_f32_16x16x32_bf16 v[70:73], v[170:173], v[222:225], v[70:73]
	v_mfma_f32_16x16x32_bf16 v[66:69], v[178:181], v[222:225], v[66:69]
	s_setprio 0
	s_barrier
	s_add_i32 s51, s43, s35
	v_lshl_add_u64 v[202:203], s[28:29], 0, v[132:133]
	s_mov_b32 m0, s51
	ds_read_b128 v[182:185], v149 offset:16384
	ds_read_b128 v[186:189], v149 offset:17408
	ds_read_b128 v[190:193], v149 offset:18432
	ds_read_b128 v[198:201], v149 offset:19456
	ds_read_b128 v[210:213], v149 offset:20480
	ds_read_b128 v[214:217], v149 offset:21504
	ds_read_b128 v[218:221], v149 offset:22528
	ds_read_b128 v[222:225], v149 offset:23552
	global_load_lds_dwordx4 v[202:203], off sc0
	s_add_i32 m0, s51, 0x2000
	s_add_u32 s52, s28, 0x20000
	v_lshl_add_u64 v[206:207], s[28:29], 0, v[134:135]
	s_addc_u32 s53, s29, 0
	s_add_i32 s51, s44, s35
	global_load_lds_dwordx4 v[206:207], off sc0
	v_lshl_add_u64 v[226:227], s[52:53], 0, v[132:133]
	s_mov_b32 m0, s51
	v_lshl_add_u64 v[228:229], s[30:31], 0, v[136:137]
	global_load_lds_dwordx4 v[226:227], off sc0
	v_lshl_add_u64 v[226:227], s[52:53], 0, v[134:135]
	s_add_i32 m0, s51, 0x2000
	s_nop 0
	global_load_lds_dwordx4 v[226:227], off sc0
	v_lshl_add_u64 v[226:227], s[30:31], 0, v[130:131]
	s_mov_b32 m0, s36
	s_nop 0
	global_load_lds_dwordx4 v[226:227], off sc0
	s_mov_b32 m0, s37
	s_nop 0
	global_load_lds_dwordx4 v[228:229], off sc0
	s_waitcnt vmcnt(8)
	s_waitcnt lgkmcnt(0)
	s_barrier
	s_setprio 1
	s_waitcnt lgkmcnt(0)
	v_mfma_f32_16x16x32_bf16 v[62:65], v[150:153], v[182:185], 0
	v_mfma_f32_16x16x32_bf16 v[58:61], v[158:161], v[182:185], 0
	v_mfma_f32_16x16x32_bf16 v[54:57], v[150:153], v[190:193], 0
	v_mfma_f32_16x16x32_bf16 v[50:53], v[158:161], v[190:193], 0
	v_mfma_f32_16x16x32_bf16 v[38:41], v[150:153], v[210:213], 0
	v_mfma_f32_16x16x32_bf16 v[34:37], v[158:161], v[210:213], 0
	v_mfma_f32_16x16x32_bf16 v[22:25], v[150:153], v[218:221], 0
	v_mfma_f32_16x16x32_bf16 v[18:21], v[158:161], v[218:221], 0
	v_mfma_f32_16x16x32_bf16 v[62:65], v[154:157], v[186:189], v[62:65]
	v_mfma_f32_16x16x32_bf16 v[58:61], v[162:165], v[186:189], v[58:61]
	v_mfma_f32_16x16x32_bf16 v[54:57], v[154:157], v[198:201], v[54:57]
	v_mfma_f32_16x16x32_bf16 v[50:53], v[162:165], v[198:201], v[50:53]
	v_mfma_f32_16x16x32_bf16 v[38:41], v[154:157], v[214:217], v[38:41]
	v_mfma_f32_16x16x32_bf16 v[34:37], v[162:165], v[214:217], v[34:37]
	v_mfma_f32_16x16x32_bf16 v[22:25], v[154:157], v[222:225], v[22:25]
	v_mfma_f32_16x16x32_bf16 v[18:21], v[162:165], v[222:225], v[18:21]
	s_setprio 0
	s_setprio 1
	v_mfma_f32_16x16x32_bf16 v[46:49], v[166:169], v[182:185], 0
	v_mfma_f32_16x16x32_bf16 v[42:45], v[174:177], v[182:185], 0
	v_mfma_f32_16x16x32_bf16 v[30:33], v[166:169], v[190:193], 0
	v_mfma_f32_16x16x32_bf16 v[26:29], v[174:177], v[190:193], 0
	v_mfma_f32_16x16x32_bf16 v[14:17], v[166:169], v[210:213], 0
	v_mfma_f32_16x16x32_bf16 v[10:13], v[174:177], v[210:213], 0
	v_mfma_f32_16x16x32_bf16 v[6:9], v[166:169], v[218:221], 0
	v_mfma_f32_16x16x32_bf16 v[2:5], v[174:177], v[218:221], 0
	v_mfma_f32_16x16x32_bf16 v[46:49], v[170:173], v[186:189], v[46:49]
	v_mfma_f32_16x16x32_bf16 v[42:45], v[178:181], v[186:189], v[42:45]
	v_mfma_f32_16x16x32_bf16 v[30:33], v[170:173], v[198:201], v[30:33]
	v_mfma_f32_16x16x32_bf16 v[26:29], v[178:181], v[198:201], v[26:29]
	v_mfma_f32_16x16x32_bf16 v[14:17], v[170:173], v[214:217], v[14:17]
	v_mfma_f32_16x16x32_bf16 v[10:13], v[178:181], v[214:217], v[10:13]
	v_mfma_f32_16x16x32_bf16 v[6:9], v[170:173], v[222:225], v[6:9]
	v_mfma_f32_16x16x32_bf16 v[2:5], v[178:181], v[222:225], v[2:5]
	s_setprio 0
	s_barrier
	s_add_i32 s51, 0, 0x18000
	s_add_i32 s52, 0, 0x1c000
	v_add_u32_e32 v162, s51, v145
	v_add_u32_e32 v178, s52, v145
	ds_read_b128 v[150:153], v162
	ds_read_b128 v[154:157], v162 offset:1024
	ds_read_b128 v[158:161], v162 offset:2048
	ds_read_b128 v[162:165], v162 offset:3072
	ds_read_b128 v[166:169], v178
	ds_read_b128 v[170:173], v178 offset:1024
	ds_read_b128 v[174:177], v178 offset:2048
	ds_read_b128 v[178:181], v178 offset:3072
	s_add_u32 s30, s30, 0x20000
	s_addc_u32 s31, s31, 0
	s_mov_b32 m0, s38
	v_lshl_add_u64 v[230:231], s[30:31], 0, v[130:131]
	ds_read_b128 v[182:185], v149 offset:32768
	ds_read_b128 v[186:189], v149 offset:33792
	ds_read_b128 v[190:193], v149 offset:34816
	ds_read_b128 v[198:201], v149 offset:35840
	ds_read_b128 v[210:213], v149 offset:36864
	ds_read_b128 v[214:217], v149 offset:37888
	ds_read_b128 v[218:221], v149 offset:38912
	ds_read_b128 v[222:225], v149 offset:39936
	global_load_lds_dwordx4 v[230:231], off sc0
	v_lshl_add_u64 v[230:231], s[30:31], 0, v[136:137]
	s_mov_b32 m0, s39
	s_nop 0
	global_load_lds_dwordx4 v[230:231], off sc0
	s_waitcnt vmcnt(8)
	s_waitcnt lgkmcnt(0)
	s_barrier
	s_setprio 1
	s_waitcnt lgkmcnt(0)
	v_mfma_f32_16x16x32_bf16 v[126:129], v[150:153], v[182:185], v[126:129]
	v_mfma_f32_16x16x32_bf16 v[122:125], v[158:161], v[182:185], v[122:125]
	v_mfma_f32_16x16x32_bf16 v[118:121], v[150:153], v[190:193], v[118:121]
	v_mfma_f32_16x16x32_bf16 v[114:117], v[158:161], v[190:193], v[114:117]
	v_mfma_f32_16x16x32_bf16 v[102:105], v[150:153], v[210:213], v[102:105]
	v_mfma_f32_16x16x32_bf16 v[98:101], v[158:161], v[210:213], v[98:101]
	v_mfma_f32_16x16x32_bf16 v[86:89], v[150:153], v[218:221], v[86:89]
	v_mfma_f32_16x16x32_bf16 v[82:85], v[158:161], v[218:221], v[82:85]
	v_mfma_f32_16x16x32_bf16 v[126:129], v[154:157], v[186:189], v[126:129]
	v_mfma_f32_16x16x32_bf16 v[122:125], v[162:165], v[186:189], v[122:125]
	v_mfma_f32_16x16x32_bf16 v[118:121], v[154:157], v[198:201], v[118:121]
	v_mfma_f32_16x16x32_bf16 v[114:117], v[162:165], v[198:201], v[114:117]
	v_mfma_f32_16x16x32_bf16 v[102:105], v[154:157], v[214:217], v[102:105]
	v_mfma_f32_16x16x32_bf16 v[98:101], v[162:165], v[214:217], v[98:101]
	v_mfma_f32_16x16x32_bf16 v[86:89], v[154:157], v[222:225], v[86:89]
	v_mfma_f32_16x16x32_bf16 v[82:85], v[162:165], v[222:225], v[82:85]
	s_setprio 0
	s_setprio 1
	v_mfma_f32_16x16x32_bf16 v[110:113], v[166:169], v[182:185], v[110:113]
	v_mfma_f32_16x16x32_bf16 v[106:109], v[174:177], v[182:185], v[106:109]
	v_mfma_f32_16x16x32_bf16 v[94:97], v[166:169], v[190:193], v[94:97]
	v_mfma_f32_16x16x32_bf16 v[90:93], v[174:177], v[190:193], v[90:93]
	v_mfma_f32_16x16x32_bf16 v[78:81], v[166:169], v[210:213], v[78:81]
	v_mfma_f32_16x16x32_bf16 v[74:77], v[174:177], v[210:213], v[74:77]
	v_mfma_f32_16x16x32_bf16 v[70:73], v[166:169], v[218:221], v[70:73]
	v_mfma_f32_16x16x32_bf16 v[66:69], v[174:177], v[218:221], v[66:69]
	v_mfma_f32_16x16x32_bf16 v[110:113], v[170:173], v[186:189], v[110:113]
	v_mfma_f32_16x16x32_bf16 v[106:109], v[178:181], v[186:189], v[106:109]
	v_mfma_f32_16x16x32_bf16 v[94:97], v[170:173], v[198:201], v[94:97]
	v_mfma_f32_16x16x32_bf16 v[90:93], v[178:181], v[198:201], v[90:93]
	v_mfma_f32_16x16x32_bf16 v[78:81], v[170:173], v[214:217], v[78:81]
	v_mfma_f32_16x16x32_bf16 v[74:77], v[178:181], v[214:217], v[74:77]
	v_mfma_f32_16x16x32_bf16 v[70:73], v[170:173], v[222:225], v[70:73]
	v_mfma_f32_16x16x32_bf16 v[66:69], v[178:181], v[222:225], v[66:69]
	s_setprio 0
	s_barrier
	s_add_i32 s30, s51, s35
	v_lshl_add_u64 v[202:203], v[202:203], 0, s[8:9]
	s_mov_b32 m0, s30
	ds_read_b128 v[182:185], v149 offset:49152
	ds_read_b128 v[186:189], v149 offset:50176
	ds_read_b128 v[190:193], v149 offset:51200
	ds_read_b128 v[198:201], v149 offset:52224
	ds_read_b128 v[210:213], v149 offset:53248
	ds_read_b128 v[214:217], v149 offset:54272
	ds_read_b128 v[218:221], v149 offset:55296
	ds_read_b128 v[222:225], v149 offset:56320
	global_load_lds_dwordx4 v[202:203], off sc0
	s_add_i32 m0, s30, 0x2000
	s_add_u32 s28, s28, 0x20080
	v_lshl_add_u64 v[202:203], v[206:207], 0, s[8:9]
	s_addc_u32 s29, s29, 0
	s_add_i32 s30, s52, s35
	global_load_lds_dwordx4 v[202:203], off sc0
	v_lshl_add_u64 v[202:203], s[28:29], 0, v[132:133]
	s_mov_b32 m0, s30
	s_nop 0
	global_load_lds_dwordx4 v[202:203], off sc0
	v_lshl_add_u64 v[202:203], s[28:29], 0, v[134:135]
	s_add_i32 m0, s30, 0x2000
	s_nop 0
	global_load_lds_dwordx4 v[202:203], off sc0
	v_lshl_add_u64 v[202:203], v[226:227], 0, s[8:9]
	s_mov_b32 m0, s41
	s_nop 0
	global_load_lds_dwordx4 v[202:203], off sc0
	v_lshl_add_u64 v[202:203], v[228:229], 0, s[8:9]
	s_mov_b32 m0, s42
	s_nop 0
	global_load_lds_dwordx4 v[202:203], off sc0
	s_waitcnt vmcnt(8)
	s_waitcnt lgkmcnt(0)
	s_barrier
	s_setprio 1
	s_waitcnt lgkmcnt(0)
	v_mfma_f32_16x16x32_bf16 v[62:65], v[150:153], v[182:185], v[62:65]
	v_mfma_f32_16x16x32_bf16 v[58:61], v[158:161], v[182:185], v[58:61]
	v_mfma_f32_16x16x32_bf16 v[54:57], v[150:153], v[190:193], v[54:57]
	v_mfma_f32_16x16x32_bf16 v[50:53], v[158:161], v[190:193], v[50:53]
	v_mfma_f32_16x16x32_bf16 v[38:41], v[150:153], v[210:213], v[38:41]
	v_mfma_f32_16x16x32_bf16 v[34:37], v[158:161], v[210:213], v[34:37]
	v_mfma_f32_16x16x32_bf16 v[22:25], v[150:153], v[218:221], v[22:25]
	v_mfma_f32_16x16x32_bf16 v[18:21], v[158:161], v[218:221], v[18:21]
	v_mfma_f32_16x16x32_bf16 v[62:65], v[154:157], v[186:189], v[62:65]
	v_mfma_f32_16x16x32_bf16 v[58:61], v[162:165], v[186:189], v[58:61]
	v_mfma_f32_16x16x32_bf16 v[54:57], v[154:157], v[198:201], v[54:57]
	v_mfma_f32_16x16x32_bf16 v[50:53], v[162:165], v[198:201], v[50:53]
	v_mfma_f32_16x16x32_bf16 v[38:41], v[154:157], v[214:217], v[38:41]
	v_mfma_f32_16x16x32_bf16 v[34:37], v[162:165], v[214:217], v[34:37]
	v_mfma_f32_16x16x32_bf16 v[22:25], v[154:157], v[222:225], v[22:25]
	v_mfma_f32_16x16x32_bf16 v[18:21], v[162:165], v[222:225], v[18:21]
	s_setprio 0
	s_setprio 1
	v_mfma_f32_16x16x32_bf16 v[46:49], v[166:169], v[182:185], v[46:49]
	v_mfma_f32_16x16x32_bf16 v[42:45], v[174:177], v[182:185], v[42:45]
	v_mfma_f32_16x16x32_bf16 v[30:33], v[166:169], v[190:193], v[30:33]
	v_mfma_f32_16x16x32_bf16 v[26:29], v[174:177], v[190:193], v[26:29]
	v_mfma_f32_16x16x32_bf16 v[14:17], v[166:169], v[210:213], v[14:17]
	v_mfma_f32_16x16x32_bf16 v[10:13], v[174:177], v[210:213], v[10:13]
	v_mfma_f32_16x16x32_bf16 v[6:9], v[166:169], v[218:221], v[6:9]
	v_mfma_f32_16x16x32_bf16 v[2:5], v[174:177], v[218:221], v[2:5]
	v_mfma_f32_16x16x32_bf16 v[46:49], v[170:173], v[186:189], v[46:49]
	v_mfma_f32_16x16x32_bf16 v[42:45], v[178:181], v[186:189], v[42:45]
	v_mfma_f32_16x16x32_bf16 v[30:33], v[170:173], v[198:201], v[30:33]
	v_mfma_f32_16x16x32_bf16 v[26:29], v[178:181], v[198:201], v[26:29]
	v_mfma_f32_16x16x32_bf16 v[14:17], v[170:173], v[214:217], v[14:17]
	v_mfma_f32_16x16x32_bf16 v[10:13], v[178:181], v[214:217], v[10:13]
	v_mfma_f32_16x16x32_bf16 v[6:9], v[170:173], v[222:225], v[6:9]
	v_mfma_f32_16x16x32_bf16 v[2:5], v[178:181], v[222:225], v[2:5]
	s_setprio 0
	s_barrier
	s_add_i32 s50, s50, 2
	s_add_u32 s26, s26, 0x100
	s_addc_u32 s27, s27, 0
	s_add_u32 s48, s48, 0x100
	s_addc_u32 s49, s49, 0
	s_cmp_gt_u32 s50, 5
	s_cbranch_scc0 .LBB0_690
	s_branch .Lpeeldone_10
.LBB0_690:
	ds_read_b128 v[150:153], v147
	ds_read_b128 v[154:157], v147 offset:1024
	ds_read_b128 v[158:161], v147 offset:2048
	ds_read_b128 v[162:165], v147 offset:3072
	ds_read_b128 v[166:169], v148
	ds_read_b128 v[170:173], v148 offset:1024
	ds_read_b128 v[174:177], v148 offset:2048
	ds_read_b128 v[178:181], v148 offset:3072
	s_add_u32 s28, s26, 0xfffe0080
	s_addc_u32 s29, s27, -1
	s_cmp_eq_u32 s50, 4
	s_cselect_b32 s31, s13, s29
	s_cselect_b32 s30, s46, s28
	s_cselect_b32 s29, s17, s49
	s_cselect_b32 s28, s47, s48
	v_lshl_add_u64 v[202:203], s[26:27], 0, v[138:139]
	s_add_i32 m0, s36, 0xc000
	ds_read_b128 v[182:185], v149
	ds_read_b128 v[186:189], v149 offset:1024
	ds_read_b128 v[190:193], v149 offset:2048
	ds_read_b128 v[198:201], v149 offset:3072
	ds_read_b128 v[210:213], v149 offset:4096
	ds_read_b128 v[214:217], v149 offset:5120
	ds_read_b128 v[218:221], v149 offset:6144
	ds_read_b128 v[222:225], v149 offset:7168
	global_load_lds_dwordx4 v[202:203], off sc0
	v_lshl_add_u64 v[202:203], s[26:27], 0, v[140:141]
	s_add_i32 m0, s36, 0xe000
	s_nop 0
	global_load_lds_dwordx4 v[202:203], off sc0
	s_waitcnt vmcnt(8)
	s_waitcnt lgkmcnt(0)
	s_barrier
	s_setprio 1
	s_waitcnt lgkmcnt(0)
	v_mfma_f32_16x16x32_bf16 v[126:129], v[150:153], v[182:185], v[126:129]
	v_mfma_f32_16x16x32_bf16 v[122:125], v[158:161], v[182:185], v[122:125]
	v_mfma_f32_16x16x32_bf16 v[118:121], v[150:153], v[190:193], v[118:121]
	v_mfma_f32_16x16x32_bf16 v[114:117], v[158:161], v[190:193], v[114:117]
	v_mfma_f32_16x16x32_bf16 v[102:105], v[150:153], v[210:213], v[102:105]
	v_mfma_f32_16x16x32_bf16 v[98:101], v[158:161], v[210:213], v[98:101]
	v_mfma_f32_16x16x32_bf16 v[86:89], v[150:153], v[218:221], v[86:89]
	v_mfma_f32_16x16x32_bf16 v[82:85], v[158:161], v[218:221], v[82:85]
	v_mfma_f32_16x16x32_bf16 v[126:129], v[154:157], v[186:189], v[126:129]
	v_mfma_f32_16x16x32_bf16 v[122:125], v[162:165], v[186:189], v[122:125]
	v_mfma_f32_16x16x32_bf16 v[118:121], v[154:157], v[198:201], v[118:121]
	v_mfma_f32_16x16x32_bf16 v[114:117], v[162:165], v[198:201], v[114:117]
	v_mfma_f32_16x16x32_bf16 v[102:105], v[154:157], v[214:217], v[102:105]
	v_mfma_f32_16x16x32_bf16 v[98:101], v[162:165], v[214:217], v[98:101]
	v_mfma_f32_16x16x32_bf16 v[86:89], v[154:157], v[222:225], v[86:89]
	v_mfma_f32_16x16x32_bf16 v[82:85], v[162:165], v[222:225], v[82:85]
	s_setprio 0
	s_setprio 1
	v_mfma_f32_16x16x32_bf16 v[110:113], v[166:169], v[182:185], v[110:113]
	v_mfma_f32_16x16x32_bf16 v[106:109], v[174:177], v[182:185], v[106:109]
	v_mfma_f32_16x16x32_bf16 v[94:97], v[166:169], v[190:193], v[94:97]
	v_mfma_f32_16x16x32_bf16 v[90:93], v[174:177], v[190:193], v[90:93]
	v_mfma_f32_16x16x32_bf16 v[78:81], v[166:169], v[210:213], v[78:81]
	v_mfma_f32_16x16x32_bf16 v[74:77], v[174:177], v[210:213], v[74:77]
	v_mfma_f32_16x16x32_bf16 v[70:73], v[166:169], v[218:221], v[70:73]
	v_mfma_f32_16x16x32_bf16 v[66:69], v[174:177], v[218:221], v[66:69]
	v_mfma_f32_16x16x32_bf16 v[110:113], v[170:173], v[186:189], v[110:113]
	v_mfma_f32_16x16x32_bf16 v[106:109], v[178:181], v[186:189], v[106:109]
	v_mfma_f32_16x16x32_bf16 v[94:97], v[170:173], v[198:201], v[94:97]
	v_mfma_f32_16x16x32_bf16 v[90:93], v[178:181], v[198:201], v[90:93]
	v_mfma_f32_16x16x32_bf16 v[78:81], v[170:173], v[214:217], v[78:81]
	v_mfma_f32_16x16x32_bf16 v[74:77], v[178:181], v[214:217], v[74:77]
	v_mfma_f32_16x16x32_bf16 v[70:73], v[170:173], v[222:225], v[70:73]
	v_mfma_f32_16x16x32_bf16 v[66:69], v[178:181], v[222:225], v[66:69]
	s_setprio 0
	s_barrier
	s_add_i32 s51, s43, s35
	v_lshl_add_u64 v[202:203], s[28:29], 0, v[132:133]
	s_mov_b32 m0, s51
	ds_read_b128 v[182:185], v149 offset:16384
	ds_read_b128 v[186:189], v149 offset:17408
	ds_read_b128 v[190:193], v149 offset:18432
	ds_read_b128 v[198:201], v149 offset:19456
	ds_read_b128 v[210:213], v149 offset:20480
	ds_read_b128 v[214:217], v149 offset:21504
	ds_read_b128 v[218:221], v149 offset:22528
	ds_read_b128 v[222:225], v149 offset:23552
	global_load_lds_dwordx4 v[202:203], off sc0
	s_add_i32 m0, s51, 0x2000
	s_add_u32 s52, s28, 0x20000
	v_lshl_add_u64 v[206:207], s[28:29], 0, v[134:135]
	s_addc_u32 s53, s29, 0
	s_add_i32 s51, s44, s35
	global_load_lds_dwordx4 v[206:207], off sc0
	v_lshl_add_u64 v[226:227], s[52:53], 0, v[132:133]
	s_mov_b32 m0, s51
	v_lshl_add_u64 v[228:229], s[30:31], 0, v[136:137]
	global_load_lds_dwordx4 v[226:227], off sc0
	v_lshl_add_u64 v[226:227], s[52:53], 0, v[134:135]
	s_add_i32 m0, s51, 0x2000
	s_nop 0
	global_load_lds_dwordx4 v[226:227], off sc0
	v_lshl_add_u64 v[226:227], s[30:31], 0, v[130:131]
	s_mov_b32 m0, s36
	s_nop 0
	global_load_lds_dwordx4 v[226:227], off sc0
	s_mov_b32 m0, s37
	s_nop 0
	global_load_lds_dwordx4 v[228:229], off sc0
	s_waitcnt vmcnt(8)
	s_waitcnt lgkmcnt(0)
	s_barrier
	s_setprio 1
	s_waitcnt lgkmcnt(0)
	v_mfma_f32_16x16x32_bf16 v[62:65], v[150:153], v[182:185], v[62:65]
	v_mfma_f32_16x16x32_bf16 v[58:61], v[158:161], v[182:185], v[58:61]
	v_mfma_f32_16x16x32_bf16 v[54:57], v[150:153], v[190:193], v[54:57]
	v_mfma_f32_16x16x32_bf16 v[50:53], v[158:161], v[190:193], v[50:53]
	v_mfma_f32_16x16x32_bf16 v[38:41], v[150:153], v[210:213], v[38:41]
	v_mfma_f32_16x16x32_bf16 v[34:37], v[158:161], v[210:213], v[34:37]
	v_mfma_f32_16x16x32_bf16 v[22:25], v[150:153], v[218:221], v[22:25]
	v_mfma_f32_16x16x32_bf16 v[18:21], v[158:161], v[218:221], v[18:21]
	v_mfma_f32_16x16x32_bf16 v[62:65], v[154:157], v[186:189], v[62:65]
	v_mfma_f32_16x16x32_bf16 v[58:61], v[162:165], v[186:189], v[58:61]
	v_mfma_f32_16x16x32_bf16 v[54:57], v[154:157], v[198:201], v[54:57]
	v_mfma_f32_16x16x32_bf16 v[50:53], v[162:165], v[198:201], v[50:53]
	v_mfma_f32_16x16x32_bf16 v[38:41], v[154:157], v[214:217], v[38:41]
	v_mfma_f32_16x16x32_bf16 v[34:37], v[162:165], v[214:217], v[34:37]
	v_mfma_f32_16x16x32_bf16 v[22:25], v[154:157], v[222:225], v[22:25]
	v_mfma_f32_16x16x32_bf16 v[18:21], v[162:165], v[222:225], v[18:21]
	s_setprio 0
	s_setprio 1
	v_mfma_f32_16x16x32_bf16 v[46:49], v[166:169], v[182:185], v[46:49]
	v_mfma_f32_16x16x32_bf16 v[42:45], v[174:177], v[182:185], v[42:45]
	v_mfma_f32_16x16x32_bf16 v[30:33], v[166:169], v[190:193], v[30:33]
	v_mfma_f32_16x16x32_bf16 v[26:29], v[174:177], v[190:193], v[26:29]
	v_mfma_f32_16x16x32_bf16 v[14:17], v[166:169], v[210:213], v[14:17]
	v_mfma_f32_16x16x32_bf16 v[10:13], v[174:177], v[210:213], v[10:13]
	v_mfma_f32_16x16x32_bf16 v[6:9], v[166:169], v[218:221], v[6:9]
	v_mfma_f32_16x16x32_bf16 v[2:5], v[174:177], v[218:221], v[2:5]
	v_mfma_f32_16x16x32_bf16 v[46:49], v[170:173], v[186:189], v[46:49]
	v_mfma_f32_16x16x32_bf16 v[42:45], v[178:181], v[186:189], v[42:45]
	v_mfma_f32_16x16x32_bf16 v[30:33], v[170:173], v[198:201], v[30:33]
	v_mfma_f32_16x16x32_bf16 v[26:29], v[178:181], v[198:201], v[26:29]
	v_mfma_f32_16x16x32_bf16 v[14:17], v[170:173], v[214:217], v[14:17]
	v_mfma_f32_16x16x32_bf16 v[10:13], v[178:181], v[214:217], v[10:13]
	v_mfma_f32_16x16x32_bf16 v[6:9], v[170:173], v[222:225], v[6:9]
	v_mfma_f32_16x16x32_bf16 v[2:5], v[178:181], v[222:225], v[2:5]
	s_setprio 0
	s_barrier
	s_add_i32 s51, 0, 0x18000
	s_add_i32 s52, 0, 0x1c000
	v_add_u32_e32 v162, s51, v145
	v_add_u32_e32 v178, s52, v145
	ds_read_b128 v[150:153], v162
	ds_read_b128 v[154:157], v162 offset:1024
	ds_read_b128 v[158:161], v162 offset:2048
	ds_read_b128 v[162:165], v162 offset:3072
	ds_read_b128 v[166:169], v178
	ds_read_b128 v[170:173], v178 offset:1024
	ds_read_b128 v[174:177], v178 offset:2048
	ds_read_b128 v[178:181], v178 offset:3072
	s_add_u32 s30, s30, 0x20000
	s_addc_u32 s31, s31, 0
	s_mov_b32 m0, s38
	v_lshl_add_u64 v[230:231], s[30:31], 0, v[130:131]
	ds_read_b128 v[182:185], v149 offset:32768
	ds_read_b128 v[186:189], v149 offset:33792
	ds_read_b128 v[190:193], v149 offset:34816
	ds_read_b128 v[198:201], v149 offset:35840
	ds_read_b128 v[210:213], v149 offset:36864
	ds_read_b128 v[214:217], v149 offset:37888
	ds_read_b128 v[218:221], v149 offset:38912
	ds_read_b128 v[222:225], v149 offset:39936
	global_load_lds_dwordx4 v[230:231], off sc0
	v_lshl_add_u64 v[230:231], s[30:31], 0, v[136:137]
	s_mov_b32 m0, s39
	s_nop 0
	global_load_lds_dwordx4 v[230:231], off sc0
	s_waitcnt vmcnt(8)
	s_waitcnt lgkmcnt(0)
	s_barrier
	s_setprio 1
	s_waitcnt lgkmcnt(0)
	v_mfma_f32_16x16x32_bf16 v[126:129], v[150:153], v[182:185], v[126:129]
	v_mfma_f32_16x16x32_bf16 v[122:125], v[158:161], v[182:185], v[122:125]
	v_mfma_f32_16x16x32_bf16 v[118:121], v[150:153], v[190:193], v[118:121]
	v_mfma_f32_16x16x32_bf16 v[114:117], v[158:161], v[190:193], v[114:117]
	v_mfma_f32_16x16x32_bf16 v[102:105], v[150:153], v[210:213], v[102:105]
	v_mfma_f32_16x16x32_bf16 v[98:101], v[158:161], v[210:213], v[98:101]
	v_mfma_f32_16x16x32_bf16 v[86:89], v[150:153], v[218:221], v[86:89]
	v_mfma_f32_16x16x32_bf16 v[82:85], v[158:161], v[218:221], v[82:85]
	v_mfma_f32_16x16x32_bf16 v[126:129], v[154:157], v[186:189], v[126:129]
	v_mfma_f32_16x16x32_bf16 v[122:125], v[162:165], v[186:189], v[122:125]
	v_mfma_f32_16x16x32_bf16 v[118:121], v[154:157], v[198:201], v[118:121]
	v_mfma_f32_16x16x32_bf16 v[114:117], v[162:165], v[198:201], v[114:117]
	v_mfma_f32_16x16x32_bf16 v[102:105], v[154:157], v[214:217], v[102:105]
	v_mfma_f32_16x16x32_bf16 v[98:101], v[162:165], v[214:217], v[98:101]
	v_mfma_f32_16x16x32_bf16 v[86:89], v[154:157], v[222:225], v[86:89]
	v_mfma_f32_16x16x32_bf16 v[82:85], v[162:165], v[222:225], v[82:85]
	s_setprio 0
	s_setprio 1
	v_mfma_f32_16x16x32_bf16 v[110:113], v[166:169], v[182:185], v[110:113]
	v_mfma_f32_16x16x32_bf16 v[106:109], v[174:177], v[182:185], v[106:109]
	v_mfma_f32_16x16x32_bf16 v[94:97], v[166:169], v[190:193], v[94:97]
	v_mfma_f32_16x16x32_bf16 v[90:93], v[174:177], v[190:193], v[90:93]
	v_mfma_f32_16x16x32_bf16 v[78:81], v[166:169], v[210:213], v[78:81]
	v_mfma_f32_16x16x32_bf16 v[74:77], v[174:177], v[210:213], v[74:77]
	v_mfma_f32_16x16x32_bf16 v[70:73], v[166:169], v[218:221], v[70:73]
	v_mfma_f32_16x16x32_bf16 v[66:69], v[174:177], v[218:221], v[66:69]
	v_mfma_f32_16x16x32_bf16 v[110:113], v[170:173], v[186:189], v[110:113]
	v_mfma_f32_16x16x32_bf16 v[106:109], v[178:181], v[186:189], v[106:109]
	v_mfma_f32_16x16x32_bf16 v[94:97], v[170:173], v[198:201], v[94:97]
	v_mfma_f32_16x16x32_bf16 v[90:93], v[178:181], v[198:201], v[90:93]
	v_mfma_f32_16x16x32_bf16 v[78:81], v[170:173], v[214:217], v[78:81]
	v_mfma_f32_16x16x32_bf16 v[74:77], v[178:181], v[214:217], v[74:77]
	v_mfma_f32_16x16x32_bf16 v[70:73], v[170:173], v[222:225], v[70:73]
	v_mfma_f32_16x16x32_bf16 v[66:69], v[178:181], v[222:225], v[66:69]
	s_setprio 0
	s_barrier
	s_add_i32 s30, s51, s35
	v_lshl_add_u64 v[202:203], v[202:203], 0, s[8:9]
	s_mov_b32 m0, s30
	ds_read_b128 v[182:185], v149 offset:49152
	ds_read_b128 v[186:189], v149 offset:50176
	ds_read_b128 v[190:193], v149 offset:51200
	ds_read_b128 v[198:201], v149 offset:52224
	ds_read_b128 v[210:213], v149 offset:53248
	ds_read_b128 v[214:217], v149 offset:54272
	ds_read_b128 v[218:221], v149 offset:55296
	ds_read_b128 v[222:225], v149 offset:56320
	global_load_lds_dwordx4 v[202:203], off sc0
	s_add_i32 m0, s30, 0x2000
	s_add_u32 s28, s28, 0x20080
	v_lshl_add_u64 v[202:203], v[206:207], 0, s[8:9]
	s_addc_u32 s29, s29, 0
	s_add_i32 s30, s52, s35
	global_load_lds_dwordx4 v[202:203], off sc0
	v_lshl_add_u64 v[202:203], s[28:29], 0, v[132:133]
	s_mov_b32 m0, s30
	s_nop 0
	global_load_lds_dwordx4 v[202:203], off sc0
	v_lshl_add_u64 v[202:203], s[28:29], 0, v[134:135]
	s_add_i32 m0, s30, 0x2000
	s_nop 0
	global_load_lds_dwordx4 v[202:203], off sc0
	v_lshl_add_u64 v[202:203], v[226:227], 0, s[8:9]
	s_mov_b32 m0, s41
	s_nop 0
	global_load_lds_dwordx4 v[202:203], off sc0
	v_lshl_add_u64 v[202:203], v[228:229], 0, s[8:9]
	s_mov_b32 m0, s42
	s_nop 0
	global_load_lds_dwordx4 v[202:203], off sc0
	s_waitcnt vmcnt(8)
	s_waitcnt lgkmcnt(0)
	s_barrier
	s_setprio 1
	s_waitcnt lgkmcnt(0)
	v_mfma_f32_16x16x32_bf16 v[62:65], v[150:153], v[182:185], v[62:65]
	v_mfma_f32_16x16x32_bf16 v[58:61], v[158:161], v[182:185], v[58:61]
	v_mfma_f32_16x16x32_bf16 v[54:57], v[150:153], v[190:193], v[54:57]
	v_mfma_f32_16x16x32_bf16 v[50:53], v[158:161], v[190:193], v[50:53]
	v_mfma_f32_16x16x32_bf16 v[38:41], v[150:153], v[210:213], v[38:41]
	v_mfma_f32_16x16x32_bf16 v[34:37], v[158:161], v[210:213], v[34:37]
	v_mfma_f32_16x16x32_bf16 v[22:25], v[150:153], v[218:221], v[22:25]
	v_mfma_f32_16x16x32_bf16 v[18:21], v[158:161], v[218:221], v[18:21]
	v_mfma_f32_16x16x32_bf16 v[62:65], v[154:157], v[186:189], v[62:65]
	v_mfma_f32_16x16x32_bf16 v[58:61], v[162:165], v[186:189], v[58:61]
	v_mfma_f32_16x16x32_bf16 v[54:57], v[154:157], v[198:201], v[54:57]
	v_mfma_f32_16x16x32_bf16 v[50:53], v[162:165], v[198:201], v[50:53]
	v_mfma_f32_16x16x32_bf16 v[38:41], v[154:157], v[214:217], v[38:41]
	v_mfma_f32_16x16x32_bf16 v[34:37], v[162:165], v[214:217], v[34:37]
	v_mfma_f32_16x16x32_bf16 v[22:25], v[154:157], v[222:225], v[22:25]
	v_mfma_f32_16x16x32_bf16 v[18:21], v[162:165], v[222:225], v[18:21]
	s_setprio 0
	s_setprio 1
	v_mfma_f32_16x16x32_bf16 v[46:49], v[166:169], v[182:185], v[46:49]
	v_mfma_f32_16x16x32_bf16 v[42:45], v[174:177], v[182:185], v[42:45]
	v_mfma_f32_16x16x32_bf16 v[30:33], v[166:169], v[190:193], v[30:33]
	v_mfma_f32_16x16x32_bf16 v[26:29], v[174:177], v[190:193], v[26:29]
	v_mfma_f32_16x16x32_bf16 v[14:17], v[166:169], v[210:213], v[14:17]
	v_mfma_f32_16x16x32_bf16 v[10:13], v[174:177], v[210:213], v[10:13]
	v_mfma_f32_16x16x32_bf16 v[6:9], v[166:169], v[218:221], v[6:9]
	v_mfma_f32_16x16x32_bf16 v[2:5], v[174:177], v[218:221], v[2:5]
	v_mfma_f32_16x16x32_bf16 v[46:49], v[170:173], v[186:189], v[46:49]
	v_mfma_f32_16x16x32_bf16 v[42:45], v[178:181], v[186:189], v[42:45]
	v_mfma_f32_16x16x32_bf16 v[30:33], v[170:173], v[198:201], v[30:33]
	v_mfma_f32_16x16x32_bf16 v[26:29], v[178:181], v[198:201], v[26:29]
	v_mfma_f32_16x16x32_bf16 v[14:17], v[170:173], v[214:217], v[14:17]
	v_mfma_f32_16x16x32_bf16 v[10:13], v[178:181], v[214:217], v[10:13]
	v_mfma_f32_16x16x32_bf16 v[6:9], v[170:173], v[222:225], v[6:9]
	v_mfma_f32_16x16x32_bf16 v[2:5], v[178:181], v[222:225], v[2:5]
	s_setprio 0
	s_barrier
	s_add_i32 s50, s50, 2
	s_add_u32 s26, s26, 0x100
	s_addc_u32 s27, s27, 0
	s_add_u32 s48, s48, 0x100
	s_addc_u32 s49, s49, 0
	s_cmp_gt_u32 s50, 5
	s_cbranch_scc0 .LBB0_690

.LBB0_702:
	s_add_u32 s2, s82, 0x31100000
	s_addc_u32 s3, s83, 0
	s_add_u32 s33, s82, 0x11f00000
	s_addc_u32 s40, s83, 0
	s_ashr_i32 s4, s7, 3
	s_add_i32 s4, s8, s4
	s_ashr_i32 s5, s4, 31
	s_lshr_b32 s5, s5, 26
	s_add_i32 s5, s4, s5
	s_ashr_i32 s7, s5, 6
	s_andn2_b32 s5, s5, 63
	s_sub_i32 s4, s4, s5
	s_bfe_i32 s5, s4, 0x80000
	s_bfe_u32 s5, s5, 0x3000c
	s_add_i32 s5, s4, s5
	s_bfe_i32 s8, s5, 0x80000
	s_and_b32 s5, s5, 0xf8
	s_sub_i32 s4, s4, s5
	s_lshl_b32 s7, s7, 3
	s_sext_i32_i16 s8, s8
	s_sext_i32_i8 s4, s4
	s_lshr_b32 s8, s8, 3
	s_add_i32 s26, s7, s4
	s_lshr_b32 s6, s9, 6
	s_ashr_i32 s27, s26, 31
	s_bfe_i64 s[12:13], s[8:9], 0x100000
	s_lshr_b32 s10, s9, 8
	s_lshl_b32 s41, s6, 10
	s_lshl_b64 s[4:5], s[26:27], 18
	s_lshl_b64 s[12:13], s[12:13], 18
	s_add_u32 s36, s33, s12
	s_addc_u32 s37, s40, s13
	s_add_i32 s27, s41, 0
	s_add_i32 m0, s27, 0x10000
	v_mov_b32_e32 v133, 0
	global_load_lds_dwordx4 v132, s[36:37] sc0
	s_add_i32 m0, s27, 0x12000
	s_add_u32 s12, s36, 0x20000
	global_load_lds_dwordx4 v134, s[36:37] sc0
	s_addc_u32 s13, s37, 0
	s_add_i32 m0, s27, 0x14000
	v_mov_b32_e32 v135, v133
	global_load_lds_dwordx4 v132, s[12:13] sc0
	s_add_i32 m0, s27, 0x16000
	s_add_u32 s34, s2, s4
	s_addc_u32 s35, s3, s5
	s_add_i32 s42, s27, 0x2000
	global_load_lds_dwordx4 v134, s[12:13] sc0
	s_mov_b32 m0, s27
	s_add_u32 s4, s34, 0x20000
	global_load_lds_dwordx4 v130, s[34:35] sc0
	s_mov_b32 m0, s42
	s_addc_u32 s5, s35, 0
	s_add_i32 s43, s27, 0x4000
	global_load_lds_dwordx4 v136, s[34:35] sc0
	s_mov_b32 m0, s43
	s_add_i32 s44, s27, 0x6000
	global_load_lds_dwordx4 v130, s[4:5] sc0
	s_mov_b32 m0, s44
	v_mov_b32_e32 v131, v133
	global_load_lds_dwordx4 v136, s[4:5] sc0
	v_mov_b32_e32 v137, v133
	s_cmp_eq_u32 s10, 1
	s_mov_b32 s45, 0
	v_lshl_add_u64 v[8:9], s[36:37], 0, v[132:133]
	v_lshl_add_u64 v[6:7], s[36:37], 0, v[134:135]
	v_lshl_add_u64 v[2:3], s[34:35], 0, v[130:131]
	s_cselect_b64 s[4:5], -1, 0
	s_cmp_lg_u32 s10, 1
	v_lshl_add_u64 v[4:5], s[34:35], 0, v[136:137]
	s_cbranch_scc1 .LBB0_704
	s_barrier
.LBB0_704:
	s_lshl_b32 s6, s6, 5
	s_and_b32 s16, s6, 0x60
	s_mov_b64 s[6:7], 0x80
	s_add_i32 m0, s27, 0x18000
	v_lshl_add_u64 v[8:9], v[8:9], 0, s[6:7]
	s_lshl_b32 s11, s10, 13
	s_waitcnt vmcnt(2)
	s_barrier
	global_load_lds_dwordx4 v[8:9], off sc0
	v_lshl_add_u64 v[6:7], v[6:7], 0, s[6:7]
	s_add_i32 m0, s27, 0x1a000
	s_add_i32 s46, s27, 0x8000
	s_add_i32 s47, s27, 0xa000
	global_load_lds_dwordx4 v[6:7], off sc0
	v_lshl_add_u64 v[2:3], v[2:3], 0, s[6:7]
	s_mov_b32 m0, s46
	s_add_u32 s12, s36, 0x20080
	global_load_lds_dwordx4 v[2:3], off sc0
	v_lshl_add_u64 v[2:3], v[4:5], 0, s[6:7]
	s_mov_b32 m0, s47
	s_addc_u32 s13, s37, 0
	global_load_lds_dwordx4 v[2:3], off sc0
	s_add_i32 m0, s27, 0x1c000
	v_lshl_add_u64 v[2:3], s[12:13], 0, v[132:133]
	global_load_lds_dwordx4 v[2:3], off sc0
	v_lshl_add_u64 v[2:3], s[12:13], 0, v[134:135]
	s_add_i32 m0, s27, 0x1e000
	s_cmpk_lt_u32 s9, 0x100
	global_load_lds_dwordx4 v[2:3], off sc0
	v_lshlrev_b32_e32 v3, 2, v205
	v_lshl_or_b32 v2, v205, 6, v142
	v_and_b32_e32 v3, 32, v3
	s_waitcnt vmcnt(6)
	s_sext_i32_i8 s54, s8
	v_bitop3_b32 v2, v2, s11, v3 bitop3:0xde
	v_lshl_or_b32 v139, s16, 7, v143
	s_cselect_b64 s[8:9], -1, 0
	s_add_i32 s48, 0, 0x10000
	s_add_i32 s49, 0, 0x14000
	v_lshl_or_b32 v138, s10, 6, v205
	v_or_b32_e32 v1, s16, v1
	v_add_u32_e32 v140, s48, v139
	v_add_u32_e32 v141, s49, v139
	v_add_u32_e32 v142, 0, v2
	s_mov_b64 s[10:11], 0x80000
	s_mov_b32 s50, 0x80000
	s_mov_b64 s[12:13], 0x90000
	s_mov_b32 s51, 0x90000
	s_mov_b64 s[16:17], 0xa0000
	s_mov_b32 s52, 0xa0000
	s_mov_b64 s[18:19], 0xb0000
	s_mov_b32 s53, 0xb0000
	s_barrier
	s_branch .LBB0_707

.Lpeel_9:
	ds_read_b128 v[144:147], v140
	ds_read_b128 v[148:151], v140 offset:1024
	ds_read_b128 v[152:155], v140 offset:2048
	ds_read_b128 v[156:159], v140 offset:3072
	ds_read_b128 v[160:163], v141
	ds_read_b128 v[164:167], v141 offset:1024
	ds_read_b128 v[168:171], v141 offset:2048
	ds_read_b128 v[172:175], v141 offset:3072
	s_add_u32 s36, s34, 0xfffe0080
	s_addc_u32 s37, s35, -1
	s_cmp_eq_u32 s59, 4
	s_cselect_b32 s39, s21, s37
	s_cselect_b32 s38, s55, s36
	s_cselect_b32 s37, s25, s58
	s_cselect_b32 s36, s56, s57
	v_lshl_add_u64 v[192:193], s[34:35], 0, v[130:131]
	s_add_i32 m0, s27, 0xc000
	ds_read_b128 v[176:179], v142
	ds_read_b128 v[180:183], v142 offset:1024
	ds_read_b128 v[184:187], v142 offset:2048
	ds_read_b128 v[188:191], v142 offset:3072
	ds_read_b128 v[198:201], v142 offset:4096
	ds_read_b128 v[210:213], v142 offset:5120
	ds_read_b128 v[214:217], v142 offset:6144
	ds_read_b128 v[218:221], v142 offset:7168
	global_load_lds_dwordx4 v[192:193], off sc0
	v_lshl_add_u64 v[192:193], s[34:35], 0, v[136:137]
	s_add_i32 m0, s27, 0xe000
	s_nop 0
	global_load_lds_dwordx4 v[192:193], off sc0
	s_waitcnt vmcnt(8)
	s_waitcnt lgkmcnt(0)
	s_barrier
	s_setprio 1
	s_waitcnt lgkmcnt(0)
	v_mfma_f32_16x16x32_bf16 v[126:129], v[144:147], v[176:179], 0
	v_mfma_f32_16x16x32_bf16 v[122:125], v[152:155], v[176:179], 0
	v_mfma_f32_16x16x32_bf16 v[118:121], v[144:147], v[184:187], 0
	v_mfma_f32_16x16x32_bf16 v[114:117], v[152:155], v[184:187], 0
	v_mfma_f32_16x16x32_bf16 v[102:105], v[144:147], v[198:201], 0
	v_mfma_f32_16x16x32_bf16 v[98:101], v[152:155], v[198:201], 0
	v_mfma_f32_16x16x32_bf16 v[86:89], v[144:147], v[214:217], 0
	v_mfma_f32_16x16x32_bf16 v[82:85], v[152:155], v[214:217], 0
	v_mfma_f32_16x16x32_bf16 v[126:129], v[148:151], v[180:183], v[126:129]
	v_mfma_f32_16x16x32_bf16 v[122:125], v[156:159], v[180:183], v[122:125]
	v_mfma_f32_16x16x32_bf16 v[118:121], v[148:151], v[188:191], v[118:121]
	v_mfma_f32_16x16x32_bf16 v[114:117], v[156:159], v[188:191], v[114:117]
	v_mfma_f32_16x16x32_bf16 v[102:105], v[148:151], v[210:213], v[102:105]
	v_mfma_f32_16x16x32_bf16 v[98:101], v[156:159], v[210:213], v[98:101]
	v_mfma_f32_16x16x32_bf16 v[86:89], v[148:151], v[218:221], v[86:89]
	v_mfma_f32_16x16x32_bf16 v[82:85], v[156:159], v[218:221], v[82:85]
	s_setprio 0
	s_setprio 1
	v_mfma_f32_16x16x32_bf16 v[110:113], v[160:163], v[176:179], 0
	v_mfma_f32_16x16x32_bf16 v[106:109], v[168:171], v[176:179], 0
	v_mfma_f32_16x16x32_bf16 v[94:97], v[160:163], v[184:187], 0
	v_mfma_f32_16x16x32_bf16 v[90:93], v[168:171], v[184:187], 0
	v_mfma_f32_16x16x32_bf16 v[78:81], v[160:163], v[198:201], 0
	v_mfma_f32_16x16x32_bf16 v[74:77], v[168:171], v[198:201], 0
	v_mfma_f32_16x16x32_bf16 v[70:73], v[160:163], v[214:217], 0
	v_mfma_f32_16x16x32_bf16 v[66:69], v[168:171], v[214:217], 0
	v_mfma_f32_16x16x32_bf16 v[110:113], v[164:167], v[180:183], v[110:113]
	v_mfma_f32_16x16x32_bf16 v[106:109], v[172:175], v[180:183], v[106:109]
	v_mfma_f32_16x16x32_bf16 v[94:97], v[164:167], v[188:191], v[94:97]
	v_mfma_f32_16x16x32_bf16 v[90:93], v[172:175], v[188:191], v[90:93]
	v_mfma_f32_16x16x32_bf16 v[78:81], v[164:167], v[210:213], v[78:81]
	v_mfma_f32_16x16x32_bf16 v[74:77], v[172:175], v[210:213], v[74:77]
	v_mfma_f32_16x16x32_bf16 v[70:73], v[164:167], v[218:221], v[70:73]
	v_mfma_f32_16x16x32_bf16 v[66:69], v[172:175], v[218:221], v[66:69]
	s_setprio 0
	s_barrier
	s_add_i32 s60, s48, s41
	v_lshl_add_u64 v[192:193], s[36:37], 0, v[132:133]
	s_mov_b32 m0, s60
	ds_read_b128 v[176:179], v142 offset:16384
	ds_read_b128 v[180:183], v142 offset:17408
	ds_read_b128 v[184:187], v142 offset:18432
	ds_read_b128 v[188:191], v142 offset:19456
	ds_read_b128 v[198:201], v142 offset:20480
	ds_read_b128 v[210:213], v142 offset:21504
	ds_read_b128 v[214:217], v142 offset:22528
	ds_read_b128 v[218:221], v142 offset:23552
	global_load_lds_dwordx4 v[192:193], off sc0
	s_add_i32 m0, s60, 0x2000
	s_add_u32 s60, s36, 0x20000
	v_lshl_add_u64 v[202:203], s[36:37], 0, v[134:135]
	s_addc_u32 s61, s37, 0
	s_add_i32 s62, s49, s41
	global_load_lds_dwordx4 v[202:203], off sc0
	v_lshl_add_u64 v[206:207], s[60:61], 0, v[132:133]
	s_mov_b32 m0, s62
	v_lshl_add_u64 v[222:223], s[38:39], 0, v[136:137]
	global_load_lds_dwordx4 v[206:207], off sc0
	v_lshl_add_u64 v[206:207], s[60:61], 0, v[134:135]
	s_add_i32 m0, s62, 0x2000
	s_nop 0
	global_load_lds_dwordx4 v[206:207], off sc0
	v_lshl_add_u64 v[206:207], s[38:39], 0, v[130:131]
	s_mov_b32 m0, s27
	s_nop 0
	global_load_lds_dwordx4 v[206:207], off sc0
	s_mov_b32 m0, s42
	s_nop 0
	global_load_lds_dwordx4 v[222:223], off sc0
	s_waitcnt vmcnt(8)
	s_waitcnt lgkmcnt(0)
	s_barrier
	s_setprio 1
	s_waitcnt lgkmcnt(0)
	v_mfma_f32_16x16x32_bf16 v[62:65], v[144:147], v[176:179], 0
	v_mfma_f32_16x16x32_bf16 v[58:61], v[152:155], v[176:179], 0
	v_mfma_f32_16x16x32_bf16 v[54:57], v[144:147], v[184:187], 0
	v_mfma_f32_16x16x32_bf16 v[50:53], v[152:155], v[184:187], 0
	v_mfma_f32_16x16x32_bf16 v[38:41], v[144:147], v[198:201], 0
	v_mfma_f32_16x16x32_bf16 v[34:37], v[152:155], v[198:201], 0
	v_mfma_f32_16x16x32_bf16 v[22:25], v[144:147], v[214:217], 0
	v_mfma_f32_16x16x32_bf16 v[18:21], v[152:155], v[214:217], 0
	v_mfma_f32_16x16x32_bf16 v[62:65], v[148:151], v[180:183], v[62:65]
	v_mfma_f32_16x16x32_bf16 v[58:61], v[156:159], v[180:183], v[58:61]
	v_mfma_f32_16x16x32_bf16 v[54:57], v[148:151], v[188:191], v[54:57]
	v_mfma_f32_16x16x32_bf16 v[50:53], v[156:159], v[188:191], v[50:53]
	v_mfma_f32_16x16x32_bf16 v[38:41], v[148:151], v[210:213], v[38:41]
	v_mfma_f32_16x16x32_bf16 v[34:37], v[156:159], v[210:213], v[34:37]
	v_mfma_f32_16x16x32_bf16 v[22:25], v[148:151], v[218:221], v[22:25]
	v_mfma_f32_16x16x32_bf16 v[18:21], v[156:159], v[218:221], v[18:21]
	s_setprio 0
	s_setprio 1
	v_mfma_f32_16x16x32_bf16 v[46:49], v[160:163], v[176:179], 0
	v_mfma_f32_16x16x32_bf16 v[42:45], v[168:171], v[176:179], 0
	v_mfma_f32_16x16x32_bf16 v[30:33], v[160:163], v[184:187], 0
	v_mfma_f32_16x16x32_bf16 v[26:29], v[168:171], v[184:187], 0
	v_mfma_f32_16x16x32_bf16 v[14:17], v[160:163], v[198:201], 0
	v_mfma_f32_16x16x32_bf16 v[10:13], v[168:171], v[198:201], 0
	v_mfma_f32_16x16x32_bf16 v[6:9], v[160:163], v[214:217], 0
	v_mfma_f32_16x16x32_bf16 v[2:5], v[168:171], v[214:217], 0
	v_mfma_f32_16x16x32_bf16 v[46:49], v[164:167], v[180:183], v[46:49]
	v_mfma_f32_16x16x32_bf16 v[42:45], v[172:175], v[180:183], v[42:45]
	v_mfma_f32_16x16x32_bf16 v[30:33], v[164:167], v[188:191], v[30:33]
	v_mfma_f32_16x16x32_bf16 v[26:29], v[172:175], v[188:191], v[26:29]
	v_mfma_f32_16x16x32_bf16 v[14:17], v[164:167], v[210:213], v[14:17]
	v_mfma_f32_16x16x32_bf16 v[10:13], v[172:175], v[210:213], v[10:13]
	v_mfma_f32_16x16x32_bf16 v[6:9], v[164:167], v[218:221], v[6:9]
	v_mfma_f32_16x16x32_bf16 v[2:5], v[172:175], v[218:221], v[2:5]
	s_setprio 0
	s_barrier
	s_add_i32 s60, 0, 0x18000
	v_add_u32_e32 v143, s60, v139
	s_add_i32 s61, 0, 0x1c000
	ds_read_b128 v[144:147], v143
	ds_read_b128 v[148:151], v143 offset:1024
	ds_read_b128 v[152:155], v143 offset:2048
	ds_read_b128 v[156:159], v143 offset:3072
	v_add_u32_e32 v143, s61, v139
	ds_read_b128 v[160:163], v143
	ds_read_b128 v[164:167], v143 offset:1024
	ds_read_b128 v[168:171], v143 offset:2048
	ds_read_b128 v[172:175], v143 offset:3072
	s_add_u32 s38, s38, 0x20000
	s_addc_u32 s39, s39, 0
	s_mov_b32 m0, s43
	v_lshl_add_u64 v[224:225], s[38:39], 0, v[130:131]
	ds_read_b128 v[176:179], v142 offset:32768
	ds_read_b128 v[180:183], v142 offset:33792
	ds_read_b128 v[184:187], v142 offset:34816
	ds_read_b128 v[188:191], v142 offset:35840
	ds_read_b128 v[198:201], v142 offset:36864
	ds_read_b128 v[210:213], v142 offset:37888
	ds_read_b128 v[214:217], v142 offset:38912
	ds_read_b128 v[218:221], v142 offset:39936
	global_load_lds_dwordx4 v[224:225], off sc0
	v_lshl_add_u64 v[224:225], s[38:39], 0, v[136:137]
	s_mov_b32 m0, s44
	s_nop 0
	global_load_lds_dwordx4 v[224:225], off sc0
	s_waitcnt vmcnt(8)
	s_waitcnt lgkmcnt(0)
	s_barrier
	s_setprio 1
	s_waitcnt lgkmcnt(0)
	v_mfma_f32_16x16x32_bf16 v[126:129], v[144:147], v[176:179], v[126:129]
	v_mfma_f32_16x16x32_bf16 v[122:125], v[152:155], v[176:179], v[122:125]
	v_mfma_f32_16x16x32_bf16 v[118:121], v[144:147], v[184:187], v[118:121]
	v_mfma_f32_16x16x32_bf16 v[114:117], v[152:155], v[184:187], v[114:117]
	v_mfma_f32_16x16x32_bf16 v[102:105], v[144:147], v[198:201], v[102:105]
	v_mfma_f32_16x16x32_bf16 v[98:101], v[152:155], v[198:201], v[98:101]
	v_mfma_f32_16x16x32_bf16 v[86:89], v[144:147], v[214:217], v[86:89]
	v_mfma_f32_16x16x32_bf16 v[82:85], v[152:155], v[214:217], v[82:85]
	v_mfma_f32_16x16x32_bf16 v[126:129], v[148:151], v[180:183], v[126:129]
	v_mfma_f32_16x16x32_bf16 v[122:125], v[156:159], v[180:183], v[122:125]
	v_mfma_f32_16x16x32_bf16 v[118:121], v[148:151], v[188:191], v[118:121]
	v_mfma_f32_16x16x32_bf16 v[114:117], v[156:159], v[188:191], v[114:117]
	v_mfma_f32_16x16x32_bf16 v[102:105], v[148:151], v[210:213], v[102:105]
	v_mfma_f32_16x16x32_bf16 v[98:101], v[156:159], v[210:213], v[98:101]
	v_mfma_f32_16x16x32_bf16 v[86:89], v[148:151], v[218:221], v[86:89]
	v_mfma_f32_16x16x32_bf16 v[82:85], v[156:159], v[218:221], v[82:85]
	s_setprio 0
	s_setprio 1
	v_mfma_f32_16x16x32_bf16 v[110:113], v[160:163], v[176:179], v[110:113]
	v_mfma_f32_16x16x32_bf16 v[106:109], v[168:171], v[176:179], v[106:109]
	v_mfma_f32_16x16x32_bf16 v[94:97], v[160:163], v[184:187], v[94:97]
	v_mfma_f32_16x16x32_bf16 v[90:93], v[168:171], v[184:187], v[90:93]
	v_mfma_f32_16x16x32_bf16 v[78:81], v[160:163], v[198:201], v[78:81]
	v_mfma_f32_16x16x32_bf16 v[74:77], v[168:171], v[198:201], v[74:77]
	v_mfma_f32_16x16x32_bf16 v[70:73], v[160:163], v[214:217], v[70:73]
	v_mfma_f32_16x16x32_bf16 v[66:69], v[168:171], v[214:217], v[66:69]
	v_mfma_f32_16x16x32_bf16 v[110:113], v[164:167], v[180:183], v[110:113]
	v_mfma_f32_16x16x32_bf16 v[106:109], v[172:175], v[180:183], v[106:109]
	v_mfma_f32_16x16x32_bf16 v[94:97], v[164:167], v[188:191], v[94:97]
	v_mfma_f32_16x16x32_bf16 v[90:93], v[172:175], v[188:191], v[90:93]
	v_mfma_f32_16x16x32_bf16 v[78:81], v[164:167], v[210:213], v[78:81]
	v_mfma_f32_16x16x32_bf16 v[74:77], v[172:175], v[210:213], v[74:77]
	v_mfma_f32_16x16x32_bf16 v[70:73], v[164:167], v[218:221], v[70:73]
	v_mfma_f32_16x16x32_bf16 v[66:69], v[172:175], v[218:221], v[66:69]
	s_setprio 0
	s_barrier
	s_add_i32 s38, s60, s41
	v_lshl_add_u64 v[192:193], v[192:193], 0, s[6:7]
	s_mov_b32 m0, s38
	ds_read_b128 v[176:179], v142 offset:49152
	ds_read_b128 v[180:183], v142 offset:50176
	ds_read_b128 v[184:187], v142 offset:51200
	ds_read_b128 v[188:191], v142 offset:52224
	ds_read_b128 v[198:201], v142 offset:53248
	ds_read_b128 v[210:213], v142 offset:54272
	ds_read_b128 v[214:217], v142 offset:55296
	ds_read_b128 v[218:221], v142 offset:56320
	global_load_lds_dwordx4 v[192:193], off sc0
	s_add_i32 m0, s38, 0x2000
	s_add_u32 s36, s36, 0x20080
	v_lshl_add_u64 v[192:193], v[202:203], 0, s[6:7]
	s_addc_u32 s37, s37, 0
	s_add_i32 s38, s61, s41
	global_load_lds_dwordx4 v[192:193], off sc0
	v_lshl_add_u64 v[192:193], s[36:37], 0, v[132:133]
	s_mov_b32 m0, s38
	s_nop 0
	global_load_lds_dwordx4 v[192:193], off sc0
	v_lshl_add_u64 v[192:193], s[36:37], 0, v[134:135]
	s_add_i32 m0, s38, 0x2000
	s_nop 0
	global_load_lds_dwordx4 v[192:193], off sc0
	v_lshl_add_u64 v[192:193], v[206:207], 0, s[6:7]
	s_mov_b32 m0, s46
	s_nop 0
	global_load_lds_dwordx4 v[192:193], off sc0
	v_lshl_add_u64 v[192:193], v[222:223], 0, s[6:7]
	s_mov_b32 m0, s47
	s_nop 0
	global_load_lds_dwordx4 v[192:193], off sc0
	s_waitcnt vmcnt(8)
	s_waitcnt lgkmcnt(0)
	s_barrier
	s_setprio 1
	s_waitcnt lgkmcnt(0)
	v_mfma_f32_16x16x32_bf16 v[62:65], v[144:147], v[176:179], v[62:65]
	v_mfma_f32_16x16x32_bf16 v[58:61], v[152:155], v[176:179], v[58:61]
	v_mfma_f32_16x16x32_bf16 v[54:57], v[144:147], v[184:187], v[54:57]
	v_mfma_f32_16x16x32_bf16 v[50:53], v[152:155], v[184:187], v[50:53]
	v_mfma_f32_16x16x32_bf16 v[38:41], v[144:147], v[198:201], v[38:41]
	v_mfma_f32_16x16x32_bf16 v[34:37], v[152:155], v[198:201], v[34:37]
	v_mfma_f32_16x16x32_bf16 v[22:25], v[144:147], v[214:217], v[22:25]
	v_mfma_f32_16x16x32_bf16 v[18:21], v[152:155], v[214:217], v[18:21]
	v_mfma_f32_16x16x32_bf16 v[62:65], v[148:151], v[180:183], v[62:65]
	v_mfma_f32_16x16x32_bf16 v[58:61], v[156:159], v[180:183], v[58:61]
	v_mfma_f32_16x16x32_bf16 v[54:57], v[148:151], v[188:191], v[54:57]
	v_mfma_f32_16x16x32_bf16 v[50:53], v[156:159], v[188:191], v[50:53]
	v_mfma_f32_16x16x32_bf16 v[38:41], v[148:151], v[210:213], v[38:41]
	v_mfma_f32_16x16x32_bf16 v[34:37], v[156:159], v[210:213], v[34:37]
	v_mfma_f32_16x16x32_bf16 v[22:25], v[148:151], v[218:221], v[22:25]
	v_mfma_f32_16x16x32_bf16 v[18:21], v[156:159], v[218:221], v[18:21]
	s_setprio 0
	s_setprio 1
	v_mfma_f32_16x16x32_bf16 v[46:49], v[160:163], v[176:179], v[46:49]
	v_mfma_f32_16x16x32_bf16 v[42:45], v[168:171], v[176:179], v[42:45]
	v_mfma_f32_16x16x32_bf16 v[30:33], v[160:163], v[184:187], v[30:33]
	v_mfma_f32_16x16x32_bf16 v[26:29], v[168:171], v[184:187], v[26:29]
	v_mfma_f32_16x16x32_bf16 v[14:17], v[160:163], v[198:201], v[14:17]
	v_mfma_f32_16x16x32_bf16 v[10:13], v[168:171], v[198:201], v[10:13]
	v_mfma_f32_16x16x32_bf16 v[6:9], v[160:163], v[214:217], v[6:9]
	v_mfma_f32_16x16x32_bf16 v[2:5], v[168:171], v[214:217], v[2:5]
	v_mfma_f32_16x16x32_bf16 v[46:49], v[164:167], v[180:183], v[46:49]
	v_mfma_f32_16x16x32_bf16 v[42:45], v[172:175], v[180:183], v[42:45]
	v_mfma_f32_16x16x32_bf16 v[30:33], v[164:167], v[188:191], v[30:33]
	v_mfma_f32_16x16x32_bf16 v[26:29], v[172:175], v[188:191], v[26:29]
	v_mfma_f32_16x16x32_bf16 v[14:17], v[164:167], v[210:213], v[14:17]
	v_mfma_f32_16x16x32_bf16 v[10:13], v[172:175], v[210:213], v[10:13]
	v_mfma_f32_16x16x32_bf16 v[6:9], v[164:167], v[218:221], v[6:9]
	v_mfma_f32_16x16x32_bf16 v[2:5], v[172:175], v[218:221], v[2:5]
	s_setprio 0
	s_barrier
	s_add_i32 s59, s59, 2
	s_add_u32 s34, s34, 0x100
	s_addc_u32 s35, s35, 0
	s_add_u32 s57, s57, 0x100
	s_addc_u32 s58, s58, 0
	s_cmp_gt_u32 s59, 5
	s_cbranch_scc0 .LBB0_714
	s_branch .Lpeeldone_9
.LBB0_714:
	ds_read_b128 v[144:147], v140
	ds_read_b128 v[148:151], v140 offset:1024
	ds_read_b128 v[152:155], v140 offset:2048
	ds_read_b128 v[156:159], v140 offset:3072
	ds_read_b128 v[160:163], v141
	ds_read_b128 v[164:167], v141 offset:1024
	ds_read_b128 v[168:171], v141 offset:2048
	ds_read_b128 v[172:175], v141 offset:3072
	s_add_u32 s36, s34, 0xfffe0080
	s_addc_u32 s37, s35, -1
	s_cmp_eq_u32 s59, 4
	s_cselect_b32 s39, s21, s37
	s_cselect_b32 s38, s55, s36
	s_cselect_b32 s37, s25, s58
	s_cselect_b32 s36, s56, s57
	v_lshl_add_u64 v[192:193], s[34:35], 0, v[130:131]
	s_add_i32 m0, s27, 0xc000
	ds_read_b128 v[176:179], v142
	ds_read_b128 v[180:183], v142 offset:1024
	ds_read_b128 v[184:187], v142 offset:2048
	ds_read_b128 v[188:191], v142 offset:3072
	ds_read_b128 v[198:201], v142 offset:4096
	ds_read_b128 v[210:213], v142 offset:5120
	ds_read_b128 v[214:217], v142 offset:6144
	ds_read_b128 v[218:221], v142 offset:7168
	global_load_lds_dwordx4 v[192:193], off sc0
	v_lshl_add_u64 v[192:193], s[34:35], 0, v[136:137]
	s_add_i32 m0, s27, 0xe000
	s_nop 0
	global_load_lds_dwordx4 v[192:193], off sc0
	s_waitcnt vmcnt(8)
	s_waitcnt lgkmcnt(0)
	s_barrier
	s_setprio 1
	s_waitcnt lgkmcnt(0)
	v_mfma_f32_16x16x32_bf16 v[126:129], v[144:147], v[176:179], v[126:129]
	v_mfma_f32_16x16x32_bf16 v[122:125], v[152:155], v[176:179], v[122:125]
	v_mfma_f32_16x16x32_bf16 v[118:121], v[144:147], v[184:187], v[118:121]
	v_mfma_f32_16x16x32_bf16 v[114:117], v[152:155], v[184:187], v[114:117]
	v_mfma_f32_16x16x32_bf16 v[102:105], v[144:147], v[198:201], v[102:105]
	v_mfma_f32_16x16x32_bf16 v[98:101], v[152:155], v[198:201], v[98:101]
	v_mfma_f32_16x16x32_bf16 v[86:89], v[144:147], v[214:217], v[86:89]
	v_mfma_f32_16x16x32_bf16 v[82:85], v[152:155], v[214:217], v[82:85]
	v_mfma_f32_16x16x32_bf16 v[126:129], v[148:151], v[180:183], v[126:129]
	v_mfma_f32_16x16x32_bf16 v[122:125], v[156:159], v[180:183], v[122:125]
	v_mfma_f32_16x16x32_bf16 v[118:121], v[148:151], v[188:191], v[118:121]
	v_mfma_f32_16x16x32_bf16 v[114:117], v[156:159], v[188:191], v[114:117]
	v_mfma_f32_16x16x32_bf16 v[102:105], v[148:151], v[210:213], v[102:105]
	v_mfma_f32_16x16x32_bf16 v[98:101], v[156:159], v[210:213], v[98:101]
	v_mfma_f32_16x16x32_bf16 v[86:89], v[148:151], v[218:221], v[86:89]
	v_mfma_f32_16x16x32_bf16 v[82:85], v[156:159], v[218:221], v[82:85]
	s_setprio 0
	s_setprio 1
	v_mfma_f32_16x16x32_bf16 v[110:113], v[160:163], v[176:179], v[110:113]
	v_mfma_f32_16x16x32_bf16 v[106:109], v[168:171], v[176:179], v[106:109]
	v_mfma_f32_16x16x32_bf16 v[94:97], v[160:163], v[184:187], v[94:97]
	v_mfma_f32_16x16x32_bf16 v[90:93], v[168:171], v[184:187], v[90:93]
	v_mfma_f32_16x16x32_bf16 v[78:81], v[160:163], v[198:201], v[78:81]
	v_mfma_f32_16x16x32_bf16 v[74:77], v[168:171], v[198:201], v[74:77]
	v_mfma_f32_16x16x32_bf16 v[70:73], v[160:163], v[214:217], v[70:73]
	v_mfma_f32_16x16x32_bf16 v[66:69], v[168:171], v[214:217], v[66:69]
	v_mfma_f32_16x16x32_bf16 v[110:113], v[164:167], v[180:183], v[110:113]
	v_mfma_f32_16x16x32_bf16 v[106:109], v[172:175], v[180:183], v[106:109]
	v_mfma_f32_16x16x32_bf16 v[94:97], v[164:167], v[188:191], v[94:97]
	v_mfma_f32_16x16x32_bf16 v[90:93], v[172:175], v[188:191], v[90:93]
	v_mfma_f32_16x16x32_bf16 v[78:81], v[164:167], v[210:213], v[78:81]
	v_mfma_f32_16x16x32_bf16 v[74:77], v[172:175], v[210:213], v[74:77]
	v_mfma_f32_16x16x32_bf16 v[70:73], v[164:167], v[218:221], v[70:73]
	v_mfma_f32_16x16x32_bf16 v[66:69], v[172:175], v[218:221], v[66:69]
	s_setprio 0
	s_barrier
	s_add_i32 s60, s48, s41
	v_lshl_add_u64 v[192:193], s[36:37], 0, v[132:133]
	s_mov_b32 m0, s60
	ds_read_b128 v[176:179], v142 offset:16384
	ds_read_b128 v[180:183], v142 offset:17408
	ds_read_b128 v[184:187], v142 offset:18432
	ds_read_b128 v[188:191], v142 offset:19456
	ds_read_b128 v[198:201], v142 offset:20480
	ds_read_b128 v[210:213], v142 offset:21504
	ds_read_b128 v[214:217], v142 offset:22528
	ds_read_b128 v[218:221], v142 offset:23552
	global_load_lds_dwordx4 v[192:193], off sc0
	s_add_i32 m0, s60, 0x2000
	s_add_u32 s60, s36, 0x20000
	v_lshl_add_u64 v[202:203], s[36:37], 0, v[134:135]
	s_addc_u32 s61, s37, 0
	s_add_i32 s62, s49, s41
	global_load_lds_dwordx4 v[202:203], off sc0
	v_lshl_add_u64 v[206:207], s[60:61], 0, v[132:133]
	s_mov_b32 m0, s62
	v_lshl_add_u64 v[222:223], s[38:39], 0, v[136:137]
	global_load_lds_dwordx4 v[206:207], off sc0
	v_lshl_add_u64 v[206:207], s[60:61], 0, v[134:135]
	s_add_i32 m0, s62, 0x2000
	s_nop 0
	global_load_lds_dwordx4 v[206:207], off sc0
	v_lshl_add_u64 v[206:207], s[38:39], 0, v[130:131]
	s_mov_b32 m0, s27
	s_nop 0
	global_load_lds_dwordx4 v[206:207], off sc0
	s_mov_b32 m0, s42
	s_nop 0
	global_load_lds_dwordx4 v[222:223], off sc0
	s_waitcnt vmcnt(8)
	s_waitcnt lgkmcnt(0)
	s_barrier
	s_setprio 1
	s_waitcnt lgkmcnt(0)
	v_mfma_f32_16x16x32_bf16 v[62:65], v[144:147], v[176:179], v[62:65]
	v_mfma_f32_16x16x32_bf16 v[58:61], v[152:155], v[176:179], v[58:61]
	v_mfma_f32_16x16x32_bf16 v[54:57], v[144:147], v[184:187], v[54:57]
	v_mfma_f32_16x16x32_bf16 v[50:53], v[152:155], v[184:187], v[50:53]
	v_mfma_f32_16x16x32_bf16 v[38:41], v[144:147], v[198:201], v[38:41]
	v_mfma_f32_16x16x32_bf16 v[34:37], v[152:155], v[198:201], v[34:37]
	v_mfma_f32_16x16x32_bf16 v[22:25], v[144:147], v[214:217], v[22:25]
	v_mfma_f32_16x16x32_bf16 v[18:21], v[152:155], v[214:217], v[18:21]
	v_mfma_f32_16x16x32_bf16 v[62:65], v[148:151], v[180:183], v[62:65]
	v_mfma_f32_16x16x32_bf16 v[58:61], v[156:159], v[180:183], v[58:61]
	v_mfma_f32_16x16x32_bf16 v[54:57], v[148:151], v[188:191], v[54:57]
	v_mfma_f32_16x16x32_bf16 v[50:53], v[156:159], v[188:191], v[50:53]
	v_mfma_f32_16x16x32_bf16 v[38:41], v[148:151], v[210:213], v[38:41]
	v_mfma_f32_16x16x32_bf16 v[34:37], v[156:159], v[210:213], v[34:37]
	v_mfma_f32_16x16x32_bf16 v[22:25], v[148:151], v[218:221], v[22:25]
	v_mfma_f32_16x16x32_bf16 v[18:21], v[156:159], v[218:221], v[18:21]
	s_setprio 0
	s_setprio 1
	v_mfma_f32_16x16x32_bf16 v[46:49], v[160:163], v[176:179], v[46:49]
	v_mfma_f32_16x16x32_bf16 v[42:45], v[168:171], v[176:179], v[42:45]
	v_mfma_f32_16x16x32_bf16 v[30:33], v[160:163], v[184:187], v[30:33]
	v_mfma_f32_16x16x32_bf16 v[26:29], v[168:171], v[184:187], v[26:29]
	v_mfma_f32_16x16x32_bf16 v[14:17], v[160:163], v[198:201], v[14:17]
	v_mfma_f32_16x16x32_bf16 v[10:13], v[168:171], v[198:201], v[10:13]
	v_mfma_f32_16x16x32_bf16 v[6:9], v[160:163], v[214:217], v[6:9]
	v_mfma_f32_16x16x32_bf16 v[2:5], v[168:171], v[214:217], v[2:5]
	v_mfma_f32_16x16x32_bf16 v[46:49], v[164:167], v[180:183], v[46:49]
	v_mfma_f32_16x16x32_bf16 v[42:45], v[172:175], v[180:183], v[42:45]
	v_mfma_f32_16x16x32_bf16 v[30:33], v[164:167], v[188:191], v[30:33]
	v_mfma_f32_16x16x32_bf16 v[26:29], v[172:175], v[188:191], v[26:29]
	v_mfma_f32_16x16x32_bf16 v[14:17], v[164:167], v[210:213], v[14:17]
	v_mfma_f32_16x16x32_bf16 v[10:13], v[172:175], v[210:213], v[10:13]
	v_mfma_f32_16x16x32_bf16 v[6:9], v[164:167], v[218:221], v[6:9]
	v_mfma_f32_16x16x32_bf16 v[2:5], v[172:175], v[218:221], v[2:5]
	s_setprio 0
	s_barrier
	s_add_i32 s60, 0, 0x18000
	v_add_u32_e32 v143, s60, v139
	s_add_i32 s61, 0, 0x1c000
	ds_read_b128 v[144:147], v143
	ds_read_b128 v[148:151], v143 offset:1024
	ds_read_b128 v[152:155], v143 offset:2048
	ds_read_b128 v[156:159], v143 offset:3072
	v_add_u32_e32 v143, s61, v139
	ds_read_b128 v[160:163], v143
	ds_read_b128 v[164:167], v143 offset:1024
	ds_read_b128 v[168:171], v143 offset:2048
	ds_read_b128 v[172:175], v143 offset:3072
	s_add_u32 s38, s38, 0x20000
	s_addc_u32 s39, s39, 0
	s_mov_b32 m0, s43
	v_lshl_add_u64 v[224:225], s[38:39], 0, v[130:131]
	ds_read_b128 v[176:179], v142 offset:32768
	ds_read_b128 v[180:183], v142 offset:33792
	ds_read_b128 v[184:187], v142 offset:34816
	ds_read_b128 v[188:191], v142 offset:35840
	ds_read_b128 v[198:201], v142 offset:36864
	ds_read_b128 v[210:213], v142 offset:37888
	ds_read_b128 v[214:217], v142 offset:38912
	ds_read_b128 v[218:221], v142 offset:39936
	global_load_lds_dwordx4 v[224:225], off sc0
	v_lshl_add_u64 v[224:225], s[38:39], 0, v[136:137]
	s_mov_b32 m0, s44
	s_nop 0
	global_load_lds_dwordx4 v[224:225], off sc0
	s_waitcnt vmcnt(8)
	s_waitcnt lgkmcnt(0)
	s_barrier
	s_setprio 1
	s_waitcnt lgkmcnt(0)
	v_mfma_f32_16x16x32_bf16 v[126:129], v[144:147], v[176:179], v[126:129]
	v_mfma_f32_16x16x32_bf16 v[122:125], v[152:155], v[176:179], v[122:125]
	v_mfma_f32_16x16x32_bf16 v[118:121], v[144:147], v[184:187], v[118:121]
	v_mfma_f32_16x16x32_bf16 v[114:117], v[152:155], v[184:187], v[114:117]
	v_mfma_f32_16x16x32_bf16 v[102:105], v[144:147], v[198:201], v[102:105]
	v_mfma_f32_16x16x32_bf16 v[98:101], v[152:155], v[198:201], v[98:101]
	v_mfma_f32_16x16x32_bf16 v[86:89], v[144:147], v[214:217], v[86:89]
	v_mfma_f32_16x16x32_bf16 v[82:85], v[152:155], v[214:217], v[82:85]
	v_mfma_f32_16x16x32_bf16 v[126:129], v[148:151], v[180:183], v[126:129]
	v_mfma_f32_16x16x32_bf16 v[122:125], v[156:159], v[180:183], v[122:125]
	v_mfma_f32_16x16x32_bf16 v[118:121], v[148:151], v[188:191], v[118:121]
	v_mfma_f32_16x16x32_bf16 v[114:117], v[156:159], v[188:191], v[114:117]
	v_mfma_f32_16x16x32_bf16 v[102:105], v[148:151], v[210:213], v[102:105]
	v_mfma_f32_16x16x32_bf16 v[98:101], v[156:159], v[210:213], v[98:101]
	v_mfma_f32_16x16x32_bf16 v[86:89], v[148:151], v[218:221], v[86:89]
	v_mfma_f32_16x16x32_bf16 v[82:85], v[156:159], v[218:221], v[82:85]
	s_setprio 0
	s_setprio 1
	v_mfma_f32_16x16x32_bf16 v[110:113], v[160:163], v[176:179], v[110:113]
	v_mfma_f32_16x16x32_bf16 v[106:109], v[168:171], v[176:179], v[106:109]
	v_mfma_f32_16x16x32_bf16 v[94:97], v[160:163], v[184:187], v[94:97]
	v_mfma_f32_16x16x32_bf16 v[90:93], v[168:171], v[184:187], v[90:93]
	v_mfma_f32_16x16x32_bf16 v[78:81], v[160:163], v[198:201], v[78:81]
	v_mfma_f32_16x16x32_bf16 v[74:77], v[168:171], v[198:201], v[74:77]
	v_mfma_f32_16x16x32_bf16 v[70:73], v[160:163], v[214:217], v[70:73]
	v_mfma_f32_16x16x32_bf16 v[66:69], v[168:171], v[214:217], v[66:69]
	v_mfma_f32_16x16x32_bf16 v[110:113], v[164:167], v[180:183], v[110:113]
	v_mfma_f32_16x16x32_bf16 v[106:109], v[172:175], v[180:183], v[106:109]
	v_mfma_f32_16x16x32_bf16 v[94:97], v[164:167], v[188:191], v[94:97]
	v_mfma_f32_16x16x32_bf16 v[90:93], v[172:175], v[188:191], v[90:93]
	v_mfma_f32_16x16x32_bf16 v[78:81], v[164:167], v[210:213], v[78:81]
	v_mfma_f32_16x16x32_bf16 v[74:77], v[172:175], v[210:213], v[74:77]
	v_mfma_f32_16x16x32_bf16 v[70:73], v[164:167], v[218:221], v[70:73]
	v_mfma_f32_16x16x32_bf16 v[66:69], v[172:175], v[218:221], v[66:69]
	s_setprio 0
	s_barrier
	s_add_i32 s38, s60, s41
	v_lshl_add_u64 v[192:193], v[192:193], 0, s[6:7]
	s_mov_b32 m0, s38
	ds_read_b128 v[176:179], v142 offset:49152
	ds_read_b128 v[180:183], v142 offset:50176
	ds_read_b128 v[184:187], v142 offset:51200
	ds_read_b128 v[188:191], v142 offset:52224
	ds_read_b128 v[198:201], v142 offset:53248
	ds_read_b128 v[210:213], v142 offset:54272
	ds_read_b128 v[214:217], v142 offset:55296
	ds_read_b128 v[218:221], v142 offset:56320
	global_load_lds_dwordx4 v[192:193], off sc0
	s_add_i32 m0, s38, 0x2000
	s_add_u32 s36, s36, 0x20080
	v_lshl_add_u64 v[192:193], v[202:203], 0, s[6:7]
	s_addc_u32 s37, s37, 0
	s_add_i32 s38, s61, s41
	global_load_lds_dwordx4 v[192:193], off sc0
	v_lshl_add_u64 v[192:193], s[36:37], 0, v[132:133]
	s_mov_b32 m0, s38
	s_nop 0
	global_load_lds_dwordx4 v[192:193], off sc0
	v_lshl_add_u64 v[192:193], s[36:37], 0, v[134:135]
	s_add_i32 m0, s38, 0x2000
	s_nop 0
	global_load_lds_dwordx4 v[192:193], off sc0
	v_lshl_add_u64 v[192:193], v[206:207], 0, s[6:7]
	s_mov_b32 m0, s46
	s_nop 0
	global_load_lds_dwordx4 v[192:193], off sc0
	v_lshl_add_u64 v[192:193], v[222:223], 0, s[6:7]
	s_mov_b32 m0, s47
	s_nop 0
	global_load_lds_dwordx4 v[192:193], off sc0
	s_waitcnt vmcnt(8)
	s_waitcnt lgkmcnt(0)
	s_barrier
	s_setprio 1
	s_waitcnt lgkmcnt(0)
	v_mfma_f32_16x16x32_bf16 v[62:65], v[144:147], v[176:179], v[62:65]
	v_mfma_f32_16x16x32_bf16 v[58:61], v[152:155], v[176:179], v[58:61]
	v_mfma_f32_16x16x32_bf16 v[54:57], v[144:147], v[184:187], v[54:57]
	v_mfma_f32_16x16x32_bf16 v[50:53], v[152:155], v[184:187], v[50:53]
	v_mfma_f32_16x16x32_bf16 v[38:41], v[144:147], v[198:201], v[38:41]
	v_mfma_f32_16x16x32_bf16 v[34:37], v[152:155], v[198:201], v[34:37]
	v_mfma_f32_16x16x32_bf16 v[22:25], v[144:147], v[214:217], v[22:25]
	v_mfma_f32_16x16x32_bf16 v[18:21], v[152:155], v[214:217], v[18:21]
	v_mfma_f32_16x16x32_bf16 v[62:65], v[148:151], v[180:183], v[62:65]
	v_mfma_f32_16x16x32_bf16 v[58:61], v[156:159], v[180:183], v[58:61]
	v_mfma_f32_16x16x32_bf16 v[54:57], v[148:151], v[188:191], v[54:57]
	v_mfma_f32_16x16x32_bf16 v[50:53], v[156:159], v[188:191], v[50:53]
	v_mfma_f32_16x16x32_bf16 v[38:41], v[148:151], v[210:213], v[38:41]
	v_mfma_f32_16x16x32_bf16 v[34:37], v[156:159], v[210:213], v[34:37]
	v_mfma_f32_16x16x32_bf16 v[22:25], v[148:151], v[218:221], v[22:25]
	v_mfma_f32_16x16x32_bf16 v[18:21], v[156:159], v[218:221], v[18:21]
	s_setprio 0
	s_setprio 1
	v_mfma_f32_16x16x32_bf16 v[46:49], v[160:163], v[176:179], v[46:49]
	v_mfma_f32_16x16x32_bf16 v[42:45], v[168:171], v[176:179], v[42:45]
	v_mfma_f32_16x16x32_bf16 v[30:33], v[160:163], v[184:187], v[30:33]
	v_mfma_f32_16x16x32_bf16 v[26:29], v[168:171], v[184:187], v[26:29]
	v_mfma_f32_16x16x32_bf16 v[14:17], v[160:163], v[198:201], v[14:17]
	v_mfma_f32_16x16x32_bf16 v[10:13], v[168:171], v[198:201], v[10:13]
	v_mfma_f32_16x16x32_bf16 v[6:9], v[160:163], v[214:217], v[6:9]
	v_mfma_f32_16x16x32_bf16 v[2:5], v[168:171], v[214:217], v[2:5]
	v_mfma_f32_16x16x32_bf16 v[46:49], v[164:167], v[180:183], v[46:49]
	v_mfma_f32_16x16x32_bf16 v[42:45], v[172:175], v[180:183], v[42:45]
	v_mfma_f32_16x16x32_bf16 v[30:33], v[164:167], v[188:191], v[30:33]
	v_mfma_f32_16x16x32_bf16 v[26:29], v[172:175], v[188:191], v[26:29]
	v_mfma_f32_16x16x32_bf16 v[14:17], v[164:167], v[210:213], v[14:17]
	v_mfma_f32_16x16x32_bf16 v[10:13], v[172:175], v[210:213], v[10:13]
	v_mfma_f32_16x16x32_bf16 v[6:9], v[164:167], v[218:221], v[6:9]
	v_mfma_f32_16x16x32_bf16 v[2:5], v[172:175], v[218:221], v[2:5]
	s_setprio 0
	s_barrier
	s_add_i32 s59, s59, 2
	s_add_u32 s34, s34, 0x100
	s_addc_u32 s35, s35, 0
	s_add_u32 s57, s57, 0x100
	s_addc_u32 s58, s58, 0
	s_cmp_gt_u32 s59, 5
	s_cbranch_scc0 .LBB0_714

.LBB0_1108:
	s_add_u32 s2, s82, 0x12100000
	s_addc_u32 s3, s83, 0
	s_ashr_i32 s10, s8, 31
	s_lshr_b32 s10, s10, 29
	s_add_i32 s10, s8, s10
	s_lshr_b32 s12, s14, 6
	s_ashr_i32 s11, s10, 3
	s_and_b32 s10, s10, -8
	s_lshr_b32 s7, s14, 8
	s_lshl_b32 s33, s12, 10
	s_sub_i32 s8, s8, s10
	s_cmp_lt_i32 s8, 0
	s_cselect_b32 s10, 49, 48
	s_mul_i32 s8, s10, s8
	s_add_i32 s8, s8, s11
	s_ashr_i32 s10, s8, 31
	s_lshr_b32 s10, s10, 26
	s_add_i32 s10, s8, s10
	s_ashr_i32 s11, s10, 6
	v_lshrrev_b32_e32 v3, 1, v0
	s_lshl_b32 s11, s11, 3
	v_and_b32_e32 v15, 24, v3
	v_lshrrev_b32_e32 v3, 5, v0
	s_sub_i32 s13, 48, s11
	v_lshlrev_b32_e32 v2, 4, v0
	v_and_b32_e32 v1, 32, v0
	v_and_b32_e32 v3, 4, v3
	v_bfe_u32 v4, v0, 2, 2
	s_min_i32 s13, s13, 8
	v_bfe_u32 v14, v0, 2, 4
	v_bitop3_b32 v12, v2, v1, 48 bitop3:0x6c
	v_and_b32_e32 v13, 64, v0
	v_or3_b32 v3, v3, v4, v15
	v_lshrrev_b32_e32 v4, 3, v0
	s_abs_i32 s15, s13
	v_or_b32_e32 v1, v12, v13
	v_and_or_b32 v5, v4, 48, v14
	v_and_or_b32 v4, v4, 32, v3
	v_or_b32_e32 v16, 0x2000, v2
	v_cvt_f32_u32_e32 v6, s15
	v_lshl_or_b32 v148, v4, 12, v1
	v_lshrrev_b32_e32 v4, 7, v16
	s_movk_i32 s9, 0x70
	v_lshl_or_b32 v146, v5, 12, v1
	v_and_or_b32 v5, v4, s9, v14
	s_movk_i32 s9, 0x60
	v_and_or_b32 v3, v4, s9, v3
	v_lshl_or_b32 v150, v5, 12, v1
	v_lshl_or_b32 v152, v3, 12, v1
	v_rcp_iflag_f32_e32 v1, v6
	s_sub_i32 s17, 0, s15
	s_andn2_b32 s10, s10, 63
	s_sub_i32 s8, s8, s10
	v_mul_f32_e32 v1, 0x4f7ffffe, v1
	v_cvt_u32_f32_e32 v1, v1
	s_abs_i32 s10, s8
	s_xor_b32 s9, s8, s13
	s_ashr_i32 s9, s9, 31
	v_readfirstlane_b32 s18, v1
	s_mul_i32 s17, s17, s18
	s_mul_hi_u32 s17, s18, s17
	s_add_i32 s18, s18, s17
	s_mul_hi_u32 s17, s10, s18
	s_mul_i32 s18, s17, s15
	s_sub_i32 s10, s10, s18
	s_add_i32 s18, s17, 1
	s_sub_i32 s19, s10, s15
	s_cmp_ge_u32 s10, s15
	s_cselect_b32 s17, s18, s17
	s_cselect_b32 s10, s19, s10
	s_add_i32 s18, s17, 1
	s_cmp_ge_u32 s10, s15
	s_cselect_b32 s10, s18, s17
	s_xor_b32 s10, s10, s9
	s_sub_i32 s28, s10, s9
	s_mul_i32 s9, s28, s13
	s_sub_i32 s8, s8, s9
	s_add_i32 s26, s11, s8
	s_ashr_i32 s27, s26, 31
	s_lshl_b64 s[8:9], s[26:27], 20
	v_readlane_b32 s10, v249, 54
	v_readlane_b32 s11, v249, 55
	s_add_u32 s10, s10, s8
	s_addc_u32 s11, s11, s9
	s_ashr_i32 s29, s28, 31
	s_lshl_b64 s[8:9], s[28:29], 20
	s_add_u32 s8, s2, s8
	s_addc_u32 s9, s3, s9
	s_add_u32 s36, s8, s0
	s_addc_u32 s37, s9, s1
	s_add_i32 s27, s33, 0
	s_add_i32 m0, s27, 0x10000
	v_mov_b32_e32 v149, 0
	global_load_lds_dwordx4 v148, s[36:37] sc0
	s_add_i32 m0, s27, 0x12000
	s_add_u32 s8, s36, 0x80000
	global_load_lds_dwordx4 v152, s[36:37] sc0
	s_addc_u32 s9, s37, 0
	s_add_i32 m0, s27, 0x14000
	v_mov_b32_e32 v153, v149
	global_load_lds_dwordx4 v148, s[8:9] sc0
	s_add_i32 m0, s27, 0x16000
	s_add_u32 s34, s10, s0
	s_addc_u32 s35, s11, s1
	s_add_i32 s29, s27, 0x2000
	global_load_lds_dwordx4 v152, s[8:9] sc0
	s_mov_b32 m0, s27
	s_add_u32 s0, s34, 0x80000
	global_load_lds_dwordx4 v146, s[34:35] sc0
	s_mov_b32 m0, s29
	s_addc_u32 s1, s35, 0
	s_add_i32 s42, s27, 0x4000
	global_load_lds_dwordx4 v150, s[34:35] sc0
	s_mov_b32 m0, s42
	s_add_i32 s43, s27, 0x6000
	global_load_lds_dwordx4 v146, s[0:1] sc0
	s_mov_b32 m0, s43
	v_mov_b32_e32 v147, v149
	global_load_lds_dwordx4 v150, s[0:1] sc0
	v_mov_b32_e32 v151, v149
	s_cmp_eq_u32 s7, 1
	s_movk_i32 s44, 0x2000
	s_mov_b32 s45, 0x10000
	v_lshl_add_u64 v[10:11], s[36:37], 0, v[148:149]
	v_lshl_add_u64 v[6:7], s[36:37], 0, v[152:153]
	s_mov_b32 s46, 0x12000
	s_mov_b32 s47, 0x14000
	s_mov_b32 s48, 0x16000
	v_lshl_add_u64 v[8:9], s[34:35], 0, v[146:147]
	v_lshl_add_u64 v[4:5], s[34:35], 0, v[150:151]
	s_movk_i32 s49, 0x4000
	s_cselect_b64 s[8:9], -1, 0
	s_cmp_lg_u32 s7, 1
	s_movk_i32 s50, 0x6000
	s_cbranch_scc1 .LBB0_1110
	s_barrier
.LBB0_1110:
	s_add_u32 s10, s82, 0x27100000
	s_addc_u32 s11, s83, 0
	s_add_u32 s51, s82, 0x20a000
	s_addc_u32 s52, s83, 0
	s_lshl_b32 s0, s12, 5
	s_mov_b64 s[12:13], 0x80
	s_and_b32 s17, s0, 0x60
	s_add_i32 m0, s27, 0x18000
	v_lshl_add_u64 v[10:11], v[10:11], 0, s[12:13]
	s_lshl_b32 s15, s7, 13
	s_lshl_b32 s18, s17, 7
	s_waitcnt vmcnt(2)
	s_barrier
	global_load_lds_dwordx4 v[10:11], off sc0
	v_lshl_add_u64 v[6:7], v[6:7], 0, s[12:13]
	s_add_i32 m0, s27, 0x1a000
	s_add_i32 s53, s27, 0x8000
	s_add_i32 s54, s27, 0xa000
	global_load_lds_dwordx4 v[6:7], off sc0
	v_lshl_add_u64 v[6:7], v[8:9], 0, s[12:13]
	s_mov_b32 m0, s53
	s_add_u32 s0, s36, 0x80080
	global_load_lds_dwordx4 v[6:7], off sc0
	v_lshl_add_u64 v[4:5], v[4:5], 0, s[12:13]
	s_mov_b32 m0, s54
	s_addc_u32 s1, s37, 0
	global_load_lds_dwordx4 v[4:5], off sc0
	s_add_i32 m0, s27, 0x1c000
	v_lshl_add_u64 v[4:5], s[0:1], 0, v[148:149]
	global_load_lds_dwordx4 v[4:5], off sc0
	v_lshl_add_u64 v[4:5], s[0:1], 0, v[152:153]
	s_add_i32 m0, s27, 0x1e000
	v_lshlrev_b32_e32 v3, 1, v15
	global_load_lds_dwordx4 v[4:5], off sc0
	v_lshl_or_b32 v4, v205, 6, v3
	v_and_b32_e32 v5, 32, v196
	v_bitop3_b32 v4, v4, s15, v5 bitop3:0xde
	s_movk_i32 s0, 0x3c0
	v_readlane_b32 s15, v249, 0
	v_and_or_b32 v3, v209, s0, v3
	s_ashr_i32 s0, s15, 31
	v_bitop3_b32 v168, s18, v3, v5 bitop3:0xf6
	s_lshr_b32 s0, s0, 25
	v_mov_b32_e32 v3, v149
	s_add_i32 s0, s15, s0
	v_lshl_add_u64 v[154:155], s[78:79], 0, v[2:3]
	v_lshlrev_b32_e32 v2, 9, v0
	s_and_b32 s1, s0, 0xffffff80
	v_and_b32_e32 v2, 0x30000, v2
	v_lshlrev_b32_e32 v3, 12, v14
	s_sub_i32 s60, s15, s1
	s_ashr_i32 s0, s0, 7
	v_or3_b32 v2, v12, v2, v3
	s_addk_i32 s60, 0x100
	s_lshl_b32 s61, s0, 4
	v_add_u32_e32 v156, v2, v13
	v_lshlrev_b32_e32 v2, 5, v16
	s_waitcnt vmcnt(6)
	s_cmpk_lt_u32 s14, 0x100
	v_and_b32_e32 v2, 0x70000, v2
	v_lshl_or_b32 v1, s7, 6, v205
	s_mov_b32 s7, 0
	s_cselect_b64 s[14:15], -1, 0
	s_lshr_b32 s0, s16, 2
	v_or3_b32 v2, v12, v2, v3
	s_add_i32 s63, 0, 0x10000
	s_add_i32 s64, 0, 0x14000
	s_mov_b32 s55, 0x18000
	s_mov_b32 s56, 0x1a000
	s_mov_b32 s57, 0x8000
	s_mov_b32 s58, 0xa000
	s_mov_b32 s59, 0x1c000
	s_xor_b32 s62, s0, 1
	v_or_b32_e32 v169, s17, v15
	v_mov_b32_e32 v157, v149
	v_add_u32_e32 v158, v2, v13
	v_mov_b32_e32 v159, v149
	s_mov_b64 s[30:31], -1
	v_add_u32_e32 v170, s63, v168
	v_add_u32_e32 v171, s64, v168
	v_add_u32_e32 v172, 0, v4
	s_mov_b32 s65, 0xc000
	s_mov_b32 s66, 0xe000
	s_mov_b32 s17, s7
	s_barrier
	s_branch .LBB0_1113

.Lpeel_8:
	ds_read_b128 v[130:133], v170
	ds_read_b128 v[134:137], v170 offset:1024
	ds_read_b128 v[138:141], v170 offset:2048
	ds_read_b128 v[142:145], v170 offset:3072
	ds_read_b128 v[160:163], v171
	ds_read_b128 v[164:167], v171 offset:1024
	ds_read_b128 v[174:177], v171 offset:2048
	ds_read_b128 v[178:181], v171 offset:3072
	s_add_i32 s31, s21, 2
	s_add_u32 s36, s34, 0xfff80080
	s_addc_u32 s37, s35, -1
	s_cmp_eq_u32 s30, s21
	s_cselect_b32 s39, s23, s37
	s_cselect_b32 s38, s22, s36
	s_cselect_b32 s37, s25, s19
	s_cselect_b32 s36, s24, s17
	v_lshl_add_u64 v[202:203], s[34:35], 0, v[156:157]
	s_add_i32 m0, s27, 0xc000
	ds_read_b128 v[182:185], v172
	ds_read_b128 v[186:189], v172 offset:1024
	ds_read_b128 v[190:193], v172 offset:2048
	ds_read_b128 v[198:201], v172 offset:3072
	ds_read_b128 v[210:213], v172 offset:4096
	ds_read_b128 v[214:217], v172 offset:5120
	ds_read_b128 v[218:221], v172 offset:6144
	ds_read_b128 v[222:225], v172 offset:7168
	global_load_lds_dwordx4 v[202:203], off sc0
	v_lshl_add_u64 v[202:203], s[34:35], 0, v[158:159]
	s_add_i32 m0, s27, 0xe000
	s_nop 0
	global_load_lds_dwordx4 v[202:203], off sc0
	s_waitcnt vmcnt(8)
	s_waitcnt lgkmcnt(0)
	s_barrier
	s_setprio 1
	s_waitcnt lgkmcnt(0)
	v_mfma_f32_16x16x32_bf16 v[126:129], v[130:133], v[182:185], 0
	v_mfma_f32_16x16x32_bf16 v[122:125], v[138:141], v[182:185], 0
	v_mfma_f32_16x16x32_bf16 v[118:121], v[130:133], v[190:193], 0
	v_mfma_f32_16x16x32_bf16 v[110:113], v[138:141], v[190:193], 0
	v_mfma_f32_16x16x32_bf16 v[94:97], v[130:133], v[210:213], 0
	v_mfma_f32_16x16x32_bf16 v[90:93], v[138:141], v[210:213], 0
	v_mfma_f32_16x16x32_bf16 v[78:81], v[130:133], v[218:221], 0
	v_mfma_f32_16x16x32_bf16 v[74:77], v[138:141], v[218:221], 0
	v_mfma_f32_16x16x32_bf16 v[126:129], v[134:137], v[186:189], v[126:129]
	v_mfma_f32_16x16x32_bf16 v[122:125], v[142:145], v[186:189], v[122:125]
	v_mfma_f32_16x16x32_bf16 v[118:121], v[134:137], v[198:201], v[118:121]
	v_mfma_f32_16x16x32_bf16 v[110:113], v[142:145], v[198:201], v[110:113]
	v_mfma_f32_16x16x32_bf16 v[94:97], v[134:137], v[214:217], v[94:97]
	v_mfma_f32_16x16x32_bf16 v[90:93], v[142:145], v[214:217], v[90:93]
	v_mfma_f32_16x16x32_bf16 v[78:81], v[134:137], v[222:225], v[78:81]
	v_mfma_f32_16x16x32_bf16 v[74:77], v[142:145], v[222:225], v[74:77]
	s_setprio 0
	s_setprio 1
	v_mfma_f32_16x16x32_bf16 v[114:117], v[160:163], v[182:185], 0
	v_mfma_f32_16x16x32_bf16 v[106:109], v[174:177], v[182:185], 0
	v_mfma_f32_16x16x32_bf16 v[102:105], v[160:163], v[190:193], 0
	v_mfma_f32_16x16x32_bf16 v[98:101], v[174:177], v[190:193], 0
	v_mfma_f32_16x16x32_bf16 v[86:89], v[160:163], v[210:213], 0
	v_mfma_f32_16x16x32_bf16 v[82:85], v[174:177], v[210:213], 0
	v_mfma_f32_16x16x32_bf16 v[70:73], v[160:163], v[218:221], 0
	v_mfma_f32_16x16x32_bf16 v[66:69], v[174:177], v[218:221], 0
	v_mfma_f32_16x16x32_bf16 v[114:117], v[164:167], v[186:189], v[114:117]
	v_mfma_f32_16x16x32_bf16 v[106:109], v[178:181], v[186:189], v[106:109]
	v_mfma_f32_16x16x32_bf16 v[102:105], v[164:167], v[198:201], v[102:105]
	v_mfma_f32_16x16x32_bf16 v[98:101], v[178:181], v[198:201], v[98:101]
	v_mfma_f32_16x16x32_bf16 v[86:89], v[164:167], v[214:217], v[86:89]
	v_mfma_f32_16x16x32_bf16 v[82:85], v[178:181], v[214:217], v[82:85]
	v_mfma_f32_16x16x32_bf16 v[70:73], v[164:167], v[222:225], v[70:73]
	v_mfma_f32_16x16x32_bf16 v[66:69], v[178:181], v[222:225], v[66:69]
	s_setprio 0
	s_barrier
	s_add_i32 s21, s63, s33
	v_lshl_add_u64 v[202:203], s[36:37], 0, v[148:149]
	s_mov_b32 m0, s21
	ds_read_b128 v[182:185], v172 offset:16384
	ds_read_b128 v[186:189], v172 offset:17408
	ds_read_b128 v[190:193], v172 offset:18432
	ds_read_b128 v[198:201], v172 offset:19456
	ds_read_b128 v[210:213], v172 offset:20480
	ds_read_b128 v[214:217], v172 offset:21504
	ds_read_b128 v[218:221], v172 offset:22528
	ds_read_b128 v[222:225], v172 offset:23552
	global_load_lds_dwordx4 v[202:203], off sc0
	s_add_i32 m0, s21, 0x2000
	s_add_u32 s40, s36, 0x80000
	v_lshl_add_u64 v[206:207], s[36:37], 0, v[152:153]
	s_addc_u32 s41, s37, 0
	s_add_i32 s21, s64, s33
	global_load_lds_dwordx4 v[206:207], off sc0
	v_lshl_add_u64 v[226:227], s[40:41], 0, v[148:149]
	s_mov_b32 m0, s21
	v_lshl_add_u64 v[228:229], s[38:39], 0, v[150:151]
	global_load_lds_dwordx4 v[226:227], off sc0
	v_lshl_add_u64 v[226:227], s[40:41], 0, v[152:153]
	s_add_i32 m0, s21, 0x2000
	s_nop 0
	global_load_lds_dwordx4 v[226:227], off sc0
	v_lshl_add_u64 v[226:227], s[38:39], 0, v[146:147]
	s_mov_b32 m0, s27
	s_nop 0
	global_load_lds_dwordx4 v[226:227], off sc0
	s_mov_b32 m0, s29
	s_nop 0
	global_load_lds_dwordx4 v[228:229], off sc0
	s_waitcnt vmcnt(8)
	s_waitcnt lgkmcnt(0)
	s_barrier
	s_setprio 1
	s_waitcnt lgkmcnt(0)
	v_mfma_f32_16x16x32_bf16 v[62:65], v[130:133], v[182:185], 0
	v_mfma_f32_16x16x32_bf16 v[58:61], v[138:141], v[182:185], 0
	v_mfma_f32_16x16x32_bf16 v[46:49], v[130:133], v[190:193], 0
	v_mfma_f32_16x16x32_bf16 v[42:45], v[138:141], v[190:193], 0
	v_mfma_f32_16x16x32_bf16 v[30:33], v[130:133], v[210:213], 0
	v_mfma_f32_16x16x32_bf16 v[26:29], v[138:141], v[210:213], 0
	v_mfma_f32_16x16x32_bf16 v[14:17], v[130:133], v[218:221], 0
	v_mfma_f32_16x16x32_bf16 v[10:13], v[138:141], v[218:221], 0
	v_mfma_f32_16x16x32_bf16 v[62:65], v[134:137], v[186:189], v[62:65]
	v_mfma_f32_16x16x32_bf16 v[58:61], v[142:145], v[186:189], v[58:61]
	v_mfma_f32_16x16x32_bf16 v[46:49], v[134:137], v[198:201], v[46:49]
	v_mfma_f32_16x16x32_bf16 v[42:45], v[142:145], v[198:201], v[42:45]
	v_mfma_f32_16x16x32_bf16 v[30:33], v[134:137], v[214:217], v[30:33]
	v_mfma_f32_16x16x32_bf16 v[26:29], v[142:145], v[214:217], v[26:29]
	v_mfma_f32_16x16x32_bf16 v[14:17], v[134:137], v[222:225], v[14:17]
	v_mfma_f32_16x16x32_bf16 v[10:13], v[142:145], v[222:225], v[10:13]
	s_setprio 0
	s_setprio 1
	v_mfma_f32_16x16x32_bf16 v[54:57], v[160:163], v[182:185], 0
	v_mfma_f32_16x16x32_bf16 v[50:53], v[174:177], v[182:185], 0
	v_mfma_f32_16x16x32_bf16 v[38:41], v[160:163], v[190:193], 0
	v_mfma_f32_16x16x32_bf16 v[34:37], v[174:177], v[190:193], 0
	v_mfma_f32_16x16x32_bf16 v[22:25], v[160:163], v[210:213], 0
	v_mfma_f32_16x16x32_bf16 v[18:21], v[174:177], v[210:213], 0
	v_mfma_f32_16x16x32_bf16 v[6:9], v[160:163], v[218:221], 0
	v_mfma_f32_16x16x32_bf16 v[2:5], v[174:177], v[218:221], 0
	v_mfma_f32_16x16x32_bf16 v[54:57], v[164:167], v[186:189], v[54:57]
	v_mfma_f32_16x16x32_bf16 v[50:53], v[178:181], v[186:189], v[50:53]
	v_mfma_f32_16x16x32_bf16 v[38:41], v[164:167], v[198:201], v[38:41]
	v_mfma_f32_16x16x32_bf16 v[34:37], v[178:181], v[198:201], v[34:37]
	v_mfma_f32_16x16x32_bf16 v[22:25], v[164:167], v[214:217], v[22:25]
	v_mfma_f32_16x16x32_bf16 v[18:21], v[178:181], v[214:217], v[18:21]
	v_mfma_f32_16x16x32_bf16 v[6:9], v[164:167], v[222:225], v[6:9]
	v_mfma_f32_16x16x32_bf16 v[2:5], v[178:181], v[222:225], v[2:5]
	s_setprio 0
	s_barrier
	s_add_i32 s21, 0, 0x18000
	s_add_i32 s40, 0, 0x1c000
	v_add_u32_e32 v142, s21, v168
	v_add_u32_e32 v173, s40, v168
	ds_read_b128 v[130:133], v142
	ds_read_b128 v[134:137], v142 offset:1024
	ds_read_b128 v[138:141], v142 offset:2048
	ds_read_b128 v[142:145], v142 offset:3072
	ds_read_b128 v[160:163], v173
	ds_read_b128 v[164:167], v173 offset:1024
	ds_read_b128 v[174:177], v173 offset:2048
	ds_read_b128 v[178:181], v173 offset:3072
	s_add_u32 s38, s38, 0x80000
	s_addc_u32 s39, s39, 0
	s_mov_b32 m0, s42
	v_lshl_add_u64 v[230:231], s[38:39], 0, v[146:147]
	ds_read_b128 v[182:185], v172 offset:32768
	ds_read_b128 v[186:189], v172 offset:33792
	ds_read_b128 v[190:193], v172 offset:34816
	ds_read_b128 v[198:201], v172 offset:35840
	ds_read_b128 v[210:213], v172 offset:36864
	ds_read_b128 v[214:217], v172 offset:37888
	ds_read_b128 v[218:221], v172 offset:38912
	ds_read_b128 v[222:225], v172 offset:39936
	global_load_lds_dwordx4 v[230:231], off sc0
	v_lshl_add_u64 v[230:231], s[38:39], 0, v[150:151]
	s_mov_b32 m0, s43
	s_nop 0
	global_load_lds_dwordx4 v[230:231], off sc0
	s_waitcnt vmcnt(8)
	s_waitcnt lgkmcnt(0)
	s_barrier
	s_setprio 1
	s_waitcnt lgkmcnt(0)
	v_mfma_f32_16x16x32_bf16 v[126:129], v[130:133], v[182:185], v[126:129]
	v_mfma_f32_16x16x32_bf16 v[122:125], v[138:141], v[182:185], v[122:125]
	v_mfma_f32_16x16x32_bf16 v[118:121], v[130:133], v[190:193], v[118:121]
	v_mfma_f32_16x16x32_bf16 v[110:113], v[138:141], v[190:193], v[110:113]
	v_mfma_f32_16x16x32_bf16 v[94:97], v[130:133], v[210:213], v[94:97]
	v_mfma_f32_16x16x32_bf16 v[90:93], v[138:141], v[210:213], v[90:93]
	v_mfma_f32_16x16x32_bf16 v[78:81], v[130:133], v[218:221], v[78:81]
	v_mfma_f32_16x16x32_bf16 v[74:77], v[138:141], v[218:221], v[74:77]
	v_mfma_f32_16x16x32_bf16 v[126:129], v[134:137], v[186:189], v[126:129]
	v_mfma_f32_16x16x32_bf16 v[122:125], v[142:145], v[186:189], v[122:125]
	v_mfma_f32_16x16x32_bf16 v[118:121], v[134:137], v[198:201], v[118:121]
	v_mfma_f32_16x16x32_bf16 v[110:113], v[142:145], v[198:201], v[110:113]
	v_mfma_f32_16x16x32_bf16 v[94:97], v[134:137], v[214:217], v[94:97]
	v_mfma_f32_16x16x32_bf16 v[90:93], v[142:145], v[214:217], v[90:93]
	v_mfma_f32_16x16x32_bf16 v[78:81], v[134:137], v[222:225], v[78:81]
	v_mfma_f32_16x16x32_bf16 v[74:77], v[142:145], v[222:225], v[74:77]
	s_setprio 0
	s_setprio 1
	v_mfma_f32_16x16x32_bf16 v[114:117], v[160:163], v[182:185], v[114:117]
	v_mfma_f32_16x16x32_bf16 v[106:109], v[174:177], v[182:185], v[106:109]
	v_mfma_f32_16x16x32_bf16 v[102:105], v[160:163], v[190:193], v[102:105]
	v_mfma_f32_16x16x32_bf16 v[98:101], v[174:177], v[190:193], v[98:101]
	v_mfma_f32_16x16x32_bf16 v[86:89], v[160:163], v[210:213], v[86:89]
	v_mfma_f32_16x16x32_bf16 v[82:85], v[174:177], v[210:213], v[82:85]
	v_mfma_f32_16x16x32_bf16 v[70:73], v[160:163], v[218:221], v[70:73]
	v_mfma_f32_16x16x32_bf16 v[66:69], v[174:177], v[218:221], v[66:69]
	v_mfma_f32_16x16x32_bf16 v[114:117], v[164:167], v[186:189], v[114:117]
	v_mfma_f32_16x16x32_bf16 v[106:109], v[178:181], v[186:189], v[106:109]
	v_mfma_f32_16x16x32_bf16 v[102:105], v[164:167], v[198:201], v[102:105]
	v_mfma_f32_16x16x32_bf16 v[98:101], v[178:181], v[198:201], v[98:101]
	v_mfma_f32_16x16x32_bf16 v[86:89], v[164:167], v[214:217], v[86:89]
	v_mfma_f32_16x16x32_bf16 v[82:85], v[178:181], v[214:217], v[82:85]
	v_mfma_f32_16x16x32_bf16 v[70:73], v[164:167], v[222:225], v[70:73]
	v_mfma_f32_16x16x32_bf16 v[66:69], v[178:181], v[222:225], v[66:69]
	s_setprio 0
	s_barrier
	s_add_i32 s21, s21, s33
	v_lshl_add_u64 v[202:203], v[202:203], 0, s[12:13]
	s_mov_b32 m0, s21
	ds_read_b128 v[182:185], v172 offset:49152
	ds_read_b128 v[186:189], v172 offset:50176
	ds_read_b128 v[190:193], v172 offset:51200
	ds_read_b128 v[198:201], v172 offset:52224
	ds_read_b128 v[210:213], v172 offset:53248
	ds_read_b128 v[214:217], v172 offset:54272
	ds_read_b128 v[218:221], v172 offset:55296
	ds_read_b128 v[222:225], v172 offset:56320
	global_load_lds_dwordx4 v[202:203], off sc0
	s_add_i32 m0, s21, 0x2000
	s_add_u32 s36, s36, 0x80080
	v_lshl_add_u64 v[202:203], v[206:207], 0, s[12:13]
	s_addc_u32 s37, s37, 0
	s_add_i32 s21, s40, s33
	global_load_lds_dwordx4 v[202:203], off sc0
	v_lshl_add_u64 v[202:203], s[36:37], 0, v[148:149]
	s_mov_b32 m0, s21
	s_nop 0
	global_load_lds_dwordx4 v[202:203], off sc0
	v_lshl_add_u64 v[202:203], s[36:37], 0, v[152:153]
	s_add_i32 m0, s21, 0x2000
	s_nop 0
	global_load_lds_dwordx4 v[202:203], off sc0
	v_lshl_add_u64 v[202:203], v[226:227], 0, s[12:13]
	s_mov_b32 m0, s53
	s_nop 0
	global_load_lds_dwordx4 v[202:203], off sc0
	v_lshl_add_u64 v[202:203], v[228:229], 0, s[12:13]
	s_mov_b32 m0, s54
	s_nop 0
	global_load_lds_dwordx4 v[202:203], off sc0
	s_waitcnt vmcnt(8)
	s_waitcnt lgkmcnt(0)
	s_barrier
	s_setprio 1
	s_waitcnt lgkmcnt(0)
	v_mfma_f32_16x16x32_bf16 v[62:65], v[130:133], v[182:185], v[62:65]
	v_mfma_f32_16x16x32_bf16 v[58:61], v[138:141], v[182:185], v[58:61]
	v_mfma_f32_16x16x32_bf16 v[46:49], v[130:133], v[190:193], v[46:49]
	v_mfma_f32_16x16x32_bf16 v[42:45], v[138:141], v[190:193], v[42:45]
	v_mfma_f32_16x16x32_bf16 v[30:33], v[130:133], v[210:213], v[30:33]
	v_mfma_f32_16x16x32_bf16 v[26:29], v[138:141], v[210:213], v[26:29]
	v_mfma_f32_16x16x32_bf16 v[14:17], v[130:133], v[218:221], v[14:17]
	v_mfma_f32_16x16x32_bf16 v[10:13], v[138:141], v[218:221], v[10:13]
	v_mfma_f32_16x16x32_bf16 v[62:65], v[134:137], v[186:189], v[62:65]
	v_mfma_f32_16x16x32_bf16 v[58:61], v[142:145], v[186:189], v[58:61]
	v_mfma_f32_16x16x32_bf16 v[46:49], v[134:137], v[198:201], v[46:49]
	v_mfma_f32_16x16x32_bf16 v[42:45], v[142:145], v[198:201], v[42:45]
	v_mfma_f32_16x16x32_bf16 v[30:33], v[134:137], v[214:217], v[30:33]
	v_mfma_f32_16x16x32_bf16 v[26:29], v[142:145], v[214:217], v[26:29]
	v_mfma_f32_16x16x32_bf16 v[14:17], v[134:137], v[222:225], v[14:17]
	v_mfma_f32_16x16x32_bf16 v[10:13], v[142:145], v[222:225], v[10:13]
	s_setprio 0
	s_setprio 1
	v_mfma_f32_16x16x32_bf16 v[54:57], v[160:163], v[182:185], v[54:57]
	v_mfma_f32_16x16x32_bf16 v[50:53], v[174:177], v[182:185], v[50:53]
	v_mfma_f32_16x16x32_bf16 v[38:41], v[160:163], v[190:193], v[38:41]
	v_mfma_f32_16x16x32_bf16 v[34:37], v[174:177], v[190:193], v[34:37]
	v_mfma_f32_16x16x32_bf16 v[22:25], v[160:163], v[210:213], v[22:25]
	v_mfma_f32_16x16x32_bf16 v[18:21], v[174:177], v[210:213], v[18:21]
	v_mfma_f32_16x16x32_bf16 v[6:9], v[160:163], v[218:221], v[6:9]
	v_mfma_f32_16x16x32_bf16 v[2:5], v[174:177], v[218:221], v[2:5]
	v_mfma_f32_16x16x32_bf16 v[54:57], v[164:167], v[186:189], v[54:57]
	v_mfma_f32_16x16x32_bf16 v[50:53], v[178:181], v[186:189], v[50:53]
	v_mfma_f32_16x16x32_bf16 v[38:41], v[164:167], v[198:201], v[38:41]
	v_mfma_f32_16x16x32_bf16 v[34:37], v[178:181], v[198:201], v[34:37]
	v_mfma_f32_16x16x32_bf16 v[22:25], v[164:167], v[214:217], v[22:25]
	v_mfma_f32_16x16x32_bf16 v[18:21], v[178:181], v[214:217], v[18:21]
	v_mfma_f32_16x16x32_bf16 v[6:9], v[164:167], v[222:225], v[6:9]
	v_mfma_f32_16x16x32_bf16 v[2:5], v[178:181], v[222:225], v[2:5]
	s_setprio 0
	s_barrier
	s_add_u32 s34, s34, 0x100
	s_addc_u32 s35, s35, 0
	s_add_u32 s17, s17, 0x100
	s_addc_u32 s19, s19, 0
	s_cmp_ge_i32 s31, s69
	s_mov_b32 s21, s31
	s_cbranch_scc0 .LBB0_1122
	s_branch .Lpeeldone_8
.LBB0_1122:
	ds_read_b128 v[130:133], v170
	ds_read_b128 v[134:137], v170 offset:1024
	ds_read_b128 v[138:141], v170 offset:2048
	ds_read_b128 v[142:145], v170 offset:3072
	ds_read_b128 v[160:163], v171
	ds_read_b128 v[164:167], v171 offset:1024
	ds_read_b128 v[174:177], v171 offset:2048
	ds_read_b128 v[178:181], v171 offset:3072
	s_add_i32 s31, s21, 2
	s_add_u32 s36, s34, 0xfff80080
	s_addc_u32 s37, s35, -1
	s_cmp_eq_u32 s30, s21
	s_cselect_b32 s39, s23, s37
	s_cselect_b32 s38, s22, s36
	s_cselect_b32 s37, s25, s19
	s_cselect_b32 s36, s24, s17
	v_lshl_add_u64 v[202:203], s[34:35], 0, v[156:157]
	s_add_i32 m0, s27, 0xc000
	ds_read_b128 v[182:185], v172
	ds_read_b128 v[186:189], v172 offset:1024
	ds_read_b128 v[190:193], v172 offset:2048
	ds_read_b128 v[198:201], v172 offset:3072
	ds_read_b128 v[210:213], v172 offset:4096
	ds_read_b128 v[214:217], v172 offset:5120
	ds_read_b128 v[218:221], v172 offset:6144
	ds_read_b128 v[222:225], v172 offset:7168
	global_load_lds_dwordx4 v[202:203], off sc0
	v_lshl_add_u64 v[202:203], s[34:35], 0, v[158:159]
	s_add_i32 m0, s27, 0xe000
	s_nop 0
	global_load_lds_dwordx4 v[202:203], off sc0
	s_waitcnt vmcnt(8)
	s_waitcnt lgkmcnt(0)
	s_barrier
	s_setprio 1
	s_waitcnt lgkmcnt(0)
	v_mfma_f32_16x16x32_bf16 v[126:129], v[130:133], v[182:185], v[126:129]
	v_mfma_f32_16x16x32_bf16 v[122:125], v[138:141], v[182:185], v[122:125]
	v_mfma_f32_16x16x32_bf16 v[118:121], v[130:133], v[190:193], v[118:121]
	v_mfma_f32_16x16x32_bf16 v[110:113], v[138:141], v[190:193], v[110:113]
	v_mfma_f32_16x16x32_bf16 v[94:97], v[130:133], v[210:213], v[94:97]
	v_mfma_f32_16x16x32_bf16 v[90:93], v[138:141], v[210:213], v[90:93]
	v_mfma_f32_16x16x32_bf16 v[78:81], v[130:133], v[218:221], v[78:81]
	v_mfma_f32_16x16x32_bf16 v[74:77], v[138:141], v[218:221], v[74:77]
	v_mfma_f32_16x16x32_bf16 v[126:129], v[134:137], v[186:189], v[126:129]
	v_mfma_f32_16x16x32_bf16 v[122:125], v[142:145], v[186:189], v[122:125]
	v_mfma_f32_16x16x32_bf16 v[118:121], v[134:137], v[198:201], v[118:121]
	v_mfma_f32_16x16x32_bf16 v[110:113], v[142:145], v[198:201], v[110:113]
	v_mfma_f32_16x16x32_bf16 v[94:97], v[134:137], v[214:217], v[94:97]
	v_mfma_f32_16x16x32_bf16 v[90:93], v[142:145], v[214:217], v[90:93]
	v_mfma_f32_16x16x32_bf16 v[78:81], v[134:137], v[222:225], v[78:81]
	v_mfma_f32_16x16x32_bf16 v[74:77], v[142:145], v[222:225], v[74:77]
	s_setprio 0
	s_setprio 1
	v_mfma_f32_16x16x32_bf16 v[114:117], v[160:163], v[182:185], v[114:117]
	v_mfma_f32_16x16x32_bf16 v[106:109], v[174:177], v[182:185], v[106:109]
	v_mfma_f32_16x16x32_bf16 v[102:105], v[160:163], v[190:193], v[102:105]
	v_mfma_f32_16x16x32_bf16 v[98:101], v[174:177], v[190:193], v[98:101]
	v_mfma_f32_16x16x32_bf16 v[86:89], v[160:163], v[210:213], v[86:89]
	v_mfma_f32_16x16x32_bf16 v[82:85], v[174:177], v[210:213], v[82:85]
	v_mfma_f32_16x16x32_bf16 v[70:73], v[160:163], v[218:221], v[70:73]
	v_mfma_f32_16x16x32_bf16 v[66:69], v[174:177], v[218:221], v[66:69]
	v_mfma_f32_16x16x32_bf16 v[114:117], v[164:167], v[186:189], v[114:117]
	v_mfma_f32_16x16x32_bf16 v[106:109], v[178:181], v[186:189], v[106:109]
	v_mfma_f32_16x16x32_bf16 v[102:105], v[164:167], v[198:201], v[102:105]
	v_mfma_f32_16x16x32_bf16 v[98:101], v[178:181], v[198:201], v[98:101]
	v_mfma_f32_16x16x32_bf16 v[86:89], v[164:167], v[214:217], v[86:89]
	v_mfma_f32_16x16x32_bf16 v[82:85], v[178:181], v[214:217], v[82:85]
	v_mfma_f32_16x16x32_bf16 v[70:73], v[164:167], v[222:225], v[70:73]
	v_mfma_f32_16x16x32_bf16 v[66:69], v[178:181], v[222:225], v[66:69]
	s_setprio 0
	s_barrier
	s_add_i32 s21, s63, s33
	v_lshl_add_u64 v[202:203], s[36:37], 0, v[148:149]
	s_mov_b32 m0, s21
	ds_read_b128 v[182:185], v172 offset:16384
	ds_read_b128 v[186:189], v172 offset:17408
	ds_read_b128 v[190:193], v172 offset:18432
	ds_read_b128 v[198:201], v172 offset:19456
	ds_read_b128 v[210:213], v172 offset:20480
	ds_read_b128 v[214:217], v172 offset:21504
	ds_read_b128 v[218:221], v172 offset:22528
	ds_read_b128 v[222:225], v172 offset:23552
	global_load_lds_dwordx4 v[202:203], off sc0
	s_add_i32 m0, s21, 0x2000
	s_add_u32 s40, s36, 0x80000
	v_lshl_add_u64 v[206:207], s[36:37], 0, v[152:153]
	s_addc_u32 s41, s37, 0
	s_add_i32 s21, s64, s33
	global_load_lds_dwordx4 v[206:207], off sc0
	v_lshl_add_u64 v[226:227], s[40:41], 0, v[148:149]
	s_mov_b32 m0, s21
	v_lshl_add_u64 v[228:229], s[38:39], 0, v[150:151]
	global_load_lds_dwordx4 v[226:227], off sc0
	v_lshl_add_u64 v[226:227], s[40:41], 0, v[152:153]
	s_add_i32 m0, s21, 0x2000
	s_nop 0
	global_load_lds_dwordx4 v[226:227], off sc0
	v_lshl_add_u64 v[226:227], s[38:39], 0, v[146:147]
	s_mov_b32 m0, s27
	s_nop 0
	global_load_lds_dwordx4 v[226:227], off sc0
	s_mov_b32 m0, s29
	s_nop 0
	global_load_lds_dwordx4 v[228:229], off sc0
	s_waitcnt vmcnt(8)
	s_waitcnt lgkmcnt(0)
	s_barrier
	s_setprio 1
	s_waitcnt lgkmcnt(0)
	v_mfma_f32_16x16x32_bf16 v[62:65], v[130:133], v[182:185], v[62:65]
	v_mfma_f32_16x16x32_bf16 v[58:61], v[138:141], v[182:185], v[58:61]
	v_mfma_f32_16x16x32_bf16 v[46:49], v[130:133], v[190:193], v[46:49]
	v_mfma_f32_16x16x32_bf16 v[42:45], v[138:141], v[190:193], v[42:45]
	v_mfma_f32_16x16x32_bf16 v[30:33], v[130:133], v[210:213], v[30:33]
	v_mfma_f32_16x16x32_bf16 v[26:29], v[138:141], v[210:213], v[26:29]
	v_mfma_f32_16x16x32_bf16 v[14:17], v[130:133], v[218:221], v[14:17]
	v_mfma_f32_16x16x32_bf16 v[10:13], v[138:141], v[218:221], v[10:13]
	v_mfma_f32_16x16x32_bf16 v[62:65], v[134:137], v[186:189], v[62:65]
	v_mfma_f32_16x16x32_bf16 v[58:61], v[142:145], v[186:189], v[58:61]
	v_mfma_f32_16x16x32_bf16 v[46:49], v[134:137], v[198:201], v[46:49]
	v_mfma_f32_16x16x32_bf16 v[42:45], v[142:145], v[198:201], v[42:45]
	v_mfma_f32_16x16x32_bf16 v[30:33], v[134:137], v[214:217], v[30:33]
	v_mfma_f32_16x16x32_bf16 v[26:29], v[142:145], v[214:217], v[26:29]
	v_mfma_f32_16x16x32_bf16 v[14:17], v[134:137], v[222:225], v[14:17]
	v_mfma_f32_16x16x32_bf16 v[10:13], v[142:145], v[222:225], v[10:13]
	s_setprio 0
	s_setprio 1
	v_mfma_f32_16x16x32_bf16 v[54:57], v[160:163], v[182:185], v[54:57]
	v_mfma_f32_16x16x32_bf16 v[50:53], v[174:177], v[182:185], v[50:53]
	v_mfma_f32_16x16x32_bf16 v[38:41], v[160:163], v[190:193], v[38:41]
	v_mfma_f32_16x16x32_bf16 v[34:37], v[174:177], v[190:193], v[34:37]
	v_mfma_f32_16x16x32_bf16 v[22:25], v[160:163], v[210:213], v[22:25]
	v_mfma_f32_16x16x32_bf16 v[18:21], v[174:177], v[210:213], v[18:21]
	v_mfma_f32_16x16x32_bf16 v[6:9], v[160:163], v[218:221], v[6:9]
	v_mfma_f32_16x16x32_bf16 v[2:5], v[174:177], v[218:221], v[2:5]
	v_mfma_f32_16x16x32_bf16 v[54:57], v[164:167], v[186:189], v[54:57]
	v_mfma_f32_16x16x32_bf16 v[50:53], v[178:181], v[186:189], v[50:53]
	v_mfma_f32_16x16x32_bf16 v[38:41], v[164:167], v[198:201], v[38:41]
	v_mfma_f32_16x16x32_bf16 v[34:37], v[178:181], v[198:201], v[34:37]
	v_mfma_f32_16x16x32_bf16 v[22:25], v[164:167], v[214:217], v[22:25]
	v_mfma_f32_16x16x32_bf16 v[18:21], v[178:181], v[214:217], v[18:21]
	v_mfma_f32_16x16x32_bf16 v[6:9], v[164:167], v[222:225], v[6:9]
	v_mfma_f32_16x16x32_bf16 v[2:5], v[178:181], v[222:225], v[2:5]
	s_setprio 0
	s_barrier
	s_add_i32 s21, 0, 0x18000
	s_add_i32 s40, 0, 0x1c000
	v_add_u32_e32 v142, s21, v168
	v_add_u32_e32 v173, s40, v168
	ds_read_b128 v[130:133], v142
	ds_read_b128 v[134:137], v142 offset:1024
	ds_read_b128 v[138:141], v142 offset:2048
	ds_read_b128 v[142:145], v142 offset:3072
	ds_read_b128 v[160:163], v173
	ds_read_b128 v[164:167], v173 offset:1024
	ds_read_b128 v[174:177], v173 offset:2048
	ds_read_b128 v[178:181], v173 offset:3072
	s_add_u32 s38, s38, 0x80000
	s_addc_u32 s39, s39, 0
	s_mov_b32 m0, s42
	v_lshl_add_u64 v[230:231], s[38:39], 0, v[146:147]
	ds_read_b128 v[182:185], v172 offset:32768
	ds_read_b128 v[186:189], v172 offset:33792
	ds_read_b128 v[190:193], v172 offset:34816
	ds_read_b128 v[198:201], v172 offset:35840
	ds_read_b128 v[210:213], v172 offset:36864
	ds_read_b128 v[214:217], v172 offset:37888
	ds_read_b128 v[218:221], v172 offset:38912
	ds_read_b128 v[222:225], v172 offset:39936
	global_load_lds_dwordx4 v[230:231], off sc0
	v_lshl_add_u64 v[230:231], s[38:39], 0, v[150:151]
	s_mov_b32 m0, s43
	s_nop 0
	global_load_lds_dwordx4 v[230:231], off sc0
	s_waitcnt vmcnt(8)
	s_waitcnt lgkmcnt(0)
	s_barrier
	s_setprio 1
	s_waitcnt lgkmcnt(0)
	v_mfma_f32_16x16x32_bf16 v[126:129], v[130:133], v[182:185], v[126:129]
	v_mfma_f32_16x16x32_bf16 v[122:125], v[138:141], v[182:185], v[122:125]
	v_mfma_f32_16x16x32_bf16 v[118:121], v[130:133], v[190:193], v[118:121]
	v_mfma_f32_16x16x32_bf16 v[110:113], v[138:141], v[190:193], v[110:113]
	v_mfma_f32_16x16x32_bf16 v[94:97], v[130:133], v[210:213], v[94:97]
	v_mfma_f32_16x16x32_bf16 v[90:93], v[138:141], v[210:213], v[90:93]
	v_mfma_f32_16x16x32_bf16 v[78:81], v[130:133], v[218:221], v[78:81]
	v_mfma_f32_16x16x32_bf16 v[74:77], v[138:141], v[218:221], v[74:77]
	v_mfma_f32_16x16x32_bf16 v[126:129], v[134:137], v[186:189], v[126:129]
	v_mfma_f32_16x16x32_bf16 v[122:125], v[142:145], v[186:189], v[122:125]
	v_mfma_f32_16x16x32_bf16 v[118:121], v[134:137], v[198:201], v[118:121]
	v_mfma_f32_16x16x32_bf16 v[110:113], v[142:145], v[198:201], v[110:113]
	v_mfma_f32_16x16x32_bf16 v[94:97], v[134:137], v[214:217], v[94:97]
	v_mfma_f32_16x16x32_bf16 v[90:93], v[142:145], v[214:217], v[90:93]
	v_mfma_f32_16x16x32_bf16 v[78:81], v[134:137], v[222:225], v[78:81]
	v_mfma_f32_16x16x32_bf16 v[74:77], v[142:145], v[222:225], v[74:77]
	s_setprio 0
	s_setprio 1
	v_mfma_f32_16x16x32_bf16 v[114:117], v[160:163], v[182:185], v[114:117]
	v_mfma_f32_16x16x32_bf16 v[106:109], v[174:177], v[182:185], v[106:109]
	v_mfma_f32_16x16x32_bf16 v[102:105], v[160:163], v[190:193], v[102:105]
	v_mfma_f32_16x16x32_bf16 v[98:101], v[174:177], v[190:193], v[98:101]
	v_mfma_f32_16x16x32_bf16 v[86:89], v[160:163], v[210:213], v[86:89]
	v_mfma_f32_16x16x32_bf16 v[82:85], v[174:177], v[210:213], v[82:85]
	v_mfma_f32_16x16x32_bf16 v[70:73], v[160:163], v[218:221], v[70:73]
	v_mfma_f32_16x16x32_bf16 v[66:69], v[174:177], v[218:221], v[66:69]
	v_mfma_f32_16x16x32_bf16 v[114:117], v[164:167], v[186:189], v[114:117]
	v_mfma_f32_16x16x32_bf16 v[106:109], v[178:181], v[186:189], v[106:109]
	v_mfma_f32_16x16x32_bf16 v[102:105], v[164:167], v[198:201], v[102:105]
	v_mfma_f32_16x16x32_bf16 v[98:101], v[178:181], v[198:201], v[98:101]
	v_mfma_f32_16x16x32_bf16 v[86:89], v[164:167], v[214:217], v[86:89]
	v_mfma_f32_16x16x32_bf16 v[82:85], v[178:181], v[214:217], v[82:85]
	v_mfma_f32_16x16x32_bf16 v[70:73], v[164:167], v[222:225], v[70:73]
	v_mfma_f32_16x16x32_bf16 v[66:69], v[178:181], v[222:225], v[66:69]
	s_setprio 0
	s_barrier
	s_add_i32 s21, s21, s33
	v_lshl_add_u64 v[202:203], v[202:203], 0, s[12:13]
	s_mov_b32 m0, s21
	ds_read_b128 v[182:185], v172 offset:49152
	ds_read_b128 v[186:189], v172 offset:50176
	ds_read_b128 v[190:193], v172 offset:51200
	ds_read_b128 v[198:201], v172 offset:52224
	ds_read_b128 v[210:213], v172 offset:53248
	ds_read_b128 v[214:217], v172 offset:54272
	ds_read_b128 v[218:221], v172 offset:55296
	ds_read_b128 v[222:225], v172 offset:56320
	global_load_lds_dwordx4 v[202:203], off sc0
	s_add_i32 m0, s21, 0x2000
	s_add_u32 s36, s36, 0x80080
	v_lshl_add_u64 v[202:203], v[206:207], 0, s[12:13]
	s_addc_u32 s37, s37, 0
	s_add_i32 s21, s40, s33
	global_load_lds_dwordx4 v[202:203], off sc0
	v_lshl_add_u64 v[202:203], s[36:37], 0, v[148:149]
	s_mov_b32 m0, s21
	s_nop 0
	global_load_lds_dwordx4 v[202:203], off sc0
	v_lshl_add_u64 v[202:203], s[36:37], 0, v[152:153]
	s_add_i32 m0, s21, 0x2000
	s_nop 0
	global_load_lds_dwordx4 v[202:203], off sc0
	v_lshl_add_u64 v[202:203], v[226:227], 0, s[12:13]
	s_mov_b32 m0, s53
	s_nop 0
	global_load_lds_dwordx4 v[202:203], off sc0
	v_lshl_add_u64 v[202:203], v[228:229], 0, s[12:13]
	s_mov_b32 m0, s54
	s_nop 0
	global_load_lds_dwordx4 v[202:203], off sc0
	s_waitcnt vmcnt(8)
	s_waitcnt lgkmcnt(0)
	s_barrier
	s_setprio 1
	s_waitcnt lgkmcnt(0)
	v_mfma_f32_16x16x32_bf16 v[62:65], v[130:133], v[182:185], v[62:65]
	v_mfma_f32_16x16x32_bf16 v[58:61], v[138:141], v[182:185], v[58:61]
	v_mfma_f32_16x16x32_bf16 v[46:49], v[130:133], v[190:193], v[46:49]
	v_mfma_f32_16x16x32_bf16 v[42:45], v[138:141], v[190:193], v[42:45]
	v_mfma_f32_16x16x32_bf16 v[30:33], v[130:133], v[210:213], v[30:33]
	v_mfma_f32_16x16x32_bf16 v[26:29], v[138:141], v[210:213], v[26:29]
	v_mfma_f32_16x16x32_bf16 v[14:17], v[130:133], v[218:221], v[14:17]
	v_mfma_f32_16x16x32_bf16 v[10:13], v[138:141], v[218:221], v[10:13]
	v_mfma_f32_16x16x32_bf16 v[62:65], v[134:137], v[186:189], v[62:65]
	v_mfma_f32_16x16x32_bf16 v[58:61], v[142:145], v[186:189], v[58:61]
	v_mfma_f32_16x16x32_bf16 v[46:49], v[134:137], v[198:201], v[46:49]
	v_mfma_f32_16x16x32_bf16 v[42:45], v[142:145], v[198:201], v[42:45]
	v_mfma_f32_16x16x32_bf16 v[30:33], v[134:137], v[214:217], v[30:33]
	v_mfma_f32_16x16x32_bf16 v[26:29], v[142:145], v[214:217], v[26:29]
	v_mfma_f32_16x16x32_bf16 v[14:17], v[134:137], v[222:225], v[14:17]
	v_mfma_f32_16x16x32_bf16 v[10:13], v[142:145], v[222:225], v[10:13]
	s_setprio 0
	s_setprio 1
	v_mfma_f32_16x16x32_bf16 v[54:57], v[160:163], v[182:185], v[54:57]
	v_mfma_f32_16x16x32_bf16 v[50:53], v[174:177], v[182:185], v[50:53]
	v_mfma_f32_16x16x32_bf16 v[38:41], v[160:163], v[190:193], v[38:41]
	v_mfma_f32_16x16x32_bf16 v[34:37], v[174:177], v[190:193], v[34:37]
	v_mfma_f32_16x16x32_bf16 v[22:25], v[160:163], v[210:213], v[22:25]
	v_mfma_f32_16x16x32_bf16 v[18:21], v[174:177], v[210:213], v[18:21]
	v_mfma_f32_16x16x32_bf16 v[6:9], v[160:163], v[218:221], v[6:9]
	v_mfma_f32_16x16x32_bf16 v[2:5], v[174:177], v[218:221], v[2:5]
	v_mfma_f32_16x16x32_bf16 v[54:57], v[164:167], v[186:189], v[54:57]
	v_mfma_f32_16x16x32_bf16 v[50:53], v[178:181], v[186:189], v[50:53]
	v_mfma_f32_16x16x32_bf16 v[38:41], v[164:167], v[198:201], v[38:41]
	v_mfma_f32_16x16x32_bf16 v[34:37], v[178:181], v[198:201], v[34:37]
	v_mfma_f32_16x16x32_bf16 v[22:25], v[164:167], v[214:217], v[22:25]
	v_mfma_f32_16x16x32_bf16 v[18:21], v[178:181], v[214:217], v[18:21]
	v_mfma_f32_16x16x32_bf16 v[6:9], v[164:167], v[222:225], v[6:9]
	v_mfma_f32_16x16x32_bf16 v[2:5], v[178:181], v[222:225], v[2:5]
	s_setprio 0
	s_barrier
	s_add_u32 s34, s34, 0x100
	s_addc_u32 s35, s35, 0
	s_add_u32 s17, s17, 0x100
	s_addc_u32 s19, s19, 0
	s_cmp_ge_i32 s31, s69
	s_mov_b32 s21, s31
	s_cbranch_scc0 .LBB0_1122

.LBB0_1300:
	v_lshrrev_b32_e32 v3, 1, v0
	v_and_b32_e32 v15, 24, v3
	v_lshrrev_b32_e32 v3, 5, v0
	s_add_u32 s2, s82, 0x3000000
	v_lshlrev_b32_e32 v2, 4, v0
	v_and_b32_e32 v1, 32, v0
	v_and_b32_e32 v3, 4, v3
	v_bfe_u32 v4, v0, 2, 2
	s_addc_u32 s3, s83, 0
	v_bfe_u32 v14, v0, 2, 4
	v_bitop3_b32 v12, v2, v1, 48 bitop3:0x6c
	v_and_b32_e32 v13, 64, v0
	v_or3_b32 v3, v3, v4, v15
	v_lshrrev_b32_e32 v4, 3, v0
	s_ashr_i32 s14, s11, 31
	v_or_b32_e32 v1, v12, v13
	v_and_or_b32 v5, v4, 48, v14
	v_and_or_b32 v4, v4, 32, v3
	v_or_b32_e32 v16, 0x2000, v2
	s_lshr_b32 s14, s14, 29
	v_lshl_or_b32 v132, v4, 12, v1
	v_lshrrev_b32_e32 v4, 7, v16
	s_movk_i32 s10, 0x70
	s_add_i32 s14, s11, s14
	v_lshl_or_b32 v130, v5, 12, v1
	v_and_or_b32 v5, v4, s10, v14
	s_lshr_b32 s10, s12, 6
	s_ashr_i32 s15, s14, 3
	s_and_b32 s14, s14, -8
	s_lshr_b32 s7, s12, 8
	s_lshl_b32 s33, s10, 10
	s_sub_i32 s11, s11, s14
	s_cmp_lt_i32 s11, 0
	s_movk_i32 s40, 0x109
	s_cselect_b32 s14, s40, 0x108
	s_mul_i32 s11, s14, s11
	s_add_i32 s11, s11, s15
	s_mul_hi_i32 s14, s11, 0x2e8ba2e9
	s_lshr_b32 s15, s14, 31
	s_ashr_i32 s14, s14, 6
	s_add_i32 s14, s14, s15
	s_lshl_b32 s15, s14, 3
	s_sub_i32 s16, 48, s15
	s_min_i32 s16, s16, 8
	s_abs_i32 s17, s16
	v_cvt_f32_u32_e32 v6, s17
	s_movk_i32 s13, 0x60
	v_and_or_b32 v3, v4, s13, v3
	v_lshl_or_b32 v134, v5, 12, v1
	v_lshl_or_b32 v136, v3, 12, v1
	v_rcp_iflag_f32_e32 v1, v6
	s_sub_i32 s18, 0, s17
	s_mulk_i32 s14, 0x160
	s_sub_i32 s11, s11, s14
	v_mul_f32_e32 v1, 0x4f7ffffe, v1
	v_cvt_u32_f32_e32 v1, v1
	s_abs_i32 s14, s11
	s_xor_b32 s13, s11, s16
	s_ashr_i32 s13, s13, 31
	v_readfirstlane_b32 s19, v1
	s_mul_i32 s18, s18, s19
	s_mul_hi_u32 s18, s19, s18
	s_add_i32 s19, s19, s18
	s_mul_hi_u32 s18, s14, s19
	s_mul_i32 s19, s18, s17
	s_sub_i32 s14, s14, s19
	s_add_i32 s19, s18, 1
	s_sub_i32 s20, s14, s17
	s_cmp_ge_u32 s14, s17
	s_cselect_b32 s18, s19, s18
	s_cselect_b32 s14, s20, s14
	s_add_i32 s19, s18, 1
	s_cmp_ge_u32 s14, s17
	s_cselect_b32 s14, s19, s18
	s_xor_b32 s14, s14, s13
	s_sub_i32 s26, s14, s13
	s_mul_i32 s13, s26, s16
	s_sub_i32 s11, s11, s13
	s_add_i32 s24, s15, s11
	s_ashr_i32 s25, s24, 31
	s_lshl_b64 s[14:15], s[24:25], 20
	v_readlane_b32 s16, v249, 50
	v_readlane_b32 s17, v249, 51
	s_add_u32 s11, s16, s14
	s_addc_u32 s13, s17, s15
	s_ashr_i32 s27, s26, 31
	s_lshl_b64 s[14:15], s[26:27], 20
	s_add_u32 s14, s2, s14
	s_addc_u32 s15, s3, s15
	s_add_u32 s34, s14, s8
	s_addc_u32 s35, s15, s9
	s_add_i32 s27, s33, 0
	s_add_i32 m0, s27, 0x10000
	v_mov_b32_e32 v133, 0
	global_load_lds_dwordx4 v132, s[34:35] sc0
	s_add_i32 m0, s27, 0x12000
	s_add_u32 s14, s34, 0x80000
	global_load_lds_dwordx4 v136, s[34:35] sc0
	s_addc_u32 s15, s35, 0
	s_add_i32 m0, s27, 0x14000
	v_mov_b32_e32 v137, v133
	global_load_lds_dwordx4 v132, s[14:15] sc0
	s_add_i32 m0, s27, 0x16000
	s_add_u32 s30, s11, s8
	s_addc_u32 s31, s13, s9
	s_add_i32 s41, s27, 0x2000
	global_load_lds_dwordx4 v136, s[14:15] sc0
	s_mov_b32 m0, s27
	s_add_u32 s8, s30, 0x80000
	global_load_lds_dwordx4 v130, s[30:31] sc0
	s_mov_b32 m0, s41
	s_addc_u32 s9, s31, 0
	s_add_i32 s42, s27, 0x4000
	global_load_lds_dwordx4 v134, s[30:31] sc0
	s_mov_b32 m0, s42
	s_add_i32 s43, s27, 0x6000
	global_load_lds_dwordx4 v130, s[8:9] sc0
	s_mov_b32 m0, s43
	v_mov_b32_e32 v131, v133
	global_load_lds_dwordx4 v134, s[8:9] sc0
	v_mov_b32_e32 v135, v133
	s_cmp_eq_u32 s7, 1
	s_movk_i32 s44, 0x2000
	s_mov_b32 s45, 0x10000
	v_lshl_add_u64 v[10:11], s[34:35], 0, v[132:133]
	v_lshl_add_u64 v[6:7], s[34:35], 0, v[136:137]
	s_mov_b32 s46, 0x12000
	s_mov_b32 s47, 0x14000
	s_mov_b32 s48, 0x16000
	v_lshl_add_u64 v[8:9], s[30:31], 0, v[130:131]
	v_lshl_add_u64 v[4:5], s[30:31], 0, v[134:135]
	s_movk_i32 s49, 0x4000
	s_cselect_b64 s[8:9], -1, 0
	s_cmp_lg_u32 s7, 1
	s_movk_i32 s50, 0x6000
	s_cbranch_scc1 .LBB0_1302
	s_barrier
.LBB0_1302:
	s_lshl_b32 s10, s10, 5
	s_and_b32 s16, s10, 0x60
	s_mov_b64 s[10:11], 0x80
	s_add_i32 m0, s27, 0x18000
	v_lshl_add_u64 v[10:11], v[10:11], 0, s[10:11]
	s_lshl_b32 s13, s7, 13
	s_lshl_b32 s17, s16, 7
	s_waitcnt vmcnt(2)
	s_barrier
	global_load_lds_dwordx4 v[10:11], off sc0
	v_lshl_add_u64 v[6:7], v[6:7], 0, s[10:11]
	s_add_i32 m0, s27, 0x1a000
	s_add_i32 s51, s27, 0x8000
	s_add_i32 s52, s27, 0xa000
	global_load_lds_dwordx4 v[6:7], off sc0
	v_lshl_add_u64 v[6:7], v[8:9], 0, s[10:11]
	s_mov_b32 m0, s51
	s_add_u32 s14, s34, 0x80080
	global_load_lds_dwordx4 v[6:7], off sc0
	v_lshl_add_u64 v[4:5], v[4:5], 0, s[10:11]
	s_mov_b32 m0, s52
	s_addc_u32 s15, s35, 0
	global_load_lds_dwordx4 v[4:5], off sc0
	s_add_i32 m0, s27, 0x1c000
	v_lshl_add_u64 v[4:5], s[14:15], 0, v[132:133]
	global_load_lds_dwordx4 v[4:5], off sc0
	v_lshl_add_u64 v[4:5], s[14:15], 0, v[136:137]
	s_add_i32 m0, s27, 0x1e000
	v_lshlrev_b32_e32 v3, 1, v15
	global_load_lds_dwordx4 v[4:5], off sc0
	v_lshl_or_b32 v1, s7, 6, v205
	v_lshl_or_b32 v4, v205, 6, v3
	v_and_b32_e32 v5, 32, v196
	s_movk_i32 s7, 0x3c0
	v_readlane_b32 s15, v249, 0
	v_bitop3_b32 v4, v4, s13, v5 bitop3:0xde
	v_and_or_b32 v3, v209, s7, v3
	s_ashr_i32 s13, s15, 31
	v_bitop3_b32 v146, s17, v3, v5 bitop3:0xf6
	s_lshr_b32 s13, s13, 26
	v_mov_b32_e32 v3, v133
	s_add_i32 s13, s15, s13
	v_lshl_add_u64 v[138:139], s[78:79], 0, v[2:3]
	v_lshlrev_b32_e32 v2, 9, v0
	s_and_b32 s14, s13, 0xffffffc0
	v_and_b32_e32 v2, 0x30000, v2
	v_lshlrev_b32_e32 v3, 12, v14
	s_sub_i32 s58, s15, s14
	s_ashr_i32 s13, s13, 6
	v_or3_b32 v2, v12, v2, v3
	s_addk_i32 s58, 0x800
	s_lshl_b32 s59, s13, 3
	v_add_u32_e32 v140, v2, v13
	v_lshlrev_b32_e32 v2, 5, v16
	s_waitcnt vmcnt(6)
	s_cmpk_lt_u32 s12, 0x100
	v_and_b32_e32 v2, 0x70000, v2
	s_mov_b32 s7, 0
	s_cselect_b64 s[12:13], -1, 0
	v_or3_b32 v2, v12, v2, v3
	s_add_i32 s60, 0, 0x10000
	s_add_i32 s61, 0, 0x14000
	s_mov_b32 s53, 0x18000
	s_mov_b32 s54, 0x1a000
	s_mov_b32 s55, 0x8000
	s_mov_b32 s56, 0xa000
	s_mov_b32 s57, 0x1c000
	v_or_b32_e32 v147, s16, v15
	v_mov_b32_e32 v141, v133
	v_add_u32_e32 v142, v2, v13
	v_mov_b32_e32 v143, v133
	v_add_u32_e32 v148, s60, v146
	v_add_u32_e32 v149, s61, v146
	v_add_u32_e32 v150, 0, v4
	s_mov_b32 s62, 0xc000
	s_mov_b32 s63, 0xe000
	s_movk_i32 s64, 0x2c00
	s_mov_b32 s25, s7
	s_barrier
	s_branch .LBB0_1305

.Lpeel_7:
	ds_read_b128 v[152:155], v148
	ds_read_b128 v[156:159], v148 offset:1024
	ds_read_b128 v[160:163], v148 offset:2048
	ds_read_b128 v[164:167], v148 offset:3072
	ds_read_b128 v[168:171], v149
	ds_read_b128 v[172:175], v149 offset:1024
	ds_read_b128 v[176:179], v149 offset:2048
	ds_read_b128 v[180:183], v149 offset:3072
	s_add_i32 s29, s19, 2
	s_add_u32 s34, s30, 0xfff80080
	s_addc_u32 s35, s31, -1
	s_cmp_eq_u32 s28, s19
	s_cselect_b32 s37, s21, s35
	s_cselect_b32 s36, s20, s34
	s_cselect_b32 s35, s23, s17
	s_cselect_b32 s34, s22, s15
	v_lshl_add_u64 v[144:145], s[30:31], 0, v[140:141]
	s_add_i32 m0, s27, 0xc000
	ds_read_b128 v[184:187], v150
	ds_read_b128 v[188:191], v150 offset:1024
	ds_read_b128 v[198:201], v150 offset:2048
	ds_read_b128 v[210:213], v150 offset:3072
	ds_read_b128 v[214:217], v150 offset:4096
	ds_read_b128 v[218:221], v150 offset:5120
	ds_read_b128 v[222:225], v150 offset:6144
	ds_read_b128 v[226:229], v150 offset:7168
	global_load_lds_dwordx4 v[144:145], off sc0
	v_lshl_add_u64 v[144:145], s[30:31], 0, v[142:143]
	s_add_i32 m0, s27, 0xe000
	s_nop 0
	global_load_lds_dwordx4 v[144:145], off sc0
	s_waitcnt vmcnt(8)
	s_waitcnt lgkmcnt(0)
	s_barrier
	s_setprio 1
	s_waitcnt lgkmcnt(0)
	v_mfma_f32_16x16x32_bf16 v[126:129], v[152:155], v[184:187], 0
	v_mfma_f32_16x16x32_bf16 v[122:125], v[160:163], v[184:187], 0
	v_mfma_f32_16x16x32_bf16 v[110:113], v[152:155], v[198:201], 0
	v_mfma_f32_16x16x32_bf16 v[106:109], v[160:163], v[198:201], 0
	v_mfma_f32_16x16x32_bf16 v[94:97], v[152:155], v[214:217], 0
	v_mfma_f32_16x16x32_bf16 v[90:93], v[160:163], v[214:217], 0
	v_mfma_f32_16x16x32_bf16 v[78:81], v[152:155], v[222:225], 0
	v_mfma_f32_16x16x32_bf16 v[74:77], v[160:163], v[222:225], 0
	v_mfma_f32_16x16x32_bf16 v[126:129], v[156:159], v[188:191], v[126:129]
	v_mfma_f32_16x16x32_bf16 v[122:125], v[164:167], v[188:191], v[122:125]
	v_mfma_f32_16x16x32_bf16 v[110:113], v[156:159], v[210:213], v[110:113]
	v_mfma_f32_16x16x32_bf16 v[106:109], v[164:167], v[210:213], v[106:109]
	v_mfma_f32_16x16x32_bf16 v[94:97], v[156:159], v[218:221], v[94:97]
	v_mfma_f32_16x16x32_bf16 v[90:93], v[164:167], v[218:221], v[90:93]
	v_mfma_f32_16x16x32_bf16 v[78:81], v[156:159], v[226:229], v[78:81]
	v_mfma_f32_16x16x32_bf16 v[74:77], v[164:167], v[226:229], v[74:77]
	s_setprio 0
	s_setprio 1
	v_mfma_f32_16x16x32_bf16 v[118:121], v[168:171], v[184:187], 0
	v_mfma_f32_16x16x32_bf16 v[114:117], v[176:179], v[184:187], 0
	v_mfma_f32_16x16x32_bf16 v[102:105], v[168:171], v[198:201], 0
	v_mfma_f32_16x16x32_bf16 v[98:101], v[176:179], v[198:201], 0
	v_mfma_f32_16x16x32_bf16 v[86:89], v[168:171], v[214:217], 0
	v_mfma_f32_16x16x32_bf16 v[82:85], v[176:179], v[214:217], 0
	v_mfma_f32_16x16x32_bf16 v[70:73], v[168:171], v[222:225], 0
	v_mfma_f32_16x16x32_bf16 v[66:69], v[176:179], v[222:225], 0
	v_mfma_f32_16x16x32_bf16 v[118:121], v[172:175], v[188:191], v[118:121]
	v_mfma_f32_16x16x32_bf16 v[114:117], v[180:183], v[188:191], v[114:117]
	v_mfma_f32_16x16x32_bf16 v[102:105], v[172:175], v[210:213], v[102:105]
	v_mfma_f32_16x16x32_bf16 v[98:101], v[180:183], v[210:213], v[98:101]
	v_mfma_f32_16x16x32_bf16 v[86:89], v[172:175], v[218:221], v[86:89]
	v_mfma_f32_16x16x32_bf16 v[82:85], v[180:183], v[218:221], v[82:85]
	v_mfma_f32_16x16x32_bf16 v[70:73], v[172:175], v[226:229], v[70:73]
	v_mfma_f32_16x16x32_bf16 v[66:69], v[180:183], v[226:229], v[66:69]
	s_setprio 0
	s_barrier
	s_add_i32 s19, s60, s33
	v_lshl_add_u64 v[144:145], s[34:35], 0, v[132:133]
	s_mov_b32 m0, s19
	ds_read_b128 v[184:187], v150 offset:16384
	ds_read_b128 v[188:191], v150 offset:17408
	ds_read_b128 v[198:201], v150 offset:18432
	ds_read_b128 v[210:213], v150 offset:19456
	ds_read_b128 v[214:217], v150 offset:20480
	ds_read_b128 v[218:221], v150 offset:21504
	ds_read_b128 v[222:225], v150 offset:22528
	ds_read_b128 v[226:229], v150 offset:23552
	global_load_lds_dwordx4 v[144:145], off sc0
	s_add_i32 m0, s19, 0x2000
	s_add_u32 s38, s34, 0x80000
	v_lshl_add_u64 v[192:193], s[34:35], 0, v[136:137]
	s_addc_u32 s39, s35, 0
	s_add_i32 s19, s61, s33
	global_load_lds_dwordx4 v[192:193], off sc0
	v_lshl_add_u64 v[202:203], s[38:39], 0, v[132:133]
	s_mov_b32 m0, s19
	v_lshl_add_u64 v[206:207], s[36:37], 0, v[134:135]
	global_load_lds_dwordx4 v[202:203], off sc0
	v_lshl_add_u64 v[202:203], s[38:39], 0, v[136:137]
	s_add_i32 m0, s19, 0x2000
	s_nop 0
	global_load_lds_dwordx4 v[202:203], off sc0
	v_lshl_add_u64 v[202:203], s[36:37], 0, v[130:131]
	s_mov_b32 m0, s27
	s_nop 0
	global_load_lds_dwordx4 v[202:203], off sc0
	s_mov_b32 m0, s41
	s_nop 0
	global_load_lds_dwordx4 v[206:207], off sc0
	s_waitcnt vmcnt(8)
	s_waitcnt lgkmcnt(0)
	s_barrier
	s_setprio 1
	s_waitcnt lgkmcnt(0)
	v_mfma_f32_16x16x32_bf16 v[62:65], v[152:155], v[184:187], 0
	v_mfma_f32_16x16x32_bf16 v[58:61], v[160:163], v[184:187], 0
	v_mfma_f32_16x16x32_bf16 v[46:49], v[152:155], v[198:201], 0
	v_mfma_f32_16x16x32_bf16 v[42:45], v[160:163], v[198:201], 0
	v_mfma_f32_16x16x32_bf16 v[30:33], v[152:155], v[214:217], 0
	v_mfma_f32_16x16x32_bf16 v[26:29], v[160:163], v[214:217], 0
	v_mfma_f32_16x16x32_bf16 v[14:17], v[152:155], v[222:225], 0
	v_mfma_f32_16x16x32_bf16 v[10:13], v[160:163], v[222:225], 0
	v_mfma_f32_16x16x32_bf16 v[62:65], v[156:159], v[188:191], v[62:65]
	v_mfma_f32_16x16x32_bf16 v[58:61], v[164:167], v[188:191], v[58:61]
	v_mfma_f32_16x16x32_bf16 v[46:49], v[156:159], v[210:213], v[46:49]
	v_mfma_f32_16x16x32_bf16 v[42:45], v[164:167], v[210:213], v[42:45]
	v_mfma_f32_16x16x32_bf16 v[30:33], v[156:159], v[218:221], v[30:33]
	v_mfma_f32_16x16x32_bf16 v[26:29], v[164:167], v[218:221], v[26:29]
	v_mfma_f32_16x16x32_bf16 v[14:17], v[156:159], v[226:229], v[14:17]
	v_mfma_f32_16x16x32_bf16 v[10:13], v[164:167], v[226:229], v[10:13]
	s_setprio 0
	s_setprio 1
	v_mfma_f32_16x16x32_bf16 v[54:57], v[168:171], v[184:187], 0
	v_mfma_f32_16x16x32_bf16 v[50:53], v[176:179], v[184:187], 0
	v_mfma_f32_16x16x32_bf16 v[38:41], v[168:171], v[198:201], 0
	v_mfma_f32_16x16x32_bf16 v[34:37], v[176:179], v[198:201], 0
	v_mfma_f32_16x16x32_bf16 v[22:25], v[168:171], v[214:217], 0
	v_mfma_f32_16x16x32_bf16 v[18:21], v[176:179], v[214:217], 0
	v_mfma_f32_16x16x32_bf16 v[6:9], v[168:171], v[222:225], 0
	v_mfma_f32_16x16x32_bf16 v[2:5], v[176:179], v[222:225], 0
	v_mfma_f32_16x16x32_bf16 v[54:57], v[172:175], v[188:191], v[54:57]
	v_mfma_f32_16x16x32_bf16 v[50:53], v[180:183], v[188:191], v[50:53]
	v_mfma_f32_16x16x32_bf16 v[38:41], v[172:175], v[210:213], v[38:41]
	v_mfma_f32_16x16x32_bf16 v[34:37], v[180:183], v[210:213], v[34:37]
	v_mfma_f32_16x16x32_bf16 v[22:25], v[172:175], v[218:221], v[22:25]
	v_mfma_f32_16x16x32_bf16 v[18:21], v[180:183], v[218:221], v[18:21]
	v_mfma_f32_16x16x32_bf16 v[6:9], v[172:175], v[226:229], v[6:9]
	v_mfma_f32_16x16x32_bf16 v[2:5], v[180:183], v[226:229], v[2:5]
	s_setprio 0
	s_barrier
	s_add_i32 s19, 0, 0x18000
	v_add_u32_e32 v151, s19, v146
	s_add_i32 s38, 0, 0x1c000
	ds_read_b128 v[152:155], v151
	ds_read_b128 v[156:159], v151 offset:1024
	ds_read_b128 v[160:163], v151 offset:2048
	ds_read_b128 v[164:167], v151 offset:3072
	v_add_u32_e32 v151, s38, v146
	ds_read_b128 v[168:171], v151
	ds_read_b128 v[172:175], v151 offset:1024
	ds_read_b128 v[176:179], v151 offset:2048
	ds_read_b128 v[180:183], v151 offset:3072
	s_add_u32 s36, s36, 0x80000
	s_addc_u32 s37, s37, 0
	s_mov_b32 m0, s42
	v_lshl_add_u64 v[230:231], s[36:37], 0, v[130:131]
	ds_read_b128 v[184:187], v150 offset:32768
	ds_read_b128 v[188:191], v150 offset:33792
	ds_read_b128 v[198:201], v150 offset:34816
	ds_read_b128 v[210:213], v150 offset:35840
	ds_read_b128 v[214:217], v150 offset:36864
	ds_read_b128 v[218:221], v150 offset:37888
	ds_read_b128 v[222:225], v150 offset:38912
	ds_read_b128 v[226:229], v150 offset:39936
	global_load_lds_dwordx4 v[230:231], off sc0
	v_lshl_add_u64 v[230:231], s[36:37], 0, v[134:135]
	s_mov_b32 m0, s43
	s_nop 0
	global_load_lds_dwordx4 v[230:231], off sc0
	s_waitcnt vmcnt(8)
	s_waitcnt lgkmcnt(0)
	s_barrier
	s_setprio 1
	s_waitcnt lgkmcnt(0)
	v_mfma_f32_16x16x32_bf16 v[126:129], v[152:155], v[184:187], v[126:129]
	v_mfma_f32_16x16x32_bf16 v[122:125], v[160:163], v[184:187], v[122:125]
	v_mfma_f32_16x16x32_bf16 v[110:113], v[152:155], v[198:201], v[110:113]
	v_mfma_f32_16x16x32_bf16 v[106:109], v[160:163], v[198:201], v[106:109]
	v_mfma_f32_16x16x32_bf16 v[94:97], v[152:155], v[214:217], v[94:97]
	v_mfma_f32_16x16x32_bf16 v[90:93], v[160:163], v[214:217], v[90:93]
	v_mfma_f32_16x16x32_bf16 v[78:81], v[152:155], v[222:225], v[78:81]
	v_mfma_f32_16x16x32_bf16 v[74:77], v[160:163], v[222:225], v[74:77]
	v_mfma_f32_16x16x32_bf16 v[126:129], v[156:159], v[188:191], v[126:129]
	v_mfma_f32_16x16x32_bf16 v[122:125], v[164:167], v[188:191], v[122:125]
	v_mfma_f32_16x16x32_bf16 v[110:113], v[156:159], v[210:213], v[110:113]
	v_mfma_f32_16x16x32_bf16 v[106:109], v[164:167], v[210:213], v[106:109]
	v_mfma_f32_16x16x32_bf16 v[94:97], v[156:159], v[218:221], v[94:97]
	v_mfma_f32_16x16x32_bf16 v[90:93], v[164:167], v[218:221], v[90:93]
	v_mfma_f32_16x16x32_bf16 v[78:81], v[156:159], v[226:229], v[78:81]
	v_mfma_f32_16x16x32_bf16 v[74:77], v[164:167], v[226:229], v[74:77]
	s_setprio 0
	s_setprio 1
	v_mfma_f32_16x16x32_bf16 v[118:121], v[168:171], v[184:187], v[118:121]
	v_mfma_f32_16x16x32_bf16 v[114:117], v[176:179], v[184:187], v[114:117]
	v_mfma_f32_16x16x32_bf16 v[102:105], v[168:171], v[198:201], v[102:105]
	v_mfma_f32_16x16x32_bf16 v[98:101], v[176:179], v[198:201], v[98:101]
	v_mfma_f32_16x16x32_bf16 v[86:89], v[168:171], v[214:217], v[86:89]
	v_mfma_f32_16x16x32_bf16 v[82:85], v[176:179], v[214:217], v[82:85]
	v_mfma_f32_16x16x32_bf16 v[70:73], v[168:171], v[222:225], v[70:73]
	v_mfma_f32_16x16x32_bf16 v[66:69], v[176:179], v[222:225], v[66:69]
	v_mfma_f32_16x16x32_bf16 v[118:121], v[172:175], v[188:191], v[118:121]
	v_mfma_f32_16x16x32_bf16 v[114:117], v[180:183], v[188:191], v[114:117]
	v_mfma_f32_16x16x32_bf16 v[102:105], v[172:175], v[210:213], v[102:105]
	v_mfma_f32_16x16x32_bf16 v[98:101], v[180:183], v[210:213], v[98:101]
	v_mfma_f32_16x16x32_bf16 v[86:89], v[172:175], v[218:221], v[86:89]
	v_mfma_f32_16x16x32_bf16 v[82:85], v[180:183], v[218:221], v[82:85]
	v_mfma_f32_16x16x32_bf16 v[70:73], v[172:175], v[226:229], v[70:73]
	v_mfma_f32_16x16x32_bf16 v[66:69], v[180:183], v[226:229], v[66:69]
	s_setprio 0
	s_barrier
	s_add_i32 s19, s19, s33
	v_lshl_add_u64 v[144:145], v[144:145], 0, s[10:11]
	s_mov_b32 m0, s19
	ds_read_b128 v[184:187], v150 offset:49152
	ds_read_b128 v[188:191], v150 offset:50176
	ds_read_b128 v[198:201], v150 offset:51200
	ds_read_b128 v[210:213], v150 offset:52224
	ds_read_b128 v[214:217], v150 offset:53248
	ds_read_b128 v[218:221], v150 offset:54272
	ds_read_b128 v[222:225], v150 offset:55296
	ds_read_b128 v[226:229], v150 offset:56320
	global_load_lds_dwordx4 v[144:145], off sc0
	s_add_i32 m0, s19, 0x2000
	s_add_u32 s34, s34, 0x80080
	v_lshl_add_u64 v[144:145], v[192:193], 0, s[10:11]
	s_addc_u32 s35, s35, 0
	s_add_i32 s19, s38, s33
	global_load_lds_dwordx4 v[144:145], off sc0
	v_lshl_add_u64 v[144:145], s[34:35], 0, v[132:133]
	s_mov_b32 m0, s19
	s_nop 0
	global_load_lds_dwordx4 v[144:145], off sc0
	v_lshl_add_u64 v[144:145], s[34:35], 0, v[136:137]
	s_add_i32 m0, s19, 0x2000
	s_nop 0
	global_load_lds_dwordx4 v[144:145], off sc0
	v_lshl_add_u64 v[144:145], v[202:203], 0, s[10:11]
	s_mov_b32 m0, s51
	s_nop 0
	global_load_lds_dwordx4 v[144:145], off sc0
	v_lshl_add_u64 v[144:145], v[206:207], 0, s[10:11]
	s_mov_b32 m0, s52
	s_nop 0
	global_load_lds_dwordx4 v[144:145], off sc0
	s_waitcnt vmcnt(8)
	s_waitcnt lgkmcnt(0)
	s_barrier
	s_setprio 1
	s_waitcnt lgkmcnt(0)
	v_mfma_f32_16x16x32_bf16 v[62:65], v[152:155], v[184:187], v[62:65]
	v_mfma_f32_16x16x32_bf16 v[58:61], v[160:163], v[184:187], v[58:61]
	v_mfma_f32_16x16x32_bf16 v[46:49], v[152:155], v[198:201], v[46:49]
	v_mfma_f32_16x16x32_bf16 v[42:45], v[160:163], v[198:201], v[42:45]
	v_mfma_f32_16x16x32_bf16 v[30:33], v[152:155], v[214:217], v[30:33]
	v_mfma_f32_16x16x32_bf16 v[26:29], v[160:163], v[214:217], v[26:29]
	v_mfma_f32_16x16x32_bf16 v[14:17], v[152:155], v[222:225], v[14:17]
	v_mfma_f32_16x16x32_bf16 v[10:13], v[160:163], v[222:225], v[10:13]
	v_mfma_f32_16x16x32_bf16 v[62:65], v[156:159], v[188:191], v[62:65]
	v_mfma_f32_16x16x32_bf16 v[58:61], v[164:167], v[188:191], v[58:61]
	v_mfma_f32_16x16x32_bf16 v[46:49], v[156:159], v[210:213], v[46:49]
	v_mfma_f32_16x16x32_bf16 v[42:45], v[164:167], v[210:213], v[42:45]
	v_mfma_f32_16x16x32_bf16 v[30:33], v[156:159], v[218:221], v[30:33]
	v_mfma_f32_16x16x32_bf16 v[26:29], v[164:167], v[218:221], v[26:29]
	v_mfma_f32_16x16x32_bf16 v[14:17], v[156:159], v[226:229], v[14:17]
	v_mfma_f32_16x16x32_bf16 v[10:13], v[164:167], v[226:229], v[10:13]
	s_setprio 0
	s_setprio 1
	v_mfma_f32_16x16x32_bf16 v[54:57], v[168:171], v[184:187], v[54:57]
	v_mfma_f32_16x16x32_bf16 v[50:53], v[176:179], v[184:187], v[50:53]
	v_mfma_f32_16x16x32_bf16 v[38:41], v[168:171], v[198:201], v[38:41]
	v_mfma_f32_16x16x32_bf16 v[34:37], v[176:179], v[198:201], v[34:37]
	v_mfma_f32_16x16x32_bf16 v[22:25], v[168:171], v[214:217], v[22:25]
	v_mfma_f32_16x16x32_bf16 v[18:21], v[176:179], v[214:217], v[18:21]
	v_mfma_f32_16x16x32_bf16 v[6:9], v[168:171], v[222:225], v[6:9]
	v_mfma_f32_16x16x32_bf16 v[2:5], v[176:179], v[222:225], v[2:5]
	v_mfma_f32_16x16x32_bf16 v[54:57], v[172:175], v[188:191], v[54:57]
	v_mfma_f32_16x16x32_bf16 v[50:53], v[180:183], v[188:191], v[50:53]
	v_mfma_f32_16x16x32_bf16 v[38:41], v[172:175], v[210:213], v[38:41]
	v_mfma_f32_16x16x32_bf16 v[34:37], v[180:183], v[210:213], v[34:37]
	v_mfma_f32_16x16x32_bf16 v[22:25], v[172:175], v[218:221], v[22:25]
	v_mfma_f32_16x16x32_bf16 v[18:21], v[180:183], v[218:221], v[18:21]
	v_mfma_f32_16x16x32_bf16 v[6:9], v[172:175], v[226:229], v[6:9]
	v_mfma_f32_16x16x32_bf16 v[2:5], v[180:183], v[226:229], v[2:5]
	s_setprio 0
	s_barrier
	s_add_u32 s30, s30, 0x100
	s_addc_u32 s31, s31, 0
	s_add_u32 s15, s15, 0x100
	s_addc_u32 s17, s17, 0
	s_cmp_ge_i32 s29, s68
	s_mov_b32 s19, s29
	s_cbranch_scc0 .LBB0_1315
	s_branch .Lpeeldone_7
.LBB0_1315:
	ds_read_b128 v[152:155], v148
	ds_read_b128 v[156:159], v148 offset:1024
	ds_read_b128 v[160:163], v148 offset:2048
	ds_read_b128 v[164:167], v148 offset:3072
	ds_read_b128 v[168:171], v149
	ds_read_b128 v[172:175], v149 offset:1024
	ds_read_b128 v[176:179], v149 offset:2048
	ds_read_b128 v[180:183], v149 offset:3072
	s_add_i32 s29, s19, 2
	s_add_u32 s34, s30, 0xfff80080
	s_addc_u32 s35, s31, -1
	s_cmp_eq_u32 s28, s19
	s_cselect_b32 s37, s21, s35
	s_cselect_b32 s36, s20, s34
	s_cselect_b32 s35, s23, s17
	s_cselect_b32 s34, s22, s15
	v_lshl_add_u64 v[144:145], s[30:31], 0, v[140:141]
	s_add_i32 m0, s27, 0xc000
	ds_read_b128 v[184:187], v150
	ds_read_b128 v[188:191], v150 offset:1024
	ds_read_b128 v[198:201], v150 offset:2048
	ds_read_b128 v[210:213], v150 offset:3072
	ds_read_b128 v[214:217], v150 offset:4096
	ds_read_b128 v[218:221], v150 offset:5120
	ds_read_b128 v[222:225], v150 offset:6144
	ds_read_b128 v[226:229], v150 offset:7168
	global_load_lds_dwordx4 v[144:145], off sc0
	v_lshl_add_u64 v[144:145], s[30:31], 0, v[142:143]
	s_add_i32 m0, s27, 0xe000
	s_nop 0
	global_load_lds_dwordx4 v[144:145], off sc0
	s_waitcnt vmcnt(8)
	s_waitcnt lgkmcnt(0)
	s_barrier
	s_setprio 1
	s_waitcnt lgkmcnt(0)
	v_mfma_f32_16x16x32_bf16 v[126:129], v[152:155], v[184:187], v[126:129]
	v_mfma_f32_16x16x32_bf16 v[122:125], v[160:163], v[184:187], v[122:125]
	v_mfma_f32_16x16x32_bf16 v[110:113], v[152:155], v[198:201], v[110:113]
	v_mfma_f32_16x16x32_bf16 v[106:109], v[160:163], v[198:201], v[106:109]
	v_mfma_f32_16x16x32_bf16 v[94:97], v[152:155], v[214:217], v[94:97]
	v_mfma_f32_16x16x32_bf16 v[90:93], v[160:163], v[214:217], v[90:93]
	v_mfma_f32_16x16x32_bf16 v[78:81], v[152:155], v[222:225], v[78:81]
	v_mfma_f32_16x16x32_bf16 v[74:77], v[160:163], v[222:225], v[74:77]
	v_mfma_f32_16x16x32_bf16 v[126:129], v[156:159], v[188:191], v[126:129]
	v_mfma_f32_16x16x32_bf16 v[122:125], v[164:167], v[188:191], v[122:125]
	v_mfma_f32_16x16x32_bf16 v[110:113], v[156:159], v[210:213], v[110:113]
	v_mfma_f32_16x16x32_bf16 v[106:109], v[164:167], v[210:213], v[106:109]
	v_mfma_f32_16x16x32_bf16 v[94:97], v[156:159], v[218:221], v[94:97]
	v_mfma_f32_16x16x32_bf16 v[90:93], v[164:167], v[218:221], v[90:93]
	v_mfma_f32_16x16x32_bf16 v[78:81], v[156:159], v[226:229], v[78:81]
	v_mfma_f32_16x16x32_bf16 v[74:77], v[164:167], v[226:229], v[74:77]
	s_setprio 0
	s_setprio 1
	v_mfma_f32_16x16x32_bf16 v[118:121], v[168:171], v[184:187], v[118:121]
	v_mfma_f32_16x16x32_bf16 v[114:117], v[176:179], v[184:187], v[114:117]
	v_mfma_f32_16x16x32_bf16 v[102:105], v[168:171], v[198:201], v[102:105]
	v_mfma_f32_16x16x32_bf16 v[98:101], v[176:179], v[198:201], v[98:101]
	v_mfma_f32_16x16x32_bf16 v[86:89], v[168:171], v[214:217], v[86:89]
	v_mfma_f32_16x16x32_bf16 v[82:85], v[176:179], v[214:217], v[82:85]
	v_mfma_f32_16x16x32_bf16 v[70:73], v[168:171], v[222:225], v[70:73]
	v_mfma_f32_16x16x32_bf16 v[66:69], v[176:179], v[222:225], v[66:69]
	v_mfma_f32_16x16x32_bf16 v[118:121], v[172:175], v[188:191], v[118:121]
	v_mfma_f32_16x16x32_bf16 v[114:117], v[180:183], v[188:191], v[114:117]
	v_mfma_f32_16x16x32_bf16 v[102:105], v[172:175], v[210:213], v[102:105]
	v_mfma_f32_16x16x32_bf16 v[98:101], v[180:183], v[210:213], v[98:101]
	v_mfma_f32_16x16x32_bf16 v[86:89], v[172:175], v[218:221], v[86:89]
	v_mfma_f32_16x16x32_bf16 v[82:85], v[180:183], v[218:221], v[82:85]
	v_mfma_f32_16x16x32_bf16 v[70:73], v[172:175], v[226:229], v[70:73]
	v_mfma_f32_16x16x32_bf16 v[66:69], v[180:183], v[226:229], v[66:69]
	s_setprio 0
	s_barrier
	s_add_i32 s19, s60, s33
	v_lshl_add_u64 v[144:145], s[34:35], 0, v[132:133]
	s_mov_b32 m0, s19
	ds_read_b128 v[184:187], v150 offset:16384
	ds_read_b128 v[188:191], v150 offset:17408
	ds_read_b128 v[198:201], v150 offset:18432
	ds_read_b128 v[210:213], v150 offset:19456
	ds_read_b128 v[214:217], v150 offset:20480
	ds_read_b128 v[218:221], v150 offset:21504
	ds_read_b128 v[222:225], v150 offset:22528
	ds_read_b128 v[226:229], v150 offset:23552
	global_load_lds_dwordx4 v[144:145], off sc0
	s_add_i32 m0, s19, 0x2000
	s_add_u32 s38, s34, 0x80000
	v_lshl_add_u64 v[192:193], s[34:35], 0, v[136:137]
	s_addc_u32 s39, s35, 0
	s_add_i32 s19, s61, s33
	global_load_lds_dwordx4 v[192:193], off sc0
	v_lshl_add_u64 v[202:203], s[38:39], 0, v[132:133]
	s_mov_b32 m0, s19
	v_lshl_add_u64 v[206:207], s[36:37], 0, v[134:135]
	global_load_lds_dwordx4 v[202:203], off sc0
	v_lshl_add_u64 v[202:203], s[38:39], 0, v[136:137]
	s_add_i32 m0, s19, 0x2000
	s_nop 0
	global_load_lds_dwordx4 v[202:203], off sc0
	v_lshl_add_u64 v[202:203], s[36:37], 0, v[130:131]
	s_mov_b32 m0, s27
	s_nop 0
	global_load_lds_dwordx4 v[202:203], off sc0
	s_mov_b32 m0, s41
	s_nop 0
	global_load_lds_dwordx4 v[206:207], off sc0
	s_waitcnt vmcnt(8)
	s_waitcnt lgkmcnt(0)
	s_barrier
	s_setprio 1
	s_waitcnt lgkmcnt(0)
	v_mfma_f32_16x16x32_bf16 v[62:65], v[152:155], v[184:187], v[62:65]
	v_mfma_f32_16x16x32_bf16 v[58:61], v[160:163], v[184:187], v[58:61]
	v_mfma_f32_16x16x32_bf16 v[46:49], v[152:155], v[198:201], v[46:49]
	v_mfma_f32_16x16x32_bf16 v[42:45], v[160:163], v[198:201], v[42:45]
	v_mfma_f32_16x16x32_bf16 v[30:33], v[152:155], v[214:217], v[30:33]
	v_mfma_f32_16x16x32_bf16 v[26:29], v[160:163], v[214:217], v[26:29]
	v_mfma_f32_16x16x32_bf16 v[14:17], v[152:155], v[222:225], v[14:17]
	v_mfma_f32_16x16x32_bf16 v[10:13], v[160:163], v[222:225], v[10:13]
	v_mfma_f32_16x16x32_bf16 v[62:65], v[156:159], v[188:191], v[62:65]
	v_mfma_f32_16x16x32_bf16 v[58:61], v[164:167], v[188:191], v[58:61]
	v_mfma_f32_16x16x32_bf16 v[46:49], v[156:159], v[210:213], v[46:49]
	v_mfma_f32_16x16x32_bf16 v[42:45], v[164:167], v[210:213], v[42:45]
	v_mfma_f32_16x16x32_bf16 v[30:33], v[156:159], v[218:221], v[30:33]
	v_mfma_f32_16x16x32_bf16 v[26:29], v[164:167], v[218:221], v[26:29]
	v_mfma_f32_16x16x32_bf16 v[14:17], v[156:159], v[226:229], v[14:17]
	v_mfma_f32_16x16x32_bf16 v[10:13], v[164:167], v[226:229], v[10:13]
	s_setprio 0
	s_setprio 1
	v_mfma_f32_16x16x32_bf16 v[54:57], v[168:171], v[184:187], v[54:57]
	v_mfma_f32_16x16x32_bf16 v[50:53], v[176:179], v[184:187], v[50:53]
	v_mfma_f32_16x16x32_bf16 v[38:41], v[168:171], v[198:201], v[38:41]
	v_mfma_f32_16x16x32_bf16 v[34:37], v[176:179], v[198:201], v[34:37]
	v_mfma_f32_16x16x32_bf16 v[22:25], v[168:171], v[214:217], v[22:25]
	v_mfma_f32_16x16x32_bf16 v[18:21], v[176:179], v[214:217], v[18:21]
	v_mfma_f32_16x16x32_bf16 v[6:9], v[168:171], v[222:225], v[6:9]
	v_mfma_f32_16x16x32_bf16 v[2:5], v[176:179], v[222:225], v[2:5]
	v_mfma_f32_16x16x32_bf16 v[54:57], v[172:175], v[188:191], v[54:57]
	v_mfma_f32_16x16x32_bf16 v[50:53], v[180:183], v[188:191], v[50:53]
	v_mfma_f32_16x16x32_bf16 v[38:41], v[172:175], v[210:213], v[38:41]
	v_mfma_f32_16x16x32_bf16 v[34:37], v[180:183], v[210:213], v[34:37]
	v_mfma_f32_16x16x32_bf16 v[22:25], v[172:175], v[218:221], v[22:25]
	v_mfma_f32_16x16x32_bf16 v[18:21], v[180:183], v[218:221], v[18:21]
	v_mfma_f32_16x16x32_bf16 v[6:9], v[172:175], v[226:229], v[6:9]
	v_mfma_f32_16x16x32_bf16 v[2:5], v[180:183], v[226:229], v[2:5]
	s_setprio 0
	s_barrier
	s_add_i32 s19, 0, 0x18000
	v_add_u32_e32 v151, s19, v146
	s_add_i32 s38, 0, 0x1c000
	ds_read_b128 v[152:155], v151
	ds_read_b128 v[156:159], v151 offset:1024
	ds_read_b128 v[160:163], v151 offset:2048
	ds_read_b128 v[164:167], v151 offset:3072
	v_add_u32_e32 v151, s38, v146
	ds_read_b128 v[168:171], v151
	ds_read_b128 v[172:175], v151 offset:1024
	ds_read_b128 v[176:179], v151 offset:2048
	ds_read_b128 v[180:183], v151 offset:3072
	s_add_u32 s36, s36, 0x80000
	s_addc_u32 s37, s37, 0
	s_mov_b32 m0, s42
	v_lshl_add_u64 v[230:231], s[36:37], 0, v[130:131]
	ds_read_b128 v[184:187], v150 offset:32768
	ds_read_b128 v[188:191], v150 offset:33792
	ds_read_b128 v[198:201], v150 offset:34816
	ds_read_b128 v[210:213], v150 offset:35840
	ds_read_b128 v[214:217], v150 offset:36864
	ds_read_b128 v[218:221], v150 offset:37888
	ds_read_b128 v[222:225], v150 offset:38912
	ds_read_b128 v[226:229], v150 offset:39936
	global_load_lds_dwordx4 v[230:231], off sc0
	v_lshl_add_u64 v[230:231], s[36:37], 0, v[134:135]
	s_mov_b32 m0, s43
	s_nop 0
	global_load_lds_dwordx4 v[230:231], off sc0
	s_waitcnt vmcnt(8)
	s_waitcnt lgkmcnt(0)
	s_barrier
	s_setprio 1
	s_waitcnt lgkmcnt(0)
	v_mfma_f32_16x16x32_bf16 v[126:129], v[152:155], v[184:187], v[126:129]
	v_mfma_f32_16x16x32_bf16 v[122:125], v[160:163], v[184:187], v[122:125]
	v_mfma_f32_16x16x32_bf16 v[110:113], v[152:155], v[198:201], v[110:113]
	v_mfma_f32_16x16x32_bf16 v[106:109], v[160:163], v[198:201], v[106:109]
	v_mfma_f32_16x16x32_bf16 v[94:97], v[152:155], v[214:217], v[94:97]
	v_mfma_f32_16x16x32_bf16 v[90:93], v[160:163], v[214:217], v[90:93]
	v_mfma_f32_16x16x32_bf16 v[78:81], v[152:155], v[222:225], v[78:81]
	v_mfma_f32_16x16x32_bf16 v[74:77], v[160:163], v[222:225], v[74:77]
	v_mfma_f32_16x16x32_bf16 v[126:129], v[156:159], v[188:191], v[126:129]
	v_mfma_f32_16x16x32_bf16 v[122:125], v[164:167], v[188:191], v[122:125]
	v_mfma_f32_16x16x32_bf16 v[110:113], v[156:159], v[210:213], v[110:113]
	v_mfma_f32_16x16x32_bf16 v[106:109], v[164:167], v[210:213], v[106:109]
	v_mfma_f32_16x16x32_bf16 v[94:97], v[156:159], v[218:221], v[94:97]
	v_mfma_f32_16x16x32_bf16 v[90:93], v[164:167], v[218:221], v[90:93]
	v_mfma_f32_16x16x32_bf16 v[78:81], v[156:159], v[226:229], v[78:81]
	v_mfma_f32_16x16x32_bf16 v[74:77], v[164:167], v[226:229], v[74:77]
	s_setprio 0
	s_setprio 1
	v_mfma_f32_16x16x32_bf16 v[118:121], v[168:171], v[184:187], v[118:121]
	v_mfma_f32_16x16x32_bf16 v[114:117], v[176:179], v[184:187], v[114:117]
	v_mfma_f32_16x16x32_bf16 v[102:105], v[168:171], v[198:201], v[102:105]
	v_mfma_f32_16x16x32_bf16 v[98:101], v[176:179], v[198:201], v[98:101]
	v_mfma_f32_16x16x32_bf16 v[86:89], v[168:171], v[214:217], v[86:89]
	v_mfma_f32_16x16x32_bf16 v[82:85], v[176:179], v[214:217], v[82:85]
	v_mfma_f32_16x16x32_bf16 v[70:73], v[168:171], v[222:225], v[70:73]
	v_mfma_f32_16x16x32_bf16 v[66:69], v[176:179], v[222:225], v[66:69]
	v_mfma_f32_16x16x32_bf16 v[118:121], v[172:175], v[188:191], v[118:121]
	v_mfma_f32_16x16x32_bf16 v[114:117], v[180:183], v[188:191], v[114:117]
	v_mfma_f32_16x16x32_bf16 v[102:105], v[172:175], v[210:213], v[102:105]
	v_mfma_f32_16x16x32_bf16 v[98:101], v[180:183], v[210:213], v[98:101]
	v_mfma_f32_16x16x32_bf16 v[86:89], v[172:175], v[218:221], v[86:89]
	v_mfma_f32_16x16x32_bf16 v[82:85], v[180:183], v[218:221], v[82:85]
	v_mfma_f32_16x16x32_bf16 v[70:73], v[172:175], v[226:229], v[70:73]
	v_mfma_f32_16x16x32_bf16 v[66:69], v[180:183], v[226:229], v[66:69]
	s_setprio 0
	s_barrier
	s_add_i32 s19, s19, s33
	v_lshl_add_u64 v[144:145], v[144:145], 0, s[10:11]
	s_mov_b32 m0, s19
	ds_read_b128 v[184:187], v150 offset:49152
	ds_read_b128 v[188:191], v150 offset:50176
	ds_read_b128 v[198:201], v150 offset:51200
	ds_read_b128 v[210:213], v150 offset:52224
	ds_read_b128 v[214:217], v150 offset:53248
	ds_read_b128 v[218:221], v150 offset:54272
	ds_read_b128 v[222:225], v150 offset:55296
	ds_read_b128 v[226:229], v150 offset:56320
	global_load_lds_dwordx4 v[144:145], off sc0
	s_add_i32 m0, s19, 0x2000
	s_add_u32 s34, s34, 0x80080
	v_lshl_add_u64 v[144:145], v[192:193], 0, s[10:11]
	s_addc_u32 s35, s35, 0
	s_add_i32 s19, s38, s33
	global_load_lds_dwordx4 v[144:145], off sc0
	v_lshl_add_u64 v[144:145], s[34:35], 0, v[132:133]
	s_mov_b32 m0, s19
	s_nop 0
	global_load_lds_dwordx4 v[144:145], off sc0
	v_lshl_add_u64 v[144:145], s[34:35], 0, v[136:137]
	s_add_i32 m0, s19, 0x2000
	s_nop 0
	global_load_lds_dwordx4 v[144:145], off sc0
	v_lshl_add_u64 v[144:145], v[202:203], 0, s[10:11]
	s_mov_b32 m0, s51
	s_nop 0
	global_load_lds_dwordx4 v[144:145], off sc0
	v_lshl_add_u64 v[144:145], v[206:207], 0, s[10:11]
	s_mov_b32 m0, s52
	s_nop 0
	global_load_lds_dwordx4 v[144:145], off sc0
	s_waitcnt vmcnt(8)
	s_waitcnt lgkmcnt(0)
	s_barrier
	s_setprio 1
	s_waitcnt lgkmcnt(0)
	v_mfma_f32_16x16x32_bf16 v[62:65], v[152:155], v[184:187], v[62:65]
	v_mfma_f32_16x16x32_bf16 v[58:61], v[160:163], v[184:187], v[58:61]
	v_mfma_f32_16x16x32_bf16 v[46:49], v[152:155], v[198:201], v[46:49]
	v_mfma_f32_16x16x32_bf16 v[42:45], v[160:163], v[198:201], v[42:45]
	v_mfma_f32_16x16x32_bf16 v[30:33], v[152:155], v[214:217], v[30:33]
	v_mfma_f32_16x16x32_bf16 v[26:29], v[160:163], v[214:217], v[26:29]
	v_mfma_f32_16x16x32_bf16 v[14:17], v[152:155], v[222:225], v[14:17]
	v_mfma_f32_16x16x32_bf16 v[10:13], v[160:163], v[222:225], v[10:13]
	v_mfma_f32_16x16x32_bf16 v[62:65], v[156:159], v[188:191], v[62:65]
	v_mfma_f32_16x16x32_bf16 v[58:61], v[164:167], v[188:191], v[58:61]
	v_mfma_f32_16x16x32_bf16 v[46:49], v[156:159], v[210:213], v[46:49]
	v_mfma_f32_16x16x32_bf16 v[42:45], v[164:167], v[210:213], v[42:45]
	v_mfma_f32_16x16x32_bf16 v[30:33], v[156:159], v[218:221], v[30:33]
	v_mfma_f32_16x16x32_bf16 v[26:29], v[164:167], v[218:221], v[26:29]
	v_mfma_f32_16x16x32_bf16 v[14:17], v[156:159], v[226:229], v[14:17]
	v_mfma_f32_16x16x32_bf16 v[10:13], v[164:167], v[226:229], v[10:13]
	s_setprio 0
	s_setprio 1
	v_mfma_f32_16x16x32_bf16 v[54:57], v[168:171], v[184:187], v[54:57]
	v_mfma_f32_16x16x32_bf16 v[50:53], v[176:179], v[184:187], v[50:53]
	v_mfma_f32_16x16x32_bf16 v[38:41], v[168:171], v[198:201], v[38:41]
	v_mfma_f32_16x16x32_bf16 v[34:37], v[176:179], v[198:201], v[34:37]
	v_mfma_f32_16x16x32_bf16 v[22:25], v[168:171], v[214:217], v[22:25]
	v_mfma_f32_16x16x32_bf16 v[18:21], v[176:179], v[214:217], v[18:21]
	v_mfma_f32_16x16x32_bf16 v[6:9], v[168:171], v[222:225], v[6:9]
	v_mfma_f32_16x16x32_bf16 v[2:5], v[176:179], v[222:225], v[2:5]
	v_mfma_f32_16x16x32_bf16 v[54:57], v[172:175], v[188:191], v[54:57]
	v_mfma_f32_16x16x32_bf16 v[50:53], v[180:183], v[188:191], v[50:53]
	v_mfma_f32_16x16x32_bf16 v[38:41], v[172:175], v[210:213], v[38:41]
	v_mfma_f32_16x16x32_bf16 v[34:37], v[180:183], v[210:213], v[34:37]
	v_mfma_f32_16x16x32_bf16 v[22:25], v[172:175], v[218:221], v[22:25]
	v_mfma_f32_16x16x32_bf16 v[18:21], v[180:183], v[218:221], v[18:21]
	v_mfma_f32_16x16x32_bf16 v[6:9], v[172:175], v[226:229], v[6:9]
	v_mfma_f32_16x16x32_bf16 v[2:5], v[180:183], v[226:229], v[2:5]
	s_setprio 0
	s_barrier
	s_add_u32 s30, s30, 0x100
	s_addc_u32 s31, s31, 0
	s_add_u32 s15, s15, 0x100
	s_addc_u32 s17, s17, 0
	s_cmp_ge_i32 s29, s68
	s_mov_b32 s19, s29
	s_cbranch_scc0 .LBB0_1315

.LBB0_1437:
	v_lshrrev_b32_e32 v4, 1, v0
	v_and_b32_e32 v14, 24, v4
	v_lshrrev_b32_e32 v4, 5, v0
	v_lshlrev_b32_e32 v2, 4, v0
	v_and_b32_e32 v1, 32, v0
	v_and_b32_e32 v4, 4, v4
	v_bfe_u32 v5, v0, 2, 2
	v_bfe_u32 v3, v0, 2, 4
	v_bitop3_b32 v12, v2, v1, 48 bitop3:0x6c
	v_and_b32_e32 v13, 64, v0
	v_or3_b32 v4, v4, v5, v14
	v_lshrrev_b32_e32 v5, 3, v0
	v_or_b32_e32 v1, v12, v13
	v_and_or_b32 v6, v5, 48, v3
	v_and_or_b32 v5, v5, 32, v4
	v_lshrrev_b32_e32 v1, 1, v1
	v_mul_u32_u24_e32 v5, 0x1600, v5
	v_or_b32_e32 v5, v5, v1
	v_lshlrev_b32_e32 v132, 1, v5
	v_bfe_u32 v5, v0, 3, 25
	v_or_b32_e32 v5, 64, v5
	s_movk_i32 s9, 0x70
	s_add_u32 s2, s82, 0xca00000
	v_and_or_b32 v3, v5, s9, v3
	s_movk_i32 s9, 0x60
	s_addc_u32 s3, s83, 0
	v_and_or_b32 v4, v5, s9, v4
	s_ashr_i32 s9, s8, 31
	s_lshr_b32 s9, s9, 29
	s_add_i32 s9, s8, s9
	s_lshr_b32 s12, s14, 6
	s_ashr_i32 s10, s9, 3
	s_and_b32 s9, s9, -8
	s_lshr_b32 s7, s14, 8
	s_lshl_b32 s33, s12, 10
	s_sub_i32 s8, s8, s9
	s_cmp_lt_i32 s8, 0
	s_cselect_b32 s9, 49, 48
	s_mul_i32 s8, s9, s8
	s_add_i32 s8, s8, s10
	s_ashr_i32 s9, s8, 31
	s_lshr_b32 s9, s9, 26
	s_add_i32 s9, s8, s9
	s_ashr_i32 s10, s9, 6
	s_lshl_b32 s10, s10, 3
	s_sub_i32 s11, 48, s10
	v_mul_u32_u24_e32 v16, 0x1600, v3
	s_min_i32 s11, s11, 8
	v_or_b32_e32 v3, v16, v1
	s_abs_i32 s13, s11
	v_lshlrev_b32_e32 v134, 1, v3
	v_cvt_f32_u32_e32 v3, s13
	v_mul_u32_u24_e32 v15, 0x1600, v6
	v_mul_u32_u24_e32 v4, 0x1600, v4
	v_or_b32_e32 v6, v1, v15
	v_or_b32_e32 v1, v4, v1
	v_lshlrev_b32_e32 v136, 1, v1
	v_rcp_iflag_f32_e32 v1, v3
	s_sub_i32 s17, 0, s13
	s_andn2_b32 s9, s9, 63
	s_sub_i32 s8, s8, s9
	v_mul_f32_e32 v1, 0x4f7ffffe, v1
	v_cvt_u32_f32_e32 v1, v1
	s_abs_i32 s15, s8
	s_xor_b32 s9, s8, s11
	s_ashr_i32 s9, s9, 31
	v_readfirstlane_b32 s18, v1
	s_mul_i32 s17, s17, s18
	s_mul_hi_u32 s17, s18, s17
	s_add_i32 s18, s18, s17
	s_mul_hi_u32 s17, s15, s18
	s_mul_i32 s18, s17, s13
	s_sub_i32 s15, s15, s18
	s_add_i32 s18, s17, 1
	s_sub_i32 s19, s15, s13
	s_cmp_ge_u32 s15, s13
	s_cselect_b32 s17, s18, s17
	s_cselect_b32 s15, s19, s15
	s_add_i32 s18, s17, 1
	s_cmp_ge_u32 s15, s13
	s_cselect_b32 s13, s18, s17
	s_xor_b32 s13, s13, s9
	s_sub_i32 s66, s13, s9
	s_mul_i32 s9, s66, s11
	s_sub_i32 s8, s8, s9
	s_add_i32 s65, s10, s8
	s_mul_i32 s9, s65, 0x2c0000
	s_mul_hi_i32 s8, s65, 0x2c0000
	s_add_u32 s10, s72, s9
	s_addc_u32 s11, s73, s8
	s_mul_i32 s9, s66, 0x2c0000
	s_mul_hi_i32 s8, s66, 0x2c0000
	s_add_u32 s9, s2, s9
	s_addc_u32 s8, s3, s8
	s_add_u32 s26, s9, s0
	s_addc_u32 s27, s8, s1
	s_add_i32 s34, s33, 0
	s_add_i32 m0, s34, 0x10000
	v_lshlrev_b32_e32 v130, 1, v6
	global_load_lds_dwordx4 v132, s[26:27] sc0
	s_add_i32 m0, s34, 0x12000
	s_add_u32 s8, s26, 0x160000
	global_load_lds_dwordx4 v136, s[26:27] sc0
	s_addc_u32 s9, s27, 0
	s_add_i32 m0, s34, 0x14000
	v_mov_b32_e32 v133, 0
	global_load_lds_dwordx4 v132, s[8:9] sc0
	s_add_i32 m0, s34, 0x16000
	s_add_u32 s24, s10, s0
	s_addc_u32 s25, s11, s1
	s_add_i32 s35, s34, 0x2000
	global_load_lds_dwordx4 v136, s[8:9] sc0
	s_mov_b32 m0, s34
	s_add_u32 s0, s24, 0x160000
	global_load_lds_dwordx4 v130, s[24:25] sc0
	s_mov_b32 m0, s35
	s_addc_u32 s1, s25, 0
	s_add_i32 s36, s34, 0x4000
	global_load_lds_dwordx4 v134, s[24:25] sc0
	s_mov_b32 m0, s36
	s_add_i32 s37, s34, 0x6000
	global_load_lds_dwordx4 v130, s[0:1] sc0
	s_mov_b32 m0, s37
	v_mov_b32_e32 v137, v133
	global_load_lds_dwordx4 v134, s[0:1] sc0
	v_mov_b32_e32 v131, v133
	v_mov_b32_e32 v135, v133
	s_cmp_eq_u32 s7, 1
	s_mov_b32 s38, 0x10000
	v_lshl_add_u64 v[10:11], s[26:27], 0, v[132:133]
	v_lshl_add_u64 v[6:7], s[26:27], 0, v[136:137]
	s_mov_b32 s39, 0x12000
	s_mov_b32 s40, 0x14000
	s_mov_b32 s41, 0x16000
	v_lshl_add_u64 v[8:9], s[24:25], 0, v[130:131]
	v_lshl_add_u64 v[4:5], s[24:25], 0, v[134:135]
	s_movk_i32 s42, 0x2000
	s_movk_i32 s43, 0x4000
	s_cselect_b64 s[8:9], -1, 0
	s_cmp_lg_u32 s7, 1
	s_movk_i32 s44, 0x6000
	s_cbranch_scc1 .LBB0_1439
	s_barrier
.LBB0_1439:
	s_add_u32 s10, s82, 0x27100000
	s_addc_u32 s11, s83, 0
	s_add_u32 s45, s82, 0x210000
	s_addc_u32 s46, s83, 0
	s_lshl_b32 s0, s12, 5
	s_mov_b64 s[12:13], 0x80
	s_and_b32 s17, s0, 0x60
	s_add_i32 m0, s34, 0x18000
	v_lshl_add_u64 v[10:11], v[10:11], 0, s[12:13]
	s_lshl_b32 s15, s7, 13
	s_lshl_b32 s18, s17, 7
	s_waitcnt vmcnt(2)
	s_barrier
	global_load_lds_dwordx4 v[10:11], off sc0
	v_lshl_add_u64 v[6:7], v[6:7], 0, s[12:13]
	s_add_i32 m0, s34, 0x1a000
	s_add_i32 s47, s34, 0x8000
	s_add_i32 s48, s34, 0xa000
	global_load_lds_dwordx4 v[6:7], off sc0
	v_lshl_add_u64 v[6:7], v[8:9], 0, s[12:13]
	s_mov_b32 m0, s47
	s_add_u32 s0, s26, 0x160080
	global_load_lds_dwordx4 v[6:7], off sc0
	v_lshl_add_u64 v[4:5], v[4:5], 0, s[12:13]
	s_mov_b32 m0, s48
	s_addc_u32 s1, s27, 0
	global_load_lds_dwordx4 v[4:5], off sc0
	s_add_i32 m0, s34, 0x1c000
	v_lshl_add_u64 v[4:5], s[0:1], 0, v[132:133]
	global_load_lds_dwordx4 v[4:5], off sc0
	v_lshl_add_u64 v[4:5], s[0:1], 0, v[136:137]
	s_add_i32 m0, s34, 0x1e000
	v_lshlrev_b32_e32 v3, 1, v14
	global_load_lds_dwordx4 v[4:5], off sc0
	v_lshl_or_b32 v4, v205, 6, v3
	v_and_b32_e32 v5, 32, v196
	v_bitop3_b32 v4, v4, s15, v5 bitop3:0xde
	s_movk_i32 s0, 0x3c0
	v_readlane_b32 s15, v249, 0
	v_and_or_b32 v3, v209, s0, v3
	s_ashr_i32 s0, s15, 31
	s_lshr_b32 s0, s0, 25
	s_add_i32 s0, s15, s0
	s_and_b32 s1, s0, 0xffffff80
	s_sub_i32 s54, s15, s1
	v_bitop3_b32 v164, s18, v3, v5 bitop3:0xf6
	s_addk_i32 s54, 0x100
	s_ashr_i32 s55, s0, 7
	v_mov_b32_e32 v3, v133
	s_waitcnt vmcnt(6)
	s_cmpk_lt_u32 s14, 0x100
	v_lshl_add_u64 v[138:139], s[78:79], 0, v[2:3]
	v_add_u16_e32 v2, v12, v13
	v_lshl_or_b32 v1, s7, 6, v205
	s_mov_b32 s7, 0
	s_cselect_b64 s[14:15], -1, 0
	s_lshr_b32 s0, s16, 2
	v_lshrrev_b16_e32 v2, 1, v2
	s_add_i32 s57, 0, 0x10000
	s_add_i32 s58, 0, 0x14000
	s_mov_b32 s49, 0x18000
	s_mov_b32 s50, 0x1a000
	s_mov_b32 s51, 0x8000
	s_mov_b32 s52, 0xa000
	s_mov_b32 s53, 0x1c000
	s_mul_i32 s55, s55, 44
	s_xor_b32 s56, s0, 1
	v_or_b32_e32 v165, s17, v14
	v_add_lshl_u32 v140, v15, v2, 1
	v_mov_b32_e32 v141, v133
	v_add_lshl_u32 v142, v16, v2, 1
	v_mov_b32_e32 v143, v133
	s_mov_b64 s[22:23], -1
	v_add_u32_e32 v166, s57, v164
	v_add_u32_e32 v167, s58, v164
	v_add_u32_e32 v168, 0, v4
	s_mov_b32 s59, 0xc000
	s_mov_b32 s60, 0xe000
	s_mov_b32 s17, s7
	s_barrier
	s_branch .LBB0_1442

.Lpeel_6:
	ds_read_b128 v[144:147], v166
	ds_read_b128 v[148:151], v166 offset:1024
	ds_read_b128 v[152:155], v166 offset:2048
	ds_read_b128 v[156:159], v166 offset:3072
	ds_read_b128 v[160:163], v167
	ds_read_b128 v[170:173], v167 offset:1024
	ds_read_b128 v[174:177], v167 offset:2048
	ds_read_b128 v[178:181], v167 offset:3072
	s_add_i32 s30, s26, 2
	s_add_u32 s27, s24, 0xffea0080
	s_addc_u32 s28, s25, -1
	s_cmp_eq_u32 s22, s26
	s_cselect_b32 s26, s20, s17
	s_cselect_b32 s29, s19, s28
	s_cselect_b32 s28, s18, s27
	s_cselect_b32 s27, s21, s23
	v_lshl_add_u64 v[202:203], s[24:25], 0, v[140:141]
	s_add_i32 m0, s34, 0xc000
	ds_read_b128 v[182:185], v168
	ds_read_b128 v[186:189], v168 offset:1024
	ds_read_b128 v[190:193], v168 offset:2048
	ds_read_b128 v[198:201], v168 offset:3072
	ds_read_b128 v[210:213], v168 offset:4096
	ds_read_b128 v[214:217], v168 offset:5120
	ds_read_b128 v[218:221], v168 offset:6144
	ds_read_b128 v[222:225], v168 offset:7168
	global_load_lds_dwordx4 v[202:203], off sc0
	v_lshl_add_u64 v[202:203], s[24:25], 0, v[142:143]
	s_add_i32 m0, s34, 0xe000
	s_nop 0
	global_load_lds_dwordx4 v[202:203], off sc0
	s_waitcnt vmcnt(8)
	s_waitcnt lgkmcnt(0)
	s_barrier
	s_setprio 1
	s_waitcnt lgkmcnt(0)
	v_mfma_f32_16x16x32_bf16 v[126:129], v[144:147], v[182:185], 0
	v_mfma_f32_16x16x32_bf16 v[122:125], v[152:155], v[182:185], 0
	v_mfma_f32_16x16x32_bf16 v[114:117], v[144:147], v[190:193], 0
	v_mfma_f32_16x16x32_bf16 v[106:109], v[152:155], v[190:193], 0
	v_mfma_f32_16x16x32_bf16 v[94:97], v[144:147], v[210:213], 0
	v_mfma_f32_16x16x32_bf16 v[90:93], v[152:155], v[210:213], 0
	v_mfma_f32_16x16x32_bf16 v[78:81], v[144:147], v[218:221], 0
	v_mfma_f32_16x16x32_bf16 v[74:77], v[152:155], v[218:221], 0
	v_mfma_f32_16x16x32_bf16 v[126:129], v[148:151], v[186:189], v[126:129]
	v_mfma_f32_16x16x32_bf16 v[122:125], v[156:159], v[186:189], v[122:125]
	v_mfma_f32_16x16x32_bf16 v[114:117], v[148:151], v[198:201], v[114:117]
	v_mfma_f32_16x16x32_bf16 v[106:109], v[156:159], v[198:201], v[106:109]
	v_mfma_f32_16x16x32_bf16 v[94:97], v[148:151], v[214:217], v[94:97]
	v_mfma_f32_16x16x32_bf16 v[90:93], v[156:159], v[214:217], v[90:93]
	v_mfma_f32_16x16x32_bf16 v[78:81], v[148:151], v[222:225], v[78:81]
	v_mfma_f32_16x16x32_bf16 v[74:77], v[156:159], v[222:225], v[74:77]
	s_setprio 0
	s_setprio 1
	v_mfma_f32_16x16x32_bf16 v[118:121], v[160:163], v[182:185], 0
	v_mfma_f32_16x16x32_bf16 v[110:113], v[174:177], v[182:185], 0
	v_mfma_f32_16x16x32_bf16 v[102:105], v[160:163], v[190:193], 0
	v_mfma_f32_16x16x32_bf16 v[98:101], v[174:177], v[190:193], 0
	v_mfma_f32_16x16x32_bf16 v[86:89], v[160:163], v[210:213], 0
	v_mfma_f32_16x16x32_bf16 v[82:85], v[174:177], v[210:213], 0
	v_mfma_f32_16x16x32_bf16 v[70:73], v[160:163], v[218:221], 0
	v_mfma_f32_16x16x32_bf16 v[66:69], v[174:177], v[218:221], 0
	v_mfma_f32_16x16x32_bf16 v[118:121], v[170:173], v[186:189], v[118:121]
	v_mfma_f32_16x16x32_bf16 v[110:113], v[178:181], v[186:189], v[110:113]
	v_mfma_f32_16x16x32_bf16 v[102:105], v[170:173], v[198:201], v[102:105]
	v_mfma_f32_16x16x32_bf16 v[98:101], v[178:181], v[198:201], v[98:101]
	v_mfma_f32_16x16x32_bf16 v[86:89], v[170:173], v[214:217], v[86:89]
	v_mfma_f32_16x16x32_bf16 v[82:85], v[178:181], v[214:217], v[82:85]
	v_mfma_f32_16x16x32_bf16 v[70:73], v[170:173], v[222:225], v[70:73]
	v_mfma_f32_16x16x32_bf16 v[66:69], v[178:181], v[222:225], v[66:69]
	s_setprio 0
	s_barrier
	s_add_i32 s31, s57, s33
	v_lshl_add_u64 v[202:203], s[26:27], 0, v[132:133]
	s_mov_b32 m0, s31
	ds_read_b128 v[182:185], v168 offset:16384
	ds_read_b128 v[186:189], v168 offset:17408
	ds_read_b128 v[190:193], v168 offset:18432
	ds_read_b128 v[198:201], v168 offset:19456
	ds_read_b128 v[210:213], v168 offset:20480
	ds_read_b128 v[214:217], v168 offset:21504
	ds_read_b128 v[218:221], v168 offset:22528
	ds_read_b128 v[222:225], v168 offset:23552
	global_load_lds_dwordx4 v[202:203], off sc0
	s_add_i32 m0, s31, 0x2000
	s_add_u32 s68, s26, 0x160000
	v_lshl_add_u64 v[206:207], s[26:27], 0, v[136:137]
	s_addc_u32 s69, s27, 0
	s_add_i32 s31, s58, s33
	global_load_lds_dwordx4 v[206:207], off sc0
	v_lshl_add_u64 v[226:227], s[68:69], 0, v[132:133]
	s_mov_b32 m0, s31
	v_lshl_add_u64 v[228:229], s[28:29], 0, v[134:135]
	global_load_lds_dwordx4 v[226:227], off sc0
	v_lshl_add_u64 v[226:227], s[68:69], 0, v[136:137]
	s_add_i32 m0, s31, 0x2000
	s_nop 0
	global_load_lds_dwordx4 v[226:227], off sc0
	v_lshl_add_u64 v[226:227], s[28:29], 0, v[130:131]
	s_mov_b32 m0, s34
	s_nop 0
	global_load_lds_dwordx4 v[226:227], off sc0
	s_mov_b32 m0, s35
	s_nop 0
	global_load_lds_dwordx4 v[228:229], off sc0
	s_waitcnt vmcnt(8)
	s_waitcnt lgkmcnt(0)
	s_barrier
	s_setprio 1
	s_waitcnt lgkmcnt(0)
	v_mfma_f32_16x16x32_bf16 v[62:65], v[144:147], v[182:185], 0
	v_mfma_f32_16x16x32_bf16 v[58:61], v[152:155], v[182:185], 0
	v_mfma_f32_16x16x32_bf16 v[46:49], v[144:147], v[190:193], 0
	v_mfma_f32_16x16x32_bf16 v[42:45], v[152:155], v[190:193], 0
	v_mfma_f32_16x16x32_bf16 v[30:33], v[144:147], v[210:213], 0
	v_mfma_f32_16x16x32_bf16 v[26:29], v[152:155], v[210:213], 0
	v_mfma_f32_16x16x32_bf16 v[14:17], v[144:147], v[218:221], 0
	v_mfma_f32_16x16x32_bf16 v[10:13], v[152:155], v[218:221], 0
	v_mfma_f32_16x16x32_bf16 v[62:65], v[148:151], v[186:189], v[62:65]
	v_mfma_f32_16x16x32_bf16 v[58:61], v[156:159], v[186:189], v[58:61]
	v_mfma_f32_16x16x32_bf16 v[46:49], v[148:151], v[198:201], v[46:49]
	v_mfma_f32_16x16x32_bf16 v[42:45], v[156:159], v[198:201], v[42:45]
	v_mfma_f32_16x16x32_bf16 v[30:33], v[148:151], v[214:217], v[30:33]
	v_mfma_f32_16x16x32_bf16 v[26:29], v[156:159], v[214:217], v[26:29]
	v_mfma_f32_16x16x32_bf16 v[14:17], v[148:151], v[222:225], v[14:17]
	v_mfma_f32_16x16x32_bf16 v[10:13], v[156:159], v[222:225], v[10:13]
	s_setprio 0
	s_setprio 1
	v_mfma_f32_16x16x32_bf16 v[54:57], v[160:163], v[182:185], 0
	v_mfma_f32_16x16x32_bf16 v[50:53], v[174:177], v[182:185], 0
	v_mfma_f32_16x16x32_bf16 v[38:41], v[160:163], v[190:193], 0
	v_mfma_f32_16x16x32_bf16 v[34:37], v[174:177], v[190:193], 0
	v_mfma_f32_16x16x32_bf16 v[22:25], v[160:163], v[210:213], 0
	v_mfma_f32_16x16x32_bf16 v[18:21], v[174:177], v[210:213], 0
	v_mfma_f32_16x16x32_bf16 v[6:9], v[160:163], v[218:221], 0
	v_mfma_f32_16x16x32_bf16 v[2:5], v[174:177], v[218:221], 0
	v_mfma_f32_16x16x32_bf16 v[54:57], v[170:173], v[186:189], v[54:57]
	v_mfma_f32_16x16x32_bf16 v[50:53], v[178:181], v[186:189], v[50:53]
	v_mfma_f32_16x16x32_bf16 v[38:41], v[170:173], v[198:201], v[38:41]
	v_mfma_f32_16x16x32_bf16 v[34:37], v[178:181], v[198:201], v[34:37]
	v_mfma_f32_16x16x32_bf16 v[22:25], v[170:173], v[214:217], v[22:25]
	v_mfma_f32_16x16x32_bf16 v[18:21], v[178:181], v[214:217], v[18:21]
	v_mfma_f32_16x16x32_bf16 v[6:9], v[170:173], v[222:225], v[6:9]
	v_mfma_f32_16x16x32_bf16 v[2:5], v[178:181], v[222:225], v[2:5]
	s_setprio 0
	s_barrier
	s_add_i32 s31, 0, 0x18000
	s_add_i32 s68, 0, 0x1c000
	v_add_u32_e32 v156, s31, v164
	v_add_u32_e32 v169, s68, v164
	ds_read_b128 v[144:147], v156
	ds_read_b128 v[148:151], v156 offset:1024
	ds_read_b128 v[152:155], v156 offset:2048
	ds_read_b128 v[156:159], v156 offset:3072
	ds_read_b128 v[160:163], v169
	ds_read_b128 v[170:173], v169 offset:1024
	ds_read_b128 v[174:177], v169 offset:2048
	ds_read_b128 v[178:181], v169 offset:3072
	s_add_u32 s28, s28, 0x160000
	s_addc_u32 s29, s29, 0
	s_mov_b32 m0, s36
	v_lshl_add_u64 v[230:231], s[28:29], 0, v[130:131]
	ds_read_b128 v[182:185], v168 offset:32768
	ds_read_b128 v[186:189], v168 offset:33792
	ds_read_b128 v[190:193], v168 offset:34816
	ds_read_b128 v[198:201], v168 offset:35840
	ds_read_b128 v[210:213], v168 offset:36864
	ds_read_b128 v[214:217], v168 offset:37888
	ds_read_b128 v[218:221], v168 offset:38912
	ds_read_b128 v[222:225], v168 offset:39936
	global_load_lds_dwordx4 v[230:231], off sc0
	v_lshl_add_u64 v[230:231], s[28:29], 0, v[134:135]
	s_mov_b32 m0, s37
	s_nop 0
	global_load_lds_dwordx4 v[230:231], off sc0
	s_waitcnt vmcnt(8)
	s_waitcnt lgkmcnt(0)
	s_barrier
	s_setprio 1
	s_waitcnt lgkmcnt(0)
	v_mfma_f32_16x16x32_bf16 v[126:129], v[144:147], v[182:185], v[126:129]
	v_mfma_f32_16x16x32_bf16 v[122:125], v[152:155], v[182:185], v[122:125]
	v_mfma_f32_16x16x32_bf16 v[114:117], v[144:147], v[190:193], v[114:117]
	v_mfma_f32_16x16x32_bf16 v[106:109], v[152:155], v[190:193], v[106:109]
	v_mfma_f32_16x16x32_bf16 v[94:97], v[144:147], v[210:213], v[94:97]
	v_mfma_f32_16x16x32_bf16 v[90:93], v[152:155], v[210:213], v[90:93]
	v_mfma_f32_16x16x32_bf16 v[78:81], v[144:147], v[218:221], v[78:81]
	v_mfma_f32_16x16x32_bf16 v[74:77], v[152:155], v[218:221], v[74:77]
	v_mfma_f32_16x16x32_bf16 v[126:129], v[148:151], v[186:189], v[126:129]
	v_mfma_f32_16x16x32_bf16 v[122:125], v[156:159], v[186:189], v[122:125]
	v_mfma_f32_16x16x32_bf16 v[114:117], v[148:151], v[198:201], v[114:117]
	v_mfma_f32_16x16x32_bf16 v[106:109], v[156:159], v[198:201], v[106:109]
	v_mfma_f32_16x16x32_bf16 v[94:97], v[148:151], v[214:217], v[94:97]
	v_mfma_f32_16x16x32_bf16 v[90:93], v[156:159], v[214:217], v[90:93]
	v_mfma_f32_16x16x32_bf16 v[78:81], v[148:151], v[222:225], v[78:81]
	v_mfma_f32_16x16x32_bf16 v[74:77], v[156:159], v[222:225], v[74:77]
	s_setprio 0
	s_setprio 1
	v_mfma_f32_16x16x32_bf16 v[118:121], v[160:163], v[182:185], v[118:121]
	v_mfma_f32_16x16x32_bf16 v[110:113], v[174:177], v[182:185], v[110:113]
	v_mfma_f32_16x16x32_bf16 v[102:105], v[160:163], v[190:193], v[102:105]
	v_mfma_f32_16x16x32_bf16 v[98:101], v[174:177], v[190:193], v[98:101]
	v_mfma_f32_16x16x32_bf16 v[86:89], v[160:163], v[210:213], v[86:89]
	v_mfma_f32_16x16x32_bf16 v[82:85], v[174:177], v[210:213], v[82:85]
	v_mfma_f32_16x16x32_bf16 v[70:73], v[160:163], v[218:221], v[70:73]
	v_mfma_f32_16x16x32_bf16 v[66:69], v[174:177], v[218:221], v[66:69]
	v_mfma_f32_16x16x32_bf16 v[118:121], v[170:173], v[186:189], v[118:121]
	v_mfma_f32_16x16x32_bf16 v[110:113], v[178:181], v[186:189], v[110:113]
	v_mfma_f32_16x16x32_bf16 v[102:105], v[170:173], v[198:201], v[102:105]
	v_mfma_f32_16x16x32_bf16 v[98:101], v[178:181], v[198:201], v[98:101]
	v_mfma_f32_16x16x32_bf16 v[86:89], v[170:173], v[214:217], v[86:89]
	v_mfma_f32_16x16x32_bf16 v[82:85], v[178:181], v[214:217], v[82:85]
	v_mfma_f32_16x16x32_bf16 v[70:73], v[170:173], v[222:225], v[70:73]
	v_mfma_f32_16x16x32_bf16 v[66:69], v[178:181], v[222:225], v[66:69]
	s_setprio 0
	s_barrier
	s_add_i32 s28, s31, s33
	v_lshl_add_u64 v[202:203], v[202:203], 0, s[12:13]
	s_mov_b32 m0, s28
	ds_read_b128 v[182:185], v168 offset:49152
	ds_read_b128 v[186:189], v168 offset:50176
	ds_read_b128 v[190:193], v168 offset:51200
	ds_read_b128 v[198:201], v168 offset:52224
	ds_read_b128 v[210:213], v168 offset:53248
	ds_read_b128 v[214:217], v168 offset:54272
	ds_read_b128 v[218:221], v168 offset:55296
	ds_read_b128 v[222:225], v168 offset:56320
	global_load_lds_dwordx4 v[202:203], off sc0
	s_add_i32 m0, s28, 0x2000
	s_add_u32 s26, s26, 0x160080
	v_lshl_add_u64 v[202:203], v[206:207], 0, s[12:13]
	s_addc_u32 s27, s27, 0
	s_add_i32 s28, s68, s33
	global_load_lds_dwordx4 v[202:203], off sc0
	v_lshl_add_u64 v[202:203], s[26:27], 0, v[132:133]
	s_mov_b32 m0, s28
	s_nop 0
	global_load_lds_dwordx4 v[202:203], off sc0
	v_lshl_add_u64 v[202:203], s[26:27], 0, v[136:137]
	s_add_i32 m0, s28, 0x2000
	s_nop 0
	global_load_lds_dwordx4 v[202:203], off sc0
	v_lshl_add_u64 v[202:203], v[226:227], 0, s[12:13]
	s_mov_b32 m0, s47
	s_nop 0
	global_load_lds_dwordx4 v[202:203], off sc0
	v_lshl_add_u64 v[202:203], v[228:229], 0, s[12:13]
	s_mov_b32 m0, s48
	s_nop 0
	global_load_lds_dwordx4 v[202:203], off sc0
	s_waitcnt vmcnt(8)
	s_waitcnt lgkmcnt(0)
	s_barrier
	s_setprio 1
	s_waitcnt lgkmcnt(0)
	v_mfma_f32_16x16x32_bf16 v[62:65], v[144:147], v[182:185], v[62:65]
	v_mfma_f32_16x16x32_bf16 v[58:61], v[152:155], v[182:185], v[58:61]
	v_mfma_f32_16x16x32_bf16 v[46:49], v[144:147], v[190:193], v[46:49]
	v_mfma_f32_16x16x32_bf16 v[42:45], v[152:155], v[190:193], v[42:45]
	v_mfma_f32_16x16x32_bf16 v[30:33], v[144:147], v[210:213], v[30:33]
	v_mfma_f32_16x16x32_bf16 v[26:29], v[152:155], v[210:213], v[26:29]
	v_mfma_f32_16x16x32_bf16 v[14:17], v[144:147], v[218:221], v[14:17]
	v_mfma_f32_16x16x32_bf16 v[10:13], v[152:155], v[218:221], v[10:13]
	v_mfma_f32_16x16x32_bf16 v[62:65], v[148:151], v[186:189], v[62:65]
	v_mfma_f32_16x16x32_bf16 v[58:61], v[156:159], v[186:189], v[58:61]
	v_mfma_f32_16x16x32_bf16 v[46:49], v[148:151], v[198:201], v[46:49]
	v_mfma_f32_16x16x32_bf16 v[42:45], v[156:159], v[198:201], v[42:45]
	v_mfma_f32_16x16x32_bf16 v[30:33], v[148:151], v[214:217], v[30:33]
	v_mfma_f32_16x16x32_bf16 v[26:29], v[156:159], v[214:217], v[26:29]
	v_mfma_f32_16x16x32_bf16 v[14:17], v[148:151], v[222:225], v[14:17]
	v_mfma_f32_16x16x32_bf16 v[10:13], v[156:159], v[222:225], v[10:13]
	s_setprio 0
	s_setprio 1
	v_mfma_f32_16x16x32_bf16 v[54:57], v[160:163], v[182:185], v[54:57]
	v_mfma_f32_16x16x32_bf16 v[50:53], v[174:177], v[182:185], v[50:53]
	v_mfma_f32_16x16x32_bf16 v[38:41], v[160:163], v[190:193], v[38:41]
	v_mfma_f32_16x16x32_bf16 v[34:37], v[174:177], v[190:193], v[34:37]
	v_mfma_f32_16x16x32_bf16 v[22:25], v[160:163], v[210:213], v[22:25]
	v_mfma_f32_16x16x32_bf16 v[18:21], v[174:177], v[210:213], v[18:21]
	v_mfma_f32_16x16x32_bf16 v[6:9], v[160:163], v[218:221], v[6:9]
	v_mfma_f32_16x16x32_bf16 v[2:5], v[174:177], v[218:221], v[2:5]
	v_mfma_f32_16x16x32_bf16 v[54:57], v[170:173], v[186:189], v[54:57]
	v_mfma_f32_16x16x32_bf16 v[50:53], v[178:181], v[186:189], v[50:53]
	v_mfma_f32_16x16x32_bf16 v[38:41], v[170:173], v[198:201], v[38:41]
	v_mfma_f32_16x16x32_bf16 v[34:37], v[178:181], v[198:201], v[34:37]
	v_mfma_f32_16x16x32_bf16 v[22:25], v[170:173], v[214:217], v[22:25]
	v_mfma_f32_16x16x32_bf16 v[18:21], v[178:181], v[214:217], v[18:21]
	v_mfma_f32_16x16x32_bf16 v[6:9], v[170:173], v[222:225], v[6:9]
	v_mfma_f32_16x16x32_bf16 v[2:5], v[178:181], v[222:225], v[2:5]
	s_setprio 0
	s_barrier
	s_add_u32 s24, s24, 0x100
	s_addc_u32 s25, s25, 0
	s_add_u32 s17, s17, 0x100
	s_addc_u32 s23, s23, 0
	s_cmp_ge_i32 s30, s67
	s_mov_b32 s26, s30
	s_cbranch_scc0 .LBB0_1451
	s_branch .Lpeeldone_6
.LBB0_1451:
	ds_read_b128 v[144:147], v166
	ds_read_b128 v[148:151], v166 offset:1024
	ds_read_b128 v[152:155], v166 offset:2048
	ds_read_b128 v[156:159], v166 offset:3072
	ds_read_b128 v[160:163], v167
	ds_read_b128 v[170:173], v167 offset:1024
	ds_read_b128 v[174:177], v167 offset:2048
	ds_read_b128 v[178:181], v167 offset:3072
	s_add_i32 s30, s26, 2
	s_add_u32 s27, s24, 0xffea0080
	s_addc_u32 s28, s25, -1
	s_cmp_eq_u32 s22, s26
	s_cselect_b32 s26, s20, s17
	s_cselect_b32 s29, s19, s28
	s_cselect_b32 s28, s18, s27
	s_cselect_b32 s27, s21, s23
	v_lshl_add_u64 v[202:203], s[24:25], 0, v[140:141]
	s_add_i32 m0, s34, 0xc000
	ds_read_b128 v[182:185], v168
	ds_read_b128 v[186:189], v168 offset:1024
	ds_read_b128 v[190:193], v168 offset:2048
	ds_read_b128 v[198:201], v168 offset:3072
	ds_read_b128 v[210:213], v168 offset:4096
	ds_read_b128 v[214:217], v168 offset:5120
	ds_read_b128 v[218:221], v168 offset:6144
	ds_read_b128 v[222:225], v168 offset:7168
	global_load_lds_dwordx4 v[202:203], off sc0
	v_lshl_add_u64 v[202:203], s[24:25], 0, v[142:143]
	s_add_i32 m0, s34, 0xe000
	s_nop 0
	global_load_lds_dwordx4 v[202:203], off sc0
	s_waitcnt vmcnt(8)
	s_waitcnt lgkmcnt(0)
	s_barrier
	s_setprio 1
	s_waitcnt lgkmcnt(0)
	v_mfma_f32_16x16x32_bf16 v[126:129], v[144:147], v[182:185], v[126:129]
	v_mfma_f32_16x16x32_bf16 v[122:125], v[152:155], v[182:185], v[122:125]
	v_mfma_f32_16x16x32_bf16 v[114:117], v[144:147], v[190:193], v[114:117]
	v_mfma_f32_16x16x32_bf16 v[106:109], v[152:155], v[190:193], v[106:109]
	v_mfma_f32_16x16x32_bf16 v[94:97], v[144:147], v[210:213], v[94:97]
	v_mfma_f32_16x16x32_bf16 v[90:93], v[152:155], v[210:213], v[90:93]
	v_mfma_f32_16x16x32_bf16 v[78:81], v[144:147], v[218:221], v[78:81]
	v_mfma_f32_16x16x32_bf16 v[74:77], v[152:155], v[218:221], v[74:77]
	v_mfma_f32_16x16x32_bf16 v[126:129], v[148:151], v[186:189], v[126:129]
	v_mfma_f32_16x16x32_bf16 v[122:125], v[156:159], v[186:189], v[122:125]
	v_mfma_f32_16x16x32_bf16 v[114:117], v[148:151], v[198:201], v[114:117]
	v_mfma_f32_16x16x32_bf16 v[106:109], v[156:159], v[198:201], v[106:109]
	v_mfma_f32_16x16x32_bf16 v[94:97], v[148:151], v[214:217], v[94:97]
	v_mfma_f32_16x16x32_bf16 v[90:93], v[156:159], v[214:217], v[90:93]
	v_mfma_f32_16x16x32_bf16 v[78:81], v[148:151], v[222:225], v[78:81]
	v_mfma_f32_16x16x32_bf16 v[74:77], v[156:159], v[222:225], v[74:77]
	s_setprio 0
	s_setprio 1
	v_mfma_f32_16x16x32_bf16 v[118:121], v[160:163], v[182:185], v[118:121]
	v_mfma_f32_16x16x32_bf16 v[110:113], v[174:177], v[182:185], v[110:113]
	v_mfma_f32_16x16x32_bf16 v[102:105], v[160:163], v[190:193], v[102:105]
	v_mfma_f32_16x16x32_bf16 v[98:101], v[174:177], v[190:193], v[98:101]
	v_mfma_f32_16x16x32_bf16 v[86:89], v[160:163], v[210:213], v[86:89]
	v_mfma_f32_16x16x32_bf16 v[82:85], v[174:177], v[210:213], v[82:85]
	v_mfma_f32_16x16x32_bf16 v[70:73], v[160:163], v[218:221], v[70:73]
	v_mfma_f32_16x16x32_bf16 v[66:69], v[174:177], v[218:221], v[66:69]
	v_mfma_f32_16x16x32_bf16 v[118:121], v[170:173], v[186:189], v[118:121]
	v_mfma_f32_16x16x32_bf16 v[110:113], v[178:181], v[186:189], v[110:113]
	v_mfma_f32_16x16x32_bf16 v[102:105], v[170:173], v[198:201], v[102:105]
	v_mfma_f32_16x16x32_bf16 v[98:101], v[178:181], v[198:201], v[98:101]
	v_mfma_f32_16x16x32_bf16 v[86:89], v[170:173], v[214:217], v[86:89]
	v_mfma_f32_16x16x32_bf16 v[82:85], v[178:181], v[214:217], v[82:85]
	v_mfma_f32_16x16x32_bf16 v[70:73], v[170:173], v[222:225], v[70:73]
	v_mfma_f32_16x16x32_bf16 v[66:69], v[178:181], v[222:225], v[66:69]
	s_setprio 0
	s_barrier
	s_add_i32 s31, s57, s33
	v_lshl_add_u64 v[202:203], s[26:27], 0, v[132:133]
	s_mov_b32 m0, s31
	ds_read_b128 v[182:185], v168 offset:16384
	ds_read_b128 v[186:189], v168 offset:17408
	ds_read_b128 v[190:193], v168 offset:18432
	ds_read_b128 v[198:201], v168 offset:19456
	ds_read_b128 v[210:213], v168 offset:20480
	ds_read_b128 v[214:217], v168 offset:21504
	ds_read_b128 v[218:221], v168 offset:22528
	ds_read_b128 v[222:225], v168 offset:23552
	global_load_lds_dwordx4 v[202:203], off sc0
	s_add_i32 m0, s31, 0x2000
	s_add_u32 s68, s26, 0x160000
	v_lshl_add_u64 v[206:207], s[26:27], 0, v[136:137]
	s_addc_u32 s69, s27, 0
	s_add_i32 s31, s58, s33
	global_load_lds_dwordx4 v[206:207], off sc0
	v_lshl_add_u64 v[226:227], s[68:69], 0, v[132:133]
	s_mov_b32 m0, s31
	v_lshl_add_u64 v[228:229], s[28:29], 0, v[134:135]
	global_load_lds_dwordx4 v[226:227], off sc0
	v_lshl_add_u64 v[226:227], s[68:69], 0, v[136:137]
	s_add_i32 m0, s31, 0x2000
	s_nop 0
	global_load_lds_dwordx4 v[226:227], off sc0
	v_lshl_add_u64 v[226:227], s[28:29], 0, v[130:131]
	s_mov_b32 m0, s34
	s_nop 0
	global_load_lds_dwordx4 v[226:227], off sc0
	s_mov_b32 m0, s35
	s_nop 0
	global_load_lds_dwordx4 v[228:229], off sc0
	s_waitcnt vmcnt(8)
	s_waitcnt lgkmcnt(0)
	s_barrier
	s_setprio 1
	s_waitcnt lgkmcnt(0)
	v_mfma_f32_16x16x32_bf16 v[62:65], v[144:147], v[182:185], v[62:65]
	v_mfma_f32_16x16x32_bf16 v[58:61], v[152:155], v[182:185], v[58:61]
	v_mfma_f32_16x16x32_bf16 v[46:49], v[144:147], v[190:193], v[46:49]
	v_mfma_f32_16x16x32_bf16 v[42:45], v[152:155], v[190:193], v[42:45]
	v_mfma_f32_16x16x32_bf16 v[30:33], v[144:147], v[210:213], v[30:33]
	v_mfma_f32_16x16x32_bf16 v[26:29], v[152:155], v[210:213], v[26:29]
	v_mfma_f32_16x16x32_bf16 v[14:17], v[144:147], v[218:221], v[14:17]
	v_mfma_f32_16x16x32_bf16 v[10:13], v[152:155], v[218:221], v[10:13]
	v_mfma_f32_16x16x32_bf16 v[62:65], v[148:151], v[186:189], v[62:65]
	v_mfma_f32_16x16x32_bf16 v[58:61], v[156:159], v[186:189], v[58:61]
	v_mfma_f32_16x16x32_bf16 v[46:49], v[148:151], v[198:201], v[46:49]
	v_mfma_f32_16x16x32_bf16 v[42:45], v[156:159], v[198:201], v[42:45]
	v_mfma_f32_16x16x32_bf16 v[30:33], v[148:151], v[214:217], v[30:33]
	v_mfma_f32_16x16x32_bf16 v[26:29], v[156:159], v[214:217], v[26:29]
	v_mfma_f32_16x16x32_bf16 v[14:17], v[148:151], v[222:225], v[14:17]
	v_mfma_f32_16x16x32_bf16 v[10:13], v[156:159], v[222:225], v[10:13]
	s_setprio 0
	s_setprio 1
	v_mfma_f32_16x16x32_bf16 v[54:57], v[160:163], v[182:185], v[54:57]
	v_mfma_f32_16x16x32_bf16 v[50:53], v[174:177], v[182:185], v[50:53]
	v_mfma_f32_16x16x32_bf16 v[38:41], v[160:163], v[190:193], v[38:41]
	v_mfma_f32_16x16x32_bf16 v[34:37], v[174:177], v[190:193], v[34:37]
	v_mfma_f32_16x16x32_bf16 v[22:25], v[160:163], v[210:213], v[22:25]
	v_mfma_f32_16x16x32_bf16 v[18:21], v[174:177], v[210:213], v[18:21]
	v_mfma_f32_16x16x32_bf16 v[6:9], v[160:163], v[218:221], v[6:9]
	v_mfma_f32_16x16x32_bf16 v[2:5], v[174:177], v[218:221], v[2:5]
	v_mfma_f32_16x16x32_bf16 v[54:57], v[170:173], v[186:189], v[54:57]
	v_mfma_f32_16x16x32_bf16 v[50:53], v[178:181], v[186:189], v[50:53]
	v_mfma_f32_16x16x32_bf16 v[38:41], v[170:173], v[198:201], v[38:41]
	v_mfma_f32_16x16x32_bf16 v[34:37], v[178:181], v[198:201], v[34:37]
	v_mfma_f32_16x16x32_bf16 v[22:25], v[170:173], v[214:217], v[22:25]
	v_mfma_f32_16x16x32_bf16 v[18:21], v[178:181], v[214:217], v[18:21]
	v_mfma_f32_16x16x32_bf16 v[6:9], v[170:173], v[222:225], v[6:9]
	v_mfma_f32_16x16x32_bf16 v[2:5], v[178:181], v[222:225], v[2:5]
	s_setprio 0
	s_barrier
	s_add_i32 s31, 0, 0x18000
	s_add_i32 s68, 0, 0x1c000
	v_add_u32_e32 v156, s31, v164
	v_add_u32_e32 v169, s68, v164
	ds_read_b128 v[144:147], v156
	ds_read_b128 v[148:151], v156 offset:1024
	ds_read_b128 v[152:155], v156 offset:2048
	ds_read_b128 v[156:159], v156 offset:3072
	ds_read_b128 v[160:163], v169
	ds_read_b128 v[170:173], v169 offset:1024
	ds_read_b128 v[174:177], v169 offset:2048
	ds_read_b128 v[178:181], v169 offset:3072
	s_add_u32 s28, s28, 0x160000
	s_addc_u32 s29, s29, 0
	s_mov_b32 m0, s36
	v_lshl_add_u64 v[230:231], s[28:29], 0, v[130:131]
	ds_read_b128 v[182:185], v168 offset:32768
	ds_read_b128 v[186:189], v168 offset:33792
	ds_read_b128 v[190:193], v168 offset:34816
	ds_read_b128 v[198:201], v168 offset:35840
	ds_read_b128 v[210:213], v168 offset:36864
	ds_read_b128 v[214:217], v168 offset:37888
	ds_read_b128 v[218:221], v168 offset:38912
	ds_read_b128 v[222:225], v168 offset:39936
	global_load_lds_dwordx4 v[230:231], off sc0
	v_lshl_add_u64 v[230:231], s[28:29], 0, v[134:135]
	s_mov_b32 m0, s37
	s_nop 0
	global_load_lds_dwordx4 v[230:231], off sc0
	s_waitcnt vmcnt(8)
	s_waitcnt lgkmcnt(0)
	s_barrier
	s_setprio 1
	s_waitcnt lgkmcnt(0)
	v_mfma_f32_16x16x32_bf16 v[126:129], v[144:147], v[182:185], v[126:129]
	v_mfma_f32_16x16x32_bf16 v[122:125], v[152:155], v[182:185], v[122:125]
	v_mfma_f32_16x16x32_bf16 v[114:117], v[144:147], v[190:193], v[114:117]
	v_mfma_f32_16x16x32_bf16 v[106:109], v[152:155], v[190:193], v[106:109]
	v_mfma_f32_16x16x32_bf16 v[94:97], v[144:147], v[210:213], v[94:97]
	v_mfma_f32_16x16x32_bf16 v[90:93], v[152:155], v[210:213], v[90:93]
	v_mfma_f32_16x16x32_bf16 v[78:81], v[144:147], v[218:221], v[78:81]
	v_mfma_f32_16x16x32_bf16 v[74:77], v[152:155], v[218:221], v[74:77]
	v_mfma_f32_16x16x32_bf16 v[126:129], v[148:151], v[186:189], v[126:129]
	v_mfma_f32_16x16x32_bf16 v[122:125], v[156:159], v[186:189], v[122:125]
	v_mfma_f32_16x16x32_bf16 v[114:117], v[148:151], v[198:201], v[114:117]
	v_mfma_f32_16x16x32_bf16 v[106:109], v[156:159], v[198:201], v[106:109]
	v_mfma_f32_16x16x32_bf16 v[94:97], v[148:151], v[214:217], v[94:97]
	v_mfma_f32_16x16x32_bf16 v[90:93], v[156:159], v[214:217], v[90:93]
	v_mfma_f32_16x16x32_bf16 v[78:81], v[148:151], v[222:225], v[78:81]
	v_mfma_f32_16x16x32_bf16 v[74:77], v[156:159], v[222:225], v[74:77]
	s_setprio 0
	s_setprio 1
	v_mfma_f32_16x16x32_bf16 v[118:121], v[160:163], v[182:185], v[118:121]
	v_mfma_f32_16x16x32_bf16 v[110:113], v[174:177], v[182:185], v[110:113]
	v_mfma_f32_16x16x32_bf16 v[102:105], v[160:163], v[190:193], v[102:105]
	v_mfma_f32_16x16x32_bf16 v[98:101], v[174:177], v[190:193], v[98:101]
	v_mfma_f32_16x16x32_bf16 v[86:89], v[160:163], v[210:213], v[86:89]
	v_mfma_f32_16x16x32_bf16 v[82:85], v[174:177], v[210:213], v[82:85]
	v_mfma_f32_16x16x32_bf16 v[70:73], v[160:163], v[218:221], v[70:73]
	v_mfma_f32_16x16x32_bf16 v[66:69], v[174:177], v[218:221], v[66:69]
	v_mfma_f32_16x16x32_bf16 v[118:121], v[170:173], v[186:189], v[118:121]
	v_mfma_f32_16x16x32_bf16 v[110:113], v[178:181], v[186:189], v[110:113]
	v_mfma_f32_16x16x32_bf16 v[102:105], v[170:173], v[198:201], v[102:105]
	v_mfma_f32_16x16x32_bf16 v[98:101], v[178:181], v[198:201], v[98:101]
	v_mfma_f32_16x16x32_bf16 v[86:89], v[170:173], v[214:217], v[86:89]
	v_mfma_f32_16x16x32_bf16 v[82:85], v[178:181], v[214:217], v[82:85]
	v_mfma_f32_16x16x32_bf16 v[70:73], v[170:173], v[222:225], v[70:73]
	v_mfma_f32_16x16x32_bf16 v[66:69], v[178:181], v[222:225], v[66:69]
	s_setprio 0
	s_barrier
	s_add_i32 s28, s31, s33
	v_lshl_add_u64 v[202:203], v[202:203], 0, s[12:13]
	s_mov_b32 m0, s28
	ds_read_b128 v[182:185], v168 offset:49152
	ds_read_b128 v[186:189], v168 offset:50176
	ds_read_b128 v[190:193], v168 offset:51200
	ds_read_b128 v[198:201], v168 offset:52224
	ds_read_b128 v[210:213], v168 offset:53248
	ds_read_b128 v[214:217], v168 offset:54272
	ds_read_b128 v[218:221], v168 offset:55296
	ds_read_b128 v[222:225], v168 offset:56320
	global_load_lds_dwordx4 v[202:203], off sc0
	s_add_i32 m0, s28, 0x2000
	s_add_u32 s26, s26, 0x160080
	v_lshl_add_u64 v[202:203], v[206:207], 0, s[12:13]
	s_addc_u32 s27, s27, 0
	s_add_i32 s28, s68, s33
	global_load_lds_dwordx4 v[202:203], off sc0
	v_lshl_add_u64 v[202:203], s[26:27], 0, v[132:133]
	s_mov_b32 m0, s28
	s_nop 0
	global_load_lds_dwordx4 v[202:203], off sc0
	v_lshl_add_u64 v[202:203], s[26:27], 0, v[136:137]
	s_add_i32 m0, s28, 0x2000
	s_nop 0
	global_load_lds_dwordx4 v[202:203], off sc0
	v_lshl_add_u64 v[202:203], v[226:227], 0, s[12:13]
	s_mov_b32 m0, s47
	s_nop 0
	global_load_lds_dwordx4 v[202:203], off sc0
	v_lshl_add_u64 v[202:203], v[228:229], 0, s[12:13]
	s_mov_b32 m0, s48
	s_nop 0
	global_load_lds_dwordx4 v[202:203], off sc0
	s_waitcnt vmcnt(8)
	s_waitcnt lgkmcnt(0)
	s_barrier
	s_setprio 1
	s_waitcnt lgkmcnt(0)
	v_mfma_f32_16x16x32_bf16 v[62:65], v[144:147], v[182:185], v[62:65]
	v_mfma_f32_16x16x32_bf16 v[58:61], v[152:155], v[182:185], v[58:61]
	v_mfma_f32_16x16x32_bf16 v[46:49], v[144:147], v[190:193], v[46:49]
	v_mfma_f32_16x16x32_bf16 v[42:45], v[152:155], v[190:193], v[42:45]
	v_mfma_f32_16x16x32_bf16 v[30:33], v[144:147], v[210:213], v[30:33]
	v_mfma_f32_16x16x32_bf16 v[26:29], v[152:155], v[210:213], v[26:29]
	v_mfma_f32_16x16x32_bf16 v[14:17], v[144:147], v[218:221], v[14:17]
	v_mfma_f32_16x16x32_bf16 v[10:13], v[152:155], v[218:221], v[10:13]
	v_mfma_f32_16x16x32_bf16 v[62:65], v[148:151], v[186:189], v[62:65]
	v_mfma_f32_16x16x32_bf16 v[58:61], v[156:159], v[186:189], v[58:61]
	v_mfma_f32_16x16x32_bf16 v[46:49], v[148:151], v[198:201], v[46:49]
	v_mfma_f32_16x16x32_bf16 v[42:45], v[156:159], v[198:201], v[42:45]
	v_mfma_f32_16x16x32_bf16 v[30:33], v[148:151], v[214:217], v[30:33]
	v_mfma_f32_16x16x32_bf16 v[26:29], v[156:159], v[214:217], v[26:29]
	v_mfma_f32_16x16x32_bf16 v[14:17], v[148:151], v[222:225], v[14:17]
	v_mfma_f32_16x16x32_bf16 v[10:13], v[156:159], v[222:225], v[10:13]
	s_setprio 0
	s_setprio 1
	v_mfma_f32_16x16x32_bf16 v[54:57], v[160:163], v[182:185], v[54:57]
	v_mfma_f32_16x16x32_bf16 v[50:53], v[174:177], v[182:185], v[50:53]
	v_mfma_f32_16x16x32_bf16 v[38:41], v[160:163], v[190:193], v[38:41]
	v_mfma_f32_16x16x32_bf16 v[34:37], v[174:177], v[190:193], v[34:37]
	v_mfma_f32_16x16x32_bf16 v[22:25], v[160:163], v[210:213], v[22:25]
	v_mfma_f32_16x16x32_bf16 v[18:21], v[174:177], v[210:213], v[18:21]
	v_mfma_f32_16x16x32_bf16 v[6:9], v[160:163], v[218:221], v[6:9]
	v_mfma_f32_16x16x32_bf16 v[2:5], v[174:177], v[218:221], v[2:5]
	v_mfma_f32_16x16x32_bf16 v[54:57], v[170:173], v[186:189], v[54:57]
	v_mfma_f32_16x16x32_bf16 v[50:53], v[178:181], v[186:189], v[50:53]
	v_mfma_f32_16x16x32_bf16 v[38:41], v[170:173], v[198:201], v[38:41]
	v_mfma_f32_16x16x32_bf16 v[34:37], v[178:181], v[198:201], v[34:37]
	v_mfma_f32_16x16x32_bf16 v[22:25], v[170:173], v[214:217], v[22:25]
	v_mfma_f32_16x16x32_bf16 v[18:21], v[178:181], v[214:217], v[18:21]
	v_mfma_f32_16x16x32_bf16 v[6:9], v[170:173], v[222:225], v[6:9]
	v_mfma_f32_16x16x32_bf16 v[2:5], v[178:181], v[222:225], v[2:5]
	s_setprio 0
	s_barrier
	s_add_u32 s24, s24, 0x100
	s_addc_u32 s25, s25, 0
	s_add_u32 s17, s17, 0x100
	s_addc_u32 s23, s23, 0
	s_cmp_ge_i32 s30, s67
	s_mov_b32 s26, s30
	s_cbranch_scc0 .LBB0_1451

.LBB0_1629:
	v_lshrrev_b32_e32 v3, 1, v0
	v_and_b32_e32 v15, 24, v3
	v_lshrrev_b32_e32 v3, 5, v0
	s_add_u32 s2, s82, 0x5c00000
	v_lshlrev_b32_e32 v2, 4, v0
	v_and_b32_e32 v1, 32, v0
	v_and_b32_e32 v3, 4, v3
	v_bfe_u32 v4, v0, 2, 2
	s_addc_u32 s3, s83, 0
	v_bfe_u32 v14, v0, 2, 4
	v_bitop3_b32 v12, v2, v1, 48 bitop3:0x6c
	v_and_b32_e32 v13, 64, v0
	v_or3_b32 v3, v3, v4, v15
	v_lshrrev_b32_e32 v4, 3, v0
	s_ashr_i32 s14, s11, 31
	v_or_b32_e32 v1, v12, v13
	v_and_or_b32 v5, v4, 48, v14
	v_and_or_b32 v4, v4, 32, v3
	v_or_b32_e32 v16, 0x2000, v2
	s_lshr_b32 s14, s14, 29
	v_lshl_or_b32 v132, v4, 12, v1
	v_lshrrev_b32_e32 v4, 7, v16
	s_movk_i32 s10, 0x70
	s_add_i32 s14, s11, s14
	v_lshl_or_b32 v130, v5, 12, v1
	v_and_or_b32 v5, v4, s10, v14
	s_lshr_b32 s10, s12, 6
	s_ashr_i32 s15, s14, 3
	s_and_b32 s14, s14, -8
	s_lshr_b32 s7, s12, 8
	s_lshl_b32 s33, s10, 10
	s_sub_i32 s11, s11, s14
	s_cmp_lt_i32 s11, 0
	s_movk_i32 s40, 0x109
	s_cselect_b32 s14, s40, 0x108
	s_mul_i32 s11, s14, s11
	s_add_i32 s11, s11, s15
	s_mul_hi_i32 s14, s11, 0x2e8ba2e9
	s_lshr_b32 s15, s14, 31
	s_ashr_i32 s14, s14, 6
	s_add_i32 s14, s14, s15
	s_lshl_b32 s15, s14, 3
	s_sub_i32 s16, 48, s15
	s_min_i32 s16, s16, 8
	s_abs_i32 s17, s16
	v_cvt_f32_u32_e32 v6, s17
	s_movk_i32 s13, 0x60
	v_and_or_b32 v3, v4, s13, v3
	v_lshl_or_b32 v134, v5, 12, v1
	v_lshl_or_b32 v136, v3, 12, v1
	v_rcp_iflag_f32_e32 v1, v6
	s_sub_i32 s18, 0, s17
	s_mulk_i32 s14, 0x160
	s_sub_i32 s11, s11, s14
	v_mul_f32_e32 v1, 0x4f7ffffe, v1
	v_cvt_u32_f32_e32 v1, v1
	s_abs_i32 s14, s11
	s_xor_b32 s13, s11, s16
	s_ashr_i32 s13, s13, 31
	v_readfirstlane_b32 s19, v1
	s_mul_i32 s18, s18, s19
	s_mul_hi_u32 s18, s19, s18
	s_add_i32 s19, s19, s18
	s_mul_hi_u32 s18, s14, s19
	s_mul_i32 s19, s18, s17
	s_sub_i32 s14, s14, s19
	s_add_i32 s19, s18, 1
	s_sub_i32 s20, s14, s17
	s_cmp_ge_u32 s14, s17
	s_cselect_b32 s18, s19, s18
	s_cselect_b32 s14, s20, s14
	s_add_i32 s19, s18, 1
	s_cmp_ge_u32 s14, s17
	s_cselect_b32 s14, s19, s18
	s_xor_b32 s14, s14, s13
	s_sub_i32 s26, s14, s13
	s_mul_i32 s13, s26, s16
	s_sub_i32 s11, s11, s13
	s_add_i32 s24, s15, s11
	s_ashr_i32 s25, s24, 31
	s_lshl_b64 s[14:15], s[24:25], 20
	v_readlane_b32 s16, v249, 50
	v_readlane_b32 s17, v249, 51
	s_add_u32 s11, s16, s14
	s_addc_u32 s13, s17, s15
	s_ashr_i32 s27, s26, 31
	s_lshl_b64 s[14:15], s[26:27], 20
	s_add_u32 s14, s2, s14
	s_addc_u32 s15, s3, s15
	s_add_u32 s34, s14, s8
	s_addc_u32 s35, s15, s9
	s_add_i32 s27, s33, 0
	s_add_i32 m0, s27, 0x10000
	v_mov_b32_e32 v133, 0
	global_load_lds_dwordx4 v132, s[34:35] sc0
	s_add_i32 m0, s27, 0x12000
	s_add_u32 s14, s34, 0x80000
	global_load_lds_dwordx4 v136, s[34:35] sc0
	s_addc_u32 s15, s35, 0
	s_add_i32 m0, s27, 0x14000
	v_mov_b32_e32 v137, v133
	global_load_lds_dwordx4 v132, s[14:15] sc0
	s_add_i32 m0, s27, 0x16000
	s_add_u32 s30, s11, s8
	s_addc_u32 s31, s13, s9
	s_add_i32 s41, s27, 0x2000
	global_load_lds_dwordx4 v136, s[14:15] sc0
	s_mov_b32 m0, s27
	s_add_u32 s8, s30, 0x80000
	global_load_lds_dwordx4 v130, s[30:31] sc0
	s_mov_b32 m0, s41
	s_addc_u32 s9, s31, 0
	s_add_i32 s42, s27, 0x4000
	global_load_lds_dwordx4 v134, s[30:31] sc0
	s_mov_b32 m0, s42
	s_add_i32 s43, s27, 0x6000
	global_load_lds_dwordx4 v130, s[8:9] sc0
	s_mov_b32 m0, s43
	v_mov_b32_e32 v131, v133
	global_load_lds_dwordx4 v134, s[8:9] sc0
	v_mov_b32_e32 v135, v133
	s_cmp_eq_u32 s7, 1
	s_movk_i32 s44, 0x2000
	s_mov_b32 s45, 0x10000
	v_lshl_add_u64 v[10:11], s[34:35], 0, v[132:133]
	v_lshl_add_u64 v[6:7], s[34:35], 0, v[136:137]
	s_mov_b32 s46, 0x12000
	s_mov_b32 s47, 0x14000
	s_mov_b32 s48, 0x16000
	v_lshl_add_u64 v[8:9], s[30:31], 0, v[130:131]
	v_lshl_add_u64 v[4:5], s[30:31], 0, v[134:135]
	s_movk_i32 s49, 0x4000
	s_cselect_b64 s[8:9], -1, 0
	s_cmp_lg_u32 s7, 1
	s_movk_i32 s50, 0x6000
	s_cbranch_scc1 .LBB0_1631
	s_barrier

.LBB0_1766:
	v_lshrrev_b32_e32 v4, 1, v0
	v_and_b32_e32 v14, 24, v4
	v_lshrrev_b32_e32 v4, 5, v0
	v_lshlrev_b32_e32 v2, 4, v0
	v_and_b32_e32 v1, 32, v0
	v_and_b32_e32 v4, 4, v4
	v_bfe_u32 v5, v0, 2, 2
	v_bfe_u32 v3, v0, 2, 4
	v_bitop3_b32 v12, v2, v1, 48 bitop3:0x6c
	v_and_b32_e32 v13, 64, v0
	v_or3_b32 v4, v4, v5, v14
	v_lshrrev_b32_e32 v5, 3, v0
	v_or_b32_e32 v1, v12, v13
	v_and_or_b32 v6, v5, 48, v3
	v_and_or_b32 v5, v5, 32, v4
	v_lshrrev_b32_e32 v1, 1, v1
	v_mul_u32_u24_e32 v5, 0x1600, v5
	v_or_b32_e32 v5, v5, v1
	v_lshlrev_b32_e32 v132, 1, v5
	v_bfe_u32 v5, v0, 3, 25
	v_or_b32_e32 v5, 64, v5
	s_movk_i32 s9, 0x70
	s_add_u32 s2, s82, 0xe000000
	v_and_or_b32 v3, v5, s9, v3
	s_movk_i32 s9, 0x60
	s_addc_u32 s3, s83, 0
	v_and_or_b32 v4, v5, s9, v4
	s_ashr_i32 s9, s8, 31
	s_lshr_b32 s9, s9, 29
	s_add_i32 s9, s8, s9
	s_lshr_b32 s12, s14, 6
	s_ashr_i32 s10, s9, 3
	s_and_b32 s9, s9, -8
	s_lshr_b32 s7, s14, 8
	s_lshl_b32 s33, s12, 10
	s_sub_i32 s8, s8, s9
	s_cmp_lt_i32 s8, 0
	s_cselect_b32 s9, 49, 48
	s_mul_i32 s8, s9, s8
	s_add_i32 s8, s8, s10
	s_ashr_i32 s9, s8, 31
	s_lshr_b32 s9, s9, 26
	s_add_i32 s9, s8, s9
	s_ashr_i32 s10, s9, 6
	s_lshl_b32 s10, s10, 3
	s_sub_i32 s11, 48, s10
	v_mul_u32_u24_e32 v16, 0x1600, v3
	s_min_i32 s11, s11, 8
	v_or_b32_e32 v3, v16, v1
	s_abs_i32 s13, s11
	v_lshlrev_b32_e32 v134, 1, v3
	v_cvt_f32_u32_e32 v3, s13
	v_mul_u32_u24_e32 v15, 0x1600, v6
	v_mul_u32_u24_e32 v4, 0x1600, v4
	v_or_b32_e32 v6, v1, v15
	v_or_b32_e32 v1, v4, v1
	v_lshlrev_b32_e32 v136, 1, v1
	v_rcp_iflag_f32_e32 v1, v3
	s_sub_i32 s17, 0, s13
	s_andn2_b32 s9, s9, 63
	s_sub_i32 s8, s8, s9
	v_mul_f32_e32 v1, 0x4f7ffffe, v1
	v_cvt_u32_f32_e32 v1, v1
	s_abs_i32 s15, s8
	s_xor_b32 s9, s8, s11
	s_ashr_i32 s9, s9, 31
	v_readfirstlane_b32 s18, v1
	s_mul_i32 s17, s17, s18
	s_mul_hi_u32 s17, s18, s17
	s_add_i32 s18, s18, s17
	s_mul_hi_u32 s17, s15, s18
	s_mul_i32 s18, s17, s13
	s_sub_i32 s15, s15, s18
	s_add_i32 s18, s17, 1
	s_sub_i32 s19, s15, s13
	s_cmp_ge_u32 s15, s13
	s_cselect_b32 s17, s18, s17
	s_cselect_b32 s15, s19, s15
	s_add_i32 s18, s17, 1
	s_cmp_ge_u32 s15, s13
	s_cselect_b32 s13, s18, s17
	s_xor_b32 s13, s13, s9
	s_sub_i32 s66, s13, s9
	s_mul_i32 s9, s66, s11
	s_sub_i32 s8, s8, s9
	s_add_i32 s65, s10, s8
	s_mul_i32 s9, s65, 0x2c0000
	s_mul_hi_i32 s8, s65, 0x2c0000
	s_add_u32 s10, s72, s9
	s_addc_u32 s11, s73, s8
	s_mul_i32 s9, s66, 0x2c0000
	s_mul_hi_i32 s8, s66, 0x2c0000
	s_add_u32 s9, s2, s9
	s_addc_u32 s8, s3, s8
	s_add_u32 s26, s9, s0
	s_addc_u32 s27, s8, s1
	s_add_i32 s34, s33, 0
	s_add_i32 m0, s34, 0x10000
	v_lshlrev_b32_e32 v130, 1, v6
	global_load_lds_dwordx4 v132, s[26:27] sc0
	s_add_i32 m0, s34, 0x12000
	s_add_u32 s8, s26, 0x160000
	global_load_lds_dwordx4 v136, s[26:27] sc0
	s_addc_u32 s9, s27, 0
	s_add_i32 m0, s34, 0x14000
	v_mov_b32_e32 v133, 0
	global_load_lds_dwordx4 v132, s[8:9] sc0
	s_add_i32 m0, s34, 0x16000
	s_add_u32 s24, s10, s0
	s_addc_u32 s25, s11, s1
	s_add_i32 s35, s34, 0x2000
	global_load_lds_dwordx4 v136, s[8:9] sc0
	s_mov_b32 m0, s34
	s_add_u32 s0, s24, 0x160000
	global_load_lds_dwordx4 v130, s[24:25] sc0
	s_mov_b32 m0, s35
	s_addc_u32 s1, s25, 0
	s_add_i32 s36, s34, 0x4000
	global_load_lds_dwordx4 v134, s[24:25] sc0
	s_mov_b32 m0, s36
	s_add_i32 s37, s34, 0x6000
	global_load_lds_dwordx4 v130, s[0:1] sc0
	s_mov_b32 m0, s37
	v_mov_b32_e32 v137, v133
	global_load_lds_dwordx4 v134, s[0:1] sc0
	v_mov_b32_e32 v131, v133
	v_mov_b32_e32 v135, v133
	s_cmp_eq_u32 s7, 1
	s_mov_b32 s38, 0x10000
	v_lshl_add_u64 v[10:11], s[26:27], 0, v[132:133]
	v_lshl_add_u64 v[6:7], s[26:27], 0, v[136:137]
	s_mov_b32 s39, 0x12000
	s_mov_b32 s40, 0x14000
	s_mov_b32 s41, 0x16000
	v_lshl_add_u64 v[8:9], s[24:25], 0, v[130:131]
	v_lshl_add_u64 v[4:5], s[24:25], 0, v[134:135]
	s_movk_i32 s42, 0x2000
	s_movk_i32 s43, 0x4000
	s_cselect_b64 s[8:9], -1, 0
	s_cmp_lg_u32 s7, 1
	s_movk_i32 s44, 0x6000
	s_cbranch_scc1 .LBB0_1768
	s_barrier
.LBB0_1768:
	s_add_u32 s10, s82, 0x27100000
	s_addc_u32 s11, s83, 0
	s_add_u32 s45, s82, 0x2a6000
	s_addc_u32 s46, s83, 0
	s_lshl_b32 s0, s12, 5
	s_mov_b64 s[12:13], 0x80
	s_and_b32 s17, s0, 0x60
	s_add_i32 m0, s34, 0x18000
	v_lshl_add_u64 v[10:11], v[10:11], 0, s[12:13]
	s_lshl_b32 s15, s7, 13
	s_lshl_b32 s18, s17, 7
	s_waitcnt vmcnt(2)
	s_barrier
	global_load_lds_dwordx4 v[10:11], off sc0
	v_lshl_add_u64 v[6:7], v[6:7], 0, s[12:13]
	s_add_i32 m0, s34, 0x1a000
	s_add_i32 s47, s34, 0x8000
	s_add_i32 s48, s34, 0xa000
	global_load_lds_dwordx4 v[6:7], off sc0
	v_lshl_add_u64 v[6:7], v[8:9], 0, s[12:13]
	s_mov_b32 m0, s47
	s_add_u32 s0, s26, 0x160080
	global_load_lds_dwordx4 v[6:7], off sc0
	v_lshl_add_u64 v[4:5], v[4:5], 0, s[12:13]
	s_mov_b32 m0, s48
	s_addc_u32 s1, s27, 0
	global_load_lds_dwordx4 v[4:5], off sc0
	s_add_i32 m0, s34, 0x1c000
	v_lshl_add_u64 v[4:5], s[0:1], 0, v[132:133]
	global_load_lds_dwordx4 v[4:5], off sc0
	v_lshl_add_u64 v[4:5], s[0:1], 0, v[136:137]
	s_add_i32 m0, s34, 0x1e000
	v_lshlrev_b32_e32 v3, 1, v14
	global_load_lds_dwordx4 v[4:5], off sc0
	v_lshl_or_b32 v4, v205, 6, v3
	v_and_b32_e32 v5, 32, v196
	v_bitop3_b32 v4, v4, s15, v5 bitop3:0xde
	s_movk_i32 s0, 0x3c0
	v_readlane_b32 s15, v249, 0
	v_and_or_b32 v3, v209, s0, v3
	s_ashr_i32 s0, s15, 31
	s_lshr_b32 s0, s0, 25
	s_add_i32 s0, s15, s0
	s_and_b32 s1, s0, 0xffffff80
	s_sub_i32 s54, s15, s1
	v_bitop3_b32 v164, s18, v3, v5 bitop3:0xf6
	s_addk_i32 s54, 0x100
	s_ashr_i32 s55, s0, 7
	v_mov_b32_e32 v3, v133
	s_waitcnt vmcnt(6)
	s_cmpk_lt_u32 s14, 0x100
	v_lshl_add_u64 v[138:139], s[78:79], 0, v[2:3]
	v_add_u16_e32 v2, v12, v13
	v_lshl_or_b32 v1, s7, 6, v205
	s_mov_b32 s7, 0
	s_cselect_b64 s[14:15], -1, 0
	s_lshr_b32 s0, s16, 2
	v_lshrrev_b16_e32 v2, 1, v2
	s_add_i32 s57, 0, 0x10000
	s_add_i32 s58, 0, 0x14000
	s_mov_b32 s49, 0x18000
	s_mov_b32 s50, 0x1a000
	s_mov_b32 s51, 0x8000
	s_mov_b32 s52, 0xa000
	s_mov_b32 s53, 0x1c000
	s_mul_i32 s55, s55, 44
	s_xor_b32 s56, s0, 1
	v_or_b32_e32 v165, s17, v14
	v_add_lshl_u32 v140, v15, v2, 1
	v_mov_b32_e32 v141, v133
	v_add_lshl_u32 v142, v16, v2, 1
	v_mov_b32_e32 v143, v133
	s_mov_b64 s[22:23], -1
	v_add_u32_e32 v166, s57, v164
	v_add_u32_e32 v167, s58, v164
	v_add_u32_e32 v168, 0, v4
	s_mov_b32 s59, 0xc000
	s_mov_b32 s60, 0xe000
	s_mov_b32 s17, s7
	s_barrier
	s_branch .LBB0_1771

.LBB0_1958:
	v_lshrrev_b32_e32 v3, 1, v0
	v_and_b32_e32 v15, 24, v3
	v_lshrrev_b32_e32 v3, 5, v0
	s_add_u32 s2, s82, 0x12900000
	v_lshlrev_b32_e32 v2, 4, v0
	v_and_b32_e32 v1, 32, v0
	v_and_b32_e32 v3, 4, v3
	v_bfe_u32 v4, v0, 2, 2
	s_addc_u32 s3, s83, 0
	v_bfe_u32 v14, v0, 2, 4
	v_bitop3_b32 v12, v2, v1, 48 bitop3:0x6c
	v_and_b32_e32 v13, 64, v0
	v_or3_b32 v3, v3, v4, v15
	v_lshrrev_b32_e32 v4, 3, v0
	s_ashr_i32 s13, s11, 31
	v_or_b32_e32 v1, v12, v13
	v_and_or_b32 v5, v4, 48, v14
	v_and_or_b32 v4, v4, 32, v3
	v_or_b32_e32 v16, 0x2000, v2
	s_lshr_b32 s13, s13, 29
	v_lshl_or_b32 v132, v4, 12, v1
	v_lshrrev_b32_e32 v4, 7, v16
	s_movk_i32 s10, 0x70
	s_add_i32 s13, s11, s13
	v_lshl_or_b32 v130, v5, 12, v1
	v_and_or_b32 v5, v4, s10, v14
	s_lshr_b32 s10, s16, 6
	s_ashr_i32 s14, s13, 3
	s_and_b32 s13, s13, -8
	s_lshr_b32 s7, s16, 8
	s_lshl_b32 s33, s10, 10
	s_sub_i32 s11, s11, s13
	s_cmp_lt_i32 s11, 0
	s_movk_i32 s40, 0x49
	s_cselect_b32 s13, s40, 0x48
	s_mul_i32 s11, s13, s11
	s_add_i32 s11, s11, s14
	s_mul_hi_i32 s13, s11, 0x2aaaaaab
	s_lshr_b32 s14, s13, 31
	s_ashr_i32 s13, s13, 4
	s_add_i32 s13, s13, s14
	s_lshl_b32 s14, s13, 3
	s_sub_i32 s15, 48, s14
	s_min_i32 s15, s15, 8
	s_abs_i32 s17, s15
	v_cvt_f32_u32_e32 v6, s17
	s_movk_i32 s12, 0x60
	v_and_or_b32 v3, v4, s12, v3
	v_lshl_or_b32 v134, v5, 12, v1
	v_lshl_or_b32 v136, v3, 12, v1
	v_rcp_iflag_f32_e32 v1, v6
	s_sub_i32 s18, 0, s17
	s_mulk_i32 s13, 0x60
	s_sub_i32 s11, s11, s13
	v_mul_f32_e32 v1, 0x4f7ffffe, v1
	v_cvt_u32_f32_e32 v1, v1
	s_abs_i32 s13, s11
	s_xor_b32 s12, s11, s15
	s_ashr_i32 s12, s12, 31
	v_readfirstlane_b32 s19, v1
	s_mul_i32 s18, s18, s19
	s_mul_hi_u32 s18, s19, s18
	s_add_i32 s19, s19, s18
	s_mul_hi_u32 s18, s13, s19
	s_mul_i32 s19, s18, s17
	s_sub_i32 s13, s13, s19
	s_add_i32 s19, s18, 1
	s_sub_i32 s20, s13, s17
	s_cmp_ge_u32 s13, s17
	s_cselect_b32 s18, s19, s18
	s_cselect_b32 s13, s20, s13
	s_add_i32 s19, s18, 1
	s_cmp_ge_u32 s13, s17
	s_cselect_b32 s13, s19, s18
	s_xor_b32 s13, s13, s12
	s_sub_i32 s12, s13, s12
	s_mul_i32 s13, s12, s15
	s_sub_i32 s11, s11, s13
	s_add_i32 s14, s14, s11
	s_ashr_i32 s15, s14, 31
	s_lshl_b64 s[18:19], s[14:15], 20
	v_readlane_b32 s20, v249, 50
	v_readlane_b32 s21, v249, 51
	s_add_u32 s11, s20, s18
	s_addc_u32 s17, s21, s19
	s_ashr_i32 s13, s12, 31
	s_lshl_b64 s[18:19], s[12:13], 20
	s_add_u32 s13, s2, s18
	s_addc_u32 s15, s3, s19
	s_add_u32 s34, s13, s8
	s_addc_u32 s35, s15, s9
	s_add_i32 s15, s33, 0
	s_add_i32 m0, s15, 0x10000
	v_mov_b32_e32 v133, 0
	global_load_lds_dwordx4 v132, s[34:35] sc0
	s_add_i32 m0, s15, 0x12000
	s_add_u32 s18, s34, 0x80000
	global_load_lds_dwordx4 v136, s[34:35] sc0
	s_addc_u32 s19, s35, 0
	s_add_i32 m0, s15, 0x14000
	v_mov_b32_e32 v137, v133
	global_load_lds_dwordx4 v132, s[18:19] sc0
	s_add_i32 m0, s15, 0x16000
	s_add_u32 s30, s11, s8
	s_addc_u32 s31, s17, s9
	s_add_i32 s41, s15, 0x2000
	global_load_lds_dwordx4 v136, s[18:19] sc0
	s_mov_b32 m0, s15
	s_add_u32 s8, s30, 0x80000
	global_load_lds_dwordx4 v130, s[30:31] sc0
	s_mov_b32 m0, s41
	s_addc_u32 s9, s31, 0
	s_add_i32 s42, s15, 0x4000
	global_load_lds_dwordx4 v134, s[30:31] sc0
	s_mov_b32 m0, s42
	s_add_i32 s43, s15, 0x6000
	global_load_lds_dwordx4 v130, s[8:9] sc0
	s_mov_b32 m0, s43
	v_mov_b32_e32 v131, v133
	global_load_lds_dwordx4 v134, s[8:9] sc0
	v_mov_b32_e32 v135, v133
	s_cmp_eq_u32 s7, 1
	s_movk_i32 s44, 0x2000
	s_mov_b32 s45, 0x10000
	v_lshl_add_u64 v[10:11], s[34:35], 0, v[132:133]
	v_lshl_add_u64 v[6:7], s[34:35], 0, v[136:137]
	s_mov_b32 s46, 0x12000
	s_mov_b32 s47, 0x14000
	s_mov_b32 s48, 0x16000
	v_lshl_add_u64 v[8:9], s[30:31], 0, v[130:131]
	v_lshl_add_u64 v[4:5], s[30:31], 0, v[134:135]
	s_movk_i32 s49, 0x4000
	s_cselect_b64 s[8:9], -1, 0
	s_cmp_lg_u32 s7, 1
	s_movk_i32 s50, 0x6000
	s_cbranch_scc1 .LBB0_1960
	s_barrier
.LBB0_1960:
	s_lshl_b32 s10, s10, 5
	s_and_b32 s20, s10, 0x60
	s_mov_b64 s[10:11], 0x80
	s_add_i32 m0, s15, 0x18000
	v_lshl_add_u64 v[10:11], v[10:11], 0, s[10:11]
	s_lshl_b32 s13, s7, 13
	s_lshl_b32 s17, s20, 7
	s_waitcnt vmcnt(2)
	s_barrier
	global_load_lds_dwordx4 v[10:11], off sc0
	v_lshl_add_u64 v[6:7], v[6:7], 0, s[10:11]
	s_add_i32 m0, s15, 0x1a000
	s_add_i32 s51, s15, 0x8000
	s_add_i32 s52, s15, 0xa000
	global_load_lds_dwordx4 v[6:7], off sc0
	v_lshl_add_u64 v[6:7], v[8:9], 0, s[10:11]
	s_mov_b32 m0, s51
	s_add_u32 s18, s34, 0x80080
	global_load_lds_dwordx4 v[6:7], off sc0
	v_lshl_add_u64 v[4:5], v[4:5], 0, s[10:11]
	s_mov_b32 m0, s52
	s_addc_u32 s19, s35, 0
	global_load_lds_dwordx4 v[4:5], off sc0
	s_add_i32 m0, s15, 0x1c000
	v_lshl_add_u64 v[4:5], s[18:19], 0, v[132:133]
	global_load_lds_dwordx4 v[4:5], off sc0
	v_lshl_add_u64 v[4:5], s[18:19], 0, v[136:137]
	s_add_i32 m0, s15, 0x1e000
	v_lshlrev_b32_e32 v3, 1, v15
	global_load_lds_dwordx4 v[4:5], off sc0
	v_lshl_or_b32 v1, s7, 6, v205
	v_lshl_or_b32 v4, v205, 6, v3
	v_and_b32_e32 v5, 32, v196
	s_movk_i32 s7, 0x3c0
	v_readlane_b32 s18, v249, 0
	v_bitop3_b32 v4, v4, s13, v5 bitop3:0xde
	v_and_or_b32 v3, v209, s7, v3
	s_ashr_i32 s13, s18, 31
	v_bitop3_b32 v144, s17, v3, v5 bitop3:0xf6
	s_lshr_b32 s13, s13, 26
	v_mov_b32_e32 v3, v133
	s_add_i32 s13, s18, s13
	v_lshl_add_u64 v[138:139], s[72:73], 0, v[2:3]
	v_lshlrev_b32_e32 v2, 9, v0
	s_and_b32 s17, s13, 0xffffffc0
	v_and_b32_e32 v2, 0x30000, v2
	v_lshlrev_b32_e32 v3, 12, v14
	s_sub_i32 s58, s18, s17
	s_ashr_i32 s13, s13, 6
	v_or3_b32 v2, v12, v2, v3
	s_addk_i32 s58, 0x200
	s_lshl_b32 s59, s13, 3
	v_add_u32_e32 v140, v2, v13
	v_lshlrev_b32_e32 v2, 5, v16
	s_waitcnt vmcnt(6)
	s_cmpk_lt_u32 s16, 0x100
	v_and_b32_e32 v2, 0x70000, v2
	s_mov_b32 s7, 0
	s_cselect_b64 s[16:17], -1, 0
	v_or3_b32 v2, v12, v2, v3
	s_add_i32 s60, 0, 0x10000
	s_add_i32 s61, 0, 0x14000
	s_mov_b32 s53, 0x18000
	s_mov_b32 s54, 0x1a000
	s_mov_b32 s55, 0x8000
	s_mov_b32 s56, 0xa000
	s_mov_b32 s57, 0x1c000
	v_or_b32_e32 v145, s20, v15
	v_mov_b32_e32 v141, v133
	v_add_u32_e32 v142, v2, v13
	v_mov_b32_e32 v143, v133
	v_add_u32_e32 v146, s60, v144
	v_add_u32_e32 v147, s61, v144
	v_add_u32_e32 v148, 0, v4
	s_mov_b32 s62, 0xc000
	s_mov_b32 s63, 0xe000
	s_movk_i32 s64, 0x1800
	s_mov_b32 s13, s7
	s_barrier
	s_branch .LBB0_1963

.Lpeel_3:
	ds_read_b128 v[150:153], v146
	ds_read_b128 v[154:157], v146 offset:1024
	ds_read_b128 v[158:161], v146 offset:2048
	ds_read_b128 v[162:165], v146 offset:3072
	ds_read_b128 v[166:169], v147
	ds_read_b128 v[170:173], v147 offset:1024
	ds_read_b128 v[174:177], v147 offset:2048
	ds_read_b128 v[178:181], v147 offset:3072
	s_add_i32 s29, s23, 2
	s_add_u32 s34, s30, 0xfff80080
	s_addc_u32 s35, s31, -1
	s_cmp_eq_u32 s28, s23
	s_cselect_b32 s37, s25, s35
	s_cselect_b32 s36, s24, s34
	s_cselect_b32 s35, s27, s21
	s_cselect_b32 s34, s26, s19
	v_lshl_add_u64 v[202:203], s[30:31], 0, v[140:141]
	s_add_i32 m0, s15, 0xc000
	ds_read_b128 v[182:185], v148
	ds_read_b128 v[186:189], v148 offset:1024
	ds_read_b128 v[190:193], v148 offset:2048
	ds_read_b128 v[198:201], v148 offset:3072
	ds_read_b128 v[210:213], v148 offset:4096
	ds_read_b128 v[214:217], v148 offset:5120
	ds_read_b128 v[218:221], v148 offset:6144
	ds_read_b128 v[222:225], v148 offset:7168
	global_load_lds_dwordx4 v[202:203], off sc0
	v_lshl_add_u64 v[202:203], s[30:31], 0, v[142:143]
	s_add_i32 m0, s15, 0xe000
	s_nop 0
	global_load_lds_dwordx4 v[202:203], off sc0
	s_waitcnt vmcnt(8)
	s_waitcnt lgkmcnt(0)
	s_barrier
	s_setprio 1
	s_waitcnt lgkmcnt(0)
	v_mfma_f32_16x16x32_bf16 v[126:129], v[150:153], v[182:185], 0
	v_mfma_f32_16x16x32_bf16 v[122:125], v[158:161], v[182:185], 0
	v_mfma_f32_16x16x32_bf16 v[118:121], v[150:153], v[190:193], 0
	v_mfma_f32_16x16x32_bf16 v[114:117], v[158:161], v[190:193], 0
	v_mfma_f32_16x16x32_bf16 v[110:113], v[150:153], v[210:213], 0
	v_mfma_f32_16x16x32_bf16 v[106:109], v[158:161], v[210:213], 0
	v_mfma_f32_16x16x32_bf16 v[102:105], v[150:153], v[218:221], 0
	v_mfma_f32_16x16x32_bf16 v[98:101], v[158:161], v[218:221], 0
	v_mfma_f32_16x16x32_bf16 v[126:129], v[154:157], v[186:189], v[126:129]
	v_mfma_f32_16x16x32_bf16 v[122:125], v[162:165], v[186:189], v[122:125]
	v_mfma_f32_16x16x32_bf16 v[118:121], v[154:157], v[198:201], v[118:121]
	v_mfma_f32_16x16x32_bf16 v[114:117], v[162:165], v[198:201], v[114:117]
	v_mfma_f32_16x16x32_bf16 v[110:113], v[154:157], v[214:217], v[110:113]
	v_mfma_f32_16x16x32_bf16 v[106:109], v[162:165], v[214:217], v[106:109]
	v_mfma_f32_16x16x32_bf16 v[102:105], v[154:157], v[222:225], v[102:105]
	v_mfma_f32_16x16x32_bf16 v[98:101], v[162:165], v[222:225], v[98:101]
	s_setprio 0
	s_setprio 1
	v_mfma_f32_16x16x32_bf16 v[94:97], v[166:169], v[182:185], 0
	v_mfma_f32_16x16x32_bf16 v[90:93], v[174:177], v[182:185], 0
	v_mfma_f32_16x16x32_bf16 v[86:89], v[166:169], v[190:193], 0
	v_mfma_f32_16x16x32_bf16 v[82:85], v[174:177], v[190:193], 0
	v_mfma_f32_16x16x32_bf16 v[78:81], v[166:169], v[210:213], 0
	v_mfma_f32_16x16x32_bf16 v[74:77], v[174:177], v[210:213], 0
	v_mfma_f32_16x16x32_bf16 v[70:73], v[166:169], v[218:221], 0
	v_mfma_f32_16x16x32_bf16 v[66:69], v[174:177], v[218:221], 0
	v_mfma_f32_16x16x32_bf16 v[94:97], v[170:173], v[186:189], v[94:97]
	v_mfma_f32_16x16x32_bf16 v[90:93], v[178:181], v[186:189], v[90:93]
	v_mfma_f32_16x16x32_bf16 v[86:89], v[170:173], v[198:201], v[86:89]
	v_mfma_f32_16x16x32_bf16 v[82:85], v[178:181], v[198:201], v[82:85]
	v_mfma_f32_16x16x32_bf16 v[78:81], v[170:173], v[214:217], v[78:81]
	v_mfma_f32_16x16x32_bf16 v[74:77], v[178:181], v[214:217], v[74:77]
	v_mfma_f32_16x16x32_bf16 v[70:73], v[170:173], v[222:225], v[70:73]
	v_mfma_f32_16x16x32_bf16 v[66:69], v[178:181], v[222:225], v[66:69]
	s_setprio 0
	s_barrier
	s_add_i32 s23, s60, s33
	v_lshl_add_u64 v[202:203], s[34:35], 0, v[132:133]
	s_mov_b32 m0, s23
	ds_read_b128 v[182:185], v148 offset:16384
	ds_read_b128 v[186:189], v148 offset:17408
	ds_read_b128 v[190:193], v148 offset:18432
	ds_read_b128 v[198:201], v148 offset:19456
	ds_read_b128 v[210:213], v148 offset:20480
	ds_read_b128 v[214:217], v148 offset:21504
	ds_read_b128 v[218:221], v148 offset:22528
	ds_read_b128 v[222:225], v148 offset:23552
	global_load_lds_dwordx4 v[202:203], off sc0
	s_add_i32 m0, s23, 0x2000
	s_add_u32 s38, s34, 0x80000
	v_lshl_add_u64 v[206:207], s[34:35], 0, v[136:137]
	s_addc_u32 s39, s35, 0
	s_add_i32 s23, s61, s33
	global_load_lds_dwordx4 v[206:207], off sc0
	v_lshl_add_u64 v[226:227], s[38:39], 0, v[132:133]
	s_mov_b32 m0, s23
	v_lshl_add_u64 v[228:229], s[36:37], 0, v[134:135]
	global_load_lds_dwordx4 v[226:227], off sc0
	v_lshl_add_u64 v[226:227], s[38:39], 0, v[136:137]
	s_add_i32 m0, s23, 0x2000
	s_nop 0
	global_load_lds_dwordx4 v[226:227], off sc0
	v_lshl_add_u64 v[226:227], s[36:37], 0, v[130:131]
	s_mov_b32 m0, s15
	s_nop 0
	global_load_lds_dwordx4 v[226:227], off sc0
	s_mov_b32 m0, s41
	s_nop 0
	global_load_lds_dwordx4 v[228:229], off sc0
	s_waitcnt vmcnt(8)
	s_waitcnt lgkmcnt(0)
	s_barrier
	s_setprio 1
	s_waitcnt lgkmcnt(0)
	v_mfma_f32_16x16x32_bf16 v[62:65], v[150:153], v[182:185], 0
	v_mfma_f32_16x16x32_bf16 v[58:61], v[158:161], v[182:185], 0
	v_mfma_f32_16x16x32_bf16 v[54:57], v[150:153], v[190:193], 0
	v_mfma_f32_16x16x32_bf16 v[50:53], v[158:161], v[190:193], 0
	v_mfma_f32_16x16x32_bf16 v[46:49], v[150:153], v[210:213], 0
	v_mfma_f32_16x16x32_bf16 v[42:45], v[158:161], v[210:213], 0
	v_mfma_f32_16x16x32_bf16 v[38:41], v[150:153], v[218:221], 0
	v_mfma_f32_16x16x32_bf16 v[34:37], v[158:161], v[218:221], 0
	v_mfma_f32_16x16x32_bf16 v[62:65], v[154:157], v[186:189], v[62:65]
	v_mfma_f32_16x16x32_bf16 v[58:61], v[162:165], v[186:189], v[58:61]
	v_mfma_f32_16x16x32_bf16 v[54:57], v[154:157], v[198:201], v[54:57]
	v_mfma_f32_16x16x32_bf16 v[50:53], v[162:165], v[198:201], v[50:53]
	v_mfma_f32_16x16x32_bf16 v[46:49], v[154:157], v[214:217], v[46:49]
	v_mfma_f32_16x16x32_bf16 v[42:45], v[162:165], v[214:217], v[42:45]
	v_mfma_f32_16x16x32_bf16 v[38:41], v[154:157], v[222:225], v[38:41]
	v_mfma_f32_16x16x32_bf16 v[34:37], v[162:165], v[222:225], v[34:37]
	s_setprio 0
	s_setprio 1
	v_mfma_f32_16x16x32_bf16 v[30:33], v[166:169], v[182:185], 0
	v_mfma_f32_16x16x32_bf16 v[26:29], v[174:177], v[182:185], 0
	v_mfma_f32_16x16x32_bf16 v[22:25], v[166:169], v[190:193], 0
	v_mfma_f32_16x16x32_bf16 v[18:21], v[174:177], v[190:193], 0
	v_mfma_f32_16x16x32_bf16 v[14:17], v[166:169], v[210:213], 0
	v_mfma_f32_16x16x32_bf16 v[10:13], v[174:177], v[210:213], 0
	v_mfma_f32_16x16x32_bf16 v[6:9], v[166:169], v[218:221], 0
	v_mfma_f32_16x16x32_bf16 v[2:5], v[174:177], v[218:221], 0
	v_mfma_f32_16x16x32_bf16 v[30:33], v[170:173], v[186:189], v[30:33]
	v_mfma_f32_16x16x32_bf16 v[26:29], v[178:181], v[186:189], v[26:29]
	v_mfma_f32_16x16x32_bf16 v[22:25], v[170:173], v[198:201], v[22:25]
	v_mfma_f32_16x16x32_bf16 v[18:21], v[178:181], v[198:201], v[18:21]
	v_mfma_f32_16x16x32_bf16 v[14:17], v[170:173], v[214:217], v[14:17]
	v_mfma_f32_16x16x32_bf16 v[10:13], v[178:181], v[214:217], v[10:13]
	v_mfma_f32_16x16x32_bf16 v[6:9], v[170:173], v[222:225], v[6:9]
	v_mfma_f32_16x16x32_bf16 v[2:5], v[178:181], v[222:225], v[2:5]
	s_setprio 0
	s_barrier
	s_add_i32 s23, 0, 0x18000
	v_add_u32_e32 v149, s23, v144
	s_add_i32 s38, 0, 0x1c000
	ds_read_b128 v[150:153], v149
	ds_read_b128 v[154:157], v149 offset:1024
	ds_read_b128 v[158:161], v149 offset:2048
	ds_read_b128 v[162:165], v149 offset:3072
	v_add_u32_e32 v149, s38, v144
	ds_read_b128 v[166:169], v149
	ds_read_b128 v[170:173], v149 offset:1024
	ds_read_b128 v[174:177], v149 offset:2048
	ds_read_b128 v[178:181], v149 offset:3072
	s_add_u32 s36, s36, 0x80000
	s_addc_u32 s37, s37, 0
	s_mov_b32 m0, s42
	v_lshl_add_u64 v[230:231], s[36:37], 0, v[130:131]
	ds_read_b128 v[182:185], v148 offset:32768
	ds_read_b128 v[186:189], v148 offset:33792
	ds_read_b128 v[190:193], v148 offset:34816
	ds_read_b128 v[198:201], v148 offset:35840
	ds_read_b128 v[210:213], v148 offset:36864
	ds_read_b128 v[214:217], v148 offset:37888
	ds_read_b128 v[218:221], v148 offset:38912
	ds_read_b128 v[222:225], v148 offset:39936
	global_load_lds_dwordx4 v[230:231], off sc0
	v_lshl_add_u64 v[230:231], s[36:37], 0, v[134:135]
	s_mov_b32 m0, s43
	s_nop 0
	global_load_lds_dwordx4 v[230:231], off sc0
	s_waitcnt vmcnt(8)
	s_waitcnt lgkmcnt(0)
	s_barrier
	s_setprio 1
	s_waitcnt lgkmcnt(0)
	v_mfma_f32_16x16x32_bf16 v[126:129], v[150:153], v[182:185], v[126:129]
	v_mfma_f32_16x16x32_bf16 v[122:125], v[158:161], v[182:185], v[122:125]
	v_mfma_f32_16x16x32_bf16 v[118:121], v[150:153], v[190:193], v[118:121]
	v_mfma_f32_16x16x32_bf16 v[114:117], v[158:161], v[190:193], v[114:117]
	v_mfma_f32_16x16x32_bf16 v[110:113], v[150:153], v[210:213], v[110:113]
	v_mfma_f32_16x16x32_bf16 v[106:109], v[158:161], v[210:213], v[106:109]
	v_mfma_f32_16x16x32_bf16 v[102:105], v[150:153], v[218:221], v[102:105]
	v_mfma_f32_16x16x32_bf16 v[98:101], v[158:161], v[218:221], v[98:101]
	v_mfma_f32_16x16x32_bf16 v[126:129], v[154:157], v[186:189], v[126:129]
	v_mfma_f32_16x16x32_bf16 v[122:125], v[162:165], v[186:189], v[122:125]
	v_mfma_f32_16x16x32_bf16 v[118:121], v[154:157], v[198:201], v[118:121]
	v_mfma_f32_16x16x32_bf16 v[114:117], v[162:165], v[198:201], v[114:117]
	v_mfma_f32_16x16x32_bf16 v[110:113], v[154:157], v[214:217], v[110:113]
	v_mfma_f32_16x16x32_bf16 v[106:109], v[162:165], v[214:217], v[106:109]
	v_mfma_f32_16x16x32_bf16 v[102:105], v[154:157], v[222:225], v[102:105]
	v_mfma_f32_16x16x32_bf16 v[98:101], v[162:165], v[222:225], v[98:101]
	s_setprio 0
	s_setprio 1
	v_mfma_f32_16x16x32_bf16 v[94:97], v[166:169], v[182:185], v[94:97]
	v_mfma_f32_16x16x32_bf16 v[90:93], v[174:177], v[182:185], v[90:93]
	v_mfma_f32_16x16x32_bf16 v[86:89], v[166:169], v[190:193], v[86:89]
	v_mfma_f32_16x16x32_bf16 v[82:85], v[174:177], v[190:193], v[82:85]
	v_mfma_f32_16x16x32_bf16 v[78:81], v[166:169], v[210:213], v[78:81]
	v_mfma_f32_16x16x32_bf16 v[74:77], v[174:177], v[210:213], v[74:77]
	v_mfma_f32_16x16x32_bf16 v[70:73], v[166:169], v[218:221], v[70:73]
	v_mfma_f32_16x16x32_bf16 v[66:69], v[174:177], v[218:221], v[66:69]
	v_mfma_f32_16x16x32_bf16 v[94:97], v[170:173], v[186:189], v[94:97]
	v_mfma_f32_16x16x32_bf16 v[90:93], v[178:181], v[186:189], v[90:93]
	v_mfma_f32_16x16x32_bf16 v[86:89], v[170:173], v[198:201], v[86:89]
	v_mfma_f32_16x16x32_bf16 v[82:85], v[178:181], v[198:201], v[82:85]
	v_mfma_f32_16x16x32_bf16 v[78:81], v[170:173], v[214:217], v[78:81]
	v_mfma_f32_16x16x32_bf16 v[74:77], v[178:181], v[214:217], v[74:77]
	v_mfma_f32_16x16x32_bf16 v[70:73], v[170:173], v[222:225], v[70:73]
	v_mfma_f32_16x16x32_bf16 v[66:69], v[178:181], v[222:225], v[66:69]
	s_setprio 0
	s_barrier
	s_add_i32 s23, s23, s33
	v_lshl_add_u64 v[202:203], v[202:203], 0, s[10:11]
	s_mov_b32 m0, s23
	ds_read_b128 v[182:185], v148 offset:49152
	ds_read_b128 v[186:189], v148 offset:50176
	ds_read_b128 v[190:193], v148 offset:51200
	ds_read_b128 v[198:201], v148 offset:52224
	ds_read_b128 v[210:213], v148 offset:53248
	ds_read_b128 v[214:217], v148 offset:54272
	ds_read_b128 v[218:221], v148 offset:55296
	ds_read_b128 v[222:225], v148 offset:56320
	global_load_lds_dwordx4 v[202:203], off sc0
	s_add_i32 m0, s23, 0x2000
	s_add_u32 s34, s34, 0x80080
	v_lshl_add_u64 v[202:203], v[206:207], 0, s[10:11]
	s_addc_u32 s35, s35, 0
	s_add_i32 s23, s38, s33
	global_load_lds_dwordx4 v[202:203], off sc0
	v_lshl_add_u64 v[202:203], s[34:35], 0, v[132:133]
	s_mov_b32 m0, s23
	s_nop 0
	global_load_lds_dwordx4 v[202:203], off sc0
	v_lshl_add_u64 v[202:203], s[34:35], 0, v[136:137]
	s_add_i32 m0, s23, 0x2000
	s_nop 0
	global_load_lds_dwordx4 v[202:203], off sc0
	v_lshl_add_u64 v[202:203], v[226:227], 0, s[10:11]
	s_mov_b32 m0, s51
	s_nop 0
	global_load_lds_dwordx4 v[202:203], off sc0
	v_lshl_add_u64 v[202:203], v[228:229], 0, s[10:11]
	s_mov_b32 m0, s52
	s_nop 0
	global_load_lds_dwordx4 v[202:203], off sc0
	s_waitcnt vmcnt(8)
	s_waitcnt lgkmcnt(0)
	s_barrier
	s_setprio 1
	s_waitcnt lgkmcnt(0)
	v_mfma_f32_16x16x32_bf16 v[62:65], v[150:153], v[182:185], v[62:65]
	v_mfma_f32_16x16x32_bf16 v[58:61], v[158:161], v[182:185], v[58:61]
	v_mfma_f32_16x16x32_bf16 v[54:57], v[150:153], v[190:193], v[54:57]
	v_mfma_f32_16x16x32_bf16 v[50:53], v[158:161], v[190:193], v[50:53]
	v_mfma_f32_16x16x32_bf16 v[46:49], v[150:153], v[210:213], v[46:49]
	v_mfma_f32_16x16x32_bf16 v[42:45], v[158:161], v[210:213], v[42:45]
	v_mfma_f32_16x16x32_bf16 v[38:41], v[150:153], v[218:221], v[38:41]
	v_mfma_f32_16x16x32_bf16 v[34:37], v[158:161], v[218:221], v[34:37]
	v_mfma_f32_16x16x32_bf16 v[62:65], v[154:157], v[186:189], v[62:65]
	v_mfma_f32_16x16x32_bf16 v[58:61], v[162:165], v[186:189], v[58:61]
	v_mfma_f32_16x16x32_bf16 v[54:57], v[154:157], v[198:201], v[54:57]
	v_mfma_f32_16x16x32_bf16 v[50:53], v[162:165], v[198:201], v[50:53]
	v_mfma_f32_16x16x32_bf16 v[46:49], v[154:157], v[214:217], v[46:49]
	v_mfma_f32_16x16x32_bf16 v[42:45], v[162:165], v[214:217], v[42:45]
	v_mfma_f32_16x16x32_bf16 v[38:41], v[154:157], v[222:225], v[38:41]
	v_mfma_f32_16x16x32_bf16 v[34:37], v[162:165], v[222:225], v[34:37]
	s_setprio 0
	s_setprio 1
	v_mfma_f32_16x16x32_bf16 v[30:33], v[166:169], v[182:185], v[30:33]
	v_mfma_f32_16x16x32_bf16 v[26:29], v[174:177], v[182:185], v[26:29]
	v_mfma_f32_16x16x32_bf16 v[22:25], v[166:169], v[190:193], v[22:25]
	v_mfma_f32_16x16x32_bf16 v[18:21], v[174:177], v[190:193], v[18:21]
	v_mfma_f32_16x16x32_bf16 v[14:17], v[166:169], v[210:213], v[14:17]
	v_mfma_f32_16x16x32_bf16 v[10:13], v[174:177], v[210:213], v[10:13]
	v_mfma_f32_16x16x32_bf16 v[6:9], v[166:169], v[218:221], v[6:9]
	v_mfma_f32_16x16x32_bf16 v[2:5], v[174:177], v[218:221], v[2:5]
	v_mfma_f32_16x16x32_bf16 v[30:33], v[170:173], v[186:189], v[30:33]
	v_mfma_f32_16x16x32_bf16 v[26:29], v[178:181], v[186:189], v[26:29]
	v_mfma_f32_16x16x32_bf16 v[22:25], v[170:173], v[198:201], v[22:25]
	v_mfma_f32_16x16x32_bf16 v[18:21], v[178:181], v[198:201], v[18:21]
	v_mfma_f32_16x16x32_bf16 v[14:17], v[170:173], v[214:217], v[14:17]
	v_mfma_f32_16x16x32_bf16 v[10:13], v[178:181], v[214:217], v[10:13]
	v_mfma_f32_16x16x32_bf16 v[6:9], v[170:173], v[222:225], v[6:9]
	v_mfma_f32_16x16x32_bf16 v[2:5], v[178:181], v[222:225], v[2:5]
	s_setprio 0
	s_barrier
	s_add_u32 s30, s30, 0x100
	s_addc_u32 s31, s31, 0
	s_add_u32 s19, s19, 0x100
	s_addc_u32 s21, s21, 0
	s_cmp_ge_i32 s29, s68
	s_mov_b32 s23, s29
	s_cbranch_scc0 .LBB0_1973
	s_branch .Lpeeldone_3
.LBB0_1973:
	ds_read_b128 v[150:153], v146
	ds_read_b128 v[154:157], v146 offset:1024
	ds_read_b128 v[158:161], v146 offset:2048
	ds_read_b128 v[162:165], v146 offset:3072
	ds_read_b128 v[166:169], v147
	ds_read_b128 v[170:173], v147 offset:1024
	ds_read_b128 v[174:177], v147 offset:2048
	ds_read_b128 v[178:181], v147 offset:3072
	s_add_i32 s29, s23, 2
	s_add_u32 s34, s30, 0xfff80080
	s_addc_u32 s35, s31, -1
	s_cmp_eq_u32 s28, s23
	s_cselect_b32 s37, s25, s35
	s_cselect_b32 s36, s24, s34
	s_cselect_b32 s35, s27, s21
	s_cselect_b32 s34, s26, s19
	v_lshl_add_u64 v[202:203], s[30:31], 0, v[140:141]
	s_add_i32 m0, s15, 0xc000
	ds_read_b128 v[182:185], v148
	ds_read_b128 v[186:189], v148 offset:1024
	ds_read_b128 v[190:193], v148 offset:2048
	ds_read_b128 v[198:201], v148 offset:3072
	ds_read_b128 v[210:213], v148 offset:4096
	ds_read_b128 v[214:217], v148 offset:5120
	ds_read_b128 v[218:221], v148 offset:6144
	ds_read_b128 v[222:225], v148 offset:7168
	global_load_lds_dwordx4 v[202:203], off sc0
	v_lshl_add_u64 v[202:203], s[30:31], 0, v[142:143]
	s_add_i32 m0, s15, 0xe000
	s_nop 0
	global_load_lds_dwordx4 v[202:203], off sc0
	s_waitcnt vmcnt(8)
	s_waitcnt lgkmcnt(0)
	s_barrier
	s_setprio 1
	s_waitcnt lgkmcnt(0)
	v_mfma_f32_16x16x32_bf16 v[126:129], v[150:153], v[182:185], v[126:129]
	v_mfma_f32_16x16x32_bf16 v[122:125], v[158:161], v[182:185], v[122:125]
	v_mfma_f32_16x16x32_bf16 v[118:121], v[150:153], v[190:193], v[118:121]
	v_mfma_f32_16x16x32_bf16 v[114:117], v[158:161], v[190:193], v[114:117]
	v_mfma_f32_16x16x32_bf16 v[110:113], v[150:153], v[210:213], v[110:113]
	v_mfma_f32_16x16x32_bf16 v[106:109], v[158:161], v[210:213], v[106:109]
	v_mfma_f32_16x16x32_bf16 v[102:105], v[150:153], v[218:221], v[102:105]
	v_mfma_f32_16x16x32_bf16 v[98:101], v[158:161], v[218:221], v[98:101]
	v_mfma_f32_16x16x32_bf16 v[126:129], v[154:157], v[186:189], v[126:129]
	v_mfma_f32_16x16x32_bf16 v[122:125], v[162:165], v[186:189], v[122:125]
	v_mfma_f32_16x16x32_bf16 v[118:121], v[154:157], v[198:201], v[118:121]
	v_mfma_f32_16x16x32_bf16 v[114:117], v[162:165], v[198:201], v[114:117]
	v_mfma_f32_16x16x32_bf16 v[110:113], v[154:157], v[214:217], v[110:113]
	v_mfma_f32_16x16x32_bf16 v[106:109], v[162:165], v[214:217], v[106:109]
	v_mfma_f32_16x16x32_bf16 v[102:105], v[154:157], v[222:225], v[102:105]
	v_mfma_f32_16x16x32_bf16 v[98:101], v[162:165], v[222:225], v[98:101]
	s_setprio 0
	s_setprio 1
	v_mfma_f32_16x16x32_bf16 v[94:97], v[166:169], v[182:185], v[94:97]
	v_mfma_f32_16x16x32_bf16 v[90:93], v[174:177], v[182:185], v[90:93]
	v_mfma_f32_16x16x32_bf16 v[86:89], v[166:169], v[190:193], v[86:89]
	v_mfma_f32_16x16x32_bf16 v[82:85], v[174:177], v[190:193], v[82:85]
	v_mfma_f32_16x16x32_bf16 v[78:81], v[166:169], v[210:213], v[78:81]
	v_mfma_f32_16x16x32_bf16 v[74:77], v[174:177], v[210:213], v[74:77]
	v_mfma_f32_16x16x32_bf16 v[70:73], v[166:169], v[218:221], v[70:73]
	v_mfma_f32_16x16x32_bf16 v[66:69], v[174:177], v[218:221], v[66:69]
	v_mfma_f32_16x16x32_bf16 v[94:97], v[170:173], v[186:189], v[94:97]
	v_mfma_f32_16x16x32_bf16 v[90:93], v[178:181], v[186:189], v[90:93]
	v_mfma_f32_16x16x32_bf16 v[86:89], v[170:173], v[198:201], v[86:89]
	v_mfma_f32_16x16x32_bf16 v[82:85], v[178:181], v[198:201], v[82:85]
	v_mfma_f32_16x16x32_bf16 v[78:81], v[170:173], v[214:217], v[78:81]
	v_mfma_f32_16x16x32_bf16 v[74:77], v[178:181], v[214:217], v[74:77]
	v_mfma_f32_16x16x32_bf16 v[70:73], v[170:173], v[222:225], v[70:73]
	v_mfma_f32_16x16x32_bf16 v[66:69], v[178:181], v[222:225], v[66:69]
	s_setprio 0
	s_barrier
	s_add_i32 s23, s60, s33
	v_lshl_add_u64 v[202:203], s[34:35], 0, v[132:133]
	s_mov_b32 m0, s23
	ds_read_b128 v[182:185], v148 offset:16384
	ds_read_b128 v[186:189], v148 offset:17408
	ds_read_b128 v[190:193], v148 offset:18432
	ds_read_b128 v[198:201], v148 offset:19456
	ds_read_b128 v[210:213], v148 offset:20480
	ds_read_b128 v[214:217], v148 offset:21504
	ds_read_b128 v[218:221], v148 offset:22528
	ds_read_b128 v[222:225], v148 offset:23552
	global_load_lds_dwordx4 v[202:203], off sc0
	s_add_i32 m0, s23, 0x2000
	s_add_u32 s38, s34, 0x80000
	v_lshl_add_u64 v[206:207], s[34:35], 0, v[136:137]
	s_addc_u32 s39, s35, 0
	s_add_i32 s23, s61, s33
	global_load_lds_dwordx4 v[206:207], off sc0
	v_lshl_add_u64 v[226:227], s[38:39], 0, v[132:133]
	s_mov_b32 m0, s23
	v_lshl_add_u64 v[228:229], s[36:37], 0, v[134:135]
	global_load_lds_dwordx4 v[226:227], off sc0
	v_lshl_add_u64 v[226:227], s[38:39], 0, v[136:137]
	s_add_i32 m0, s23, 0x2000
	s_nop 0
	global_load_lds_dwordx4 v[226:227], off sc0
	v_lshl_add_u64 v[226:227], s[36:37], 0, v[130:131]
	s_mov_b32 m0, s15
	s_nop 0
	global_load_lds_dwordx4 v[226:227], off sc0
	s_mov_b32 m0, s41
	s_nop 0
	global_load_lds_dwordx4 v[228:229], off sc0
	s_waitcnt vmcnt(8)
	s_waitcnt lgkmcnt(0)
	s_barrier
	s_setprio 1
	s_waitcnt lgkmcnt(0)
	v_mfma_f32_16x16x32_bf16 v[62:65], v[150:153], v[182:185], v[62:65]
	v_mfma_f32_16x16x32_bf16 v[58:61], v[158:161], v[182:185], v[58:61]
	v_mfma_f32_16x16x32_bf16 v[54:57], v[150:153], v[190:193], v[54:57]
	v_mfma_f32_16x16x32_bf16 v[50:53], v[158:161], v[190:193], v[50:53]
	v_mfma_f32_16x16x32_bf16 v[46:49], v[150:153], v[210:213], v[46:49]
	v_mfma_f32_16x16x32_bf16 v[42:45], v[158:161], v[210:213], v[42:45]
	v_mfma_f32_16x16x32_bf16 v[38:41], v[150:153], v[218:221], v[38:41]
	v_mfma_f32_16x16x32_bf16 v[34:37], v[158:161], v[218:221], v[34:37]
	v_mfma_f32_16x16x32_bf16 v[62:65], v[154:157], v[186:189], v[62:65]
	v_mfma_f32_16x16x32_bf16 v[58:61], v[162:165], v[186:189], v[58:61]
	v_mfma_f32_16x16x32_bf16 v[54:57], v[154:157], v[198:201], v[54:57]
	v_mfma_f32_16x16x32_bf16 v[50:53], v[162:165], v[198:201], v[50:53]
	v_mfma_f32_16x16x32_bf16 v[46:49], v[154:157], v[214:217], v[46:49]
	v_mfma_f32_16x16x32_bf16 v[42:45], v[162:165], v[214:217], v[42:45]
	v_mfma_f32_16x16x32_bf16 v[38:41], v[154:157], v[222:225], v[38:41]
	v_mfma_f32_16x16x32_bf16 v[34:37], v[162:165], v[222:225], v[34:37]
	s_setprio 0
	s_setprio 1
	v_mfma_f32_16x16x32_bf16 v[30:33], v[166:169], v[182:185], v[30:33]
	v_mfma_f32_16x16x32_bf16 v[26:29], v[174:177], v[182:185], v[26:29]
	v_mfma_f32_16x16x32_bf16 v[22:25], v[166:169], v[190:193], v[22:25]
	v_mfma_f32_16x16x32_bf16 v[18:21], v[174:177], v[190:193], v[18:21]
	v_mfma_f32_16x16x32_bf16 v[14:17], v[166:169], v[210:213], v[14:17]
	v_mfma_f32_16x16x32_bf16 v[10:13], v[174:177], v[210:213], v[10:13]
	v_mfma_f32_16x16x32_bf16 v[6:9], v[166:169], v[218:221], v[6:9]
	v_mfma_f32_16x16x32_bf16 v[2:5], v[174:177], v[218:221], v[2:5]
	v_mfma_f32_16x16x32_bf16 v[30:33], v[170:173], v[186:189], v[30:33]
	v_mfma_f32_16x16x32_bf16 v[26:29], v[178:181], v[186:189], v[26:29]
	v_mfma_f32_16x16x32_bf16 v[22:25], v[170:173], v[198:201], v[22:25]
	v_mfma_f32_16x16x32_bf16 v[18:21], v[178:181], v[198:201], v[18:21]
	v_mfma_f32_16x16x32_bf16 v[14:17], v[170:173], v[214:217], v[14:17]
	v_mfma_f32_16x16x32_bf16 v[10:13], v[178:181], v[214:217], v[10:13]
	v_mfma_f32_16x16x32_bf16 v[6:9], v[170:173], v[222:225], v[6:9]
	v_mfma_f32_16x16x32_bf16 v[2:5], v[178:181], v[222:225], v[2:5]
	s_setprio 0
	s_barrier
	s_add_i32 s23, 0, 0x18000
	v_add_u32_e32 v149, s23, v144
	s_add_i32 s38, 0, 0x1c000
	ds_read_b128 v[150:153], v149
	ds_read_b128 v[154:157], v149 offset:1024
	ds_read_b128 v[158:161], v149 offset:2048
	ds_read_b128 v[162:165], v149 offset:3072
	v_add_u32_e32 v149, s38, v144
	ds_read_b128 v[166:169], v149
	ds_read_b128 v[170:173], v149 offset:1024
	ds_read_b128 v[174:177], v149 offset:2048
	ds_read_b128 v[178:181], v149 offset:3072
	s_add_u32 s36, s36, 0x80000
	s_addc_u32 s37, s37, 0
	s_mov_b32 m0, s42
	v_lshl_add_u64 v[230:231], s[36:37], 0, v[130:131]
	ds_read_b128 v[182:185], v148 offset:32768
	ds_read_b128 v[186:189], v148 offset:33792
	ds_read_b128 v[190:193], v148 offset:34816
	ds_read_b128 v[198:201], v148 offset:35840
	ds_read_b128 v[210:213], v148 offset:36864
	ds_read_b128 v[214:217], v148 offset:37888
	ds_read_b128 v[218:221], v148 offset:38912
	ds_read_b128 v[222:225], v148 offset:39936
	global_load_lds_dwordx4 v[230:231], off sc0
	v_lshl_add_u64 v[230:231], s[36:37], 0, v[134:135]
	s_mov_b32 m0, s43
	s_nop 0
	global_load_lds_dwordx4 v[230:231], off sc0
	s_waitcnt vmcnt(8)
	s_waitcnt lgkmcnt(0)
	s_barrier
	s_setprio 1
	s_waitcnt lgkmcnt(0)
	v_mfma_f32_16x16x32_bf16 v[126:129], v[150:153], v[182:185], v[126:129]
	v_mfma_f32_16x16x32_bf16 v[122:125], v[158:161], v[182:185], v[122:125]
	v_mfma_f32_16x16x32_bf16 v[118:121], v[150:153], v[190:193], v[118:121]
	v_mfma_f32_16x16x32_bf16 v[114:117], v[158:161], v[190:193], v[114:117]
	v_mfma_f32_16x16x32_bf16 v[110:113], v[150:153], v[210:213], v[110:113]
	v_mfma_f32_16x16x32_bf16 v[106:109], v[158:161], v[210:213], v[106:109]
	v_mfma_f32_16x16x32_bf16 v[102:105], v[150:153], v[218:221], v[102:105]
	v_mfma_f32_16x16x32_bf16 v[98:101], v[158:161], v[218:221], v[98:101]
	v_mfma_f32_16x16x32_bf16 v[126:129], v[154:157], v[186:189], v[126:129]
	v_mfma_f32_16x16x32_bf16 v[122:125], v[162:165], v[186:189], v[122:125]
	v_mfma_f32_16x16x32_bf16 v[118:121], v[154:157], v[198:201], v[118:121]
	v_mfma_f32_16x16x32_bf16 v[114:117], v[162:165], v[198:201], v[114:117]
	v_mfma_f32_16x16x32_bf16 v[110:113], v[154:157], v[214:217], v[110:113]
	v_mfma_f32_16x16x32_bf16 v[106:109], v[162:165], v[214:217], v[106:109]
	v_mfma_f32_16x16x32_bf16 v[102:105], v[154:157], v[222:225], v[102:105]
	v_mfma_f32_16x16x32_bf16 v[98:101], v[162:165], v[222:225], v[98:101]
	s_setprio 0
	s_setprio 1
	v_mfma_f32_16x16x32_bf16 v[94:97], v[166:169], v[182:185], v[94:97]
	v_mfma_f32_16x16x32_bf16 v[90:93], v[174:177], v[182:185], v[90:93]
	v_mfma_f32_16x16x32_bf16 v[86:89], v[166:169], v[190:193], v[86:89]
	v_mfma_f32_16x16x32_bf16 v[82:85], v[174:177], v[190:193], v[82:85]
	v_mfma_f32_16x16x32_bf16 v[78:81], v[166:169], v[210:213], v[78:81]
	v_mfma_f32_16x16x32_bf16 v[74:77], v[174:177], v[210:213], v[74:77]
	v_mfma_f32_16x16x32_bf16 v[70:73], v[166:169], v[218:221], v[70:73]
	v_mfma_f32_16x16x32_bf16 v[66:69], v[174:177], v[218:221], v[66:69]
	v_mfma_f32_16x16x32_bf16 v[94:97], v[170:173], v[186:189], v[94:97]
	v_mfma_f32_16x16x32_bf16 v[90:93], v[178:181], v[186:189], v[90:93]
	v_mfma_f32_16x16x32_bf16 v[86:89], v[170:173], v[198:201], v[86:89]
	v_mfma_f32_16x16x32_bf16 v[82:85], v[178:181], v[198:201], v[82:85]
	v_mfma_f32_16x16x32_bf16 v[78:81], v[170:173], v[214:217], v[78:81]
	v_mfma_f32_16x16x32_bf16 v[74:77], v[178:181], v[214:217], v[74:77]
	v_mfma_f32_16x16x32_bf16 v[70:73], v[170:173], v[222:225], v[70:73]
	v_mfma_f32_16x16x32_bf16 v[66:69], v[178:181], v[222:225], v[66:69]
	s_setprio 0
	s_barrier
	s_add_i32 s23, s23, s33
	v_lshl_add_u64 v[202:203], v[202:203], 0, s[10:11]
	s_mov_b32 m0, s23
	ds_read_b128 v[182:185], v148 offset:49152
	ds_read_b128 v[186:189], v148 offset:50176
	ds_read_b128 v[190:193], v148 offset:51200
	ds_read_b128 v[198:201], v148 offset:52224
	ds_read_b128 v[210:213], v148 offset:53248
	ds_read_b128 v[214:217], v148 offset:54272
	ds_read_b128 v[218:221], v148 offset:55296
	ds_read_b128 v[222:225], v148 offset:56320
	global_load_lds_dwordx4 v[202:203], off sc0
	s_add_i32 m0, s23, 0x2000
	s_add_u32 s34, s34, 0x80080
	v_lshl_add_u64 v[202:203], v[206:207], 0, s[10:11]
	s_addc_u32 s35, s35, 0
	s_add_i32 s23, s38, s33
	global_load_lds_dwordx4 v[202:203], off sc0
	v_lshl_add_u64 v[202:203], s[34:35], 0, v[132:133]
	s_mov_b32 m0, s23
	s_nop 0
	global_load_lds_dwordx4 v[202:203], off sc0
	v_lshl_add_u64 v[202:203], s[34:35], 0, v[136:137]
	s_add_i32 m0, s23, 0x2000
	s_nop 0
	global_load_lds_dwordx4 v[202:203], off sc0
	v_lshl_add_u64 v[202:203], v[226:227], 0, s[10:11]
	s_mov_b32 m0, s51
	s_nop 0
	global_load_lds_dwordx4 v[202:203], off sc0
	v_lshl_add_u64 v[202:203], v[228:229], 0, s[10:11]
	s_mov_b32 m0, s52
	s_nop 0
	global_load_lds_dwordx4 v[202:203], off sc0
	s_waitcnt vmcnt(8)
	s_waitcnt lgkmcnt(0)
	s_barrier
	s_setprio 1
	s_waitcnt lgkmcnt(0)
	v_mfma_f32_16x16x32_bf16 v[62:65], v[150:153], v[182:185], v[62:65]
	v_mfma_f32_16x16x32_bf16 v[58:61], v[158:161], v[182:185], v[58:61]
	v_mfma_f32_16x16x32_bf16 v[54:57], v[150:153], v[190:193], v[54:57]
	v_mfma_f32_16x16x32_bf16 v[50:53], v[158:161], v[190:193], v[50:53]
	v_mfma_f32_16x16x32_bf16 v[46:49], v[150:153], v[210:213], v[46:49]
	v_mfma_f32_16x16x32_bf16 v[42:45], v[158:161], v[210:213], v[42:45]
	v_mfma_f32_16x16x32_bf16 v[38:41], v[150:153], v[218:221], v[38:41]
	v_mfma_f32_16x16x32_bf16 v[34:37], v[158:161], v[218:221], v[34:37]
	v_mfma_f32_16x16x32_bf16 v[62:65], v[154:157], v[186:189], v[62:65]
	v_mfma_f32_16x16x32_bf16 v[58:61], v[162:165], v[186:189], v[58:61]
	v_mfma_f32_16x16x32_bf16 v[54:57], v[154:157], v[198:201], v[54:57]
	v_mfma_f32_16x16x32_bf16 v[50:53], v[162:165], v[198:201], v[50:53]
	v_mfma_f32_16x16x32_bf16 v[46:49], v[154:157], v[214:217], v[46:49]
	v_mfma_f32_16x16x32_bf16 v[42:45], v[162:165], v[214:217], v[42:45]
	v_mfma_f32_16x16x32_bf16 v[38:41], v[154:157], v[222:225], v[38:41]
	v_mfma_f32_16x16x32_bf16 v[34:37], v[162:165], v[222:225], v[34:37]
	s_setprio 0
	s_setprio 1
	v_mfma_f32_16x16x32_bf16 v[30:33], v[166:169], v[182:185], v[30:33]
	v_mfma_f32_16x16x32_bf16 v[26:29], v[174:177], v[182:185], v[26:29]
	v_mfma_f32_16x16x32_bf16 v[22:25], v[166:169], v[190:193], v[22:25]
	v_mfma_f32_16x16x32_bf16 v[18:21], v[174:177], v[190:193], v[18:21]
	v_mfma_f32_16x16x32_bf16 v[14:17], v[166:169], v[210:213], v[14:17]
	v_mfma_f32_16x16x32_bf16 v[10:13], v[174:177], v[210:213], v[10:13]
	v_mfma_f32_16x16x32_bf16 v[6:9], v[166:169], v[218:221], v[6:9]
	v_mfma_f32_16x16x32_bf16 v[2:5], v[174:177], v[218:221], v[2:5]
	v_mfma_f32_16x16x32_bf16 v[30:33], v[170:173], v[186:189], v[30:33]
	v_mfma_f32_16x16x32_bf16 v[26:29], v[178:181], v[186:189], v[26:29]
	v_mfma_f32_16x16x32_bf16 v[22:25], v[170:173], v[198:201], v[22:25]
	v_mfma_f32_16x16x32_bf16 v[18:21], v[178:181], v[198:201], v[18:21]
	v_mfma_f32_16x16x32_bf16 v[14:17], v[170:173], v[214:217], v[14:17]
	v_mfma_f32_16x16x32_bf16 v[10:13], v[178:181], v[214:217], v[10:13]
	v_mfma_f32_16x16x32_bf16 v[6:9], v[170:173], v[222:225], v[6:9]
	v_mfma_f32_16x16x32_bf16 v[2:5], v[178:181], v[222:225], v[2:5]
	s_setprio 0
	s_barrier
	s_add_u32 s30, s30, 0x100
	s_addc_u32 s31, s31, 0
	s_add_u32 s19, s19, 0x100
	s_addc_u32 s21, s21, 0
	s_cmp_ge_i32 s29, s68
	s_mov_b32 s23, s29
	s_cbranch_scc0 .LBB0_1973

.LBB0_2341:
	s_add_u32 s2, s82, 0x13500000
	s_addc_u32 s3, s83, 0
	s_ashr_i32 s10, s8, 31
	s_lshr_b32 s10, s10, 29
	s_add_i32 s10, s8, s10
	s_lshr_b32 s12, s14, 6
	s_ashr_i32 s11, s10, 3
	s_and_b32 s10, s10, -8
	s_lshr_b32 s7, s14, 8
	s_lshl_b32 s33, s12, 10
	s_sub_i32 s8, s8, s10
	s_cmp_lt_i32 s8, 0
	s_cselect_b32 s10, 49, 48
	s_mul_i32 s8, s10, s8
	s_add_i32 s8, s8, s11
	s_ashr_i32 s10, s8, 31
	s_lshr_b32 s10, s10, 26
	s_add_i32 s10, s8, s10
	s_ashr_i32 s11, s10, 6
	v_lshrrev_b32_e32 v3, 1, v0
	s_lshl_b32 s11, s11, 3
	v_and_b32_e32 v15, 24, v3
	v_lshrrev_b32_e32 v3, 5, v0
	s_sub_i32 s13, 48, s11
	v_lshlrev_b32_e32 v2, 4, v0
	v_and_b32_e32 v1, 32, v0
	v_and_b32_e32 v3, 4, v3
	v_bfe_u32 v4, v0, 2, 2
	s_min_i32 s13, s13, 8
	v_bfe_u32 v14, v0, 2, 4
	v_bitop3_b32 v12, v2, v1, 48 bitop3:0x6c
	v_and_b32_e32 v13, 64, v0
	v_or3_b32 v3, v3, v4, v15
	v_lshrrev_b32_e32 v4, 3, v0
	s_abs_i32 s15, s13
	v_or_b32_e32 v1, v12, v13
	v_and_or_b32 v5, v4, 48, v14
	v_and_or_b32 v4, v4, 32, v3
	v_or_b32_e32 v16, 0x2000, v2
	v_cvt_f32_u32_e32 v6, s15
	v_lshl_or_b32 v148, v4, 12, v1
	v_lshrrev_b32_e32 v4, 7, v16
	s_movk_i32 s9, 0x70
	v_lshl_or_b32 v146, v5, 12, v1
	v_and_or_b32 v5, v4, s9, v14
	s_movk_i32 s9, 0x60
	v_and_or_b32 v3, v4, s9, v3
	v_lshl_or_b32 v150, v5, 12, v1
	v_lshl_or_b32 v152, v3, 12, v1
	v_rcp_iflag_f32_e32 v1, v6
	s_sub_i32 s17, 0, s15
	s_andn2_b32 s10, s10, 63
	s_sub_i32 s8, s8, s10
	v_mul_f32_e32 v1, 0x4f7ffffe, v1
	v_cvt_u32_f32_e32 v1, v1
	s_abs_i32 s10, s8
	s_xor_b32 s9, s8, s13
	s_ashr_i32 s9, s9, 31
	v_readfirstlane_b32 s18, v1
	s_mul_i32 s17, s17, s18
	s_mul_hi_u32 s17, s18, s17
	s_add_i32 s18, s18, s17
	s_mul_hi_u32 s17, s10, s18
	s_mul_i32 s18, s17, s15
	s_sub_i32 s10, s10, s18
	s_add_i32 s18, s17, 1
	s_sub_i32 s19, s10, s15
	s_cmp_ge_u32 s10, s15
	s_cselect_b32 s17, s18, s17
	s_cselect_b32 s10, s19, s10
	s_add_i32 s18, s17, 1
	s_cmp_ge_u32 s10, s15
	s_cselect_b32 s10, s18, s17
	s_xor_b32 s10, s10, s9
	s_sub_i32 s28, s10, s9
	s_mul_i32 s9, s28, s13
	s_sub_i32 s8, s8, s9
	s_add_i32 s26, s11, s8
	s_ashr_i32 s27, s26, 31
	s_lshl_b64 s[8:9], s[26:27], 20
	v_readlane_b32 s10, v249, 54
	v_readlane_b32 s11, v249, 55
	s_add_u32 s10, s10, s8
	s_addc_u32 s11, s11, s9
	s_ashr_i32 s29, s28, 31
	s_lshl_b64 s[8:9], s[28:29], 20
	s_add_u32 s8, s2, s8
	s_addc_u32 s9, s3, s9
	s_add_u32 s36, s8, s0
	s_addc_u32 s37, s9, s1
	s_add_i32 s27, s33, 0
	s_add_i32 m0, s27, 0x10000
	v_mov_b32_e32 v149, 0
	global_load_lds_dwordx4 v148, s[36:37] sc0
	s_add_i32 m0, s27, 0x12000
	s_add_u32 s8, s36, 0x80000
	global_load_lds_dwordx4 v152, s[36:37] sc0
	s_addc_u32 s9, s37, 0
	s_add_i32 m0, s27, 0x14000
	v_mov_b32_e32 v153, v149
	global_load_lds_dwordx4 v148, s[8:9] sc0
	s_add_i32 m0, s27, 0x16000
	s_add_u32 s34, s10, s0
	s_addc_u32 s35, s11, s1
	s_add_i32 s29, s27, 0x2000
	global_load_lds_dwordx4 v152, s[8:9] sc0
	s_mov_b32 m0, s27
	s_add_u32 s0, s34, 0x80000
	global_load_lds_dwordx4 v146, s[34:35] sc0
	s_mov_b32 m0, s29
	s_addc_u32 s1, s35, 0
	s_add_i32 s42, s27, 0x4000
	global_load_lds_dwordx4 v150, s[34:35] sc0
	s_mov_b32 m0, s42
	s_add_i32 s43, s27, 0x6000
	global_load_lds_dwordx4 v146, s[0:1] sc0
	s_mov_b32 m0, s43
	v_mov_b32_e32 v147, v149
	global_load_lds_dwordx4 v150, s[0:1] sc0
	v_mov_b32_e32 v151, v149
	s_cmp_eq_u32 s7, 1
	s_movk_i32 s44, 0x2000
	s_mov_b32 s45, 0x10000
	v_lshl_add_u64 v[10:11], s[36:37], 0, v[148:149]
	v_lshl_add_u64 v[6:7], s[36:37], 0, v[152:153]
	s_mov_b32 s46, 0x12000
	s_mov_b32 s47, 0x14000
	s_mov_b32 s48, 0x16000
	v_lshl_add_u64 v[8:9], s[34:35], 0, v[146:147]
	v_lshl_add_u64 v[4:5], s[34:35], 0, v[150:151]
	s_movk_i32 s49, 0x4000
	s_cselect_b64 s[8:9], -1, 0
	s_cmp_lg_u32 s7, 1
	s_movk_i32 s50, 0x6000
	s_cbranch_scc1 .LBB0_2343
	s_barrier
.LBB0_2343:
	s_add_u32 s10, s82, 0x27100000
	s_addc_u32 s11, s83, 0
	s_add_u32 s51, s82, 0x2ac000
	s_addc_u32 s52, s83, 0
	s_lshl_b32 s0, s12, 5
	s_mov_b64 s[12:13], 0x80
	s_and_b32 s17, s0, 0x60
	s_add_i32 m0, s27, 0x18000
	v_lshl_add_u64 v[10:11], v[10:11], 0, s[12:13]
	s_lshl_b32 s15, s7, 13
	s_lshl_b32 s18, s17, 7
	s_waitcnt vmcnt(2)
	s_barrier
	global_load_lds_dwordx4 v[10:11], off sc0
	v_lshl_add_u64 v[6:7], v[6:7], 0, s[12:13]
	s_add_i32 m0, s27, 0x1a000
	s_add_i32 s53, s27, 0x8000
	s_add_i32 s54, s27, 0xa000
	global_load_lds_dwordx4 v[6:7], off sc0
	v_lshl_add_u64 v[6:7], v[8:9], 0, s[12:13]
	s_mov_b32 m0, s53
	s_add_u32 s0, s36, 0x80080
	global_load_lds_dwordx4 v[6:7], off sc0
	v_lshl_add_u64 v[4:5], v[4:5], 0, s[12:13]
	s_mov_b32 m0, s54
	s_addc_u32 s1, s37, 0
	global_load_lds_dwordx4 v[4:5], off sc0
	s_add_i32 m0, s27, 0x1c000
	v_lshl_add_u64 v[4:5], s[0:1], 0, v[148:149]
	global_load_lds_dwordx4 v[4:5], off sc0
	v_lshl_add_u64 v[4:5], s[0:1], 0, v[152:153]
	s_add_i32 m0, s27, 0x1e000
	v_lshlrev_b32_e32 v3, 1, v15
	global_load_lds_dwordx4 v[4:5], off sc0
	v_lshl_or_b32 v4, v205, 6, v3
	v_and_b32_e32 v5, 32, v196
	v_bitop3_b32 v4, v4, s15, v5 bitop3:0xde
	s_movk_i32 s0, 0x3c0
	v_readlane_b32 s15, v249, 0
	v_and_or_b32 v3, v209, s0, v3
	s_ashr_i32 s0, s15, 31
	v_bitop3_b32 v168, s18, v3, v5 bitop3:0xf6
	s_lshr_b32 s0, s0, 25
	v_mov_b32_e32 v3, v149
	s_add_i32 s0, s15, s0
	v_lshl_add_u64 v[154:155], s[78:79], 0, v[2:3]
	v_lshlrev_b32_e32 v2, 9, v0
	s_and_b32 s1, s0, 0xffffff80
	v_and_b32_e32 v2, 0x30000, v2
	v_lshlrev_b32_e32 v3, 12, v14
	s_sub_i32 s60, s15, s1
	s_ashr_i32 s0, s0, 7
	v_or3_b32 v2, v12, v2, v3
	s_addk_i32 s60, 0x100
	s_lshl_b32 s61, s0, 4
	v_add_u32_e32 v156, v2, v13
	v_lshlrev_b32_e32 v2, 5, v16
	s_waitcnt vmcnt(6)
	s_cmpk_lt_u32 s14, 0x100
	v_and_b32_e32 v2, 0x70000, v2
	v_lshl_or_b32 v1, s7, 6, v205
	s_mov_b32 s7, 0
	s_cselect_b64 s[14:15], -1, 0
	s_lshr_b32 s0, s16, 2
	v_or3_b32 v2, v12, v2, v3
	s_add_i32 s63, 0, 0x10000
	s_add_i32 s64, 0, 0x14000
	s_mov_b32 s55, 0x18000
	s_mov_b32 s56, 0x1a000
	s_mov_b32 s57, 0x8000
	s_mov_b32 s58, 0xa000
	s_mov_b32 s59, 0x1c000
	s_xor_b32 s62, s0, 1
	v_or_b32_e32 v169, s17, v15
	v_mov_b32_e32 v157, v149
	v_add_u32_e32 v158, v2, v13
	v_mov_b32_e32 v159, v149
	s_mov_b64 s[30:31], -1
	v_add_u32_e32 v170, s63, v168
	v_add_u32_e32 v171, s64, v168
	v_add_u32_e32 v172, 0, v4
	s_mov_b32 s65, 0xc000
	s_mov_b32 s66, 0xe000
	s_mov_b32 s17, s7
	s_barrier
	s_branch .LBB0_2346

.LBB0_2532:
	v_lshrrev_b32_e32 v3, 1, v0
	v_and_b32_e32 v15, 24, v3
	v_lshrrev_b32_e32 v3, 5, v0
	s_add_u32 s2, s82, 0x8800000
	v_lshlrev_b32_e32 v2, 4, v0
	v_and_b32_e32 v1, 32, v0
	v_and_b32_e32 v3, 4, v3
	v_bfe_u32 v4, v0, 2, 2
	s_addc_u32 s3, s83, 0
	v_bfe_u32 v14, v0, 2, 4
	v_bitop3_b32 v12, v2, v1, 48 bitop3:0x6c
	v_and_b32_e32 v13, 64, v0
	v_or3_b32 v3, v3, v4, v15
	v_lshrrev_b32_e32 v4, 3, v0
	s_ashr_i32 s14, s11, 31
	v_or_b32_e32 v1, v12, v13
	v_and_or_b32 v5, v4, 48, v14
	v_and_or_b32 v4, v4, 32, v3
	v_or_b32_e32 v16, 0x2000, v2
	s_lshr_b32 s14, s14, 29
	v_lshl_or_b32 v132, v4, 12, v1
	v_lshrrev_b32_e32 v4, 7, v16
	s_movk_i32 s10, 0x70
	s_add_i32 s14, s11, s14
	v_lshl_or_b32 v130, v5, 12, v1
	v_and_or_b32 v5, v4, s10, v14
	s_lshr_b32 s10, s12, 6
	s_ashr_i32 s15, s14, 3
	s_and_b32 s14, s14, -8
	s_lshr_b32 s7, s12, 8
	s_lshl_b32 s33, s10, 10
	s_sub_i32 s11, s11, s14
	s_cmp_lt_i32 s11, 0
	s_movk_i32 s40, 0x109
	s_cselect_b32 s14, s40, 0x108
	s_mul_i32 s11, s14, s11
	s_add_i32 s11, s11, s15
	s_mul_hi_i32 s14, s11, 0x2e8ba2e9
	s_lshr_b32 s15, s14, 31
	s_ashr_i32 s14, s14, 6
	s_add_i32 s14, s14, s15
	s_lshl_b32 s15, s14, 3
	s_sub_i32 s16, 48, s15
	s_min_i32 s16, s16, 8
	s_abs_i32 s17, s16
	v_cvt_f32_u32_e32 v6, s17
	s_movk_i32 s13, 0x60
	v_and_or_b32 v3, v4, s13, v3
	v_lshl_or_b32 v134, v5, 12, v1
	v_lshl_or_b32 v136, v3, 12, v1
	v_rcp_iflag_f32_e32 v1, v6
	s_sub_i32 s18, 0, s17
	s_mulk_i32 s14, 0x160
	s_sub_i32 s11, s11, s14
	v_mul_f32_e32 v1, 0x4f7ffffe, v1
	v_cvt_u32_f32_e32 v1, v1
	s_abs_i32 s14, s11
	s_xor_b32 s13, s11, s16
	s_ashr_i32 s13, s13, 31
	v_readfirstlane_b32 s19, v1
	s_mul_i32 s18, s18, s19
	s_mul_hi_u32 s18, s19, s18
	s_add_i32 s19, s19, s18
	s_mul_hi_u32 s18, s14, s19
	s_mul_i32 s19, s18, s17
	s_sub_i32 s14, s14, s19
	s_add_i32 s19, s18, 1
	s_sub_i32 s20, s14, s17
	s_cmp_ge_u32 s14, s17
	s_cselect_b32 s18, s19, s18
	s_cselect_b32 s14, s20, s14
	s_add_i32 s19, s18, 1
	s_cmp_ge_u32 s14, s17
	s_cselect_b32 s14, s19, s18
	s_xor_b32 s14, s14, s13
	s_sub_i32 s26, s14, s13
	s_mul_i32 s13, s26, s16
	s_sub_i32 s11, s11, s13
	s_add_i32 s24, s15, s11
	s_ashr_i32 s25, s24, 31
	s_lshl_b64 s[14:15], s[24:25], 20
	v_readlane_b32 s16, v249, 50
	v_readlane_b32 s17, v249, 51
	s_add_u32 s11, s16, s14
	s_addc_u32 s13, s17, s15
	s_ashr_i32 s27, s26, 31
	s_lshl_b64 s[14:15], s[26:27], 20
	s_add_u32 s14, s2, s14
	s_addc_u32 s15, s3, s15
	s_add_u32 s34, s14, s8
	s_addc_u32 s35, s15, s9
	s_add_i32 s27, s33, 0
	s_add_i32 m0, s27, 0x10000
	v_mov_b32_e32 v133, 0
	global_load_lds_dwordx4 v132, s[34:35] sc0
	s_add_i32 m0, s27, 0x12000
	s_add_u32 s14, s34, 0x80000
	global_load_lds_dwordx4 v136, s[34:35] sc0
	s_addc_u32 s15, s35, 0
	s_add_i32 m0, s27, 0x14000
	v_mov_b32_e32 v137, v133
	global_load_lds_dwordx4 v132, s[14:15] sc0
	s_add_i32 m0, s27, 0x16000
	s_add_u32 s30, s11, s8
	s_addc_u32 s31, s13, s9
	s_add_i32 s41, s27, 0x2000
	global_load_lds_dwordx4 v136, s[14:15] sc0
	s_mov_b32 m0, s27
	s_add_u32 s8, s30, 0x80000
	global_load_lds_dwordx4 v130, s[30:31] sc0
	s_mov_b32 m0, s41
	s_addc_u32 s9, s31, 0
	s_add_i32 s42, s27, 0x4000
	global_load_lds_dwordx4 v134, s[30:31] sc0
	s_mov_b32 m0, s42
	s_add_i32 s43, s27, 0x6000
	global_load_lds_dwordx4 v130, s[8:9] sc0
	s_mov_b32 m0, s43
	v_mov_b32_e32 v131, v133
	global_load_lds_dwordx4 v134, s[8:9] sc0
	v_mov_b32_e32 v135, v133
	s_cmp_eq_u32 s7, 1
	s_movk_i32 s44, 0x2000
	s_mov_b32 s45, 0x10000
	v_lshl_add_u64 v[10:11], s[34:35], 0, v[132:133]
	v_lshl_add_u64 v[6:7], s[34:35], 0, v[136:137]
	s_mov_b32 s46, 0x12000
	s_mov_b32 s47, 0x14000
	s_mov_b32 s48, 0x16000
	v_lshl_add_u64 v[8:9], s[30:31], 0, v[130:131]
	v_lshl_add_u64 v[4:5], s[30:31], 0, v[134:135]
	s_movk_i32 s49, 0x4000
	s_cselect_b64 s[8:9], -1, 0
	s_cmp_lg_u32 s7, 1
	s_movk_i32 s50, 0x6000
	s_cbranch_scc1 .LBB0_2534
	s_barrier
.LBB0_2534:
	s_lshl_b32 s10, s10, 5
	s_and_b32 s16, s10, 0x60
	s_mov_b64 s[10:11], 0x80
	s_add_i32 m0, s27, 0x18000
	v_lshl_add_u64 v[10:11], v[10:11], 0, s[10:11]
	s_lshl_b32 s13, s7, 13
	s_lshl_b32 s17, s16, 7
	s_waitcnt vmcnt(2)
	s_barrier
	global_load_lds_dwordx4 v[10:11], off sc0
	v_lshl_add_u64 v[6:7], v[6:7], 0, s[10:11]
	s_add_i32 m0, s27, 0x1a000
	s_add_i32 s51, s27, 0x8000
	s_add_i32 s52, s27, 0xa000
	global_load_lds_dwordx4 v[6:7], off sc0
	v_lshl_add_u64 v[6:7], v[8:9], 0, s[10:11]
	s_mov_b32 m0, s51
	s_add_u32 s14, s34, 0x80080
	global_load_lds_dwordx4 v[6:7], off sc0
	v_lshl_add_u64 v[4:5], v[4:5], 0, s[10:11]
	s_mov_b32 m0, s52
	s_addc_u32 s15, s35, 0
	global_load_lds_dwordx4 v[4:5], off sc0
	s_add_i32 m0, s27, 0x1c000
	v_lshl_add_u64 v[4:5], s[14:15], 0, v[132:133]
	global_load_lds_dwordx4 v[4:5], off sc0
	v_lshl_add_u64 v[4:5], s[14:15], 0, v[136:137]
	s_add_i32 m0, s27, 0x1e000
	v_lshlrev_b32_e32 v3, 1, v15
	global_load_lds_dwordx4 v[4:5], off sc0
	v_lshl_or_b32 v1, s7, 6, v205
	v_lshl_or_b32 v4, v205, 6, v3
	v_and_b32_e32 v5, 32, v196
	s_movk_i32 s7, 0x3c0
	v_readlane_b32 s15, v249, 0
	v_bitop3_b32 v4, v4, s13, v5 bitop3:0xde
	v_and_or_b32 v3, v209, s7, v3
	s_ashr_i32 s13, s15, 31
	v_bitop3_b32 v146, s17, v3, v5 bitop3:0xf6
	s_lshr_b32 s13, s13, 26
	v_mov_b32_e32 v3, v133
	s_add_i32 s13, s15, s13
	v_lshl_add_u64 v[138:139], s[78:79], 0, v[2:3]
	v_lshlrev_b32_e32 v2, 9, v0
	s_ashr_i32 s14, s13, 6
	s_andn2_b32 s13, s13, 63
	v_and_b32_e32 v2, 0x30000, v2
	v_lshlrev_b32_e32 v3, 12, v14
	s_sub_i32 s58, s15, s13
	v_or3_b32 v2, v12, v2, v3
	s_addk_i32 s58, 0x800
	s_lshl_b32 s59, s14, 3
	v_add_u32_e32 v140, v2, v13
	v_lshlrev_b32_e32 v2, 5, v16
	s_waitcnt vmcnt(6)
	s_cmpk_lt_u32 s12, 0x100
	v_and_b32_e32 v2, 0x70000, v2
	s_mov_b32 s7, 0
	s_cselect_b64 s[12:13], -1, 0
	v_or3_b32 v2, v12, v2, v3
	s_add_i32 s60, 0, 0x10000
	s_add_i32 s61, 0, 0x14000
	s_mov_b32 s53, 0x18000
	s_mov_b32 s54, 0x1a000
	s_mov_b32 s55, 0x8000
	s_mov_b32 s56, 0xa000
	s_mov_b32 s57, 0x1c000
	v_or_b32_e32 v147, s16, v15
	v_mov_b32_e32 v141, v133
	v_add_u32_e32 v142, v2, v13
	v_mov_b32_e32 v143, v133
	v_add_u32_e32 v148, s60, v146
	v_add_u32_e32 v149, s61, v146
	v_add_u32_e32 v150, 0, v4
	s_mov_b32 s62, 0xc000
	s_mov_b32 s63, 0xe000
	s_movk_i32 s64, 0x2c00
	s_mov_b32 s25, s7
	s_barrier
	s_branch .LBB0_2537

.Lpeel_1:
	ds_read_b128 v[152:155], v148
	ds_read_b128 v[156:159], v148 offset:1024
	ds_read_b128 v[160:163], v148 offset:2048
	ds_read_b128 v[164:167], v148 offset:3072
	ds_read_b128 v[168:171], v149
	ds_read_b128 v[172:175], v149 offset:1024
	ds_read_b128 v[176:179], v149 offset:2048
	ds_read_b128 v[180:183], v149 offset:3072
	s_add_i32 s29, s19, 2
	s_add_u32 s34, s30, 0xfff80080
	s_addc_u32 s35, s31, -1
	s_cmp_eq_u32 s28, s19
	s_cselect_b32 s37, s21, s35
	s_cselect_b32 s36, s20, s34
	s_cselect_b32 s35, s23, s17
	s_cselect_b32 s34, s22, s15
	v_lshl_add_u64 v[144:145], s[30:31], 0, v[140:141]
	s_add_i32 m0, s27, 0xc000
	ds_read_b128 v[184:187], v150
	ds_read_b128 v[188:191], v150 offset:1024
	ds_read_b128 v[192:195], v150 offset:2048
	ds_read_b128 v[198:201], v150 offset:3072
	ds_read_b128 v[210:213], v150 offset:4096
	ds_read_b128 v[214:217], v150 offset:5120
	ds_read_b128 v[218:221], v150 offset:6144
	ds_read_b128 v[222:225], v150 offset:7168
	global_load_lds_dwordx4 v[144:145], off sc0
	v_lshl_add_u64 v[144:145], s[30:31], 0, v[142:143]
	s_add_i32 m0, s27, 0xe000
	s_nop 0
	global_load_lds_dwordx4 v[144:145], off sc0
	s_waitcnt vmcnt(8)
	s_waitcnt lgkmcnt(0)
	s_barrier
	s_setprio 1
	s_waitcnt lgkmcnt(0)
	v_mfma_f32_16x16x32_bf16 v[126:129], v[152:155], v[184:187], 0
	v_mfma_f32_16x16x32_bf16 v[122:125], v[160:163], v[184:187], 0
	v_mfma_f32_16x16x32_bf16 v[110:113], v[152:155], v[192:195], 0
	v_mfma_f32_16x16x32_bf16 v[106:109], v[160:163], v[192:195], 0
	v_mfma_f32_16x16x32_bf16 v[94:97], v[152:155], v[210:213], 0
	v_mfma_f32_16x16x32_bf16 v[90:93], v[160:163], v[210:213], 0
	v_mfma_f32_16x16x32_bf16 v[78:81], v[152:155], v[218:221], 0
	v_mfma_f32_16x16x32_bf16 v[74:77], v[160:163], v[218:221], 0
	v_mfma_f32_16x16x32_bf16 v[126:129], v[156:159], v[188:191], v[126:129]
	v_mfma_f32_16x16x32_bf16 v[122:125], v[164:167], v[188:191], v[122:125]
	v_mfma_f32_16x16x32_bf16 v[110:113], v[156:159], v[198:201], v[110:113]
	v_mfma_f32_16x16x32_bf16 v[106:109], v[164:167], v[198:201], v[106:109]
	v_mfma_f32_16x16x32_bf16 v[94:97], v[156:159], v[214:217], v[94:97]
	v_mfma_f32_16x16x32_bf16 v[90:93], v[164:167], v[214:217], v[90:93]
	v_mfma_f32_16x16x32_bf16 v[78:81], v[156:159], v[222:225], v[78:81]
	v_mfma_f32_16x16x32_bf16 v[74:77], v[164:167], v[222:225], v[74:77]
	s_setprio 0
	s_setprio 1
	v_mfma_f32_16x16x32_bf16 v[118:121], v[168:171], v[184:187], 0
	v_mfma_f32_16x16x32_bf16 v[114:117], v[176:179], v[184:187], 0
	v_mfma_f32_16x16x32_bf16 v[102:105], v[168:171], v[192:195], 0
	v_mfma_f32_16x16x32_bf16 v[98:101], v[176:179], v[192:195], 0
	v_mfma_f32_16x16x32_bf16 v[86:89], v[168:171], v[210:213], 0
	v_mfma_f32_16x16x32_bf16 v[82:85], v[176:179], v[210:213], 0
	v_mfma_f32_16x16x32_bf16 v[70:73], v[168:171], v[218:221], 0
	v_mfma_f32_16x16x32_bf16 v[66:69], v[176:179], v[218:221], 0
	v_mfma_f32_16x16x32_bf16 v[118:121], v[172:175], v[188:191], v[118:121]
	v_mfma_f32_16x16x32_bf16 v[114:117], v[180:183], v[188:191], v[114:117]
	v_mfma_f32_16x16x32_bf16 v[102:105], v[172:175], v[198:201], v[102:105]
	v_mfma_f32_16x16x32_bf16 v[98:101], v[180:183], v[198:201], v[98:101]
	v_mfma_f32_16x16x32_bf16 v[86:89], v[172:175], v[214:217], v[86:89]
	v_mfma_f32_16x16x32_bf16 v[82:85], v[180:183], v[214:217], v[82:85]
	v_mfma_f32_16x16x32_bf16 v[70:73], v[172:175], v[222:225], v[70:73]
	v_mfma_f32_16x16x32_bf16 v[66:69], v[180:183], v[222:225], v[66:69]
	s_setprio 0
	s_barrier
	s_add_i32 s19, s60, s33
	v_lshl_add_u64 v[144:145], s[34:35], 0, v[132:133]
	s_mov_b32 m0, s19
	ds_read_b128 v[184:187], v150 offset:16384
	ds_read_b128 v[188:191], v150 offset:17408
	ds_read_b128 v[192:195], v150 offset:18432
	ds_read_b128 v[198:201], v150 offset:19456
	ds_read_b128 v[210:213], v150 offset:20480
	ds_read_b128 v[214:217], v150 offset:21504
	ds_read_b128 v[218:221], v150 offset:22528
	ds_read_b128 v[222:225], v150 offset:23552
	global_load_lds_dwordx4 v[144:145], off sc0
	s_add_i32 m0, s19, 0x2000
	s_add_u32 s38, s34, 0x80000
	v_lshl_add_u64 v[202:203], s[34:35], 0, v[136:137]
	s_addc_u32 s39, s35, 0
	s_add_i32 s19, s61, s33
	global_load_lds_dwordx4 v[202:203], off sc0
	v_lshl_add_u64 v[206:207], s[38:39], 0, v[132:133]
	s_mov_b32 m0, s19
	v_lshl_add_u64 v[226:227], s[36:37], 0, v[134:135]
	global_load_lds_dwordx4 v[206:207], off sc0
	v_lshl_add_u64 v[206:207], s[38:39], 0, v[136:137]
	s_add_i32 m0, s19, 0x2000
	s_nop 0
	global_load_lds_dwordx4 v[206:207], off sc0
	v_lshl_add_u64 v[206:207], s[36:37], 0, v[130:131]
	s_mov_b32 m0, s27
	s_nop 0
	global_load_lds_dwordx4 v[206:207], off sc0
	s_mov_b32 m0, s41
	s_nop 0
	global_load_lds_dwordx4 v[226:227], off sc0
	s_waitcnt vmcnt(8)
	s_waitcnt lgkmcnt(0)
	s_barrier
	s_setprio 1
	s_waitcnt lgkmcnt(0)
	v_mfma_f32_16x16x32_bf16 v[62:65], v[152:155], v[184:187], 0
	v_mfma_f32_16x16x32_bf16 v[58:61], v[160:163], v[184:187], 0
	v_mfma_f32_16x16x32_bf16 v[46:49], v[152:155], v[192:195], 0
	v_mfma_f32_16x16x32_bf16 v[42:45], v[160:163], v[192:195], 0
	v_mfma_f32_16x16x32_bf16 v[30:33], v[152:155], v[210:213], 0
	v_mfma_f32_16x16x32_bf16 v[26:29], v[160:163], v[210:213], 0
	v_mfma_f32_16x16x32_bf16 v[14:17], v[152:155], v[218:221], 0
	v_mfma_f32_16x16x32_bf16 v[10:13], v[160:163], v[218:221], 0
	v_mfma_f32_16x16x32_bf16 v[62:65], v[156:159], v[188:191], v[62:65]
	v_mfma_f32_16x16x32_bf16 v[58:61], v[164:167], v[188:191], v[58:61]
	v_mfma_f32_16x16x32_bf16 v[46:49], v[156:159], v[198:201], v[46:49]
	v_mfma_f32_16x16x32_bf16 v[42:45], v[164:167], v[198:201], v[42:45]
	v_mfma_f32_16x16x32_bf16 v[30:33], v[156:159], v[214:217], v[30:33]
	v_mfma_f32_16x16x32_bf16 v[26:29], v[164:167], v[214:217], v[26:29]
	v_mfma_f32_16x16x32_bf16 v[14:17], v[156:159], v[222:225], v[14:17]
	v_mfma_f32_16x16x32_bf16 v[10:13], v[164:167], v[222:225], v[10:13]
	s_setprio 0
	s_setprio 1
	v_mfma_f32_16x16x32_bf16 v[54:57], v[168:171], v[184:187], 0
	v_mfma_f32_16x16x32_bf16 v[50:53], v[176:179], v[184:187], 0
	v_mfma_f32_16x16x32_bf16 v[38:41], v[168:171], v[192:195], 0
	v_mfma_f32_16x16x32_bf16 v[34:37], v[176:179], v[192:195], 0
	v_mfma_f32_16x16x32_bf16 v[22:25], v[168:171], v[210:213], 0
	v_mfma_f32_16x16x32_bf16 v[18:21], v[176:179], v[210:213], 0
	v_mfma_f32_16x16x32_bf16 v[6:9], v[168:171], v[218:221], 0
	v_mfma_f32_16x16x32_bf16 v[2:5], v[176:179], v[218:221], 0
	v_mfma_f32_16x16x32_bf16 v[54:57], v[172:175], v[188:191], v[54:57]
	v_mfma_f32_16x16x32_bf16 v[50:53], v[180:183], v[188:191], v[50:53]
	v_mfma_f32_16x16x32_bf16 v[38:41], v[172:175], v[198:201], v[38:41]
	v_mfma_f32_16x16x32_bf16 v[34:37], v[180:183], v[198:201], v[34:37]
	v_mfma_f32_16x16x32_bf16 v[22:25], v[172:175], v[214:217], v[22:25]
	v_mfma_f32_16x16x32_bf16 v[18:21], v[180:183], v[214:217], v[18:21]
	v_mfma_f32_16x16x32_bf16 v[6:9], v[172:175], v[222:225], v[6:9]
	v_mfma_f32_16x16x32_bf16 v[2:5], v[180:183], v[222:225], v[2:5]
	s_setprio 0
	s_barrier
	s_add_i32 s19, 0, 0x18000
	v_add_u32_e32 v151, s19, v146
	s_add_i32 s38, 0, 0x1c000
	ds_read_b128 v[152:155], v151
	ds_read_b128 v[156:159], v151 offset:1024
	ds_read_b128 v[160:163], v151 offset:2048
	ds_read_b128 v[164:167], v151 offset:3072
	v_add_u32_e32 v151, s38, v146
	ds_read_b128 v[168:171], v151
	ds_read_b128 v[172:175], v151 offset:1024
	ds_read_b128 v[176:179], v151 offset:2048
	ds_read_b128 v[180:183], v151 offset:3072
	s_add_u32 s36, s36, 0x80000
	s_addc_u32 s37, s37, 0
	s_mov_b32 m0, s42
	v_lshl_add_u64 v[228:229], s[36:37], 0, v[130:131]
	ds_read_b128 v[184:187], v150 offset:32768
	ds_read_b128 v[188:191], v150 offset:33792
	ds_read_b128 v[192:195], v150 offset:34816
	ds_read_b128 v[198:201], v150 offset:35840
	ds_read_b128 v[210:213], v150 offset:36864
	ds_read_b128 v[214:217], v150 offset:37888
	ds_read_b128 v[218:221], v150 offset:38912
	ds_read_b128 v[222:225], v150 offset:39936
	global_load_lds_dwordx4 v[228:229], off sc0
	v_lshl_add_u64 v[228:229], s[36:37], 0, v[134:135]
	s_mov_b32 m0, s43
	s_nop 0
	global_load_lds_dwordx4 v[228:229], off sc0
	s_waitcnt vmcnt(8)
	s_waitcnt lgkmcnt(0)
	s_barrier
	s_setprio 1
	s_waitcnt lgkmcnt(0)
	v_mfma_f32_16x16x32_bf16 v[126:129], v[152:155], v[184:187], v[126:129]
	v_mfma_f32_16x16x32_bf16 v[122:125], v[160:163], v[184:187], v[122:125]
	v_mfma_f32_16x16x32_bf16 v[110:113], v[152:155], v[192:195], v[110:113]
	v_mfma_f32_16x16x32_bf16 v[106:109], v[160:163], v[192:195], v[106:109]
	v_mfma_f32_16x16x32_bf16 v[94:97], v[152:155], v[210:213], v[94:97]
	v_mfma_f32_16x16x32_bf16 v[90:93], v[160:163], v[210:213], v[90:93]
	v_mfma_f32_16x16x32_bf16 v[78:81], v[152:155], v[218:221], v[78:81]
	v_mfma_f32_16x16x32_bf16 v[74:77], v[160:163], v[218:221], v[74:77]
	v_mfma_f32_16x16x32_bf16 v[126:129], v[156:159], v[188:191], v[126:129]
	v_mfma_f32_16x16x32_bf16 v[122:125], v[164:167], v[188:191], v[122:125]
	v_mfma_f32_16x16x32_bf16 v[110:113], v[156:159], v[198:201], v[110:113]
	v_mfma_f32_16x16x32_bf16 v[106:109], v[164:167], v[198:201], v[106:109]
	v_mfma_f32_16x16x32_bf16 v[94:97], v[156:159], v[214:217], v[94:97]
	v_mfma_f32_16x16x32_bf16 v[90:93], v[164:167], v[214:217], v[90:93]
	v_mfma_f32_16x16x32_bf16 v[78:81], v[156:159], v[222:225], v[78:81]
	v_mfma_f32_16x16x32_bf16 v[74:77], v[164:167], v[222:225], v[74:77]
	s_setprio 0
	s_setprio 1
	v_mfma_f32_16x16x32_bf16 v[118:121], v[168:171], v[184:187], v[118:121]
	v_mfma_f32_16x16x32_bf16 v[114:117], v[176:179], v[184:187], v[114:117]
	v_mfma_f32_16x16x32_bf16 v[102:105], v[168:171], v[192:195], v[102:105]
	v_mfma_f32_16x16x32_bf16 v[98:101], v[176:179], v[192:195], v[98:101]
	v_mfma_f32_16x16x32_bf16 v[86:89], v[168:171], v[210:213], v[86:89]
	v_mfma_f32_16x16x32_bf16 v[82:85], v[176:179], v[210:213], v[82:85]
	v_mfma_f32_16x16x32_bf16 v[70:73], v[168:171], v[218:221], v[70:73]
	v_mfma_f32_16x16x32_bf16 v[66:69], v[176:179], v[218:221], v[66:69]
	v_mfma_f32_16x16x32_bf16 v[118:121], v[172:175], v[188:191], v[118:121]
	v_mfma_f32_16x16x32_bf16 v[114:117], v[180:183], v[188:191], v[114:117]
	v_mfma_f32_16x16x32_bf16 v[102:105], v[172:175], v[198:201], v[102:105]
	v_mfma_f32_16x16x32_bf16 v[98:101], v[180:183], v[198:201], v[98:101]
	v_mfma_f32_16x16x32_bf16 v[86:89], v[172:175], v[214:217], v[86:89]
	v_mfma_f32_16x16x32_bf16 v[82:85], v[180:183], v[214:217], v[82:85]
	v_mfma_f32_16x16x32_bf16 v[70:73], v[172:175], v[222:225], v[70:73]
	v_mfma_f32_16x16x32_bf16 v[66:69], v[180:183], v[222:225], v[66:69]
	s_setprio 0
	s_barrier
	s_add_i32 s19, s19, s33
	v_lshl_add_u64 v[144:145], v[144:145], 0, s[10:11]
	s_mov_b32 m0, s19
	ds_read_b128 v[184:187], v150 offset:49152
	ds_read_b128 v[188:191], v150 offset:50176
	ds_read_b128 v[192:195], v150 offset:51200
	ds_read_b128 v[198:201], v150 offset:52224
	ds_read_b128 v[210:213], v150 offset:53248
	ds_read_b128 v[214:217], v150 offset:54272
	ds_read_b128 v[218:221], v150 offset:55296
	ds_read_b128 v[222:225], v150 offset:56320
	global_load_lds_dwordx4 v[144:145], off sc0
	s_add_i32 m0, s19, 0x2000
	s_add_u32 s34, s34, 0x80080
	v_lshl_add_u64 v[144:145], v[202:203], 0, s[10:11]
	s_addc_u32 s35, s35, 0
	s_add_i32 s19, s38, s33
	global_load_lds_dwordx4 v[144:145], off sc0
	v_lshl_add_u64 v[144:145], s[34:35], 0, v[132:133]
	s_mov_b32 m0, s19
	s_nop 0
	global_load_lds_dwordx4 v[144:145], off sc0
	v_lshl_add_u64 v[144:145], s[34:35], 0, v[136:137]
	s_add_i32 m0, s19, 0x2000
	s_nop 0
	global_load_lds_dwordx4 v[144:145], off sc0
	v_lshl_add_u64 v[144:145], v[206:207], 0, s[10:11]
	s_mov_b32 m0, s51
	s_nop 0
	global_load_lds_dwordx4 v[144:145], off sc0
	v_lshl_add_u64 v[144:145], v[226:227], 0, s[10:11]
	s_mov_b32 m0, s52
	s_nop 0
	global_load_lds_dwordx4 v[144:145], off sc0
	s_waitcnt vmcnt(8)
	s_waitcnt lgkmcnt(0)
	s_barrier
	s_setprio 1
	s_waitcnt lgkmcnt(0)
	v_mfma_f32_16x16x32_bf16 v[62:65], v[152:155], v[184:187], v[62:65]
	v_mfma_f32_16x16x32_bf16 v[58:61], v[160:163], v[184:187], v[58:61]
	v_mfma_f32_16x16x32_bf16 v[46:49], v[152:155], v[192:195], v[46:49]
	v_mfma_f32_16x16x32_bf16 v[42:45], v[160:163], v[192:195], v[42:45]
	v_mfma_f32_16x16x32_bf16 v[30:33], v[152:155], v[210:213], v[30:33]
	v_mfma_f32_16x16x32_bf16 v[26:29], v[160:163], v[210:213], v[26:29]
	v_mfma_f32_16x16x32_bf16 v[14:17], v[152:155], v[218:221], v[14:17]
	v_mfma_f32_16x16x32_bf16 v[10:13], v[160:163], v[218:221], v[10:13]
	v_mfma_f32_16x16x32_bf16 v[62:65], v[156:159], v[188:191], v[62:65]
	v_mfma_f32_16x16x32_bf16 v[58:61], v[164:167], v[188:191], v[58:61]
	v_mfma_f32_16x16x32_bf16 v[46:49], v[156:159], v[198:201], v[46:49]
	v_mfma_f32_16x16x32_bf16 v[42:45], v[164:167], v[198:201], v[42:45]
	v_mfma_f32_16x16x32_bf16 v[30:33], v[156:159], v[214:217], v[30:33]
	v_mfma_f32_16x16x32_bf16 v[26:29], v[164:167], v[214:217], v[26:29]
	v_mfma_f32_16x16x32_bf16 v[14:17], v[156:159], v[222:225], v[14:17]
	v_mfma_f32_16x16x32_bf16 v[10:13], v[164:167], v[222:225], v[10:13]
	s_setprio 0
	s_setprio 1
	v_mfma_f32_16x16x32_bf16 v[54:57], v[168:171], v[184:187], v[54:57]
	v_mfma_f32_16x16x32_bf16 v[50:53], v[176:179], v[184:187], v[50:53]
	v_mfma_f32_16x16x32_bf16 v[38:41], v[168:171], v[192:195], v[38:41]
	v_mfma_f32_16x16x32_bf16 v[34:37], v[176:179], v[192:195], v[34:37]
	v_mfma_f32_16x16x32_bf16 v[22:25], v[168:171], v[210:213], v[22:25]
	v_mfma_f32_16x16x32_bf16 v[18:21], v[176:179], v[210:213], v[18:21]
	v_mfma_f32_16x16x32_bf16 v[6:9], v[168:171], v[218:221], v[6:9]
	v_mfma_f32_16x16x32_bf16 v[2:5], v[176:179], v[218:221], v[2:5]
	v_mfma_f32_16x16x32_bf16 v[54:57], v[172:175], v[188:191], v[54:57]
	v_mfma_f32_16x16x32_bf16 v[50:53], v[180:183], v[188:191], v[50:53]
	v_mfma_f32_16x16x32_bf16 v[38:41], v[172:175], v[198:201], v[38:41]
	v_mfma_f32_16x16x32_bf16 v[34:37], v[180:183], v[198:201], v[34:37]
	v_mfma_f32_16x16x32_bf16 v[22:25], v[172:175], v[214:217], v[22:25]
	v_mfma_f32_16x16x32_bf16 v[18:21], v[180:183], v[214:217], v[18:21]
	v_mfma_f32_16x16x32_bf16 v[6:9], v[172:175], v[222:225], v[6:9]
	v_mfma_f32_16x16x32_bf16 v[2:5], v[180:183], v[222:225], v[2:5]
	s_setprio 0
	s_barrier
	s_add_u32 s30, s30, 0x100
	s_addc_u32 s31, s31, 0
	s_add_u32 s15, s15, 0x100
	s_addc_u32 s17, s17, 0
	s_cmp_ge_i32 s29, s68
	s_mov_b32 s19, s29
	s_cbranch_scc0 .LBB0_2547
	s_branch .Lpeeldone_1
.LBB0_2547:
	ds_read_b128 v[152:155], v148
	ds_read_b128 v[156:159], v148 offset:1024
	ds_read_b128 v[160:163], v148 offset:2048
	ds_read_b128 v[164:167], v148 offset:3072
	ds_read_b128 v[168:171], v149
	ds_read_b128 v[172:175], v149 offset:1024
	ds_read_b128 v[176:179], v149 offset:2048
	ds_read_b128 v[180:183], v149 offset:3072
	s_add_i32 s29, s19, 2
	s_add_u32 s34, s30, 0xfff80080
	s_addc_u32 s35, s31, -1
	s_cmp_eq_u32 s28, s19
	s_cselect_b32 s37, s21, s35
	s_cselect_b32 s36, s20, s34
	s_cselect_b32 s35, s23, s17
	s_cselect_b32 s34, s22, s15
	v_lshl_add_u64 v[144:145], s[30:31], 0, v[140:141]
	s_add_i32 m0, s27, 0xc000
	ds_read_b128 v[184:187], v150
	ds_read_b128 v[188:191], v150 offset:1024
	ds_read_b128 v[192:195], v150 offset:2048
	ds_read_b128 v[198:201], v150 offset:3072
	ds_read_b128 v[210:213], v150 offset:4096
	ds_read_b128 v[214:217], v150 offset:5120
	ds_read_b128 v[218:221], v150 offset:6144
	ds_read_b128 v[222:225], v150 offset:7168
	global_load_lds_dwordx4 v[144:145], off sc0
	v_lshl_add_u64 v[144:145], s[30:31], 0, v[142:143]
	s_add_i32 m0, s27, 0xe000
	s_nop 0
	global_load_lds_dwordx4 v[144:145], off sc0
	s_waitcnt vmcnt(8)
	s_waitcnt lgkmcnt(0)
	s_barrier
	s_setprio 1
	s_waitcnt lgkmcnt(0)
	v_mfma_f32_16x16x32_bf16 v[126:129], v[152:155], v[184:187], v[126:129]
	v_mfma_f32_16x16x32_bf16 v[122:125], v[160:163], v[184:187], v[122:125]
	v_mfma_f32_16x16x32_bf16 v[110:113], v[152:155], v[192:195], v[110:113]
	v_mfma_f32_16x16x32_bf16 v[106:109], v[160:163], v[192:195], v[106:109]
	v_mfma_f32_16x16x32_bf16 v[94:97], v[152:155], v[210:213], v[94:97]
	v_mfma_f32_16x16x32_bf16 v[90:93], v[160:163], v[210:213], v[90:93]
	v_mfma_f32_16x16x32_bf16 v[78:81], v[152:155], v[218:221], v[78:81]
	v_mfma_f32_16x16x32_bf16 v[74:77], v[160:163], v[218:221], v[74:77]
	v_mfma_f32_16x16x32_bf16 v[126:129], v[156:159], v[188:191], v[126:129]
	v_mfma_f32_16x16x32_bf16 v[122:125], v[164:167], v[188:191], v[122:125]
	v_mfma_f32_16x16x32_bf16 v[110:113], v[156:159], v[198:201], v[110:113]
	v_mfma_f32_16x16x32_bf16 v[106:109], v[164:167], v[198:201], v[106:109]
	v_mfma_f32_16x16x32_bf16 v[94:97], v[156:159], v[214:217], v[94:97]
	v_mfma_f32_16x16x32_bf16 v[90:93], v[164:167], v[214:217], v[90:93]
	v_mfma_f32_16x16x32_bf16 v[78:81], v[156:159], v[222:225], v[78:81]
	v_mfma_f32_16x16x32_bf16 v[74:77], v[164:167], v[222:225], v[74:77]
	s_setprio 0
	s_setprio 1
	v_mfma_f32_16x16x32_bf16 v[118:121], v[168:171], v[184:187], v[118:121]
	v_mfma_f32_16x16x32_bf16 v[114:117], v[176:179], v[184:187], v[114:117]
	v_mfma_f32_16x16x32_bf16 v[102:105], v[168:171], v[192:195], v[102:105]
	v_mfma_f32_16x16x32_bf16 v[98:101], v[176:179], v[192:195], v[98:101]
	v_mfma_f32_16x16x32_bf16 v[86:89], v[168:171], v[210:213], v[86:89]
	v_mfma_f32_16x16x32_bf16 v[82:85], v[176:179], v[210:213], v[82:85]
	v_mfma_f32_16x16x32_bf16 v[70:73], v[168:171], v[218:221], v[70:73]
	v_mfma_f32_16x16x32_bf16 v[66:69], v[176:179], v[218:221], v[66:69]
	v_mfma_f32_16x16x32_bf16 v[118:121], v[172:175], v[188:191], v[118:121]
	v_mfma_f32_16x16x32_bf16 v[114:117], v[180:183], v[188:191], v[114:117]
	v_mfma_f32_16x16x32_bf16 v[102:105], v[172:175], v[198:201], v[102:105]
	v_mfma_f32_16x16x32_bf16 v[98:101], v[180:183], v[198:201], v[98:101]
	v_mfma_f32_16x16x32_bf16 v[86:89], v[172:175], v[214:217], v[86:89]
	v_mfma_f32_16x16x32_bf16 v[82:85], v[180:183], v[214:217], v[82:85]
	v_mfma_f32_16x16x32_bf16 v[70:73], v[172:175], v[222:225], v[70:73]
	v_mfma_f32_16x16x32_bf16 v[66:69], v[180:183], v[222:225], v[66:69]
	s_setprio 0
	s_barrier
	s_add_i32 s19, s60, s33
	v_lshl_add_u64 v[144:145], s[34:35], 0, v[132:133]
	s_mov_b32 m0, s19
	ds_read_b128 v[184:187], v150 offset:16384
	ds_read_b128 v[188:191], v150 offset:17408
	ds_read_b128 v[192:195], v150 offset:18432
	ds_read_b128 v[198:201], v150 offset:19456
	ds_read_b128 v[210:213], v150 offset:20480
	ds_read_b128 v[214:217], v150 offset:21504
	ds_read_b128 v[218:221], v150 offset:22528
	ds_read_b128 v[222:225], v150 offset:23552
	global_load_lds_dwordx4 v[144:145], off sc0
	s_add_i32 m0, s19, 0x2000
	s_add_u32 s38, s34, 0x80000
	v_lshl_add_u64 v[202:203], s[34:35], 0, v[136:137]
	s_addc_u32 s39, s35, 0
	s_add_i32 s19, s61, s33
	global_load_lds_dwordx4 v[202:203], off sc0
	v_lshl_add_u64 v[206:207], s[38:39], 0, v[132:133]
	s_mov_b32 m0, s19
	v_lshl_add_u64 v[226:227], s[36:37], 0, v[134:135]
	global_load_lds_dwordx4 v[206:207], off sc0
	v_lshl_add_u64 v[206:207], s[38:39], 0, v[136:137]
	s_add_i32 m0, s19, 0x2000
	s_nop 0
	global_load_lds_dwordx4 v[206:207], off sc0
	v_lshl_add_u64 v[206:207], s[36:37], 0, v[130:131]
	s_mov_b32 m0, s27
	s_nop 0
	global_load_lds_dwordx4 v[206:207], off sc0
	s_mov_b32 m0, s41
	s_nop 0
	global_load_lds_dwordx4 v[226:227], off sc0
	s_waitcnt vmcnt(8)
	s_waitcnt lgkmcnt(0)
	s_barrier
	s_setprio 1
	s_waitcnt lgkmcnt(0)
	v_mfma_f32_16x16x32_bf16 v[62:65], v[152:155], v[184:187], v[62:65]
	v_mfma_f32_16x16x32_bf16 v[58:61], v[160:163], v[184:187], v[58:61]
	v_mfma_f32_16x16x32_bf16 v[46:49], v[152:155], v[192:195], v[46:49]
	v_mfma_f32_16x16x32_bf16 v[42:45], v[160:163], v[192:195], v[42:45]
	v_mfma_f32_16x16x32_bf16 v[30:33], v[152:155], v[210:213], v[30:33]
	v_mfma_f32_16x16x32_bf16 v[26:29], v[160:163], v[210:213], v[26:29]
	v_mfma_f32_16x16x32_bf16 v[14:17], v[152:155], v[218:221], v[14:17]
	v_mfma_f32_16x16x32_bf16 v[10:13], v[160:163], v[218:221], v[10:13]
	v_mfma_f32_16x16x32_bf16 v[62:65], v[156:159], v[188:191], v[62:65]
	v_mfma_f32_16x16x32_bf16 v[58:61], v[164:167], v[188:191], v[58:61]
	v_mfma_f32_16x16x32_bf16 v[46:49], v[156:159], v[198:201], v[46:49]
	v_mfma_f32_16x16x32_bf16 v[42:45], v[164:167], v[198:201], v[42:45]
	v_mfma_f32_16x16x32_bf16 v[30:33], v[156:159], v[214:217], v[30:33]
	v_mfma_f32_16x16x32_bf16 v[26:29], v[164:167], v[214:217], v[26:29]
	v_mfma_f32_16x16x32_bf16 v[14:17], v[156:159], v[222:225], v[14:17]
	v_mfma_f32_16x16x32_bf16 v[10:13], v[164:167], v[222:225], v[10:13]
	s_setprio 0
	s_setprio 1
	v_mfma_f32_16x16x32_bf16 v[54:57], v[168:171], v[184:187], v[54:57]
	v_mfma_f32_16x16x32_bf16 v[50:53], v[176:179], v[184:187], v[50:53]
	v_mfma_f32_16x16x32_bf16 v[38:41], v[168:171], v[192:195], v[38:41]
	v_mfma_f32_16x16x32_bf16 v[34:37], v[176:179], v[192:195], v[34:37]
	v_mfma_f32_16x16x32_bf16 v[22:25], v[168:171], v[210:213], v[22:25]
	v_mfma_f32_16x16x32_bf16 v[18:21], v[176:179], v[210:213], v[18:21]
	v_mfma_f32_16x16x32_bf16 v[6:9], v[168:171], v[218:221], v[6:9]
	v_mfma_f32_16x16x32_bf16 v[2:5], v[176:179], v[218:221], v[2:5]
	v_mfma_f32_16x16x32_bf16 v[54:57], v[172:175], v[188:191], v[54:57]
	v_mfma_f32_16x16x32_bf16 v[50:53], v[180:183], v[188:191], v[50:53]
	v_mfma_f32_16x16x32_bf16 v[38:41], v[172:175], v[198:201], v[38:41]
	v_mfma_f32_16x16x32_bf16 v[34:37], v[180:183], v[198:201], v[34:37]
	v_mfma_f32_16x16x32_bf16 v[22:25], v[172:175], v[214:217], v[22:25]
	v_mfma_f32_16x16x32_bf16 v[18:21], v[180:183], v[214:217], v[18:21]
	v_mfma_f32_16x16x32_bf16 v[6:9], v[172:175], v[222:225], v[6:9]
	v_mfma_f32_16x16x32_bf16 v[2:5], v[180:183], v[222:225], v[2:5]
	s_setprio 0
	s_barrier
	s_add_i32 s19, 0, 0x18000
	v_add_u32_e32 v151, s19, v146
	s_add_i32 s38, 0, 0x1c000
	ds_read_b128 v[152:155], v151
	ds_read_b128 v[156:159], v151 offset:1024
	ds_read_b128 v[160:163], v151 offset:2048
	ds_read_b128 v[164:167], v151 offset:3072
	v_add_u32_e32 v151, s38, v146
	ds_read_b128 v[168:171], v151
	ds_read_b128 v[172:175], v151 offset:1024
	ds_read_b128 v[176:179], v151 offset:2048
	ds_read_b128 v[180:183], v151 offset:3072
	s_add_u32 s36, s36, 0x80000
	s_addc_u32 s37, s37, 0
	s_mov_b32 m0, s42
	v_lshl_add_u64 v[228:229], s[36:37], 0, v[130:131]
	ds_read_b128 v[184:187], v150 offset:32768
	ds_read_b128 v[188:191], v150 offset:33792
	ds_read_b128 v[192:195], v150 offset:34816
	ds_read_b128 v[198:201], v150 offset:35840
	ds_read_b128 v[210:213], v150 offset:36864
	ds_read_b128 v[214:217], v150 offset:37888
	ds_read_b128 v[218:221], v150 offset:38912
	ds_read_b128 v[222:225], v150 offset:39936
	global_load_lds_dwordx4 v[228:229], off sc0
	v_lshl_add_u64 v[228:229], s[36:37], 0, v[134:135]
	s_mov_b32 m0, s43
	s_nop 0
	global_load_lds_dwordx4 v[228:229], off sc0
	s_waitcnt vmcnt(8)
	s_waitcnt lgkmcnt(0)
	s_barrier
	s_setprio 1
	s_waitcnt lgkmcnt(0)
	v_mfma_f32_16x16x32_bf16 v[126:129], v[152:155], v[184:187], v[126:129]
	v_mfma_f32_16x16x32_bf16 v[122:125], v[160:163], v[184:187], v[122:125]
	v_mfma_f32_16x16x32_bf16 v[110:113], v[152:155], v[192:195], v[110:113]
	v_mfma_f32_16x16x32_bf16 v[106:109], v[160:163], v[192:195], v[106:109]
	v_mfma_f32_16x16x32_bf16 v[94:97], v[152:155], v[210:213], v[94:97]
	v_mfma_f32_16x16x32_bf16 v[90:93], v[160:163], v[210:213], v[90:93]
	v_mfma_f32_16x16x32_bf16 v[78:81], v[152:155], v[218:221], v[78:81]
	v_mfma_f32_16x16x32_bf16 v[74:77], v[160:163], v[218:221], v[74:77]
	v_mfma_f32_16x16x32_bf16 v[126:129], v[156:159], v[188:191], v[126:129]
	v_mfma_f32_16x16x32_bf16 v[122:125], v[164:167], v[188:191], v[122:125]
	v_mfma_f32_16x16x32_bf16 v[110:113], v[156:159], v[198:201], v[110:113]
	v_mfma_f32_16x16x32_bf16 v[106:109], v[164:167], v[198:201], v[106:109]
	v_mfma_f32_16x16x32_bf16 v[94:97], v[156:159], v[214:217], v[94:97]
	v_mfma_f32_16x16x32_bf16 v[90:93], v[164:167], v[214:217], v[90:93]
	v_mfma_f32_16x16x32_bf16 v[78:81], v[156:159], v[222:225], v[78:81]
	v_mfma_f32_16x16x32_bf16 v[74:77], v[164:167], v[222:225], v[74:77]
	s_setprio 0
	s_setprio 1
	v_mfma_f32_16x16x32_bf16 v[118:121], v[168:171], v[184:187], v[118:121]
	v_mfma_f32_16x16x32_bf16 v[114:117], v[176:179], v[184:187], v[114:117]
	v_mfma_f32_16x16x32_bf16 v[102:105], v[168:171], v[192:195], v[102:105]
	v_mfma_f32_16x16x32_bf16 v[98:101], v[176:179], v[192:195], v[98:101]
	v_mfma_f32_16x16x32_bf16 v[86:89], v[168:171], v[210:213], v[86:89]
	v_mfma_f32_16x16x32_bf16 v[82:85], v[176:179], v[210:213], v[82:85]
	v_mfma_f32_16x16x32_bf16 v[70:73], v[168:171], v[218:221], v[70:73]
	v_mfma_f32_16x16x32_bf16 v[66:69], v[176:179], v[218:221], v[66:69]
	v_mfma_f32_16x16x32_bf16 v[118:121], v[172:175], v[188:191], v[118:121]
	v_mfma_f32_16x16x32_bf16 v[114:117], v[180:183], v[188:191], v[114:117]
	v_mfma_f32_16x16x32_bf16 v[102:105], v[172:175], v[198:201], v[102:105]
	v_mfma_f32_16x16x32_bf16 v[98:101], v[180:183], v[198:201], v[98:101]
	v_mfma_f32_16x16x32_bf16 v[86:89], v[172:175], v[214:217], v[86:89]
	v_mfma_f32_16x16x32_bf16 v[82:85], v[180:183], v[214:217], v[82:85]
	v_mfma_f32_16x16x32_bf16 v[70:73], v[172:175], v[222:225], v[70:73]
	v_mfma_f32_16x16x32_bf16 v[66:69], v[180:183], v[222:225], v[66:69]
	s_setprio 0
	s_barrier
	s_add_i32 s19, s19, s33
	v_lshl_add_u64 v[144:145], v[144:145], 0, s[10:11]
	s_mov_b32 m0, s19
	ds_read_b128 v[184:187], v150 offset:49152
	ds_read_b128 v[188:191], v150 offset:50176
	ds_read_b128 v[192:195], v150 offset:51200
	ds_read_b128 v[198:201], v150 offset:52224
	ds_read_b128 v[210:213], v150 offset:53248
	ds_read_b128 v[214:217], v150 offset:54272
	ds_read_b128 v[218:221], v150 offset:55296
	ds_read_b128 v[222:225], v150 offset:56320
	global_load_lds_dwordx4 v[144:145], off sc0
	s_add_i32 m0, s19, 0x2000
	s_add_u32 s34, s34, 0x80080
	v_lshl_add_u64 v[144:145], v[202:203], 0, s[10:11]
	s_addc_u32 s35, s35, 0
	s_add_i32 s19, s38, s33
	global_load_lds_dwordx4 v[144:145], off sc0
	v_lshl_add_u64 v[144:145], s[34:35], 0, v[132:133]
	s_mov_b32 m0, s19
	s_nop 0
	global_load_lds_dwordx4 v[144:145], off sc0
	v_lshl_add_u64 v[144:145], s[34:35], 0, v[136:137]
	s_add_i32 m0, s19, 0x2000
	s_nop 0
	global_load_lds_dwordx4 v[144:145], off sc0
	v_lshl_add_u64 v[144:145], v[206:207], 0, s[10:11]
	s_mov_b32 m0, s51
	s_nop 0
	global_load_lds_dwordx4 v[144:145], off sc0
	v_lshl_add_u64 v[144:145], v[226:227], 0, s[10:11]
	s_mov_b32 m0, s52
	s_nop 0
	global_load_lds_dwordx4 v[144:145], off sc0
	s_waitcnt vmcnt(8)
	s_waitcnt lgkmcnt(0)
	s_barrier
	s_setprio 1
	s_waitcnt lgkmcnt(0)
	v_mfma_f32_16x16x32_bf16 v[62:65], v[152:155], v[184:187], v[62:65]
	v_mfma_f32_16x16x32_bf16 v[58:61], v[160:163], v[184:187], v[58:61]
	v_mfma_f32_16x16x32_bf16 v[46:49], v[152:155], v[192:195], v[46:49]
	v_mfma_f32_16x16x32_bf16 v[42:45], v[160:163], v[192:195], v[42:45]
	v_mfma_f32_16x16x32_bf16 v[30:33], v[152:155], v[210:213], v[30:33]
	v_mfma_f32_16x16x32_bf16 v[26:29], v[160:163], v[210:213], v[26:29]
	v_mfma_f32_16x16x32_bf16 v[14:17], v[152:155], v[218:221], v[14:17]
	v_mfma_f32_16x16x32_bf16 v[10:13], v[160:163], v[218:221], v[10:13]
	v_mfma_f32_16x16x32_bf16 v[62:65], v[156:159], v[188:191], v[62:65]
	v_mfma_f32_16x16x32_bf16 v[58:61], v[164:167], v[188:191], v[58:61]
	v_mfma_f32_16x16x32_bf16 v[46:49], v[156:159], v[198:201], v[46:49]
	v_mfma_f32_16x16x32_bf16 v[42:45], v[164:167], v[198:201], v[42:45]
	v_mfma_f32_16x16x32_bf16 v[30:33], v[156:159], v[214:217], v[30:33]
	v_mfma_f32_16x16x32_bf16 v[26:29], v[164:167], v[214:217], v[26:29]
	v_mfma_f32_16x16x32_bf16 v[14:17], v[156:159], v[222:225], v[14:17]
	v_mfma_f32_16x16x32_bf16 v[10:13], v[164:167], v[222:225], v[10:13]
	s_setprio 0
	s_setprio 1
	v_mfma_f32_16x16x32_bf16 v[54:57], v[168:171], v[184:187], v[54:57]
	v_mfma_f32_16x16x32_bf16 v[50:53], v[176:179], v[184:187], v[50:53]
	v_mfma_f32_16x16x32_bf16 v[38:41], v[168:171], v[192:195], v[38:41]
	v_mfma_f32_16x16x32_bf16 v[34:37], v[176:179], v[192:195], v[34:37]
	v_mfma_f32_16x16x32_bf16 v[22:25], v[168:171], v[210:213], v[22:25]
	v_mfma_f32_16x16x32_bf16 v[18:21], v[176:179], v[210:213], v[18:21]
	v_mfma_f32_16x16x32_bf16 v[6:9], v[168:171], v[218:221], v[6:9]
	v_mfma_f32_16x16x32_bf16 v[2:5], v[176:179], v[218:221], v[2:5]
	v_mfma_f32_16x16x32_bf16 v[54:57], v[172:175], v[188:191], v[54:57]
	v_mfma_f32_16x16x32_bf16 v[50:53], v[180:183], v[188:191], v[50:53]
	v_mfma_f32_16x16x32_bf16 v[38:41], v[172:175], v[198:201], v[38:41]
	v_mfma_f32_16x16x32_bf16 v[34:37], v[180:183], v[198:201], v[34:37]
	v_mfma_f32_16x16x32_bf16 v[22:25], v[172:175], v[214:217], v[22:25]
	v_mfma_f32_16x16x32_bf16 v[18:21], v[180:183], v[214:217], v[18:21]
	v_mfma_f32_16x16x32_bf16 v[6:9], v[172:175], v[222:225], v[6:9]
	v_mfma_f32_16x16x32_bf16 v[2:5], v[180:183], v[222:225], v[2:5]
	s_setprio 0
	s_barrier
	s_add_u32 s30, s30, 0x100
	s_addc_u32 s31, s31, 0
	s_add_u32 s15, s15, 0x100
	s_addc_u32 s17, s17, 0
	s_cmp_ge_i32 s29, s68
	s_mov_b32 s19, s29
	s_cbranch_scc0 .LBB0_2547

.LBB0_2669:
	v_lshrrev_b32_e32 v4, 1, v0
	v_and_b32_e32 v14, 24, v4
	v_lshrrev_b32_e32 v4, 5, v0
	v_lshlrev_b32_e32 v2, 4, v0
	v_and_b32_e32 v1, 32, v0
	v_and_b32_e32 v4, 4, v4
	v_bfe_u32 v5, v0, 2, 2
	v_bfe_u32 v3, v0, 2, 4
	v_bitop3_b32 v12, v2, v1, 48 bitop3:0x6c
	v_and_b32_e32 v13, 64, v0
	v_or3_b32 v4, v4, v5, v14
	v_lshrrev_b32_e32 v5, 3, v0
	v_or_b32_e32 v1, v12, v13
	v_and_or_b32 v6, v5, 48, v3
	v_and_or_b32 v5, v5, 32, v4
	v_lshrrev_b32_e32 v1, 1, v1
	v_mul_u32_u24_e32 v5, 0x1600, v5
	v_or_b32_e32 v5, v5, v1
	v_lshlrev_b32_e32 v132, 1, v5
	v_bfe_u32 v5, v0, 3, 25
	v_or_b32_e32 v5, 64, v5
	s_movk_i32 s9, 0x70
	s_add_u32 s2, s82, 0xf600000
	v_and_or_b32 v3, v5, s9, v3
	s_movk_i32 s9, 0x60
	s_addc_u32 s3, s83, 0
	v_and_or_b32 v4, v5, s9, v4
	s_ashr_i32 s9, s8, 31
	s_lshr_b32 s9, s9, 29
	s_add_i32 s9, s8, s9
	s_lshr_b32 s12, s14, 6
	s_ashr_i32 s10, s9, 3
	s_and_b32 s9, s9, -8
	s_lshr_b32 s7, s14, 8
	s_lshl_b32 s33, s12, 10
	s_sub_i32 s8, s8, s9
	s_cmp_lt_i32 s8, 0
	s_cselect_b32 s9, 49, 48
	s_mul_i32 s8, s9, s8
	s_add_i32 s8, s8, s10
	s_ashr_i32 s9, s8, 31
	s_lshr_b32 s9, s9, 26
	s_add_i32 s9, s8, s9
	s_ashr_i32 s10, s9, 6
	s_lshl_b32 s10, s10, 3
	s_sub_i32 s11, 48, s10
	v_mul_u32_u24_e32 v16, 0x1600, v3
	s_min_i32 s11, s11, 8
	v_or_b32_e32 v3, v16, v1
	s_abs_i32 s13, s11
	v_lshlrev_b32_e32 v134, 1, v3
	v_cvt_f32_u32_e32 v3, s13
	v_mul_u32_u24_e32 v15, 0x1600, v6
	v_mul_u32_u24_e32 v4, 0x1600, v4
	v_or_b32_e32 v6, v1, v15
	v_or_b32_e32 v1, v4, v1
	v_lshlrev_b32_e32 v136, 1, v1
	v_rcp_iflag_f32_e32 v1, v3
	s_sub_i32 s17, 0, s13
	s_andn2_b32 s9, s9, 63
	s_sub_i32 s8, s8, s9
	v_mul_f32_e32 v1, 0x4f7ffffe, v1
	v_cvt_u32_f32_e32 v1, v1
	s_abs_i32 s15, s8
	s_xor_b32 s9, s8, s11
	s_ashr_i32 s9, s9, 31
	v_readfirstlane_b32 s18, v1
	s_mul_i32 s17, s17, s18
	s_mul_hi_u32 s17, s18, s17
	s_add_i32 s18, s18, s17
	s_mul_hi_u32 s17, s15, s18
	s_mul_i32 s18, s17, s13
	s_sub_i32 s15, s15, s18
	s_add_i32 s18, s17, 1
	s_sub_i32 s19, s15, s13
	s_cmp_ge_u32 s15, s13
	s_cselect_b32 s17, s18, s17
	s_cselect_b32 s15, s19, s15
	s_add_i32 s18, s17, 1
	s_cmp_ge_u32 s15, s13
	s_cselect_b32 s13, s18, s17
	s_xor_b32 s13, s13, s9
	s_sub_i32 s66, s13, s9
	s_mul_i32 s9, s66, s11
	s_sub_i32 s8, s8, s9
	s_add_i32 s65, s10, s8
	s_mul_i32 s9, s65, 0x2c0000
	s_mul_hi_i32 s8, s65, 0x2c0000
	s_add_u32 s10, s72, s9
	s_addc_u32 s11, s73, s8
	s_mul_i32 s9, s66, 0x2c0000
	s_mul_hi_i32 s8, s66, 0x2c0000
	s_add_u32 s9, s2, s9
	s_addc_u32 s8, s3, s8
	s_add_u32 s26, s9, s0
	s_addc_u32 s27, s8, s1
	s_add_i32 s34, s33, 0
	s_add_i32 m0, s34, 0x10000
	v_lshlrev_b32_e32 v130, 1, v6
	global_load_lds_dwordx4 v132, s[26:27] sc0
	s_add_i32 m0, s34, 0x12000
	s_add_u32 s8, s26, 0x160000
	global_load_lds_dwordx4 v136, s[26:27] sc0
	s_addc_u32 s9, s27, 0
	s_add_i32 m0, s34, 0x14000
	v_mov_b32_e32 v133, 0
	global_load_lds_dwordx4 v132, s[8:9] sc0
	s_add_i32 m0, s34, 0x16000
	s_add_u32 s24, s10, s0
	s_addc_u32 s25, s11, s1
	s_add_i32 s35, s34, 0x2000
	global_load_lds_dwordx4 v136, s[8:9] sc0
	s_mov_b32 m0, s34
	s_add_u32 s0, s24, 0x160000
	global_load_lds_dwordx4 v130, s[24:25] sc0
	s_mov_b32 m0, s35
	s_addc_u32 s1, s25, 0
	s_add_i32 s36, s34, 0x4000
	global_load_lds_dwordx4 v134, s[24:25] sc0
	s_mov_b32 m0, s36
	s_add_i32 s37, s34, 0x6000
	global_load_lds_dwordx4 v130, s[0:1] sc0
	s_mov_b32 m0, s37
	v_mov_b32_e32 v137, v133
	global_load_lds_dwordx4 v134, s[0:1] sc0
	v_mov_b32_e32 v131, v133
	v_mov_b32_e32 v135, v133
	s_cmp_eq_u32 s7, 1
	s_mov_b32 s38, 0x10000
	v_lshl_add_u64 v[10:11], s[26:27], 0, v[132:133]
	v_lshl_add_u64 v[6:7], s[26:27], 0, v[136:137]
	s_mov_b32 s39, 0x12000
	s_mov_b32 s40, 0x14000
	s_mov_b32 s41, 0x16000
	v_lshl_add_u64 v[8:9], s[24:25], 0, v[130:131]
	v_lshl_add_u64 v[4:5], s[24:25], 0, v[134:135]
	s_movk_i32 s42, 0x2000
	s_movk_i32 s43, 0x4000
	s_cselect_b64 s[8:9], -1, 0
	s_cmp_lg_u32 s7, 1
	s_movk_i32 s44, 0x6000
	s_cbranch_scc1 .LBB0_2671
	s_barrier
.LBB0_2671:
	s_add_u32 s10, s82, 0x27100000
	s_addc_u32 s11, s83, 0
	s_add_u32 s45, s82, 0x2b2000
	s_addc_u32 s46, s83, 0
	s_lshl_b32 s0, s12, 5
	s_mov_b64 s[12:13], 0x80
	s_and_b32 s17, s0, 0x60
	s_add_i32 m0, s34, 0x18000
	v_lshl_add_u64 v[10:11], v[10:11], 0, s[12:13]
	s_lshl_b32 s15, s7, 13
	s_lshl_b32 s18, s17, 7
	s_waitcnt vmcnt(2)
	s_barrier
	global_load_lds_dwordx4 v[10:11], off sc0
	v_lshl_add_u64 v[6:7], v[6:7], 0, s[12:13]
	s_add_i32 m0, s34, 0x1a000
	s_add_i32 s47, s34, 0x8000
	s_add_i32 s48, s34, 0xa000
	global_load_lds_dwordx4 v[6:7], off sc0
	v_lshl_add_u64 v[6:7], v[8:9], 0, s[12:13]
	s_mov_b32 m0, s47
	s_add_u32 s0, s26, 0x160080
	global_load_lds_dwordx4 v[6:7], off sc0
	v_lshl_add_u64 v[4:5], v[4:5], 0, s[12:13]
	s_mov_b32 m0, s48
	s_addc_u32 s1, s27, 0
	global_load_lds_dwordx4 v[4:5], off sc0
	s_add_i32 m0, s34, 0x1c000
	v_lshl_add_u64 v[4:5], s[0:1], 0, v[132:133]
	global_load_lds_dwordx4 v[4:5], off sc0
	v_lshl_add_u64 v[4:5], s[0:1], 0, v[136:137]
	s_add_i32 m0, s34, 0x1e000
	v_lshlrev_b32_e32 v3, 1, v14
	global_load_lds_dwordx4 v[4:5], off sc0
	s_movk_i32 s0, 0x3c0
	v_readlane_b32 s1, v249, 0
	v_lshl_or_b32 v4, v205, 6, v3
	v_and_or_b32 v3, v209, s0, v3
	s_ashr_i32 s0, s1, 31
	s_lshr_b32 s0, s0, 25
	s_add_i32 s0, s1, s0
	s_ashr_i32 s55, s0, 7
	s_and_b32 s0, s0, 0xffffff80
	v_and_b32_e32 v5, 32, v196
	s_sub_i32 s54, s1, s0
	v_bitop3_b32 v168, s18, v3, v5 bitop3:0xf6
	s_addk_i32 s54, 0x100
	v_mov_b32_e32 v3, v133
	s_waitcnt vmcnt(6)
	s_cmpk_lt_u32 s14, 0x100
	v_lshl_add_u64 v[138:139], s[78:79], 0, v[2:3]
	v_add_u16_e32 v2, v12, v13
	v_lshl_or_b32 v1, s7, 6, v205
	v_bitop3_b32 v4, v4, s15, v5 bitop3:0xde
	s_mov_b32 s7, 0
	s_cselect_b64 s[14:15], -1, 0
	s_lshr_b32 s0, s16, 2
	v_lshrrev_b16_e32 v2, 1, v2
	s_add_i32 s57, 0, 0x10000
	s_add_i32 s58, 0, 0x14000
	s_mov_b32 s49, 0x18000
	s_mov_b32 s50, 0x1a000
	s_mov_b32 s51, 0x8000
	s_mov_b32 s52, 0xa000
	s_mov_b32 s53, 0x1c000
	s_mul_i32 s55, s55, 44
	s_xor_b32 s56, s0, 1
	v_or_b32_e32 v169, s17, v14
	v_add_lshl_u32 v140, v15, v2, 1
	v_mov_b32_e32 v141, v133
	v_add_lshl_u32 v142, v16, v2, 1
	v_mov_b32_e32 v143, v133
	s_mov_b64 s[22:23], -1
	v_add_u32_e32 v170, s57, v168
	v_add_u32_e32 v171, s58, v168
	v_add_u32_e32 v172, 0, v4
	s_mov_b32 s59, 0xc000
	s_mov_b32 s60, 0xe000
	s_mov_b32 s17, s7
	s_barrier
	s_branch .LBB0_2674

.Lpeel_0:
	ds_read_b128 v[144:147], v170
	ds_read_b128 v[148:151], v170 offset:1024
	ds_read_b128 v[152:155], v170 offset:2048
	ds_read_b128 v[156:159], v170 offset:3072
	ds_read_b128 v[160:163], v171
	ds_read_b128 v[164:167], v171 offset:1024
	ds_read_b128 v[174:177], v171 offset:2048
	ds_read_b128 v[178:181], v171 offset:3072
	s_add_i32 s30, s26, 2
	s_add_u32 s27, s24, 0xffea0080
	s_addc_u32 s28, s25, -1
	s_cmp_eq_u32 s22, s26
	s_cselect_b32 s26, s20, s17
	s_cselect_b32 s29, s19, s28
	s_cselect_b32 s28, s18, s27
	s_cselect_b32 s27, s21, s23
	v_lshl_add_u64 v[214:215], s[24:25], 0, v[140:141]
	s_add_i32 m0, s34, 0xc000
	ds_read_b128 v[182:185], v172
	ds_read_b128 v[186:189], v172 offset:1024
	ds_read_b128 v[190:193], v172 offset:2048
	ds_read_b128 v[194:197], v172 offset:3072
	ds_read_b128 v[198:201], v172 offset:4096
	ds_read_b128 v[202:205], v172 offset:5120
	ds_read_b128 v[206:209], v172 offset:6144
	ds_read_b128 v[210:213], v172 offset:7168
	global_load_lds_dwordx4 v[214:215], off sc0
	v_lshl_add_u64 v[214:215], s[24:25], 0, v[142:143]
	s_add_i32 m0, s34, 0xe000
	s_nop 0
	global_load_lds_dwordx4 v[214:215], off sc0
	s_waitcnt vmcnt(8)
	s_waitcnt lgkmcnt(0)
	s_barrier
	s_setprio 1
	s_waitcnt lgkmcnt(0)
	v_mfma_f32_16x16x32_bf16 v[126:129], v[144:147], v[182:185], 0
	v_mfma_f32_16x16x32_bf16 v[122:125], v[152:155], v[182:185], 0
	v_mfma_f32_16x16x32_bf16 v[118:121], v[144:147], v[190:193], 0
	v_mfma_f32_16x16x32_bf16 v[110:113], v[152:155], v[190:193], 0
	v_mfma_f32_16x16x32_bf16 v[94:97], v[144:147], v[198:201], 0
	v_mfma_f32_16x16x32_bf16 v[90:93], v[152:155], v[198:201], 0
	v_mfma_f32_16x16x32_bf16 v[82:85], v[144:147], v[206:209], 0
	v_mfma_f32_16x16x32_bf16 v[74:77], v[152:155], v[206:209], 0
	v_mfma_f32_16x16x32_bf16 v[126:129], v[148:151], v[186:189], v[126:129]
	v_mfma_f32_16x16x32_bf16 v[122:125], v[156:159], v[186:189], v[122:125]
	v_mfma_f32_16x16x32_bf16 v[118:121], v[148:151], v[194:197], v[118:121]
	v_mfma_f32_16x16x32_bf16 v[110:113], v[156:159], v[194:197], v[110:113]
	v_mfma_f32_16x16x32_bf16 v[94:97], v[148:151], v[202:205], v[94:97]
	v_mfma_f32_16x16x32_bf16 v[90:93], v[156:159], v[202:205], v[90:93]
	v_mfma_f32_16x16x32_bf16 v[82:85], v[148:151], v[210:213], v[82:85]
	v_mfma_f32_16x16x32_bf16 v[74:77], v[156:159], v[210:213], v[74:77]
	s_setprio 0
	s_setprio 1
	v_mfma_f32_16x16x32_bf16 v[114:117], v[160:163], v[182:185], 0
	v_mfma_f32_16x16x32_bf16 v[106:109], v[174:177], v[182:185], 0
	v_mfma_f32_16x16x32_bf16 v[102:105], v[160:163], v[190:193], 0
	v_mfma_f32_16x16x32_bf16 v[98:101], v[174:177], v[190:193], 0
	v_mfma_f32_16x16x32_bf16 v[86:89], v[160:163], v[198:201], 0
	v_mfma_f32_16x16x32_bf16 v[78:81], v[174:177], v[198:201], 0
	v_mfma_f32_16x16x32_bf16 v[70:73], v[160:163], v[206:209], 0
	v_mfma_f32_16x16x32_bf16 v[66:69], v[174:177], v[206:209], 0
	v_mfma_f32_16x16x32_bf16 v[114:117], v[164:167], v[186:189], v[114:117]
	v_mfma_f32_16x16x32_bf16 v[106:109], v[178:181], v[186:189], v[106:109]
	v_mfma_f32_16x16x32_bf16 v[102:105], v[164:167], v[194:197], v[102:105]
	v_mfma_f32_16x16x32_bf16 v[98:101], v[178:181], v[194:197], v[98:101]
	v_mfma_f32_16x16x32_bf16 v[86:89], v[164:167], v[202:205], v[86:89]
	v_mfma_f32_16x16x32_bf16 v[78:81], v[178:181], v[202:205], v[78:81]
	v_mfma_f32_16x16x32_bf16 v[70:73], v[164:167], v[210:213], v[70:73]
	v_mfma_f32_16x16x32_bf16 v[66:69], v[178:181], v[210:213], v[66:69]
	s_setprio 0
	s_barrier
	s_add_i32 s31, s57, s33
	v_lshl_add_u64 v[214:215], s[26:27], 0, v[132:133]
	s_mov_b32 m0, s31
	ds_read_b128 v[182:185], v172 offset:16384
	ds_read_b128 v[186:189], v172 offset:17408
	ds_read_b128 v[190:193], v172 offset:18432
	ds_read_b128 v[194:197], v172 offset:19456
	ds_read_b128 v[198:201], v172 offset:20480
	ds_read_b128 v[202:205], v172 offset:21504
	ds_read_b128 v[206:209], v172 offset:22528
	ds_read_b128 v[210:213], v172 offset:23552
	global_load_lds_dwordx4 v[214:215], off sc0
	s_add_i32 m0, s31, 0x2000
	s_add_u32 s68, s26, 0x160000
	v_lshl_add_u64 v[216:217], s[26:27], 0, v[136:137]
	s_addc_u32 s69, s27, 0
	s_add_i32 s31, s58, s33
	global_load_lds_dwordx4 v[216:217], off sc0
	v_lshl_add_u64 v[218:219], s[68:69], 0, v[132:133]
	s_mov_b32 m0, s31
	v_lshl_add_u64 v[220:221], s[28:29], 0, v[134:135]
	global_load_lds_dwordx4 v[218:219], off sc0
	v_lshl_add_u64 v[218:219], s[68:69], 0, v[136:137]
	s_add_i32 m0, s31, 0x2000
	s_nop 0
	global_load_lds_dwordx4 v[218:219], off sc0
	v_lshl_add_u64 v[218:219], s[28:29], 0, v[130:131]
	s_mov_b32 m0, s34
	s_nop 0
	global_load_lds_dwordx4 v[218:219], off sc0
	s_mov_b32 m0, s35
	s_nop 0
	global_load_lds_dwordx4 v[220:221], off sc0
	s_waitcnt vmcnt(8)
	s_waitcnt lgkmcnt(0)
	s_barrier
	s_setprio 1
	s_waitcnt lgkmcnt(0)
	v_mfma_f32_16x16x32_bf16 v[62:65], v[144:147], v[182:185], 0
	v_mfma_f32_16x16x32_bf16 v[58:61], v[152:155], v[182:185], 0
	v_mfma_f32_16x16x32_bf16 v[50:53], v[144:147], v[190:193], 0
	v_mfma_f32_16x16x32_bf16 v[42:45], v[152:155], v[190:193], 0
	v_mfma_f32_16x16x32_bf16 v[30:33], v[144:147], v[198:201], 0
	v_mfma_f32_16x16x32_bf16 v[26:29], v[152:155], v[198:201], 0
	v_mfma_f32_16x16x32_bf16 v[18:21], v[144:147], v[206:209], 0
	v_mfma_f32_16x16x32_bf16 v[10:13], v[152:155], v[206:209], 0
	v_mfma_f32_16x16x32_bf16 v[62:65], v[148:151], v[186:189], v[62:65]
	v_mfma_f32_16x16x32_bf16 v[58:61], v[156:159], v[186:189], v[58:61]
	v_mfma_f32_16x16x32_bf16 v[50:53], v[148:151], v[194:197], v[50:53]
	v_mfma_f32_16x16x32_bf16 v[42:45], v[156:159], v[194:197], v[42:45]
	v_mfma_f32_16x16x32_bf16 v[30:33], v[148:151], v[202:205], v[30:33]
	v_mfma_f32_16x16x32_bf16 v[26:29], v[156:159], v[202:205], v[26:29]
	v_mfma_f32_16x16x32_bf16 v[18:21], v[148:151], v[210:213], v[18:21]
	v_mfma_f32_16x16x32_bf16 v[10:13], v[156:159], v[210:213], v[10:13]
	s_setprio 0
	s_setprio 1
	v_mfma_f32_16x16x32_bf16 v[54:57], v[160:163], v[182:185], 0
	v_mfma_f32_16x16x32_bf16 v[46:49], v[174:177], v[182:185], 0
	v_mfma_f32_16x16x32_bf16 v[38:41], v[160:163], v[190:193], 0
	v_mfma_f32_16x16x32_bf16 v[34:37], v[174:177], v[190:193], 0
	v_mfma_f32_16x16x32_bf16 v[22:25], v[160:163], v[198:201], 0
	v_mfma_f32_16x16x32_bf16 v[14:17], v[174:177], v[198:201], 0
	v_mfma_f32_16x16x32_bf16 v[6:9], v[160:163], v[206:209], 0
	v_mfma_f32_16x16x32_bf16 v[2:5], v[174:177], v[206:209], 0
	v_mfma_f32_16x16x32_bf16 v[54:57], v[164:167], v[186:189], v[54:57]
	v_mfma_f32_16x16x32_bf16 v[46:49], v[178:181], v[186:189], v[46:49]
	v_mfma_f32_16x16x32_bf16 v[38:41], v[164:167], v[194:197], v[38:41]
	v_mfma_f32_16x16x32_bf16 v[34:37], v[178:181], v[194:197], v[34:37]
	v_mfma_f32_16x16x32_bf16 v[22:25], v[164:167], v[202:205], v[22:25]
	v_mfma_f32_16x16x32_bf16 v[14:17], v[178:181], v[202:205], v[14:17]
	v_mfma_f32_16x16x32_bf16 v[6:9], v[164:167], v[210:213], v[6:9]
	v_mfma_f32_16x16x32_bf16 v[2:5], v[178:181], v[210:213], v[2:5]
	s_setprio 0
	s_barrier
	s_add_i32 s31, 0, 0x18000
	s_add_i32 s68, 0, 0x1c000
	v_add_u32_e32 v156, s31, v168
	v_add_u32_e32 v173, s68, v168
	ds_read_b128 v[144:147], v156
	ds_read_b128 v[148:151], v156 offset:1024
	ds_read_b128 v[152:155], v156 offset:2048
	ds_read_b128 v[156:159], v156 offset:3072
	ds_read_b128 v[160:163], v173
	ds_read_b128 v[164:167], v173 offset:1024
	ds_read_b128 v[174:177], v173 offset:2048
	ds_read_b128 v[178:181], v173 offset:3072
	s_add_u32 s28, s28, 0x160000
	s_addc_u32 s29, s29, 0
	s_mov_b32 m0, s36
	v_lshl_add_u64 v[222:223], s[28:29], 0, v[130:131]
	ds_read_b128 v[182:185], v172 offset:32768
	ds_read_b128 v[186:189], v172 offset:33792
	ds_read_b128 v[190:193], v172 offset:34816
	ds_read_b128 v[194:197], v172 offset:35840
	ds_read_b128 v[198:201], v172 offset:36864
	ds_read_b128 v[202:205], v172 offset:37888
	ds_read_b128 v[206:209], v172 offset:38912
	ds_read_b128 v[210:213], v172 offset:39936
	global_load_lds_dwordx4 v[222:223], off sc0
	v_lshl_add_u64 v[222:223], s[28:29], 0, v[134:135]
	s_mov_b32 m0, s37
	s_nop 0
	global_load_lds_dwordx4 v[222:223], off sc0
	s_waitcnt vmcnt(8)
	s_waitcnt lgkmcnt(0)
	s_barrier
	s_setprio 1
	s_waitcnt lgkmcnt(0)
	v_mfma_f32_16x16x32_bf16 v[126:129], v[144:147], v[182:185], v[126:129]
	v_mfma_f32_16x16x32_bf16 v[122:125], v[152:155], v[182:185], v[122:125]
	v_mfma_f32_16x16x32_bf16 v[118:121], v[144:147], v[190:193], v[118:121]
	v_mfma_f32_16x16x32_bf16 v[110:113], v[152:155], v[190:193], v[110:113]
	v_mfma_f32_16x16x32_bf16 v[94:97], v[144:147], v[198:201], v[94:97]
	v_mfma_f32_16x16x32_bf16 v[90:93], v[152:155], v[198:201], v[90:93]
	v_mfma_f32_16x16x32_bf16 v[82:85], v[144:147], v[206:209], v[82:85]
	v_mfma_f32_16x16x32_bf16 v[74:77], v[152:155], v[206:209], v[74:77]
	v_mfma_f32_16x16x32_bf16 v[126:129], v[148:151], v[186:189], v[126:129]
	v_mfma_f32_16x16x32_bf16 v[122:125], v[156:159], v[186:189], v[122:125]
	v_mfma_f32_16x16x32_bf16 v[118:121], v[148:151], v[194:197], v[118:121]
	v_mfma_f32_16x16x32_bf16 v[110:113], v[156:159], v[194:197], v[110:113]
	v_mfma_f32_16x16x32_bf16 v[94:97], v[148:151], v[202:205], v[94:97]
	v_mfma_f32_16x16x32_bf16 v[90:93], v[156:159], v[202:205], v[90:93]
	v_mfma_f32_16x16x32_bf16 v[82:85], v[148:151], v[210:213], v[82:85]
	v_mfma_f32_16x16x32_bf16 v[74:77], v[156:159], v[210:213], v[74:77]
	s_setprio 0
	s_setprio 1
	v_mfma_f32_16x16x32_bf16 v[114:117], v[160:163], v[182:185], v[114:117]
	v_mfma_f32_16x16x32_bf16 v[106:109], v[174:177], v[182:185], v[106:109]
	v_mfma_f32_16x16x32_bf16 v[102:105], v[160:163], v[190:193], v[102:105]
	v_mfma_f32_16x16x32_bf16 v[98:101], v[174:177], v[190:193], v[98:101]
	v_mfma_f32_16x16x32_bf16 v[86:89], v[160:163], v[198:201], v[86:89]
	v_mfma_f32_16x16x32_bf16 v[78:81], v[174:177], v[198:201], v[78:81]
	v_mfma_f32_16x16x32_bf16 v[70:73], v[160:163], v[206:209], v[70:73]
	v_mfma_f32_16x16x32_bf16 v[66:69], v[174:177], v[206:209], v[66:69]
	v_mfma_f32_16x16x32_bf16 v[114:117], v[164:167], v[186:189], v[114:117]
	v_mfma_f32_16x16x32_bf16 v[106:109], v[178:181], v[186:189], v[106:109]
	v_mfma_f32_16x16x32_bf16 v[102:105], v[164:167], v[194:197], v[102:105]
	v_mfma_f32_16x16x32_bf16 v[98:101], v[178:181], v[194:197], v[98:101]
	v_mfma_f32_16x16x32_bf16 v[86:89], v[164:167], v[202:205], v[86:89]
	v_mfma_f32_16x16x32_bf16 v[78:81], v[178:181], v[202:205], v[78:81]
	v_mfma_f32_16x16x32_bf16 v[70:73], v[164:167], v[210:213], v[70:73]
	v_mfma_f32_16x16x32_bf16 v[66:69], v[178:181], v[210:213], v[66:69]
	s_setprio 0
	s_barrier
	s_add_i32 s28, s31, s33
	v_lshl_add_u64 v[214:215], v[214:215], 0, s[12:13]
	s_mov_b32 m0, s28
	ds_read_b128 v[182:185], v172 offset:49152
	ds_read_b128 v[186:189], v172 offset:50176
	ds_read_b128 v[190:193], v172 offset:51200
	ds_read_b128 v[194:197], v172 offset:52224
	ds_read_b128 v[198:201], v172 offset:53248
	ds_read_b128 v[202:205], v172 offset:54272
	ds_read_b128 v[206:209], v172 offset:55296
	ds_read_b128 v[210:213], v172 offset:56320
	global_load_lds_dwordx4 v[214:215], off sc0
	s_add_i32 m0, s28, 0x2000
	s_add_u32 s26, s26, 0x160080
	v_lshl_add_u64 v[214:215], v[216:217], 0, s[12:13]
	s_addc_u32 s27, s27, 0
	s_add_i32 s28, s68, s33
	global_load_lds_dwordx4 v[214:215], off sc0
	v_lshl_add_u64 v[214:215], s[26:27], 0, v[132:133]
	s_mov_b32 m0, s28
	s_nop 0
	global_load_lds_dwordx4 v[214:215], off sc0
	v_lshl_add_u64 v[214:215], s[26:27], 0, v[136:137]
	s_add_i32 m0, s28, 0x2000
	s_nop 0
	global_load_lds_dwordx4 v[214:215], off sc0
	v_lshl_add_u64 v[214:215], v[218:219], 0, s[12:13]
	s_mov_b32 m0, s47
	s_nop 0
	global_load_lds_dwordx4 v[214:215], off sc0
	v_lshl_add_u64 v[214:215], v[220:221], 0, s[12:13]
	s_mov_b32 m0, s48
	s_nop 0
	global_load_lds_dwordx4 v[214:215], off sc0
	s_waitcnt vmcnt(8)
	s_waitcnt lgkmcnt(0)
	s_barrier
	s_setprio 1
	s_waitcnt lgkmcnt(0)
	v_mfma_f32_16x16x32_bf16 v[62:65], v[144:147], v[182:185], v[62:65]
	v_mfma_f32_16x16x32_bf16 v[58:61], v[152:155], v[182:185], v[58:61]
	v_mfma_f32_16x16x32_bf16 v[50:53], v[144:147], v[190:193], v[50:53]
	v_mfma_f32_16x16x32_bf16 v[42:45], v[152:155], v[190:193], v[42:45]
	v_mfma_f32_16x16x32_bf16 v[30:33], v[144:147], v[198:201], v[30:33]
	v_mfma_f32_16x16x32_bf16 v[26:29], v[152:155], v[198:201], v[26:29]
	v_mfma_f32_16x16x32_bf16 v[18:21], v[144:147], v[206:209], v[18:21]
	v_mfma_f32_16x16x32_bf16 v[10:13], v[152:155], v[206:209], v[10:13]
	v_mfma_f32_16x16x32_bf16 v[62:65], v[148:151], v[186:189], v[62:65]
	v_mfma_f32_16x16x32_bf16 v[58:61], v[156:159], v[186:189], v[58:61]
	v_mfma_f32_16x16x32_bf16 v[50:53], v[148:151], v[194:197], v[50:53]
	v_mfma_f32_16x16x32_bf16 v[42:45], v[156:159], v[194:197], v[42:45]
	v_mfma_f32_16x16x32_bf16 v[30:33], v[148:151], v[202:205], v[30:33]
	v_mfma_f32_16x16x32_bf16 v[26:29], v[156:159], v[202:205], v[26:29]
	v_mfma_f32_16x16x32_bf16 v[18:21], v[148:151], v[210:213], v[18:21]
	v_mfma_f32_16x16x32_bf16 v[10:13], v[156:159], v[210:213], v[10:13]
	s_setprio 0
	s_setprio 1
	v_mfma_f32_16x16x32_bf16 v[54:57], v[160:163], v[182:185], v[54:57]
	v_mfma_f32_16x16x32_bf16 v[46:49], v[174:177], v[182:185], v[46:49]
	v_mfma_f32_16x16x32_bf16 v[38:41], v[160:163], v[190:193], v[38:41]
	v_mfma_f32_16x16x32_bf16 v[34:37], v[174:177], v[190:193], v[34:37]
	v_mfma_f32_16x16x32_bf16 v[22:25], v[160:163], v[198:201], v[22:25]
	v_mfma_f32_16x16x32_bf16 v[14:17], v[174:177], v[198:201], v[14:17]
	v_mfma_f32_16x16x32_bf16 v[6:9], v[160:163], v[206:209], v[6:9]
	v_mfma_f32_16x16x32_bf16 v[2:5], v[174:177], v[206:209], v[2:5]
	v_mfma_f32_16x16x32_bf16 v[54:57], v[164:167], v[186:189], v[54:57]
	v_mfma_f32_16x16x32_bf16 v[46:49], v[178:181], v[186:189], v[46:49]
	v_mfma_f32_16x16x32_bf16 v[38:41], v[164:167], v[194:197], v[38:41]
	v_mfma_f32_16x16x32_bf16 v[34:37], v[178:181], v[194:197], v[34:37]
	v_mfma_f32_16x16x32_bf16 v[22:25], v[164:167], v[202:205], v[22:25]
	v_mfma_f32_16x16x32_bf16 v[14:17], v[178:181], v[202:205], v[14:17]
	v_mfma_f32_16x16x32_bf16 v[6:9], v[164:167], v[210:213], v[6:9]
	v_mfma_f32_16x16x32_bf16 v[2:5], v[178:181], v[210:213], v[2:5]
	s_setprio 0
	s_barrier
	s_add_u32 s24, s24, 0x100
	s_addc_u32 s25, s25, 0
	s_add_u32 s17, s17, 0x100
	s_addc_u32 s23, s23, 0
	s_cmp_ge_i32 s30, s67
	s_mov_b32 s26, s30
	s_cbranch_scc0 .LBB0_2683
	s_branch .Lpeeldone_0
.LBB0_2683:
	ds_read_b128 v[144:147], v170
	ds_read_b128 v[148:151], v170 offset:1024
	ds_read_b128 v[152:155], v170 offset:2048
	ds_read_b128 v[156:159], v170 offset:3072
	ds_read_b128 v[160:163], v171
	ds_read_b128 v[164:167], v171 offset:1024
	ds_read_b128 v[174:177], v171 offset:2048
	ds_read_b128 v[178:181], v171 offset:3072
	s_add_i32 s30, s26, 2
	s_add_u32 s27, s24, 0xffea0080
	s_addc_u32 s28, s25, -1
	s_cmp_eq_u32 s22, s26
	s_cselect_b32 s26, s20, s17
	s_cselect_b32 s29, s19, s28
	s_cselect_b32 s28, s18, s27
	s_cselect_b32 s27, s21, s23
	v_lshl_add_u64 v[214:215], s[24:25], 0, v[140:141]
	s_add_i32 m0, s34, 0xc000
	ds_read_b128 v[182:185], v172
	ds_read_b128 v[186:189], v172 offset:1024
	ds_read_b128 v[190:193], v172 offset:2048
	ds_read_b128 v[194:197], v172 offset:3072
	ds_read_b128 v[198:201], v172 offset:4096
	ds_read_b128 v[202:205], v172 offset:5120
	ds_read_b128 v[206:209], v172 offset:6144
	ds_read_b128 v[210:213], v172 offset:7168
	global_load_lds_dwordx4 v[214:215], off sc0
	v_lshl_add_u64 v[214:215], s[24:25], 0, v[142:143]
	s_add_i32 m0, s34, 0xe000
	s_nop 0
	global_load_lds_dwordx4 v[214:215], off sc0
	s_waitcnt vmcnt(8)
	s_waitcnt lgkmcnt(0)
	s_barrier
	s_setprio 1
	s_waitcnt lgkmcnt(0)
	v_mfma_f32_16x16x32_bf16 v[126:129], v[144:147], v[182:185], v[126:129]
	v_mfma_f32_16x16x32_bf16 v[122:125], v[152:155], v[182:185], v[122:125]
	v_mfma_f32_16x16x32_bf16 v[118:121], v[144:147], v[190:193], v[118:121]
	v_mfma_f32_16x16x32_bf16 v[110:113], v[152:155], v[190:193], v[110:113]
	v_mfma_f32_16x16x32_bf16 v[94:97], v[144:147], v[198:201], v[94:97]
	v_mfma_f32_16x16x32_bf16 v[90:93], v[152:155], v[198:201], v[90:93]
	v_mfma_f32_16x16x32_bf16 v[82:85], v[144:147], v[206:209], v[82:85]
	v_mfma_f32_16x16x32_bf16 v[74:77], v[152:155], v[206:209], v[74:77]
	v_mfma_f32_16x16x32_bf16 v[126:129], v[148:151], v[186:189], v[126:129]
	v_mfma_f32_16x16x32_bf16 v[122:125], v[156:159], v[186:189], v[122:125]
	v_mfma_f32_16x16x32_bf16 v[118:121], v[148:151], v[194:197], v[118:121]
	v_mfma_f32_16x16x32_bf16 v[110:113], v[156:159], v[194:197], v[110:113]
	v_mfma_f32_16x16x32_bf16 v[94:97], v[148:151], v[202:205], v[94:97]
	v_mfma_f32_16x16x32_bf16 v[90:93], v[156:159], v[202:205], v[90:93]
	v_mfma_f32_16x16x32_bf16 v[82:85], v[148:151], v[210:213], v[82:85]
	v_mfma_f32_16x16x32_bf16 v[74:77], v[156:159], v[210:213], v[74:77]
	s_setprio 0
	s_setprio 1
	v_mfma_f32_16x16x32_bf16 v[114:117], v[160:163], v[182:185], v[114:117]
	v_mfma_f32_16x16x32_bf16 v[106:109], v[174:177], v[182:185], v[106:109]
	v_mfma_f32_16x16x32_bf16 v[102:105], v[160:163], v[190:193], v[102:105]
	v_mfma_f32_16x16x32_bf16 v[98:101], v[174:177], v[190:193], v[98:101]
	v_mfma_f32_16x16x32_bf16 v[86:89], v[160:163], v[198:201], v[86:89]
	v_mfma_f32_16x16x32_bf16 v[78:81], v[174:177], v[198:201], v[78:81]
	v_mfma_f32_16x16x32_bf16 v[70:73], v[160:163], v[206:209], v[70:73]
	v_mfma_f32_16x16x32_bf16 v[66:69], v[174:177], v[206:209], v[66:69]
	v_mfma_f32_16x16x32_bf16 v[114:117], v[164:167], v[186:189], v[114:117]
	v_mfma_f32_16x16x32_bf16 v[106:109], v[178:181], v[186:189], v[106:109]
	v_mfma_f32_16x16x32_bf16 v[102:105], v[164:167], v[194:197], v[102:105]
	v_mfma_f32_16x16x32_bf16 v[98:101], v[178:181], v[194:197], v[98:101]
	v_mfma_f32_16x16x32_bf16 v[86:89], v[164:167], v[202:205], v[86:89]
	v_mfma_f32_16x16x32_bf16 v[78:81], v[178:181], v[202:205], v[78:81]
	v_mfma_f32_16x16x32_bf16 v[70:73], v[164:167], v[210:213], v[70:73]
	v_mfma_f32_16x16x32_bf16 v[66:69], v[178:181], v[210:213], v[66:69]
	s_setprio 0
	s_barrier
	s_add_i32 s31, s57, s33
	v_lshl_add_u64 v[214:215], s[26:27], 0, v[132:133]
	s_mov_b32 m0, s31
	ds_read_b128 v[182:185], v172 offset:16384
	ds_read_b128 v[186:189], v172 offset:17408
	ds_read_b128 v[190:193], v172 offset:18432
	ds_read_b128 v[194:197], v172 offset:19456
	ds_read_b128 v[198:201], v172 offset:20480
	ds_read_b128 v[202:205], v172 offset:21504
	ds_read_b128 v[206:209], v172 offset:22528
	ds_read_b128 v[210:213], v172 offset:23552
	global_load_lds_dwordx4 v[214:215], off sc0
	s_add_i32 m0, s31, 0x2000
	s_add_u32 s68, s26, 0x160000
	v_lshl_add_u64 v[216:217], s[26:27], 0, v[136:137]
	s_addc_u32 s69, s27, 0
	s_add_i32 s31, s58, s33
	global_load_lds_dwordx4 v[216:217], off sc0
	v_lshl_add_u64 v[218:219], s[68:69], 0, v[132:133]
	s_mov_b32 m0, s31
	v_lshl_add_u64 v[220:221], s[28:29], 0, v[134:135]
	global_load_lds_dwordx4 v[218:219], off sc0
	v_lshl_add_u64 v[218:219], s[68:69], 0, v[136:137]
	s_add_i32 m0, s31, 0x2000
	s_nop 0
	global_load_lds_dwordx4 v[218:219], off sc0
	v_lshl_add_u64 v[218:219], s[28:29], 0, v[130:131]
	s_mov_b32 m0, s34
	s_nop 0
	global_load_lds_dwordx4 v[218:219], off sc0
	s_mov_b32 m0, s35
	s_nop 0
	global_load_lds_dwordx4 v[220:221], off sc0
	s_waitcnt vmcnt(8)
	s_waitcnt lgkmcnt(0)
	s_barrier
	s_setprio 1
	s_waitcnt lgkmcnt(0)
	v_mfma_f32_16x16x32_bf16 v[62:65], v[144:147], v[182:185], v[62:65]
	v_mfma_f32_16x16x32_bf16 v[58:61], v[152:155], v[182:185], v[58:61]
	v_mfma_f32_16x16x32_bf16 v[50:53], v[144:147], v[190:193], v[50:53]
	v_mfma_f32_16x16x32_bf16 v[42:45], v[152:155], v[190:193], v[42:45]
	v_mfma_f32_16x16x32_bf16 v[30:33], v[144:147], v[198:201], v[30:33]
	v_mfma_f32_16x16x32_bf16 v[26:29], v[152:155], v[198:201], v[26:29]
	v_mfma_f32_16x16x32_bf16 v[18:21], v[144:147], v[206:209], v[18:21]
	v_mfma_f32_16x16x32_bf16 v[10:13], v[152:155], v[206:209], v[10:13]
	v_mfma_f32_16x16x32_bf16 v[62:65], v[148:151], v[186:189], v[62:65]
	v_mfma_f32_16x16x32_bf16 v[58:61], v[156:159], v[186:189], v[58:61]
	v_mfma_f32_16x16x32_bf16 v[50:53], v[148:151], v[194:197], v[50:53]
	v_mfma_f32_16x16x32_bf16 v[42:45], v[156:159], v[194:197], v[42:45]
	v_mfma_f32_16x16x32_bf16 v[30:33], v[148:151], v[202:205], v[30:33]
	v_mfma_f32_16x16x32_bf16 v[26:29], v[156:159], v[202:205], v[26:29]
	v_mfma_f32_16x16x32_bf16 v[18:21], v[148:151], v[210:213], v[18:21]
	v_mfma_f32_16x16x32_bf16 v[10:13], v[156:159], v[210:213], v[10:13]
	s_setprio 0
	s_setprio 1
	v_mfma_f32_16x16x32_bf16 v[54:57], v[160:163], v[182:185], v[54:57]
	v_mfma_f32_16x16x32_bf16 v[46:49], v[174:177], v[182:185], v[46:49]
	v_mfma_f32_16x16x32_bf16 v[38:41], v[160:163], v[190:193], v[38:41]
	v_mfma_f32_16x16x32_bf16 v[34:37], v[174:177], v[190:193], v[34:37]
	v_mfma_f32_16x16x32_bf16 v[22:25], v[160:163], v[198:201], v[22:25]
	v_mfma_f32_16x16x32_bf16 v[14:17], v[174:177], v[198:201], v[14:17]
	v_mfma_f32_16x16x32_bf16 v[6:9], v[160:163], v[206:209], v[6:9]
	v_mfma_f32_16x16x32_bf16 v[2:5], v[174:177], v[206:209], v[2:5]
	v_mfma_f32_16x16x32_bf16 v[54:57], v[164:167], v[186:189], v[54:57]
	v_mfma_f32_16x16x32_bf16 v[46:49], v[178:181], v[186:189], v[46:49]
	v_mfma_f32_16x16x32_bf16 v[38:41], v[164:167], v[194:197], v[38:41]
	v_mfma_f32_16x16x32_bf16 v[34:37], v[178:181], v[194:197], v[34:37]
	v_mfma_f32_16x16x32_bf16 v[22:25], v[164:167], v[202:205], v[22:25]
	v_mfma_f32_16x16x32_bf16 v[14:17], v[178:181], v[202:205], v[14:17]
	v_mfma_f32_16x16x32_bf16 v[6:9], v[164:167], v[210:213], v[6:9]
	v_mfma_f32_16x16x32_bf16 v[2:5], v[178:181], v[210:213], v[2:5]
	s_setprio 0
	s_barrier
	s_add_i32 s31, 0, 0x18000
	s_add_i32 s68, 0, 0x1c000
	v_add_u32_e32 v156, s31, v168
	v_add_u32_e32 v173, s68, v168
	ds_read_b128 v[144:147], v156
	ds_read_b128 v[148:151], v156 offset:1024
	ds_read_b128 v[152:155], v156 offset:2048
	ds_read_b128 v[156:159], v156 offset:3072
	ds_read_b128 v[160:163], v173
	ds_read_b128 v[164:167], v173 offset:1024
	ds_read_b128 v[174:177], v173 offset:2048
	ds_read_b128 v[178:181], v173 offset:3072
	s_add_u32 s28, s28, 0x160000
	s_addc_u32 s29, s29, 0
	s_mov_b32 m0, s36
	v_lshl_add_u64 v[222:223], s[28:29], 0, v[130:131]
	ds_read_b128 v[182:185], v172 offset:32768
	ds_read_b128 v[186:189], v172 offset:33792
	ds_read_b128 v[190:193], v172 offset:34816
	ds_read_b128 v[194:197], v172 offset:35840
	ds_read_b128 v[198:201], v172 offset:36864
	ds_read_b128 v[202:205], v172 offset:37888
	ds_read_b128 v[206:209], v172 offset:38912
	ds_read_b128 v[210:213], v172 offset:39936
	global_load_lds_dwordx4 v[222:223], off sc0
	v_lshl_add_u64 v[222:223], s[28:29], 0, v[134:135]
	s_mov_b32 m0, s37
	s_nop 0
	global_load_lds_dwordx4 v[222:223], off sc0
	s_waitcnt vmcnt(8)
	s_waitcnt lgkmcnt(0)
	s_barrier
	s_setprio 1
	s_waitcnt lgkmcnt(0)
	v_mfma_f32_16x16x32_bf16 v[126:129], v[144:147], v[182:185], v[126:129]
	v_mfma_f32_16x16x32_bf16 v[122:125], v[152:155], v[182:185], v[122:125]
	v_mfma_f32_16x16x32_bf16 v[118:121], v[144:147], v[190:193], v[118:121]
	v_mfma_f32_16x16x32_bf16 v[110:113], v[152:155], v[190:193], v[110:113]
	v_mfma_f32_16x16x32_bf16 v[94:97], v[144:147], v[198:201], v[94:97]
	v_mfma_f32_16x16x32_bf16 v[90:93], v[152:155], v[198:201], v[90:93]
	v_mfma_f32_16x16x32_bf16 v[82:85], v[144:147], v[206:209], v[82:85]
	v_mfma_f32_16x16x32_bf16 v[74:77], v[152:155], v[206:209], v[74:77]
	v_mfma_f32_16x16x32_bf16 v[126:129], v[148:151], v[186:189], v[126:129]
	v_mfma_f32_16x16x32_bf16 v[122:125], v[156:159], v[186:189], v[122:125]
	v_mfma_f32_16x16x32_bf16 v[118:121], v[148:151], v[194:197], v[118:121]
	v_mfma_f32_16x16x32_bf16 v[110:113], v[156:159], v[194:197], v[110:113]
	v_mfma_f32_16x16x32_bf16 v[94:97], v[148:151], v[202:205], v[94:97]
	v_mfma_f32_16x16x32_bf16 v[90:93], v[156:159], v[202:205], v[90:93]
	v_mfma_f32_16x16x32_bf16 v[82:85], v[148:151], v[210:213], v[82:85]
	v_mfma_f32_16x16x32_bf16 v[74:77], v[156:159], v[210:213], v[74:77]
	s_setprio 0
	s_setprio 1
	v_mfma_f32_16x16x32_bf16 v[114:117], v[160:163], v[182:185], v[114:117]
	v_mfma_f32_16x16x32_bf16 v[106:109], v[174:177], v[182:185], v[106:109]
	v_mfma_f32_16x16x32_bf16 v[102:105], v[160:163], v[190:193], v[102:105]
	v_mfma_f32_16x16x32_bf16 v[98:101], v[174:177], v[190:193], v[98:101]
	v_mfma_f32_16x16x32_bf16 v[86:89], v[160:163], v[198:201], v[86:89]
	v_mfma_f32_16x16x32_bf16 v[78:81], v[174:177], v[198:201], v[78:81]
	v_mfma_f32_16x16x32_bf16 v[70:73], v[160:163], v[206:209], v[70:73]
	v_mfma_f32_16x16x32_bf16 v[66:69], v[174:177], v[206:209], v[66:69]
	v_mfma_f32_16x16x32_bf16 v[114:117], v[164:167], v[186:189], v[114:117]
	v_mfma_f32_16x16x32_bf16 v[106:109], v[178:181], v[186:189], v[106:109]
	v_mfma_f32_16x16x32_bf16 v[102:105], v[164:167], v[194:197], v[102:105]
	v_mfma_f32_16x16x32_bf16 v[98:101], v[178:181], v[194:197], v[98:101]
	v_mfma_f32_16x16x32_bf16 v[86:89], v[164:167], v[202:205], v[86:89]
	v_mfma_f32_16x16x32_bf16 v[78:81], v[178:181], v[202:205], v[78:81]
	v_mfma_f32_16x16x32_bf16 v[70:73], v[164:167], v[210:213], v[70:73]
	v_mfma_f32_16x16x32_bf16 v[66:69], v[178:181], v[210:213], v[66:69]
	s_setprio 0
	s_barrier
	s_add_i32 s28, s31, s33
	v_lshl_add_u64 v[214:215], v[214:215], 0, s[12:13]
	s_mov_b32 m0, s28
	ds_read_b128 v[182:185], v172 offset:49152
	ds_read_b128 v[186:189], v172 offset:50176
	ds_read_b128 v[190:193], v172 offset:51200
	ds_read_b128 v[194:197], v172 offset:52224
	ds_read_b128 v[198:201], v172 offset:53248
	ds_read_b128 v[202:205], v172 offset:54272
	ds_read_b128 v[206:209], v172 offset:55296
	ds_read_b128 v[210:213], v172 offset:56320
	global_load_lds_dwordx4 v[214:215], off sc0
	s_add_i32 m0, s28, 0x2000
	s_add_u32 s26, s26, 0x160080
	v_lshl_add_u64 v[214:215], v[216:217], 0, s[12:13]
	s_addc_u32 s27, s27, 0
	s_add_i32 s28, s68, s33
	global_load_lds_dwordx4 v[214:215], off sc0
	v_lshl_add_u64 v[214:215], s[26:27], 0, v[132:133]
	s_mov_b32 m0, s28
	s_nop 0
	global_load_lds_dwordx4 v[214:215], off sc0
	v_lshl_add_u64 v[214:215], s[26:27], 0, v[136:137]
	s_add_i32 m0, s28, 0x2000
	s_nop 0
	global_load_lds_dwordx4 v[214:215], off sc0
	v_lshl_add_u64 v[214:215], v[218:219], 0, s[12:13]
	s_mov_b32 m0, s47
	s_nop 0
	global_load_lds_dwordx4 v[214:215], off sc0
	v_lshl_add_u64 v[214:215], v[220:221], 0, s[12:13]
	s_mov_b32 m0, s48
	s_nop 0
	global_load_lds_dwordx4 v[214:215], off sc0
	s_waitcnt vmcnt(8)
	s_waitcnt lgkmcnt(0)
	s_barrier
	s_setprio 1
	s_waitcnt lgkmcnt(0)
	v_mfma_f32_16x16x32_bf16 v[62:65], v[144:147], v[182:185], v[62:65]
	v_mfma_f32_16x16x32_bf16 v[58:61], v[152:155], v[182:185], v[58:61]
	v_mfma_f32_16x16x32_bf16 v[50:53], v[144:147], v[190:193], v[50:53]
	v_mfma_f32_16x16x32_bf16 v[42:45], v[152:155], v[190:193], v[42:45]
	v_mfma_f32_16x16x32_bf16 v[30:33], v[144:147], v[198:201], v[30:33]
	v_mfma_f32_16x16x32_bf16 v[26:29], v[152:155], v[198:201], v[26:29]
	v_mfma_f32_16x16x32_bf16 v[18:21], v[144:147], v[206:209], v[18:21]
	v_mfma_f32_16x16x32_bf16 v[10:13], v[152:155], v[206:209], v[10:13]
	v_mfma_f32_16x16x32_bf16 v[62:65], v[148:151], v[186:189], v[62:65]
	v_mfma_f32_16x16x32_bf16 v[58:61], v[156:159], v[186:189], v[58:61]
	v_mfma_f32_16x16x32_bf16 v[50:53], v[148:151], v[194:197], v[50:53]
	v_mfma_f32_16x16x32_bf16 v[42:45], v[156:159], v[194:197], v[42:45]
	v_mfma_f32_16x16x32_bf16 v[30:33], v[148:151], v[202:205], v[30:33]
	v_mfma_f32_16x16x32_bf16 v[26:29], v[156:159], v[202:205], v[26:29]
	v_mfma_f32_16x16x32_bf16 v[18:21], v[148:151], v[210:213], v[18:21]
	v_mfma_f32_16x16x32_bf16 v[10:13], v[156:159], v[210:213], v[10:13]
	s_setprio 0
	s_setprio 1
	v_mfma_f32_16x16x32_bf16 v[54:57], v[160:163], v[182:185], v[54:57]
	v_mfma_f32_16x16x32_bf16 v[46:49], v[174:177], v[182:185], v[46:49]
	v_mfma_f32_16x16x32_bf16 v[38:41], v[160:163], v[190:193], v[38:41]
	v_mfma_f32_16x16x32_bf16 v[34:37], v[174:177], v[190:193], v[34:37]
	v_mfma_f32_16x16x32_bf16 v[22:25], v[160:163], v[198:201], v[22:25]
	v_mfma_f32_16x16x32_bf16 v[14:17], v[174:177], v[198:201], v[14:17]
	v_mfma_f32_16x16x32_bf16 v[6:9], v[160:163], v[206:209], v[6:9]
	v_mfma_f32_16x16x32_bf16 v[2:5], v[174:177], v[206:209], v[2:5]
	v_mfma_f32_16x16x32_bf16 v[54:57], v[164:167], v[186:189], v[54:57]
	v_mfma_f32_16x16x32_bf16 v[46:49], v[178:181], v[186:189], v[46:49]
	v_mfma_f32_16x16x32_bf16 v[38:41], v[164:167], v[194:197], v[38:41]
	v_mfma_f32_16x16x32_bf16 v[34:37], v[178:181], v[194:197], v[34:37]
	v_mfma_f32_16x16x32_bf16 v[22:25], v[164:167], v[202:205], v[22:25]
	v_mfma_f32_16x16x32_bf16 v[14:17], v[178:181], v[202:205], v[14:17]
	v_mfma_f32_16x16x32_bf16 v[6:9], v[164:167], v[210:213], v[6:9]
	v_mfma_f32_16x16x32_bf16 v[2:5], v[178:181], v[210:213], v[2:5]
	s_setprio 0
	s_barrier
	s_add_u32 s24, s24, 0x100
	s_addc_u32 s25, s25, 0
	s_add_u32 s17, s17, 0x100
	s_addc_u32 s23, s23, 0
	s_cmp_ge_i32 s30, s67
	s_mov_b32 s26, s30
	s_cbranch_scc0 .LBB0_2683
